# layer-0 U-table fp4 conversion overlapped with the phase-3 item loop (one row per item, load waited by the next item's input wait); phase 4 converts the V table only; P2 decay epilogue keeps w0[col] i
# speedup vs baseline: 1.0112x; 1.0112x over previous
.LBB0_838:
	s_andn2_b64 vcc, exec, s[20:21]
	s_cbranch_vccnz .LBB0_840
	v_or_b32_e32 v98, s33, v160
	v_readlane_b32 s44, v245, 28
	v_lshlrev_b64 v[70:71], 2, v[98:99]
	v_readlane_b32 s52, v245, 36
	v_readlane_b32 s53, v245, 37
	v_lshlrev_b64 v[128:129], 12, v[128:129]
	v_lshlrev_b64 v[130:131], 12, v[130:131]
	v_lshl_add_u64 v[66:67], s[52:53], 0, v[70:71]
	global_load_dword v188, v[66:67], off
	v_lshl_add_u64 v[70:71], s[16:17], 0, v[70:71]
	v_lshlrev_b64 v[132:133], 12, v[132:133]
	v_lshlrev_b64 v[134:135], 12, v[134:135]
	v_lshlrev_b64 v[136:137], 12, v[136:137]
	v_lshlrev_b64 v[138:139], 12, v[138:139]
	v_lshlrev_b64 v[140:141], 12, v[140:141]
	v_lshlrev_b64 v[142:143], 12, v[142:143]
	v_lshlrev_b64 v[144:145], 12, v[144:145]
	v_or_b32_e32 v98, 32, v98
	v_readlane_b32 s45, v245, 29
	v_readlane_b32 s46, v245, 30
	v_readlane_b32 s47, v245, 31
	v_readlane_b32 s48, v245, 32
	v_readlane_b32 s49, v245, 33
	v_readlane_b32 s50, v245, 34
	v_readlane_b32 s51, v245, 35
	v_readlane_b32 s54, v245, 38
	v_readlane_b32 s55, v245, 39
	v_readlane_b32 s56, v245, 40
	v_readlane_b32 s57, v245, 41
	v_readlane_b32 s58, v245, 42
	v_readlane_b32 s59, v245, 43
	s_waitcnt vmcnt(0)
	v_mov_b32_e32 v240, v188
	v_add_f32_e32 v188, v50, v188
	v_max_f32_e64 v50, -v188, 0
	v_mul_f32_e64 v188, |v188|, s30
	v_exp_f32_e32 v188, v188
	s_nop 0
	v_add_f32_e32 v189, 1.0, v188
	v_add_f32_e32 v190, -1.0, v189
	v_sub_f32_e32 v191, v190, v189
	v_add_f32_e32 v191, 1.0, v191
	v_sub_f32_e32 v190, v188, v190
	v_add_f32_e32 v192, v190, v191
	v_frexp_mant_f32_e32 v190, v189
	v_cmp_gt_f32_e32 vcc, s31, v190
	v_cvt_f64_f32_e32 v[190:191], v189
	v_frexp_exp_i32_f64_e32 v190, v[190:191]
	v_subbrev_co_u32_e32 v190, vcc, 0, v190, vcc
	v_sub_u32_e32 v191, 0, v190
	v_ldexp_f32 v189, v189, v191
	v_ldexp_f32 v191, v192, v191
	v_add_f32_e32 v192, -1.0, v189
	v_add_f32_e32 v193, 1.0, v192
	v_sub_f32_e32 v193, v189, v193
	v_add_f32_e32 v193, v191, v193
	v_add_f32_e32 v194, v192, v193
	v_sub_f32_e32 v192, v194, v192
	v_sub_f32_e32 v192, v193, v192
	v_add_f32_e32 v193, 1.0, v189
	v_add_f32_e32 v195, -1.0, v193
	v_sub_f32_e32 v189, v189, v195
	v_add_f32_e32 v189, v191, v189
	v_add_f32_e32 v191, v193, v189
	v_sub_f32_e32 v193, v191, v193
	v_sub_f32_e32 v189, v189, v193
	v_rcp_f32_e32 v193, v191
	v_cvt_f32_i32_e32 v190, v190
	v_cmp_neq_f32_e32 vcc, s35, v188
	v_mul_f32_e32 v195, v194, v193
	v_mul_f32_e32 v196, v191, v195
	v_fma_f32 v197, v195, v191, -v196
	v_fmac_f32_e32 v197, v195, v189
	v_add_f32_e32 v198, v196, v197
	v_sub_f32_e32 v199, v194, v198
	v_sub_f32_e32 v194, v194, v199
	v_sub_f32_e32 v196, v198, v196
	v_sub_f32_e32 v194, v194, v198
	v_add_f32_e32 v192, v192, v194
	v_sub_f32_e32 v194, v196, v197
	v_add_f32_e32 v192, v194, v192
	v_add_f32_e32 v194, v199, v192
	v_mul_f32_e32 v196, v193, v194
	v_mul_f32_e32 v197, v191, v196
	v_fma_f32 v191, v196, v191, -v197
	v_fmac_f32_e32 v191, v196, v189
	v_sub_f32_e32 v189, v199, v194
	v_add_f32_e32 v189, v192, v189
	v_add_f32_e32 v192, v197, v191
	v_sub_f32_e32 v198, v194, v192
	v_sub_f32_e32 v194, v194, v198
	v_sub_f32_e32 v197, v192, v197
	v_sub_f32_e32 v192, v194, v192
	v_add_f32_e32 v189, v189, v192
	v_sub_f32_e32 v191, v197, v191
	v_add_f32_e32 v189, v191, v189
	v_add_f32_e32 v191, v195, v196
	v_add_f32_e32 v189, v198, v189
	v_sub_f32_e32 v192, v191, v195
	v_mul_f32_e32 v189, v193, v189
	v_sub_f32_e32 v192, v196, v192
	v_add_f32_e32 v189, v192, v189
	v_mul_f32_e32 v195, 0x3f317218, v190
	v_add_f32_e32 v192, v191, v189
	v_fma_f32 v196, v190, s34, -v195
	v_mul_f32_e32 v193, v192, v192
	v_fmac_f32_e32 v196, 0xb102e308, v190
	v_sub_f32_e32 v190, v192, v191
	v_fmamk_f32 v194, v193, 0x3e9b6dac, v184
	v_sub_f32_e32 v189, v189, v190
	v_add_f32_e32 v190, v195, v196
	v_fmaak_f32 v194, v193, v194, 0x3f2aaada
	v_sub_f32_e32 v191, v190, v195
	v_ldexp_f32 v195, v192, 1
	v_mul_f32_e32 v192, v192, v193
	v_mul_f32_e32 v192, v192, v194
	v_add_f32_e32 v193, v195, v192
	v_sub_f32_e32 v194, v193, v195
	v_ldexp_f32 v189, v189, 1
	v_sub_f32_e32 v192, v192, v194
	v_add_f32_e32 v189, v189, v192
	v_add_f32_e32 v192, v193, v189
	v_sub_f32_e32 v193, v192, v193
	v_sub_f32_e32 v189, v189, v193
	v_add_f32_e32 v193, v190, v192
	v_sub_f32_e32 v194, v193, v190
	v_sub_f32_e32 v195, v193, v194
	v_sub_f32_e32 v191, v196, v191
	v_sub_f32_e32 v190, v190, v195
	v_sub_f32_e32 v192, v192, v194
	v_add_f32_e32 v190, v192, v190
	v_add_f32_e32 v192, v191, v189
	v_sub_f32_e32 v194, v192, v191
	v_sub_f32_e32 v195, v192, v194
	v_sub_f32_e32 v191, v191, v195
	v_sub_f32_e32 v189, v189, v194
	v_add_f32_e32 v190, v192, v190
	v_add_f32_e32 v189, v189, v191
	v_add_f32_e32 v191, v193, v190
	v_sub_f32_e32 v192, v191, v193
	v_sub_f32_e32 v190, v190, v192
	v_add_f32_e32 v189, v189, v190
	v_add_f32_e32 v189, v191, v189
	v_cndmask_b32_e32 v189, v185, v189, vcc
	v_cmp_ngt_f32_e32 vcc, -1.0, v188
	s_nop 1
	v_cndmask_b32_e32 v189, v186, v189, vcc
	v_cmp_neq_f32_e32 vcc, -1.0, v188
	s_nop 1
	v_cndmask_b32_e32 v189, v187, v189, vcc
	v_cmp_lt_f32_e64 vcc, |v188|, s36
	s_nop 1
	v_cndmask_b32_e32 v188, v189, v188, vcc
	v_add_f32_e32 v50, v50, v188
	v_sub_f32_e32 v50, -0.5, v50
	v_mul_f32_e32 v50, 0x3fb8aa3b, v50
	v_exp_f32_e32 v50, v50
	v_lshl_add_u64 v[188:189], v[70:71], 0, v[128:129]
	v_xor_b32_e32 v50, 0x80000000, v50
	global_store_dword v[188:189], v50, off
	v_mov_b32_e32 v50, v240
	v_add_f32_e32 v51, v51, v50
	v_max_f32_e64 v50, -v51, 0
	v_mul_f32_e64 v51, |v51|, s30
	v_exp_f32_e32 v51, v51
	s_nop 0
	v_add_f32_e32 v190, 1.0, v51
	v_add_f32_e32 v188, -1.0, v190
	v_sub_f32_e32 v189, v188, v190
	v_add_f32_e32 v189, 1.0, v189
	v_sub_f32_e32 v188, v51, v188
	v_add_f32_e32 v191, v188, v189
	v_frexp_mant_f32_e32 v188, v190
	v_cmp_gt_f32_e32 vcc, s31, v188
	v_cvt_f64_f32_e32 v[188:189], v190
	v_frexp_exp_i32_f64_e32 v188, v[188:189]
	v_subbrev_co_u32_e32 v188, vcc, 0, v188, vcc
	v_sub_u32_e32 v189, 0, v188
	v_ldexp_f32 v190, v190, v189
	v_ldexp_f32 v189, v191, v189
	v_add_f32_e32 v191, -1.0, v190
	v_add_f32_e32 v192, 1.0, v191
	v_sub_f32_e32 v192, v190, v192
	v_add_f32_e32 v192, v189, v192
	v_add_f32_e32 v193, v191, v192
	v_sub_f32_e32 v191, v193, v191
	v_sub_f32_e32 v191, v192, v191
	v_add_f32_e32 v192, 1.0, v190
	v_add_f32_e32 v194, -1.0, v192
	v_sub_f32_e32 v190, v190, v194
	v_add_f32_e32 v189, v189, v190
	v_add_f32_e32 v190, v192, v189
	v_sub_f32_e32 v192, v190, v192
	v_sub_f32_e32 v189, v189, v192
	v_rcp_f32_e32 v192, v190
	v_cvt_f32_i32_e32 v188, v188
	v_cmp_neq_f32_e32 vcc, s35, v51
	v_mul_f32_e32 v194, v193, v192
	v_mul_f32_e32 v195, v190, v194
	v_fma_f32 v196, v194, v190, -v195
	v_fmac_f32_e32 v196, v194, v189
	v_add_f32_e32 v197, v195, v196
	v_sub_f32_e32 v198, v193, v197
	v_sub_f32_e32 v193, v193, v198
	v_sub_f32_e32 v195, v197, v195
	v_sub_f32_e32 v193, v193, v197
	v_add_f32_e32 v191, v191, v193
	v_sub_f32_e32 v193, v195, v196
	v_add_f32_e32 v191, v193, v191
	v_add_f32_e32 v193, v198, v191
	v_mul_f32_e32 v195, v192, v193
	v_mul_f32_e32 v196, v190, v195
	v_fma_f32 v190, v195, v190, -v196
	v_fmac_f32_e32 v190, v195, v189
	v_sub_f32_e32 v189, v198, v193
	v_add_f32_e32 v189, v191, v189
	v_add_f32_e32 v191, v196, v190
	v_sub_f32_e32 v197, v193, v191
	v_sub_f32_e32 v193, v193, v197
	v_sub_f32_e32 v196, v191, v196
	v_sub_f32_e32 v191, v193, v191
	v_add_f32_e32 v189, v189, v191
	v_sub_f32_e32 v190, v196, v190
	v_add_f32_e32 v189, v190, v189
	v_add_f32_e32 v190, v194, v195
	v_add_f32_e32 v189, v197, v189
	v_sub_f32_e32 v191, v190, v194
	v_mul_f32_e32 v189, v192, v189
	v_sub_f32_e32 v191, v195, v191
	v_add_f32_e32 v189, v191, v189
	v_mul_f32_e32 v194, 0x3f317218, v188
	v_add_f32_e32 v191, v190, v189
	v_fma_f32 v195, v188, s34, -v194
	v_mul_f32_e32 v192, v191, v191
	v_fmac_f32_e32 v195, 0xb102e308, v188
	v_sub_f32_e32 v188, v191, v190
	v_fmamk_f32 v193, v192, 0x3e9b6dac, v184
	v_sub_f32_e32 v188, v189, v188
	v_add_f32_e32 v189, v194, v195
	v_fmaak_f32 v193, v192, v193, 0x3f2aaada
	v_sub_f32_e32 v190, v189, v194
	v_ldexp_f32 v194, v191, 1
	v_mul_f32_e32 v191, v191, v192
	v_mul_f32_e32 v191, v191, v193
	v_add_f32_e32 v192, v194, v191
	v_sub_f32_e32 v193, v192, v194
	v_ldexp_f32 v188, v188, 1
	v_sub_f32_e32 v191, v191, v193
	v_add_f32_e32 v188, v188, v191
	v_add_f32_e32 v191, v192, v188
	v_sub_f32_e32 v192, v191, v192
	v_sub_f32_e32 v188, v188, v192
	v_add_f32_e32 v192, v189, v191
	v_sub_f32_e32 v193, v192, v189
	v_sub_f32_e32 v194, v192, v193
	v_sub_f32_e32 v190, v195, v190
	v_sub_f32_e32 v189, v189, v194
	v_sub_f32_e32 v191, v191, v193
	v_add_f32_e32 v189, v191, v189
	v_add_f32_e32 v191, v190, v188
	v_sub_f32_e32 v193, v191, v190
	v_sub_f32_e32 v194, v191, v193
	v_sub_f32_e32 v190, v190, v194
	v_sub_f32_e32 v188, v188, v193
	v_add_f32_e32 v189, v191, v189
	v_add_f32_e32 v188, v188, v190
	v_add_f32_e32 v190, v192, v189
	v_sub_f32_e32 v191, v190, v192
	v_sub_f32_e32 v189, v189, v191
	v_add_f32_e32 v188, v188, v189
	v_add_f32_e32 v188, v190, v188
	v_cndmask_b32_e32 v188, v185, v188, vcc
	v_cmp_ngt_f32_e32 vcc, -1.0, v51
	s_nop 1
	v_cndmask_b32_e32 v188, v186, v188, vcc
	v_cmp_neq_f32_e32 vcc, -1.0, v51
	s_nop 1
	v_cndmask_b32_e32 v188, v187, v188, vcc
	v_cmp_lt_f32_e64 vcc, |v51|, s36
	s_nop 1
	v_cndmask_b32_e32 v51, v188, v51, vcc
	v_add_f32_e32 v50, v50, v51
	v_sub_f32_e32 v50, -0.5, v50
	v_mul_f32_e32 v50, 0x3fb8aa3b, v50
	v_exp_f32_e32 v50, v50
	s_nop 0
	v_xor_b32_e32 v188, 0x80000000, v50
	v_lshl_add_u64 v[50:51], v[70:71], 0, v[130:131]
	global_store_dword v[50:51], v188, off
	v_mov_b32_e32 v50, v240
	v_add_f32_e32 v51, v52, v50
	v_max_f32_e64 v50, -v51, 0
	v_mul_f32_e64 v51, |v51|, s30
	v_exp_f32_e32 v51, v51
	s_nop 0
	v_add_f32_e32 v52, 1.0, v51
	v_add_f32_e32 v188, -1.0, v52
	v_sub_f32_e32 v189, v188, v52
	v_add_f32_e32 v189, 1.0, v189
	v_sub_f32_e32 v188, v51, v188
	v_add_f32_e32 v190, v188, v189
	v_frexp_mant_f32_e32 v188, v52
	v_cmp_gt_f32_e32 vcc, s31, v188
	v_cvt_f64_f32_e32 v[188:189], v52
	v_frexp_exp_i32_f64_e32 v188, v[188:189]
	v_subbrev_co_u32_e32 v188, vcc, 0, v188, vcc
	v_sub_u32_e32 v189, 0, v188
	v_ldexp_f32 v52, v52, v189
	v_ldexp_f32 v189, v190, v189
	v_add_f32_e32 v190, -1.0, v52
	v_add_f32_e32 v191, 1.0, v190
	v_sub_f32_e32 v191, v52, v191
	v_add_f32_e32 v191, v189, v191
	v_add_f32_e32 v192, v190, v191
	v_sub_f32_e32 v190, v192, v190
	v_sub_f32_e32 v190, v191, v190
	v_add_f32_e32 v191, 1.0, v52
	v_add_f32_e32 v193, -1.0, v191
	v_sub_f32_e32 v52, v52, v193
	v_add_f32_e32 v52, v189, v52
	v_add_f32_e32 v189, v191, v52
	v_sub_f32_e32 v191, v189, v191
	v_sub_f32_e32 v52, v52, v191
	v_rcp_f32_e32 v191, v189
	v_cvt_f32_i32_e32 v188, v188
	v_cmp_neq_f32_e32 vcc, s35, v51
	v_mul_f32_e32 v193, v192, v191
	v_mul_f32_e32 v194, v189, v193
	v_fma_f32 v195, v193, v189, -v194
	v_fmac_f32_e32 v195, v193, v52
	v_add_f32_e32 v196, v194, v195
	v_sub_f32_e32 v197, v192, v196
	v_sub_f32_e32 v192, v192, v197
	v_sub_f32_e32 v194, v196, v194
	v_sub_f32_e32 v192, v192, v196
	v_add_f32_e32 v190, v190, v192
	v_sub_f32_e32 v192, v194, v195
	v_add_f32_e32 v190, v192, v190
	v_add_f32_e32 v192, v197, v190
	v_mul_f32_e32 v194, v191, v192
	v_mul_f32_e32 v195, v189, v194
	v_fma_f32 v189, v194, v189, -v195
	v_fmac_f32_e32 v189, v194, v52
	v_sub_f32_e32 v52, v197, v192
	v_add_f32_e32 v52, v190, v52
	v_add_f32_e32 v190, v195, v189
	v_sub_f32_e32 v196, v192, v190
	v_sub_f32_e32 v192, v192, v196
	v_sub_f32_e32 v195, v190, v195
	v_sub_f32_e32 v190, v192, v190
	v_add_f32_e32 v52, v52, v190
	v_sub_f32_e32 v189, v195, v189
	v_add_f32_e32 v52, v189, v52
	v_add_f32_e32 v189, v193, v194
	v_add_f32_e32 v52, v196, v52
	v_sub_f32_e32 v190, v189, v193
	v_mul_f32_e32 v52, v191, v52
	v_sub_f32_e32 v190, v194, v190
	v_add_f32_e32 v52, v190, v52
	v_mul_f32_e32 v193, 0x3f317218, v188
	v_add_f32_e32 v190, v189, v52
	v_fma_f32 v194, v188, s34, -v193
	v_mul_f32_e32 v191, v190, v190
	v_fmac_f32_e32 v194, 0xb102e308, v188
	v_sub_f32_e32 v188, v190, v189
	v_fmamk_f32 v192, v191, 0x3e9b6dac, v184
	v_sub_f32_e32 v52, v52, v188
	v_add_f32_e32 v188, v193, v194
	v_fmaak_f32 v192, v191, v192, 0x3f2aaada
	v_sub_f32_e32 v189, v188, v193
	v_ldexp_f32 v193, v190, 1
	v_mul_f32_e32 v190, v190, v191
	v_mul_f32_e32 v190, v190, v192
	v_add_f32_e32 v191, v193, v190
	v_sub_f32_e32 v192, v191, v193
	v_ldexp_f32 v52, v52, 1
	v_sub_f32_e32 v190, v190, v192
	v_add_f32_e32 v52, v52, v190
	v_add_f32_e32 v190, v191, v52
	v_sub_f32_e32 v191, v190, v191
	v_sub_f32_e32 v52, v52, v191
	v_add_f32_e32 v191, v188, v190
	v_sub_f32_e32 v192, v191, v188
	v_sub_f32_e32 v193, v191, v192
	v_sub_f32_e32 v189, v194, v189
	v_sub_f32_e32 v188, v188, v193
	v_sub_f32_e32 v190, v190, v192
	v_add_f32_e32 v188, v190, v188
	v_add_f32_e32 v190, v189, v52
	v_sub_f32_e32 v192, v190, v189
	v_sub_f32_e32 v193, v190, v192
	v_sub_f32_e32 v189, v189, v193
	v_sub_f32_e32 v52, v52, v192
	v_add_f32_e32 v188, v190, v188
	v_add_f32_e32 v52, v52, v189
	v_add_f32_e32 v189, v191, v188
	v_sub_f32_e32 v190, v189, v191
	v_sub_f32_e32 v188, v188, v190
	v_add_f32_e32 v52, v52, v188
	v_add_f32_e32 v52, v189, v52
	v_cndmask_b32_e32 v52, v185, v52, vcc
	v_cmp_ngt_f32_e32 vcc, -1.0, v51
	s_nop 1
	v_cndmask_b32_e32 v52, v186, v52, vcc
	v_cmp_neq_f32_e32 vcc, -1.0, v51
	s_nop 1
	v_cndmask_b32_e32 v52, v187, v52, vcc
	v_cmp_lt_f32_e64 vcc, |v51|, s36
	s_nop 1
	v_cndmask_b32_e32 v51, v52, v51, vcc
	v_add_f32_e32 v50, v50, v51
	v_sub_f32_e32 v50, -0.5, v50
	v_mul_f32_e32 v50, 0x3fb8aa3b, v50
	v_exp_f32_e32 v50, v50
	s_nop 0
	v_xor_b32_e32 v52, 0x80000000, v50
	v_lshl_add_u64 v[50:51], v[70:71], 0, v[132:133]
	global_store_dword v[50:51], v52, off
	v_mov_b32_e32 v50, v240
	v_add_f32_e32 v51, v53, v50
	v_max_f32_e64 v50, -v51, 0
	v_mul_f32_e64 v51, |v51|, s30
	v_exp_f32_e32 v51, v51
	s_nop 0
	v_add_f32_e32 v188, 1.0, v51
	v_add_f32_e32 v52, -1.0, v188
	v_sub_f32_e32 v53, v52, v188
	v_add_f32_e32 v53, 1.0, v53
	v_sub_f32_e32 v52, v51, v52
	v_add_f32_e32 v189, v52, v53
	v_frexp_mant_f32_e32 v52, v188
	v_cmp_gt_f32_e32 vcc, s31, v52
	v_cvt_f64_f32_e32 v[52:53], v188
	v_frexp_exp_i32_f64_e32 v52, v[52:53]
	v_subbrev_co_u32_e32 v52, vcc, 0, v52, vcc
	v_sub_u32_e32 v53, 0, v52
	v_ldexp_f32 v188, v188, v53
	v_ldexp_f32 v53, v189, v53
	v_add_f32_e32 v189, -1.0, v188
	v_add_f32_e32 v190, 1.0, v189
	v_sub_f32_e32 v190, v188, v190
	v_add_f32_e32 v190, v53, v190
	v_add_f32_e32 v191, v189, v190
	v_sub_f32_e32 v189, v191, v189
	v_sub_f32_e32 v189, v190, v189
	v_add_f32_e32 v190, 1.0, v188
	v_add_f32_e32 v192, -1.0, v190
	v_sub_f32_e32 v188, v188, v192
	v_add_f32_e32 v53, v53, v188
	v_add_f32_e32 v188, v190, v53
	v_sub_f32_e32 v190, v188, v190
	v_sub_f32_e32 v53, v53, v190
	v_rcp_f32_e32 v190, v188
	v_cvt_f32_i32_e32 v52, v52
	v_cmp_neq_f32_e32 vcc, s35, v51
	v_mul_f32_e32 v192, v191, v190
	v_mul_f32_e32 v193, v188, v192
	v_fma_f32 v194, v192, v188, -v193
	v_fmac_f32_e32 v194, v192, v53
	v_add_f32_e32 v195, v193, v194
	v_sub_f32_e32 v196, v191, v195
	v_sub_f32_e32 v191, v191, v196
	v_sub_f32_e32 v193, v195, v193
	v_sub_f32_e32 v191, v191, v195
	v_add_f32_e32 v189, v189, v191
	v_sub_f32_e32 v191, v193, v194
	v_add_f32_e32 v189, v191, v189
	v_add_f32_e32 v191, v196, v189
	v_mul_f32_e32 v193, v190, v191
	v_mul_f32_e32 v194, v188, v193
	v_fma_f32 v188, v193, v188, -v194
	v_fmac_f32_e32 v188, v193, v53
	v_sub_f32_e32 v53, v196, v191
	v_add_f32_e32 v53, v189, v53
	v_add_f32_e32 v189, v194, v188
	v_sub_f32_e32 v195, v191, v189
	v_sub_f32_e32 v191, v191, v195
	v_sub_f32_e32 v194, v189, v194
	v_sub_f32_e32 v189, v191, v189
	v_add_f32_e32 v53, v53, v189
	v_sub_f32_e32 v188, v194, v188
	v_add_f32_e32 v53, v188, v53
	v_add_f32_e32 v188, v192, v193
	v_add_f32_e32 v53, v195, v53
	v_sub_f32_e32 v189, v188, v192
	v_mul_f32_e32 v53, v190, v53
	v_sub_f32_e32 v189, v193, v189
	v_add_f32_e32 v53, v189, v53
	v_mul_f32_e32 v192, 0x3f317218, v52
	v_add_f32_e32 v189, v188, v53
	v_fma_f32 v193, v52, s34, -v192
	v_mul_f32_e32 v190, v189, v189
	v_fmac_f32_e32 v193, 0xb102e308, v52
	v_sub_f32_e32 v52, v189, v188
	v_fmamk_f32 v191, v190, 0x3e9b6dac, v184
	v_sub_f32_e32 v52, v53, v52
	v_add_f32_e32 v53, v192, v193
	v_fmaak_f32 v191, v190, v191, 0x3f2aaada
	v_sub_f32_e32 v188, v53, v192
	v_ldexp_f32 v192, v189, 1
	v_mul_f32_e32 v189, v189, v190
	v_mul_f32_e32 v189, v189, v191
	v_add_f32_e32 v190, v192, v189
	v_sub_f32_e32 v191, v190, v192
	v_ldexp_f32 v52, v52, 1
	v_sub_f32_e32 v189, v189, v191
	v_add_f32_e32 v52, v52, v189
	v_add_f32_e32 v189, v190, v52
	v_sub_f32_e32 v190, v189, v190
	v_sub_f32_e32 v52, v52, v190
	v_add_f32_e32 v190, v53, v189
	v_sub_f32_e32 v191, v190, v53
	v_sub_f32_e32 v192, v190, v191
	v_sub_f32_e32 v188, v193, v188
	v_sub_f32_e32 v53, v53, v192
	v_sub_f32_e32 v189, v189, v191
	v_add_f32_e32 v53, v189, v53
	v_add_f32_e32 v189, v188, v52
	v_sub_f32_e32 v191, v189, v188
	v_sub_f32_e32 v192, v189, v191
	v_sub_f32_e32 v188, v188, v192
	v_sub_f32_e32 v52, v52, v191
	v_add_f32_e32 v53, v189, v53
	v_add_f32_e32 v52, v52, v188
	v_add_f32_e32 v188, v190, v53
	v_sub_f32_e32 v189, v188, v190
	v_sub_f32_e32 v53, v53, v189
	v_add_f32_e32 v52, v52, v53
	v_add_f32_e32 v52, v188, v52
	v_cndmask_b32_e32 v52, v185, v52, vcc
	v_cmp_ngt_f32_e32 vcc, -1.0, v51
	s_nop 1
	v_cndmask_b32_e32 v52, v186, v52, vcc
	v_cmp_neq_f32_e32 vcc, -1.0, v51
	s_nop 1
	v_cndmask_b32_e32 v52, v187, v52, vcc
	v_cmp_lt_f32_e64 vcc, |v51|, s36
	s_nop 1
	v_cndmask_b32_e32 v51, v52, v51, vcc
	v_add_f32_e32 v50, v50, v51
	v_sub_f32_e32 v50, -0.5, v50
	v_mul_f32_e32 v50, 0x3fb8aa3b, v50
	v_exp_f32_e32 v50, v50
	v_lshlrev_b64 v[52:53], 12, v[156:157]
	v_xor_b32_e32 v188, 0x80000000, v50
	v_lshl_add_u64 v[50:51], v[70:71], 0, v[52:53]
	global_store_dword v[50:51], v188, off
	v_mov_b32_e32 v50, v240
	v_add_f32_e32 v51, v54, v50
	v_max_f32_e64 v50, -v51, 0
	v_mul_f32_e64 v51, |v51|, s30
	v_exp_f32_e32 v51, v51
	s_nop 0
	v_add_f32_e32 v54, 1.0, v51
	v_add_f32_e32 v156, -1.0, v54
	v_sub_f32_e32 v157, v156, v54
	v_add_f32_e32 v157, 1.0, v157
	v_sub_f32_e32 v156, v51, v156
	v_add_f32_e32 v188, v156, v157
	v_frexp_mant_f32_e32 v156, v54
	v_cmp_gt_f32_e32 vcc, s31, v156
	v_cvt_f64_f32_e32 v[156:157], v54
	v_frexp_exp_i32_f64_e32 v156, v[156:157]
	v_subbrev_co_u32_e32 v156, vcc, 0, v156, vcc
	v_sub_u32_e32 v157, 0, v156
	v_ldexp_f32 v54, v54, v157
	v_ldexp_f32 v157, v188, v157
	v_add_f32_e32 v188, -1.0, v54
	v_add_f32_e32 v189, 1.0, v188
	v_sub_f32_e32 v189, v54, v189
	v_add_f32_e32 v189, v157, v189
	v_add_f32_e32 v190, v188, v189
	v_sub_f32_e32 v188, v190, v188
	v_sub_f32_e32 v188, v189, v188
	v_add_f32_e32 v189, 1.0, v54
	v_add_f32_e32 v191, -1.0, v189
	v_sub_f32_e32 v54, v54, v191
	v_add_f32_e32 v54, v157, v54
	v_add_f32_e32 v157, v189, v54
	v_sub_f32_e32 v189, v157, v189
	v_sub_f32_e32 v54, v54, v189
	v_rcp_f32_e32 v189, v157
	v_cvt_f32_i32_e32 v156, v156
	v_cmp_neq_f32_e32 vcc, s35, v51
	v_mul_f32_e32 v191, v190, v189
	v_mul_f32_e32 v192, v157, v191
	v_fma_f32 v193, v191, v157, -v192
	v_fmac_f32_e32 v193, v191, v54
	v_add_f32_e32 v194, v192, v193
	v_sub_f32_e32 v195, v190, v194
	v_sub_f32_e32 v190, v190, v195
	v_sub_f32_e32 v192, v194, v192
	v_sub_f32_e32 v190, v190, v194
	v_add_f32_e32 v188, v188, v190
	v_sub_f32_e32 v190, v192, v193
	v_add_f32_e32 v188, v190, v188
	v_add_f32_e32 v190, v195, v188
	v_mul_f32_e32 v192, v189, v190
	v_mul_f32_e32 v193, v157, v192
	v_fma_f32 v157, v192, v157, -v193
	v_fmac_f32_e32 v157, v192, v54
	v_sub_f32_e32 v54, v195, v190
	v_add_f32_e32 v54, v188, v54
	v_add_f32_e32 v188, v193, v157
	v_sub_f32_e32 v194, v190, v188
	v_sub_f32_e32 v190, v190, v194
	v_sub_f32_e32 v193, v188, v193
	v_sub_f32_e32 v188, v190, v188
	v_add_f32_e32 v54, v54, v188
	v_sub_f32_e32 v157, v193, v157
	v_add_f32_e32 v54, v157, v54
	v_add_f32_e32 v157, v191, v192
	v_add_f32_e32 v54, v194, v54
	v_sub_f32_e32 v188, v157, v191
	v_mul_f32_e32 v54, v189, v54
	v_sub_f32_e32 v188, v192, v188
	v_add_f32_e32 v54, v188, v54
	v_mul_f32_e32 v191, 0x3f317218, v156
	v_add_f32_e32 v188, v157, v54
	v_fma_f32 v192, v156, s34, -v191
	v_mul_f32_e32 v189, v188, v188
	v_fmac_f32_e32 v192, 0xb102e308, v156
	v_sub_f32_e32 v156, v188, v157
	v_fmamk_f32 v190, v189, 0x3e9b6dac, v184
	v_sub_f32_e32 v54, v54, v156
	v_add_f32_e32 v156, v191, v192
	v_fmaak_f32 v190, v189, v190, 0x3f2aaada
	v_sub_f32_e32 v157, v156, v191
	v_ldexp_f32 v191, v188, 1
	v_mul_f32_e32 v188, v188, v189
	v_mul_f32_e32 v188, v188, v190
	v_add_f32_e32 v189, v191, v188
	v_sub_f32_e32 v190, v189, v191
	v_ldexp_f32 v54, v54, 1
	v_sub_f32_e32 v188, v188, v190
	v_add_f32_e32 v54, v54, v188
	v_add_f32_e32 v188, v189, v54
	v_sub_f32_e32 v189, v188, v189
	v_sub_f32_e32 v54, v54, v189
	v_add_f32_e32 v189, v156, v188
	v_sub_f32_e32 v190, v189, v156
	v_sub_f32_e32 v191, v189, v190
	v_sub_f32_e32 v157, v192, v157
	v_sub_f32_e32 v156, v156, v191
	v_sub_f32_e32 v188, v188, v190
	v_add_f32_e32 v156, v188, v156
	v_add_f32_e32 v188, v157, v54
	v_sub_f32_e32 v190, v188, v157
	v_sub_f32_e32 v191, v188, v190
	v_sub_f32_e32 v157, v157, v191
	v_sub_f32_e32 v54, v54, v190
	v_add_f32_e32 v156, v188, v156
	v_add_f32_e32 v54, v54, v157
	v_add_f32_e32 v157, v189, v156
	v_sub_f32_e32 v188, v157, v189
	v_sub_f32_e32 v156, v156, v188
	v_add_f32_e32 v54, v54, v156
	v_add_f32_e32 v54, v157, v54
	v_cndmask_b32_e32 v54, v185, v54, vcc
	v_cmp_ngt_f32_e32 vcc, -1.0, v51
	s_nop 1
	v_cndmask_b32_e32 v54, v186, v54, vcc
	v_cmp_neq_f32_e32 vcc, -1.0, v51
	s_nop 1
	v_cndmask_b32_e32 v54, v187, v54, vcc
	v_cmp_lt_f32_e64 vcc, |v51|, s36
	s_nop 1
	v_cndmask_b32_e32 v51, v54, v51, vcc
	v_add_f32_e32 v50, v50, v51
	v_sub_f32_e32 v50, -0.5, v50
	v_mul_f32_e32 v50, 0x3fb8aa3b, v50
	v_exp_f32_e32 v50, v50
	s_nop 0
	v_xor_b32_e32 v54, 0x80000000, v50
	v_lshl_add_u64 v[50:51], v[70:71], 0, v[134:135]
	global_store_dword v[50:51], v54, off
	v_mov_b32_e32 v50, v240
	v_add_f32_e32 v51, v55, v50
	v_max_f32_e64 v50, -v51, 0
	v_mul_f32_e64 v51, |v51|, s30
	v_exp_f32_e32 v51, v51
	s_nop 0
	v_add_f32_e32 v156, 1.0, v51
	v_add_f32_e32 v54, -1.0, v156
	v_sub_f32_e32 v55, v54, v156
	v_add_f32_e32 v55, 1.0, v55
	v_sub_f32_e32 v54, v51, v54
	v_add_f32_e32 v157, v54, v55
	v_frexp_mant_f32_e32 v54, v156
	v_cmp_gt_f32_e32 vcc, s31, v54
	v_cvt_f64_f32_e32 v[54:55], v156
	v_frexp_exp_i32_f64_e32 v54, v[54:55]
	v_subbrev_co_u32_e32 v54, vcc, 0, v54, vcc
	v_sub_u32_e32 v55, 0, v54
	v_ldexp_f32 v156, v156, v55
	v_ldexp_f32 v55, v157, v55
	v_add_f32_e32 v157, -1.0, v156
	v_add_f32_e32 v188, 1.0, v157
	v_sub_f32_e32 v188, v156, v188
	v_add_f32_e32 v188, v55, v188
	v_add_f32_e32 v189, v157, v188
	v_sub_f32_e32 v157, v189, v157
	v_sub_f32_e32 v157, v188, v157
	v_add_f32_e32 v188, 1.0, v156
	v_add_f32_e32 v190, -1.0, v188
	v_sub_f32_e32 v156, v156, v190
	v_add_f32_e32 v55, v55, v156
	v_add_f32_e32 v156, v188, v55
	v_sub_f32_e32 v188, v156, v188
	v_sub_f32_e32 v55, v55, v188
	v_rcp_f32_e32 v188, v156
	v_cvt_f32_i32_e32 v54, v54
	v_cmp_neq_f32_e32 vcc, s35, v51
	v_mul_f32_e32 v190, v189, v188
	v_mul_f32_e32 v191, v156, v190
	v_fma_f32 v192, v190, v156, -v191
	v_fmac_f32_e32 v192, v190, v55
	v_add_f32_e32 v193, v191, v192
	v_sub_f32_e32 v194, v189, v193
	v_sub_f32_e32 v189, v189, v194
	v_sub_f32_e32 v191, v193, v191
	v_sub_f32_e32 v189, v189, v193
	v_add_f32_e32 v157, v157, v189
	v_sub_f32_e32 v189, v191, v192
	v_add_f32_e32 v157, v189, v157
	v_add_f32_e32 v189, v194, v157
	v_mul_f32_e32 v191, v188, v189
	v_mul_f32_e32 v192, v156, v191
	v_fma_f32 v156, v191, v156, -v192
	v_fmac_f32_e32 v156, v191, v55
	v_sub_f32_e32 v55, v194, v189
	v_add_f32_e32 v55, v157, v55
	v_add_f32_e32 v157, v192, v156
	v_sub_f32_e32 v193, v189, v157
	v_sub_f32_e32 v189, v189, v193
	v_sub_f32_e32 v192, v157, v192
	v_sub_f32_e32 v157, v189, v157
	v_add_f32_e32 v55, v55, v157
	v_sub_f32_e32 v156, v192, v156
	v_add_f32_e32 v55, v156, v55
	v_add_f32_e32 v156, v190, v191
	v_add_f32_e32 v55, v193, v55
	v_sub_f32_e32 v157, v156, v190
	v_mul_f32_e32 v55, v188, v55
	v_sub_f32_e32 v157, v191, v157
	v_add_f32_e32 v55, v157, v55
	v_mul_f32_e32 v190, 0x3f317218, v54
	v_add_f32_e32 v157, v156, v55
	v_fma_f32 v191, v54, s34, -v190
	v_mul_f32_e32 v188, v157, v157
	v_fmac_f32_e32 v191, 0xb102e308, v54
	v_sub_f32_e32 v54, v157, v156
	v_fmamk_f32 v189, v188, 0x3e9b6dac, v184
	v_sub_f32_e32 v54, v55, v54
	v_add_f32_e32 v55, v190, v191
	v_fmaak_f32 v189, v188, v189, 0x3f2aaada
	v_sub_f32_e32 v156, v55, v190
	v_ldexp_f32 v190, v157, 1
	v_mul_f32_e32 v157, v157, v188
	v_mul_f32_e32 v157, v157, v189
	v_add_f32_e32 v188, v190, v157
	v_sub_f32_e32 v189, v188, v190
	v_ldexp_f32 v54, v54, 1
	v_sub_f32_e32 v157, v157, v189
	v_add_f32_e32 v54, v54, v157
	v_add_f32_e32 v157, v188, v54
	v_sub_f32_e32 v188, v157, v188
	v_sub_f32_e32 v54, v54, v188
	v_add_f32_e32 v188, v55, v157
	v_sub_f32_e32 v189, v188, v55
	v_sub_f32_e32 v190, v188, v189
	v_sub_f32_e32 v156, v191, v156
	v_sub_f32_e32 v55, v55, v190
	v_sub_f32_e32 v157, v157, v189
	v_add_f32_e32 v55, v157, v55
	v_add_f32_e32 v157, v156, v54
	v_sub_f32_e32 v189, v157, v156
	v_sub_f32_e32 v190, v157, v189
	v_sub_f32_e32 v156, v156, v190
	v_sub_f32_e32 v54, v54, v189
	v_add_f32_e32 v55, v157, v55
	v_add_f32_e32 v54, v54, v156
	v_add_f32_e32 v156, v188, v55
	v_sub_f32_e32 v157, v156, v188
	v_sub_f32_e32 v55, v55, v157
	v_add_f32_e32 v54, v54, v55
	v_add_f32_e32 v54, v156, v54
	v_cndmask_b32_e32 v54, v185, v54, vcc
	v_cmp_ngt_f32_e32 vcc, -1.0, v51
	s_nop 1
	v_cndmask_b32_e32 v54, v186, v54, vcc
	v_cmp_neq_f32_e32 vcc, -1.0, v51
	s_nop 1
	v_cndmask_b32_e32 v54, v187, v54, vcc
	v_cmp_lt_f32_e64 vcc, |v51|, s36
	s_nop 1
	v_cndmask_b32_e32 v51, v54, v51, vcc
	v_add_f32_e32 v50, v50, v51
	v_sub_f32_e32 v50, -0.5, v50
	v_mul_f32_e32 v50, 0x3fb8aa3b, v50
	v_exp_f32_e32 v50, v50
	v_lshlrev_b64 v[54:55], 12, v[154:155]
	v_xor_b32_e32 v156, 0x80000000, v50
	v_lshl_add_u64 v[50:51], v[70:71], 0, v[54:55]
	global_store_dword v[50:51], v156, off
	v_mov_b32_e32 v50, v240
	v_add_f32_e32 v51, v56, v50
	v_max_f32_e64 v50, -v51, 0
	v_mul_f32_e64 v51, |v51|, s30
	v_exp_f32_e32 v51, v51
	s_nop 0
	v_add_f32_e32 v56, 1.0, v51
	v_add_f32_e32 v154, -1.0, v56
	v_sub_f32_e32 v155, v154, v56
	v_add_f32_e32 v155, 1.0, v155
	v_sub_f32_e32 v154, v51, v154
	v_add_f32_e32 v156, v154, v155
	v_frexp_mant_f32_e32 v154, v56
	v_cmp_gt_f32_e32 vcc, s31, v154
	v_cvt_f64_f32_e32 v[154:155], v56
	v_frexp_exp_i32_f64_e32 v154, v[154:155]
	v_subbrev_co_u32_e32 v154, vcc, 0, v154, vcc
	v_sub_u32_e32 v155, 0, v154
	v_ldexp_f32 v56, v56, v155
	v_ldexp_f32 v155, v156, v155
	v_add_f32_e32 v156, -1.0, v56
	v_add_f32_e32 v157, 1.0, v156
	v_sub_f32_e32 v157, v56, v157
	v_add_f32_e32 v157, v155, v157
	v_add_f32_e32 v188, v156, v157
	v_sub_f32_e32 v156, v188, v156
	v_sub_f32_e32 v156, v157, v156
	v_add_f32_e32 v157, 1.0, v56
	v_add_f32_e32 v189, -1.0, v157
	v_sub_f32_e32 v56, v56, v189
	v_add_f32_e32 v56, v155, v56
	v_add_f32_e32 v155, v157, v56
	v_sub_f32_e32 v157, v155, v157
	v_sub_f32_e32 v56, v56, v157
	v_rcp_f32_e32 v157, v155
	v_cvt_f32_i32_e32 v154, v154
	v_cmp_neq_f32_e32 vcc, s35, v51
	v_mul_f32_e32 v189, v188, v157
	v_mul_f32_e32 v190, v155, v189
	v_fma_f32 v191, v189, v155, -v190
	v_fmac_f32_e32 v191, v189, v56
	v_add_f32_e32 v192, v190, v191
	v_sub_f32_e32 v193, v188, v192
	v_sub_f32_e32 v188, v188, v193
	v_sub_f32_e32 v190, v192, v190
	v_sub_f32_e32 v188, v188, v192
	v_add_f32_e32 v156, v156, v188
	v_sub_f32_e32 v188, v190, v191
	v_add_f32_e32 v156, v188, v156
	v_add_f32_e32 v188, v193, v156
	v_mul_f32_e32 v190, v157, v188
	v_mul_f32_e32 v191, v155, v190
	v_fma_f32 v155, v190, v155, -v191
	v_fmac_f32_e32 v155, v190, v56
	v_sub_f32_e32 v56, v193, v188
	v_add_f32_e32 v56, v156, v56
	v_add_f32_e32 v156, v191, v155
	v_sub_f32_e32 v192, v188, v156
	v_sub_f32_e32 v188, v188, v192
	v_sub_f32_e32 v191, v156, v191
	v_sub_f32_e32 v156, v188, v156
	v_add_f32_e32 v56, v56, v156
	v_sub_f32_e32 v155, v191, v155
	v_add_f32_e32 v56, v155, v56
	v_add_f32_e32 v155, v189, v190
	v_add_f32_e32 v56, v192, v56
	v_sub_f32_e32 v156, v155, v189
	v_mul_f32_e32 v56, v157, v56
	v_sub_f32_e32 v156, v190, v156
	v_add_f32_e32 v56, v156, v56
	v_mul_f32_e32 v189, 0x3f317218, v154
	v_add_f32_e32 v156, v155, v56
	v_fma_f32 v190, v154, s34, -v189
	v_mul_f32_e32 v157, v156, v156
	v_fmac_f32_e32 v190, 0xb102e308, v154
	v_sub_f32_e32 v154, v156, v155
	v_fmamk_f32 v188, v157, 0x3e9b6dac, v184
	v_sub_f32_e32 v56, v56, v154
	v_add_f32_e32 v154, v189, v190
	v_fmaak_f32 v188, v157, v188, 0x3f2aaada
	v_sub_f32_e32 v155, v154, v189
	v_ldexp_f32 v189, v156, 1
	v_mul_f32_e32 v156, v156, v157
	v_mul_f32_e32 v156, v156, v188
	v_add_f32_e32 v157, v189, v156
	v_sub_f32_e32 v188, v157, v189
	v_ldexp_f32 v56, v56, 1
	v_sub_f32_e32 v156, v156, v188
	v_add_f32_e32 v56, v56, v156
	v_add_f32_e32 v156, v157, v56
	v_sub_f32_e32 v157, v156, v157
	v_sub_f32_e32 v56, v56, v157
	v_add_f32_e32 v157, v154, v156
	v_sub_f32_e32 v188, v157, v154
	v_sub_f32_e32 v189, v157, v188
	v_sub_f32_e32 v155, v190, v155
	v_sub_f32_e32 v154, v154, v189
	v_sub_f32_e32 v156, v156, v188
	v_add_f32_e32 v154, v156, v154
	v_add_f32_e32 v156, v155, v56
	v_sub_f32_e32 v188, v156, v155
	v_sub_f32_e32 v189, v156, v188
	v_sub_f32_e32 v155, v155, v189
	v_sub_f32_e32 v56, v56, v188
	v_add_f32_e32 v154, v156, v154
	v_add_f32_e32 v56, v56, v155
	v_add_f32_e32 v155, v157, v154
	v_sub_f32_e32 v156, v155, v157
	v_sub_f32_e32 v154, v154, v156
	v_add_f32_e32 v56, v56, v154
	v_add_f32_e32 v56, v155, v56
	v_cndmask_b32_e32 v56, v185, v56, vcc
	v_cmp_ngt_f32_e32 vcc, -1.0, v51
	s_nop 1
	v_cndmask_b32_e32 v56, v186, v56, vcc
	v_cmp_neq_f32_e32 vcc, -1.0, v51
	s_nop 1
	v_cndmask_b32_e32 v56, v187, v56, vcc
	v_cmp_lt_f32_e64 vcc, |v51|, s36
	s_nop 1
	v_cndmask_b32_e32 v51, v56, v51, vcc
	v_add_f32_e32 v50, v50, v51
	v_sub_f32_e32 v50, -0.5, v50
	v_mul_f32_e32 v50, 0x3fb8aa3b, v50
	v_exp_f32_e32 v50, v50
	s_nop 0
	v_xor_b32_e32 v56, 0x80000000, v50
	v_lshl_add_u64 v[50:51], v[70:71], 0, v[136:137]
	global_store_dword v[50:51], v56, off
	v_mov_b32_e32 v50, v240
	v_add_f32_e32 v51, v57, v50
	v_max_f32_e64 v50, -v51, 0
	v_mul_f32_e64 v51, |v51|, s30
	v_exp_f32_e32 v51, v51
	s_nop 0
	v_add_f32_e32 v154, 1.0, v51
	v_add_f32_e32 v56, -1.0, v154
	v_sub_f32_e32 v57, v56, v154
	v_add_f32_e32 v57, 1.0, v57
	v_sub_f32_e32 v56, v51, v56
	v_add_f32_e32 v155, v56, v57
	v_frexp_mant_f32_e32 v56, v154
	v_cmp_gt_f32_e32 vcc, s31, v56
	v_cvt_f64_f32_e32 v[56:57], v154
	v_frexp_exp_i32_f64_e32 v56, v[56:57]
	v_subbrev_co_u32_e32 v56, vcc, 0, v56, vcc
	v_sub_u32_e32 v57, 0, v56
	v_ldexp_f32 v154, v154, v57
	v_ldexp_f32 v57, v155, v57
	v_add_f32_e32 v155, -1.0, v154
	v_add_f32_e32 v156, 1.0, v155
	v_sub_f32_e32 v156, v154, v156
	v_add_f32_e32 v156, v57, v156
	v_add_f32_e32 v157, v155, v156
	v_sub_f32_e32 v155, v157, v155
	v_sub_f32_e32 v155, v156, v155
	v_add_f32_e32 v156, 1.0, v154
	v_add_f32_e32 v188, -1.0, v156
	v_sub_f32_e32 v154, v154, v188
	v_add_f32_e32 v57, v57, v154
	v_add_f32_e32 v154, v156, v57
	v_sub_f32_e32 v156, v154, v156
	v_sub_f32_e32 v57, v57, v156
	v_rcp_f32_e32 v156, v154
	v_cvt_f32_i32_e32 v56, v56
	v_cmp_neq_f32_e32 vcc, s35, v51
	v_mul_f32_e32 v188, v157, v156
	v_mul_f32_e32 v189, v154, v188
	v_fma_f32 v190, v188, v154, -v189
	v_fmac_f32_e32 v190, v188, v57
	v_add_f32_e32 v191, v189, v190
	v_sub_f32_e32 v192, v157, v191
	v_sub_f32_e32 v157, v157, v192
	v_sub_f32_e32 v189, v191, v189
	v_sub_f32_e32 v157, v157, v191
	v_add_f32_e32 v155, v155, v157
	v_sub_f32_e32 v157, v189, v190
	v_add_f32_e32 v155, v157, v155
	v_add_f32_e32 v157, v192, v155
	v_mul_f32_e32 v189, v156, v157
	v_mul_f32_e32 v190, v154, v189
	v_fma_f32 v154, v189, v154, -v190
	v_fmac_f32_e32 v154, v189, v57
	v_sub_f32_e32 v57, v192, v157
	v_add_f32_e32 v57, v155, v57
	v_add_f32_e32 v155, v190, v154
	v_sub_f32_e32 v191, v157, v155
	v_sub_f32_e32 v157, v157, v191
	v_sub_f32_e32 v190, v155, v190
	v_sub_f32_e32 v155, v157, v155
	v_add_f32_e32 v57, v57, v155
	v_sub_f32_e32 v154, v190, v154
	v_add_f32_e32 v57, v154, v57
	v_add_f32_e32 v154, v188, v189
	v_add_f32_e32 v57, v191, v57
	v_sub_f32_e32 v155, v154, v188
	v_mul_f32_e32 v57, v156, v57
	v_sub_f32_e32 v155, v189, v155
	v_add_f32_e32 v57, v155, v57
	v_mul_f32_e32 v188, 0x3f317218, v56
	v_add_f32_e32 v155, v154, v57
	v_fma_f32 v189, v56, s34, -v188
	v_mul_f32_e32 v156, v155, v155
	v_fmac_f32_e32 v189, 0xb102e308, v56
	v_sub_f32_e32 v56, v155, v154
	v_fmamk_f32 v157, v156, 0x3e9b6dac, v184
	v_sub_f32_e32 v56, v57, v56
	v_add_f32_e32 v57, v188, v189
	v_fmaak_f32 v157, v156, v157, 0x3f2aaada
	v_sub_f32_e32 v154, v57, v188
	v_ldexp_f32 v188, v155, 1
	v_mul_f32_e32 v155, v155, v156
	v_mul_f32_e32 v155, v155, v157
	v_add_f32_e32 v156, v188, v155
	v_sub_f32_e32 v157, v156, v188
	v_ldexp_f32 v56, v56, 1
	v_sub_f32_e32 v155, v155, v157
	v_add_f32_e32 v56, v56, v155
	v_add_f32_e32 v155, v156, v56
	v_sub_f32_e32 v156, v155, v156
	v_sub_f32_e32 v56, v56, v156
	v_add_f32_e32 v156, v57, v155
	v_sub_f32_e32 v157, v156, v57
	v_sub_f32_e32 v188, v156, v157
	v_sub_f32_e32 v154, v189, v154
	v_sub_f32_e32 v57, v57, v188
	v_sub_f32_e32 v155, v155, v157
	v_add_f32_e32 v57, v155, v57
	v_add_f32_e32 v155, v154, v56
	v_sub_f32_e32 v157, v155, v154
	v_sub_f32_e32 v188, v155, v157
	v_sub_f32_e32 v154, v154, v188
	v_sub_f32_e32 v56, v56, v157
	v_add_f32_e32 v57, v155, v57
	v_add_f32_e32 v56, v56, v154
	v_add_f32_e32 v154, v156, v57
	v_sub_f32_e32 v155, v154, v156
	v_sub_f32_e32 v57, v57, v155
	v_add_f32_e32 v56, v56, v57
	v_add_f32_e32 v56, v154, v56
	v_cndmask_b32_e32 v56, v185, v56, vcc
	v_cmp_ngt_f32_e32 vcc, -1.0, v51
	s_nop 1
	v_cndmask_b32_e32 v56, v186, v56, vcc
	v_cmp_neq_f32_e32 vcc, -1.0, v51
	s_nop 1
	v_cndmask_b32_e32 v56, v187, v56, vcc
	v_cmp_lt_f32_e64 vcc, |v51|, s36
	s_nop 1
	v_cndmask_b32_e32 v51, v56, v51, vcc
	v_add_f32_e32 v50, v50, v51
	v_sub_f32_e32 v50, -0.5, v50
	v_mul_f32_e32 v50, 0x3fb8aa3b, v50
	v_exp_f32_e32 v50, v50
	v_lshlrev_b64 v[56:57], 12, v[152:153]
	v_xor_b32_e32 v154, 0x80000000, v50
	v_lshl_add_u64 v[50:51], v[70:71], 0, v[56:57]
	global_store_dword v[50:51], v154, off
	v_mov_b32_e32 v50, v240
	v_add_f32_e32 v51, v58, v50
	v_max_f32_e64 v50, -v51, 0
	v_mul_f32_e64 v51, |v51|, s30
	v_exp_f32_e32 v51, v51
	s_nop 0
	v_add_f32_e32 v58, 1.0, v51
	v_add_f32_e32 v152, -1.0, v58
	v_sub_f32_e32 v153, v152, v58
	v_add_f32_e32 v153, 1.0, v153
	v_sub_f32_e32 v152, v51, v152
	v_add_f32_e32 v154, v152, v153
	v_frexp_mant_f32_e32 v152, v58
	v_cmp_gt_f32_e32 vcc, s31, v152
	v_cvt_f64_f32_e32 v[152:153], v58
	v_frexp_exp_i32_f64_e32 v152, v[152:153]
	v_subbrev_co_u32_e32 v152, vcc, 0, v152, vcc
	v_sub_u32_e32 v153, 0, v152
	v_ldexp_f32 v58, v58, v153
	v_ldexp_f32 v153, v154, v153
	v_add_f32_e32 v154, -1.0, v58
	v_add_f32_e32 v155, 1.0, v154
	v_sub_f32_e32 v155, v58, v155
	v_add_f32_e32 v155, v153, v155
	v_add_f32_e32 v156, v154, v155
	v_sub_f32_e32 v154, v156, v154
	v_sub_f32_e32 v154, v155, v154
	v_add_f32_e32 v155, 1.0, v58
	v_add_f32_e32 v157, -1.0, v155
	v_sub_f32_e32 v58, v58, v157
	v_add_f32_e32 v58, v153, v58
	v_add_f32_e32 v153, v155, v58
	v_sub_f32_e32 v155, v153, v155
	v_sub_f32_e32 v58, v58, v155
	v_rcp_f32_e32 v155, v153
	v_cvt_f32_i32_e32 v152, v152
	v_cmp_neq_f32_e32 vcc, s35, v51
	v_mul_f32_e32 v157, v156, v155
	v_mul_f32_e32 v188, v153, v157
	v_fma_f32 v189, v157, v153, -v188
	v_fmac_f32_e32 v189, v157, v58
	v_add_f32_e32 v190, v188, v189
	v_sub_f32_e32 v191, v156, v190
	v_sub_f32_e32 v156, v156, v191
	v_sub_f32_e32 v188, v190, v188
	v_sub_f32_e32 v156, v156, v190
	v_add_f32_e32 v154, v154, v156
	v_sub_f32_e32 v156, v188, v189
	v_add_f32_e32 v154, v156, v154
	v_add_f32_e32 v156, v191, v154
	v_mul_f32_e32 v188, v155, v156
	v_mul_f32_e32 v189, v153, v188
	v_fma_f32 v153, v188, v153, -v189
	v_fmac_f32_e32 v153, v188, v58
	v_sub_f32_e32 v58, v191, v156
	v_add_f32_e32 v58, v154, v58
	v_add_f32_e32 v154, v189, v153
	v_sub_f32_e32 v190, v156, v154
	v_sub_f32_e32 v156, v156, v190
	v_sub_f32_e32 v189, v154, v189
	v_sub_f32_e32 v154, v156, v154
	v_add_f32_e32 v58, v58, v154
	v_sub_f32_e32 v153, v189, v153
	v_add_f32_e32 v58, v153, v58
	v_add_f32_e32 v153, v157, v188
	v_add_f32_e32 v58, v190, v58
	v_sub_f32_e32 v154, v153, v157
	v_mul_f32_e32 v58, v155, v58
	v_sub_f32_e32 v154, v188, v154
	v_add_f32_e32 v58, v154, v58
	v_mul_f32_e32 v157, 0x3f317218, v152
	v_add_f32_e32 v154, v153, v58
	v_fma_f32 v188, v152, s34, -v157
	v_mul_f32_e32 v155, v154, v154
	v_fmac_f32_e32 v188, 0xb102e308, v152
	v_sub_f32_e32 v152, v154, v153
	v_fmamk_f32 v156, v155, 0x3e9b6dac, v184
	v_sub_f32_e32 v58, v58, v152
	v_add_f32_e32 v152, v157, v188
	v_fmaak_f32 v156, v155, v156, 0x3f2aaada
	v_sub_f32_e32 v153, v152, v157
	v_ldexp_f32 v157, v154, 1
	v_mul_f32_e32 v154, v154, v155
	v_mul_f32_e32 v154, v154, v156
	v_add_f32_e32 v155, v157, v154
	v_sub_f32_e32 v156, v155, v157
	v_ldexp_f32 v58, v58, 1
	v_sub_f32_e32 v154, v154, v156
	v_add_f32_e32 v58, v58, v154
	v_add_f32_e32 v154, v155, v58
	v_sub_f32_e32 v155, v154, v155
	v_sub_f32_e32 v58, v58, v155
	v_add_f32_e32 v155, v152, v154
	v_sub_f32_e32 v156, v155, v152
	v_sub_f32_e32 v157, v155, v156
	v_sub_f32_e32 v153, v188, v153
	v_sub_f32_e32 v152, v152, v157
	v_sub_f32_e32 v154, v154, v156
	v_add_f32_e32 v152, v154, v152
	v_add_f32_e32 v154, v153, v58
	v_sub_f32_e32 v156, v154, v153
	v_sub_f32_e32 v157, v154, v156
	v_sub_f32_e32 v153, v153, v157
	v_sub_f32_e32 v58, v58, v156
	v_add_f32_e32 v152, v154, v152
	v_add_f32_e32 v58, v58, v153
	v_add_f32_e32 v153, v155, v152
	v_sub_f32_e32 v154, v153, v155
	v_sub_f32_e32 v152, v152, v154
	v_add_f32_e32 v58, v58, v152
	v_add_f32_e32 v58, v153, v58
	v_cndmask_b32_e32 v58, v185, v58, vcc
	v_cmp_ngt_f32_e32 vcc, -1.0, v51
	s_nop 1
	v_cndmask_b32_e32 v58, v186, v58, vcc
	v_cmp_neq_f32_e32 vcc, -1.0, v51
	s_nop 1
	v_cndmask_b32_e32 v58, v187, v58, vcc
	v_cmp_lt_f32_e64 vcc, |v51|, s36
	s_nop 1
	v_cndmask_b32_e32 v51, v58, v51, vcc
	v_add_f32_e32 v50, v50, v51
	v_sub_f32_e32 v50, -0.5, v50
	v_mul_f32_e32 v50, 0x3fb8aa3b, v50
	v_exp_f32_e32 v50, v50
	s_nop 0
	v_xor_b32_e32 v58, 0x80000000, v50
	v_lshl_add_u64 v[50:51], v[70:71], 0, v[138:139]
	global_store_dword v[50:51], v58, off
	v_mov_b32_e32 v50, v240
	v_add_f32_e32 v51, v59, v50
	v_max_f32_e64 v50, -v51, 0
	v_mul_f32_e64 v51, |v51|, s30
	v_exp_f32_e32 v51, v51
	s_nop 0
	v_add_f32_e32 v152, 1.0, v51
	v_add_f32_e32 v58, -1.0, v152
	v_sub_f32_e32 v59, v58, v152
	v_add_f32_e32 v59, 1.0, v59
	v_sub_f32_e32 v58, v51, v58
	v_add_f32_e32 v153, v58, v59
	v_frexp_mant_f32_e32 v58, v152
	v_cmp_gt_f32_e32 vcc, s31, v58
	v_cvt_f64_f32_e32 v[58:59], v152
	v_frexp_exp_i32_f64_e32 v58, v[58:59]
	v_subbrev_co_u32_e32 v58, vcc, 0, v58, vcc
	v_sub_u32_e32 v59, 0, v58
	v_ldexp_f32 v152, v152, v59
	v_ldexp_f32 v59, v153, v59
	v_add_f32_e32 v153, -1.0, v152
	v_add_f32_e32 v154, 1.0, v153
	v_sub_f32_e32 v154, v152, v154
	v_add_f32_e32 v154, v59, v154
	v_add_f32_e32 v155, v153, v154
	v_sub_f32_e32 v153, v155, v153
	v_sub_f32_e32 v153, v154, v153
	v_add_f32_e32 v154, 1.0, v152
	v_add_f32_e32 v156, -1.0, v154
	v_sub_f32_e32 v152, v152, v156
	v_add_f32_e32 v59, v59, v152
	v_add_f32_e32 v152, v154, v59
	v_sub_f32_e32 v154, v152, v154
	v_sub_f32_e32 v59, v59, v154
	v_rcp_f32_e32 v154, v152
	v_cvt_f32_i32_e32 v58, v58
	v_cmp_neq_f32_e32 vcc, s35, v51
	v_mul_f32_e32 v156, v155, v154
	v_mul_f32_e32 v157, v152, v156
	v_fma_f32 v188, v156, v152, -v157
	v_fmac_f32_e32 v188, v156, v59
	v_add_f32_e32 v189, v157, v188
	v_sub_f32_e32 v190, v155, v189
	v_sub_f32_e32 v155, v155, v190
	v_sub_f32_e32 v157, v189, v157
	v_sub_f32_e32 v155, v155, v189
	v_add_f32_e32 v153, v153, v155
	v_sub_f32_e32 v155, v157, v188
	v_add_f32_e32 v153, v155, v153
	v_add_f32_e32 v155, v190, v153
	v_mul_f32_e32 v157, v154, v155
	v_mul_f32_e32 v188, v152, v157
	v_fma_f32 v152, v157, v152, -v188
	v_fmac_f32_e32 v152, v157, v59
	v_sub_f32_e32 v59, v190, v155
	v_add_f32_e32 v59, v153, v59
	v_add_f32_e32 v153, v188, v152
	v_sub_f32_e32 v189, v155, v153
	v_sub_f32_e32 v155, v155, v189
	v_sub_f32_e32 v188, v153, v188
	v_sub_f32_e32 v153, v155, v153
	v_add_f32_e32 v59, v59, v153
	v_sub_f32_e32 v152, v188, v152
	v_add_f32_e32 v59, v152, v59
	v_add_f32_e32 v152, v156, v157
	v_add_f32_e32 v59, v189, v59
	v_sub_f32_e32 v153, v152, v156
	v_mul_f32_e32 v59, v154, v59
	v_sub_f32_e32 v153, v157, v153
	v_add_f32_e32 v59, v153, v59
	v_mul_f32_e32 v156, 0x3f317218, v58
	v_add_f32_e32 v153, v152, v59
	v_fma_f32 v157, v58, s34, -v156
	v_mul_f32_e32 v154, v153, v153
	v_fmac_f32_e32 v157, 0xb102e308, v58
	v_sub_f32_e32 v58, v153, v152
	v_fmamk_f32 v155, v154, 0x3e9b6dac, v184
	v_sub_f32_e32 v58, v59, v58
	v_add_f32_e32 v59, v156, v157
	v_fmaak_f32 v155, v154, v155, 0x3f2aaada
	v_sub_f32_e32 v152, v59, v156
	v_ldexp_f32 v156, v153, 1
	v_mul_f32_e32 v153, v153, v154
	v_mul_f32_e32 v153, v153, v155
	v_add_f32_e32 v154, v156, v153
	v_sub_f32_e32 v155, v154, v156
	v_ldexp_f32 v58, v58, 1
	v_sub_f32_e32 v153, v153, v155
	v_add_f32_e32 v58, v58, v153
	v_add_f32_e32 v153, v154, v58
	v_sub_f32_e32 v154, v153, v154
	v_sub_f32_e32 v58, v58, v154
	v_add_f32_e32 v154, v59, v153
	v_sub_f32_e32 v155, v154, v59
	v_sub_f32_e32 v156, v154, v155
	v_sub_f32_e32 v152, v157, v152
	v_sub_f32_e32 v59, v59, v156
	v_sub_f32_e32 v153, v153, v155
	v_add_f32_e32 v59, v153, v59
	v_add_f32_e32 v153, v152, v58
	v_sub_f32_e32 v155, v153, v152
	v_sub_f32_e32 v156, v153, v155
	v_sub_f32_e32 v152, v152, v156
	v_sub_f32_e32 v58, v58, v155
	v_add_f32_e32 v59, v153, v59
	v_add_f32_e32 v58, v58, v152
	v_add_f32_e32 v152, v154, v59
	v_sub_f32_e32 v153, v152, v154
	v_sub_f32_e32 v59, v59, v153
	v_add_f32_e32 v58, v58, v59
	v_add_f32_e32 v58, v152, v58
	v_cndmask_b32_e32 v58, v185, v58, vcc
	v_cmp_ngt_f32_e32 vcc, -1.0, v51
	s_nop 1
	v_cndmask_b32_e32 v58, v186, v58, vcc
	v_cmp_neq_f32_e32 vcc, -1.0, v51
	s_nop 1
	v_cndmask_b32_e32 v58, v187, v58, vcc
	v_cmp_lt_f32_e64 vcc, |v51|, s36
	s_nop 1
	v_cndmask_b32_e32 v51, v58, v51, vcc
	v_add_f32_e32 v50, v50, v51
	v_sub_f32_e32 v50, -0.5, v50
	v_mul_f32_e32 v50, 0x3fb8aa3b, v50
	v_exp_f32_e32 v50, v50
	v_lshlrev_b64 v[58:59], 12, v[150:151]
	v_xor_b32_e32 v152, 0x80000000, v50
	v_lshl_add_u64 v[50:51], v[70:71], 0, v[58:59]
	global_store_dword v[50:51], v152, off
	v_mov_b32_e32 v50, v240
	v_add_f32_e32 v51, v60, v50
	v_max_f32_e64 v50, -v51, 0
	v_mul_f32_e64 v51, |v51|, s30
	v_exp_f32_e32 v51, v51
	s_nop 0
	v_add_f32_e32 v60, 1.0, v51
	v_add_f32_e32 v150, -1.0, v60
	v_sub_f32_e32 v151, v150, v60
	v_add_f32_e32 v151, 1.0, v151
	v_sub_f32_e32 v150, v51, v150
	v_add_f32_e32 v152, v150, v151
	v_frexp_mant_f32_e32 v150, v60
	v_cmp_gt_f32_e32 vcc, s31, v150
	v_cvt_f64_f32_e32 v[150:151], v60
	v_frexp_exp_i32_f64_e32 v150, v[150:151]
	v_subbrev_co_u32_e32 v150, vcc, 0, v150, vcc
	v_sub_u32_e32 v151, 0, v150
	v_ldexp_f32 v60, v60, v151
	v_ldexp_f32 v151, v152, v151
	v_add_f32_e32 v152, -1.0, v60
	v_add_f32_e32 v153, 1.0, v152
	v_sub_f32_e32 v153, v60, v153
	v_add_f32_e32 v153, v151, v153
	v_add_f32_e32 v154, v152, v153
	v_sub_f32_e32 v152, v154, v152
	v_sub_f32_e32 v152, v153, v152
	v_add_f32_e32 v153, 1.0, v60
	v_add_f32_e32 v155, -1.0, v153
	v_sub_f32_e32 v60, v60, v155
	v_add_f32_e32 v60, v151, v60
	v_add_f32_e32 v151, v153, v60
	v_sub_f32_e32 v153, v151, v153
	v_sub_f32_e32 v60, v60, v153
	v_rcp_f32_e32 v153, v151
	v_cvt_f32_i32_e32 v150, v150
	v_cmp_neq_f32_e32 vcc, s35, v51
	v_mul_f32_e32 v155, v154, v153
	v_mul_f32_e32 v156, v151, v155
	v_fma_f32 v157, v155, v151, -v156
	v_fmac_f32_e32 v157, v155, v60
	v_add_f32_e32 v188, v156, v157
	v_sub_f32_e32 v189, v154, v188
	v_sub_f32_e32 v154, v154, v189
	v_sub_f32_e32 v156, v188, v156
	v_sub_f32_e32 v154, v154, v188
	v_add_f32_e32 v152, v152, v154
	v_sub_f32_e32 v154, v156, v157
	v_add_f32_e32 v152, v154, v152
	v_add_f32_e32 v154, v189, v152
	v_mul_f32_e32 v156, v153, v154
	v_mul_f32_e32 v157, v151, v156
	v_fma_f32 v151, v156, v151, -v157
	v_fmac_f32_e32 v151, v156, v60
	v_sub_f32_e32 v60, v189, v154
	v_add_f32_e32 v60, v152, v60
	v_add_f32_e32 v152, v157, v151
	v_sub_f32_e32 v188, v154, v152
	v_sub_f32_e32 v154, v154, v188
	v_sub_f32_e32 v157, v152, v157
	v_sub_f32_e32 v152, v154, v152
	v_add_f32_e32 v60, v60, v152
	v_sub_f32_e32 v151, v157, v151
	v_add_f32_e32 v60, v151, v60
	v_add_f32_e32 v151, v155, v156
	v_add_f32_e32 v60, v188, v60
	v_sub_f32_e32 v152, v151, v155
	v_mul_f32_e32 v60, v153, v60
	v_sub_f32_e32 v152, v156, v152
	v_add_f32_e32 v60, v152, v60
	v_mul_f32_e32 v155, 0x3f317218, v150
	v_add_f32_e32 v152, v151, v60
	v_fma_f32 v156, v150, s34, -v155
	v_mul_f32_e32 v153, v152, v152
	v_fmac_f32_e32 v156, 0xb102e308, v150
	v_sub_f32_e32 v150, v152, v151
	v_fmamk_f32 v154, v153, 0x3e9b6dac, v184
	v_sub_f32_e32 v60, v60, v150
	v_add_f32_e32 v150, v155, v156
	v_fmaak_f32 v154, v153, v154, 0x3f2aaada
	v_sub_f32_e32 v151, v150, v155
	v_ldexp_f32 v155, v152, 1
	v_mul_f32_e32 v152, v152, v153
	v_mul_f32_e32 v152, v152, v154
	v_add_f32_e32 v153, v155, v152
	v_sub_f32_e32 v154, v153, v155
	v_ldexp_f32 v60, v60, 1
	v_sub_f32_e32 v152, v152, v154
	v_add_f32_e32 v60, v60, v152
	v_add_f32_e32 v152, v153, v60
	v_sub_f32_e32 v153, v152, v153
	v_sub_f32_e32 v60, v60, v153
	v_add_f32_e32 v153, v150, v152
	v_sub_f32_e32 v154, v153, v150
	v_sub_f32_e32 v155, v153, v154
	v_sub_f32_e32 v151, v156, v151
	v_sub_f32_e32 v150, v150, v155
	v_sub_f32_e32 v152, v152, v154
	v_add_f32_e32 v150, v152, v150
	v_add_f32_e32 v152, v151, v60
	v_sub_f32_e32 v154, v152, v151
	v_sub_f32_e32 v155, v152, v154
	v_sub_f32_e32 v151, v151, v155
	v_sub_f32_e32 v60, v60, v154
	v_add_f32_e32 v150, v152, v150
	v_add_f32_e32 v60, v60, v151
	v_add_f32_e32 v151, v153, v150
	v_sub_f32_e32 v152, v151, v153
	v_sub_f32_e32 v150, v150, v152
	v_add_f32_e32 v60, v60, v150
	v_add_f32_e32 v60, v151, v60
	v_cndmask_b32_e32 v60, v185, v60, vcc
	v_cmp_ngt_f32_e32 vcc, -1.0, v51
	s_nop 1
	v_cndmask_b32_e32 v60, v186, v60, vcc
	v_cmp_neq_f32_e32 vcc, -1.0, v51
	s_nop 1
	v_cndmask_b32_e32 v60, v187, v60, vcc
	v_cmp_lt_f32_e64 vcc, |v51|, s36
	s_nop 1
	v_cndmask_b32_e32 v51, v60, v51, vcc
	v_add_f32_e32 v50, v50, v51
	v_sub_f32_e32 v50, -0.5, v50
	v_mul_f32_e32 v50, 0x3fb8aa3b, v50
	v_exp_f32_e32 v50, v50
	s_nop 0
	v_xor_b32_e32 v60, 0x80000000, v50
	v_lshl_add_u64 v[50:51], v[70:71], 0, v[140:141]
	global_store_dword v[50:51], v60, off
	v_mov_b32_e32 v50, v240
	v_add_f32_e32 v51, v61, v50
	v_max_f32_e64 v50, -v51, 0
	v_mul_f32_e64 v51, |v51|, s30
	v_exp_f32_e32 v51, v51
	s_nop 0
	v_add_f32_e32 v150, 1.0, v51
	v_add_f32_e32 v60, -1.0, v150
	v_sub_f32_e32 v61, v60, v150
	v_add_f32_e32 v61, 1.0, v61
	v_sub_f32_e32 v60, v51, v60
	v_add_f32_e32 v151, v60, v61
	v_frexp_mant_f32_e32 v60, v150
	v_cmp_gt_f32_e32 vcc, s31, v60
	v_cvt_f64_f32_e32 v[60:61], v150
	v_frexp_exp_i32_f64_e32 v60, v[60:61]
	v_subbrev_co_u32_e32 v60, vcc, 0, v60, vcc
	v_sub_u32_e32 v61, 0, v60
	v_ldexp_f32 v150, v150, v61
	v_ldexp_f32 v61, v151, v61
	v_add_f32_e32 v151, -1.0, v150
	v_add_f32_e32 v152, 1.0, v151
	v_sub_f32_e32 v152, v150, v152
	v_add_f32_e32 v152, v61, v152
	v_add_f32_e32 v153, v151, v152
	v_sub_f32_e32 v151, v153, v151
	v_sub_f32_e32 v151, v152, v151
	v_add_f32_e32 v152, 1.0, v150
	v_add_f32_e32 v154, -1.0, v152
	v_sub_f32_e32 v150, v150, v154
	v_add_f32_e32 v61, v61, v150
	v_add_f32_e32 v150, v152, v61
	v_sub_f32_e32 v152, v150, v152
	v_sub_f32_e32 v61, v61, v152
	v_rcp_f32_e32 v152, v150
	v_cvt_f32_i32_e32 v60, v60
	v_cmp_neq_f32_e32 vcc, s35, v51
	v_mul_f32_e32 v154, v153, v152
	v_mul_f32_e32 v155, v150, v154
	v_fma_f32 v156, v154, v150, -v155
	v_fmac_f32_e32 v156, v154, v61
	v_add_f32_e32 v157, v155, v156
	v_sub_f32_e32 v188, v153, v157
	v_sub_f32_e32 v153, v153, v188
	v_sub_f32_e32 v155, v157, v155
	v_sub_f32_e32 v153, v153, v157
	v_add_f32_e32 v151, v151, v153
	v_sub_f32_e32 v153, v155, v156
	v_add_f32_e32 v151, v153, v151
	v_add_f32_e32 v153, v188, v151
	v_mul_f32_e32 v155, v152, v153
	v_mul_f32_e32 v156, v150, v155
	v_fma_f32 v150, v155, v150, -v156
	v_fmac_f32_e32 v150, v155, v61
	v_sub_f32_e32 v61, v188, v153
	v_add_f32_e32 v61, v151, v61
	v_add_f32_e32 v151, v156, v150
	v_sub_f32_e32 v157, v153, v151
	v_sub_f32_e32 v153, v153, v157
	v_sub_f32_e32 v156, v151, v156
	v_sub_f32_e32 v151, v153, v151
	v_add_f32_e32 v61, v61, v151
	v_sub_f32_e32 v150, v156, v150
	v_add_f32_e32 v61, v150, v61
	v_add_f32_e32 v150, v154, v155
	v_add_f32_e32 v61, v157, v61
	v_sub_f32_e32 v151, v150, v154
	v_mul_f32_e32 v61, v152, v61
	v_sub_f32_e32 v151, v155, v151
	v_add_f32_e32 v61, v151, v61
	v_mul_f32_e32 v154, 0x3f317218, v60
	v_add_f32_e32 v151, v150, v61
	v_fma_f32 v155, v60, s34, -v154
	v_mul_f32_e32 v152, v151, v151
	v_fmac_f32_e32 v155, 0xb102e308, v60
	v_sub_f32_e32 v60, v151, v150
	v_fmamk_f32 v153, v152, 0x3e9b6dac, v184
	v_sub_f32_e32 v60, v61, v60
	v_add_f32_e32 v61, v154, v155
	v_fmaak_f32 v153, v152, v153, 0x3f2aaada
	v_sub_f32_e32 v150, v61, v154
	v_ldexp_f32 v154, v151, 1
	v_mul_f32_e32 v151, v151, v152
	v_mul_f32_e32 v151, v151, v153
	v_add_f32_e32 v152, v154, v151
	v_sub_f32_e32 v153, v152, v154
	v_ldexp_f32 v60, v60, 1
	v_sub_f32_e32 v151, v151, v153
	v_add_f32_e32 v60, v60, v151
	v_add_f32_e32 v151, v152, v60
	v_sub_f32_e32 v152, v151, v152
	v_sub_f32_e32 v60, v60, v152
	v_add_f32_e32 v152, v61, v151
	v_sub_f32_e32 v153, v152, v61
	v_sub_f32_e32 v154, v152, v153
	v_sub_f32_e32 v150, v155, v150
	v_sub_f32_e32 v61, v61, v154
	v_sub_f32_e32 v151, v151, v153
	v_add_f32_e32 v61, v151, v61
	v_add_f32_e32 v151, v150, v60
	v_sub_f32_e32 v153, v151, v150
	v_sub_f32_e32 v154, v151, v153
	v_sub_f32_e32 v150, v150, v154
	v_sub_f32_e32 v60, v60, v153
	v_add_f32_e32 v61, v151, v61
	v_add_f32_e32 v60, v60, v150
	v_add_f32_e32 v150, v152, v61
	v_sub_f32_e32 v151, v150, v152
	v_sub_f32_e32 v61, v61, v151
	v_add_f32_e32 v60, v60, v61
	v_add_f32_e32 v60, v150, v60
	v_cndmask_b32_e32 v60, v185, v60, vcc
	v_cmp_ngt_f32_e32 vcc, -1.0, v51
	s_nop 1
	v_cndmask_b32_e32 v60, v186, v60, vcc
	v_cmp_neq_f32_e32 vcc, -1.0, v51
	s_nop 1
	v_cndmask_b32_e32 v60, v187, v60, vcc
	v_cmp_lt_f32_e64 vcc, |v51|, s36
	s_nop 1
	v_cndmask_b32_e32 v51, v60, v51, vcc
	v_add_f32_e32 v50, v50, v51
	v_sub_f32_e32 v50, -0.5, v50
	v_mul_f32_e32 v50, 0x3fb8aa3b, v50
	v_exp_f32_e32 v50, v50
	v_lshlrev_b64 v[60:61], 12, v[148:149]
	v_xor_b32_e32 v150, 0x80000000, v50
	v_lshl_add_u64 v[50:51], v[70:71], 0, v[60:61]
	global_store_dword v[50:51], v150, off
	v_mov_b32_e32 v50, v240
	v_add_f32_e32 v51, v62, v50
	v_max_f32_e64 v50, -v51, 0
	v_mul_f32_e64 v51, |v51|, s30
	v_exp_f32_e32 v51, v51
	s_nop 0
	v_add_f32_e32 v62, 1.0, v51
	v_add_f32_e32 v148, -1.0, v62
	v_sub_f32_e32 v149, v148, v62
	v_add_f32_e32 v149, 1.0, v149
	v_sub_f32_e32 v148, v51, v148
	v_add_f32_e32 v150, v148, v149
	v_frexp_mant_f32_e32 v148, v62
	v_cmp_gt_f32_e32 vcc, s31, v148
	v_cvt_f64_f32_e32 v[148:149], v62
	v_frexp_exp_i32_f64_e32 v148, v[148:149]
	v_subbrev_co_u32_e32 v148, vcc, 0, v148, vcc
	v_sub_u32_e32 v149, 0, v148
	v_ldexp_f32 v62, v62, v149
	v_ldexp_f32 v149, v150, v149
	v_add_f32_e32 v150, -1.0, v62
	v_add_f32_e32 v151, 1.0, v150
	v_sub_f32_e32 v151, v62, v151
	v_add_f32_e32 v151, v149, v151
	v_add_f32_e32 v152, v150, v151
	v_sub_f32_e32 v150, v152, v150
	v_sub_f32_e32 v150, v151, v150
	v_add_f32_e32 v151, 1.0, v62
	v_add_f32_e32 v153, -1.0, v151
	v_sub_f32_e32 v62, v62, v153
	v_add_f32_e32 v62, v149, v62
	v_add_f32_e32 v149, v151, v62
	v_sub_f32_e32 v151, v149, v151
	v_sub_f32_e32 v62, v62, v151
	v_rcp_f32_e32 v151, v149
	v_cvt_f32_i32_e32 v148, v148
	v_cmp_neq_f32_e32 vcc, s35, v51
	v_mul_f32_e32 v153, v152, v151
	v_mul_f32_e32 v154, v149, v153
	v_fma_f32 v155, v153, v149, -v154
	v_fmac_f32_e32 v155, v153, v62
	v_add_f32_e32 v156, v154, v155
	v_sub_f32_e32 v157, v152, v156
	v_sub_f32_e32 v152, v152, v157
	v_sub_f32_e32 v154, v156, v154
	v_sub_f32_e32 v152, v152, v156
	v_add_f32_e32 v150, v150, v152
	v_sub_f32_e32 v152, v154, v155
	v_add_f32_e32 v150, v152, v150
	v_add_f32_e32 v152, v157, v150
	v_mul_f32_e32 v154, v151, v152
	v_mul_f32_e32 v155, v149, v154
	v_fma_f32 v149, v154, v149, -v155
	v_fmac_f32_e32 v149, v154, v62
	v_sub_f32_e32 v62, v157, v152
	v_add_f32_e32 v62, v150, v62
	v_add_f32_e32 v150, v155, v149
	v_sub_f32_e32 v156, v152, v150
	v_sub_f32_e32 v152, v152, v156
	v_sub_f32_e32 v155, v150, v155
	v_sub_f32_e32 v150, v152, v150
	v_add_f32_e32 v62, v62, v150
	v_sub_f32_e32 v149, v155, v149
	v_add_f32_e32 v62, v149, v62
	v_add_f32_e32 v149, v153, v154
	v_add_f32_e32 v62, v156, v62
	v_sub_f32_e32 v150, v149, v153
	v_mul_f32_e32 v62, v151, v62
	v_sub_f32_e32 v150, v154, v150
	v_add_f32_e32 v62, v150, v62
	v_mul_f32_e32 v153, 0x3f317218, v148
	v_add_f32_e32 v150, v149, v62
	v_fma_f32 v154, v148, s34, -v153
	v_mul_f32_e32 v151, v150, v150
	v_fmac_f32_e32 v154, 0xb102e308, v148
	v_sub_f32_e32 v148, v150, v149
	v_fmamk_f32 v152, v151, 0x3e9b6dac, v184
	v_sub_f32_e32 v62, v62, v148
	v_add_f32_e32 v148, v153, v154
	v_fmaak_f32 v152, v151, v152, 0x3f2aaada
	v_sub_f32_e32 v149, v148, v153
	v_ldexp_f32 v153, v150, 1
	v_mul_f32_e32 v150, v150, v151
	v_mul_f32_e32 v150, v150, v152
	v_add_f32_e32 v151, v153, v150
	v_sub_f32_e32 v152, v151, v153
	v_ldexp_f32 v62, v62, 1
	v_sub_f32_e32 v150, v150, v152
	v_add_f32_e32 v62, v62, v150
	v_add_f32_e32 v150, v151, v62
	v_sub_f32_e32 v151, v150, v151
	v_sub_f32_e32 v62, v62, v151
	v_add_f32_e32 v151, v148, v150
	v_sub_f32_e32 v152, v151, v148
	v_sub_f32_e32 v153, v151, v152
	v_sub_f32_e32 v149, v154, v149
	v_sub_f32_e32 v148, v148, v153
	v_sub_f32_e32 v150, v150, v152
	v_add_f32_e32 v148, v150, v148
	v_add_f32_e32 v150, v149, v62
	v_sub_f32_e32 v152, v150, v149
	v_sub_f32_e32 v153, v150, v152
	v_sub_f32_e32 v149, v149, v153
	v_sub_f32_e32 v62, v62, v152
	v_add_f32_e32 v148, v150, v148
	v_add_f32_e32 v62, v62, v149
	v_add_f32_e32 v149, v151, v148
	v_sub_f32_e32 v150, v149, v151
	v_sub_f32_e32 v148, v148, v150
	v_add_f32_e32 v62, v62, v148
	v_add_f32_e32 v62, v149, v62
	v_cndmask_b32_e32 v62, v185, v62, vcc
	v_cmp_ngt_f32_e32 vcc, -1.0, v51
	s_nop 1
	v_cndmask_b32_e32 v62, v186, v62, vcc
	v_cmp_neq_f32_e32 vcc, -1.0, v51
	s_nop 1
	v_cndmask_b32_e32 v62, v187, v62, vcc
	v_cmp_lt_f32_e64 vcc, |v51|, s36
	s_nop 1
	v_cndmask_b32_e32 v51, v62, v51, vcc
	v_add_f32_e32 v50, v50, v51
	v_sub_f32_e32 v50, -0.5, v50
	v_mul_f32_e32 v50, 0x3fb8aa3b, v50
	v_exp_f32_e32 v50, v50
	s_nop 0
	v_xor_b32_e32 v62, 0x80000000, v50
	v_lshl_add_u64 v[50:51], v[70:71], 0, v[142:143]
	global_store_dword v[50:51], v62, off
	v_mov_b32_e32 v50, v240
	v_add_f32_e32 v51, v63, v50
	v_max_f32_e64 v50, -v51, 0
	v_mul_f32_e64 v51, |v51|, s30
	v_exp_f32_e32 v51, v51
	s_nop 0
	v_add_f32_e32 v148, 1.0, v51
	v_add_f32_e32 v62, -1.0, v148
	v_sub_f32_e32 v63, v62, v148
	v_add_f32_e32 v63, 1.0, v63
	v_sub_f32_e32 v62, v51, v62
	v_add_f32_e32 v149, v62, v63
	v_frexp_mant_f32_e32 v62, v148
	v_cmp_gt_f32_e32 vcc, s31, v62
	v_cvt_f64_f32_e32 v[62:63], v148
	v_frexp_exp_i32_f64_e32 v62, v[62:63]
	v_subbrev_co_u32_e32 v62, vcc, 0, v62, vcc
	v_sub_u32_e32 v63, 0, v62
	v_ldexp_f32 v148, v148, v63
	v_ldexp_f32 v63, v149, v63
	v_add_f32_e32 v149, -1.0, v148
	v_add_f32_e32 v150, 1.0, v149
	v_sub_f32_e32 v150, v148, v150
	v_add_f32_e32 v150, v63, v150
	v_add_f32_e32 v151, v149, v150
	v_sub_f32_e32 v149, v151, v149
	v_sub_f32_e32 v149, v150, v149
	v_add_f32_e32 v150, 1.0, v148
	v_add_f32_e32 v152, -1.0, v150
	v_sub_f32_e32 v148, v148, v152
	v_add_f32_e32 v63, v63, v148
	v_add_f32_e32 v148, v150, v63
	v_sub_f32_e32 v150, v148, v150
	v_sub_f32_e32 v63, v63, v150
	v_rcp_f32_e32 v150, v148
	v_cvt_f32_i32_e32 v62, v62
	v_cmp_neq_f32_e32 vcc, s35, v51
	v_mul_f32_e32 v152, v151, v150
	v_mul_f32_e32 v153, v148, v152
	v_fma_f32 v154, v152, v148, -v153
	v_fmac_f32_e32 v154, v152, v63
	v_add_f32_e32 v155, v153, v154
	v_sub_f32_e32 v156, v151, v155
	v_sub_f32_e32 v151, v151, v156
	v_sub_f32_e32 v153, v155, v153
	v_sub_f32_e32 v151, v151, v155
	v_add_f32_e32 v149, v149, v151
	v_sub_f32_e32 v151, v153, v154
	v_add_f32_e32 v149, v151, v149
	v_add_f32_e32 v151, v156, v149
	v_mul_f32_e32 v153, v150, v151
	v_mul_f32_e32 v154, v148, v153
	v_fma_f32 v148, v153, v148, -v154
	v_fmac_f32_e32 v148, v153, v63
	v_sub_f32_e32 v63, v156, v151
	v_add_f32_e32 v63, v149, v63
	v_add_f32_e32 v149, v154, v148
	v_sub_f32_e32 v155, v151, v149
	v_sub_f32_e32 v151, v151, v155
	v_sub_f32_e32 v154, v149, v154
	v_sub_f32_e32 v149, v151, v149
	v_add_f32_e32 v63, v63, v149
	v_sub_f32_e32 v148, v154, v148
	v_add_f32_e32 v63, v148, v63
	v_add_f32_e32 v148, v152, v153
	v_add_f32_e32 v63, v155, v63
	v_sub_f32_e32 v149, v148, v152
	v_mul_f32_e32 v63, v150, v63
	v_sub_f32_e32 v149, v153, v149
	v_add_f32_e32 v63, v149, v63
	v_mul_f32_e32 v152, 0x3f317218, v62
	v_add_f32_e32 v149, v148, v63
	v_fma_f32 v153, v62, s34, -v152
	v_mul_f32_e32 v150, v149, v149
	v_fmac_f32_e32 v153, 0xb102e308, v62
	v_sub_f32_e32 v62, v149, v148
	v_fmamk_f32 v151, v150, 0x3e9b6dac, v184
	v_sub_f32_e32 v62, v63, v62
	v_add_f32_e32 v63, v152, v153
	v_fmaak_f32 v151, v150, v151, 0x3f2aaada
	v_sub_f32_e32 v148, v63, v152
	v_ldexp_f32 v152, v149, 1
	v_mul_f32_e32 v149, v149, v150
	v_mul_f32_e32 v149, v149, v151
	v_add_f32_e32 v150, v152, v149
	v_sub_f32_e32 v151, v150, v152
	v_ldexp_f32 v62, v62, 1
	v_sub_f32_e32 v149, v149, v151
	v_add_f32_e32 v62, v62, v149
	v_add_f32_e32 v149, v150, v62
	v_sub_f32_e32 v150, v149, v150
	v_sub_f32_e32 v62, v62, v150
	v_add_f32_e32 v150, v63, v149
	v_sub_f32_e32 v151, v150, v63
	v_sub_f32_e32 v152, v150, v151
	v_sub_f32_e32 v148, v153, v148
	v_sub_f32_e32 v63, v63, v152
	v_sub_f32_e32 v149, v149, v151
	v_add_f32_e32 v63, v149, v63
	v_add_f32_e32 v149, v148, v62
	v_sub_f32_e32 v151, v149, v148
	v_sub_f32_e32 v152, v149, v151
	v_sub_f32_e32 v148, v148, v152
	v_sub_f32_e32 v62, v62, v151
	v_add_f32_e32 v63, v149, v63
	v_add_f32_e32 v62, v62, v148
	v_add_f32_e32 v148, v150, v63
	v_sub_f32_e32 v149, v148, v150
	v_sub_f32_e32 v63, v63, v149
	v_add_f32_e32 v62, v62, v63
	v_add_f32_e32 v62, v148, v62
	v_cndmask_b32_e32 v62, v185, v62, vcc
	v_cmp_ngt_f32_e32 vcc, -1.0, v51
	s_nop 1
	v_cndmask_b32_e32 v62, v186, v62, vcc
	v_cmp_neq_f32_e32 vcc, -1.0, v51
	s_nop 1
	v_cndmask_b32_e32 v62, v187, v62, vcc
	v_cmp_lt_f32_e64 vcc, |v51|, s36
	s_nop 1
	v_cndmask_b32_e32 v51, v62, v51, vcc
	v_add_f32_e32 v50, v50, v51
	v_sub_f32_e32 v50, -0.5, v50
	v_mul_f32_e32 v50, 0x3fb8aa3b, v50
	v_exp_f32_e32 v50, v50
	v_lshlrev_b64 v[62:63], 12, v[146:147]
	v_xor_b32_e32 v148, 0x80000000, v50
	v_lshl_add_u64 v[50:51], v[70:71], 0, v[62:63]
	global_store_dword v[50:51], v148, off
	v_mov_b32_e32 v50, v240
	v_add_f32_e32 v51, v64, v50
	v_max_f32_e64 v50, -v51, 0
	v_mul_f32_e64 v51, |v51|, s30
	v_exp_f32_e32 v51, v51
	s_nop 0
	v_add_f32_e32 v64, 1.0, v51
	v_add_f32_e32 v146, -1.0, v64
	v_sub_f32_e32 v147, v146, v64
	v_add_f32_e32 v147, 1.0, v147
	v_sub_f32_e32 v146, v51, v146
	v_add_f32_e32 v148, v146, v147
	v_frexp_mant_f32_e32 v146, v64
	v_cmp_gt_f32_e32 vcc, s31, v146
	v_cvt_f64_f32_e32 v[146:147], v64
	v_frexp_exp_i32_f64_e32 v146, v[146:147]
	v_subbrev_co_u32_e32 v146, vcc, 0, v146, vcc
	v_sub_u32_e32 v147, 0, v146
	v_ldexp_f32 v64, v64, v147
	v_ldexp_f32 v147, v148, v147
	v_add_f32_e32 v148, -1.0, v64
	v_add_f32_e32 v149, 1.0, v148
	v_sub_f32_e32 v149, v64, v149
	v_add_f32_e32 v149, v147, v149
	v_add_f32_e32 v150, v148, v149
	v_sub_f32_e32 v148, v150, v148
	v_sub_f32_e32 v148, v149, v148
	v_add_f32_e32 v149, 1.0, v64
	v_add_f32_e32 v151, -1.0, v149
	v_sub_f32_e32 v64, v64, v151
	v_add_f32_e32 v64, v147, v64
	v_add_f32_e32 v147, v149, v64
	v_sub_f32_e32 v149, v147, v149
	v_sub_f32_e32 v64, v64, v149
	v_rcp_f32_e32 v149, v147
	v_cvt_f32_i32_e32 v146, v146
	v_cmp_neq_f32_e32 vcc, s35, v51
	v_mul_f32_e32 v151, v150, v149
	v_mul_f32_e32 v152, v147, v151
	v_fma_f32 v153, v151, v147, -v152
	v_fmac_f32_e32 v153, v151, v64
	v_add_f32_e32 v154, v152, v153
	v_sub_f32_e32 v155, v150, v154
	v_sub_f32_e32 v150, v150, v155
	v_sub_f32_e32 v152, v154, v152
	v_sub_f32_e32 v150, v150, v154
	v_add_f32_e32 v148, v148, v150
	v_sub_f32_e32 v150, v152, v153
	v_add_f32_e32 v148, v150, v148
	v_add_f32_e32 v150, v155, v148
	v_mul_f32_e32 v152, v149, v150
	v_mul_f32_e32 v153, v147, v152
	v_fma_f32 v147, v152, v147, -v153
	v_fmac_f32_e32 v147, v152, v64
	v_sub_f32_e32 v64, v155, v150
	v_add_f32_e32 v64, v148, v64
	v_add_f32_e32 v148, v153, v147
	v_sub_f32_e32 v154, v150, v148
	v_sub_f32_e32 v150, v150, v154
	v_sub_f32_e32 v153, v148, v153
	v_sub_f32_e32 v148, v150, v148
	v_add_f32_e32 v64, v64, v148
	v_sub_f32_e32 v147, v153, v147
	v_add_f32_e32 v64, v147, v64
	v_add_f32_e32 v147, v151, v152
	v_add_f32_e32 v64, v154, v64
	v_sub_f32_e32 v148, v147, v151
	v_mul_f32_e32 v64, v149, v64
	v_sub_f32_e32 v148, v152, v148
	v_add_f32_e32 v64, v148, v64
	v_mul_f32_e32 v151, 0x3f317218, v146
	v_add_f32_e32 v148, v147, v64
	v_fma_f32 v152, v146, s34, -v151
	v_mul_f32_e32 v149, v148, v148
	v_fmac_f32_e32 v152, 0xb102e308, v146
	v_sub_f32_e32 v146, v148, v147
	v_fmamk_f32 v150, v149, 0x3e9b6dac, v184
	v_sub_f32_e32 v64, v64, v146
	v_add_f32_e32 v146, v151, v152
	v_fmaak_f32 v150, v149, v150, 0x3f2aaada
	v_sub_f32_e32 v147, v146, v151
	v_ldexp_f32 v151, v148, 1
	v_mul_f32_e32 v148, v148, v149
	v_mul_f32_e32 v148, v148, v150
	v_add_f32_e32 v149, v151, v148
	v_sub_f32_e32 v150, v149, v151
	v_ldexp_f32 v64, v64, 1
	v_sub_f32_e32 v148, v148, v150
	v_add_f32_e32 v64, v64, v148
	v_add_f32_e32 v148, v149, v64
	v_sub_f32_e32 v149, v148, v149
	v_sub_f32_e32 v64, v64, v149
	v_add_f32_e32 v149, v146, v148
	v_sub_f32_e32 v150, v149, v146
	v_sub_f32_e32 v151, v149, v150
	v_sub_f32_e32 v147, v152, v147
	v_sub_f32_e32 v146, v146, v151
	v_sub_f32_e32 v148, v148, v150
	v_add_f32_e32 v146, v148, v146
	v_add_f32_e32 v148, v147, v64
	v_sub_f32_e32 v150, v148, v147
	v_sub_f32_e32 v151, v148, v150
	v_sub_f32_e32 v147, v147, v151
	v_sub_f32_e32 v64, v64, v150
	v_add_f32_e32 v146, v148, v146
	v_add_f32_e32 v64, v64, v147
	v_add_f32_e32 v147, v149, v146
	v_sub_f32_e32 v148, v147, v149
	v_sub_f32_e32 v146, v146, v148
	v_add_f32_e32 v64, v64, v146
	v_add_f32_e32 v64, v147, v64
	v_cndmask_b32_e32 v64, v185, v64, vcc
	v_cmp_ngt_f32_e32 vcc, -1.0, v51
	s_nop 1
	v_cndmask_b32_e32 v64, v186, v64, vcc
	v_cmp_neq_f32_e32 vcc, -1.0, v51
	s_nop 1
	v_cndmask_b32_e32 v64, v187, v64, vcc
	v_cmp_lt_f32_e64 vcc, |v51|, s36
	s_nop 1
	v_cndmask_b32_e32 v51, v64, v51, vcc
	v_add_f32_e32 v50, v50, v51
	v_sub_f32_e32 v50, -0.5, v50
	v_mul_f32_e32 v50, 0x3fb8aa3b, v50
	v_exp_f32_e32 v50, v50
	s_nop 0
	v_xor_b32_e32 v64, 0x80000000, v50
	v_lshl_add_u64 v[50:51], v[70:71], 0, v[144:145]
	global_store_dword v[50:51], v64, off
	v_mov_b32_e32 v50, v240
	v_add_f32_e32 v51, v65, v50
	v_max_f32_e64 v50, -v51, 0
	v_mul_f32_e64 v51, |v51|, s30
	v_exp_f32_e32 v51, v51
	s_nop 0
	v_add_f32_e32 v146, 1.0, v51
	v_add_f32_e32 v64, -1.0, v146
	v_sub_f32_e32 v65, v64, v146
	v_add_f32_e32 v65, 1.0, v65
	v_sub_f32_e32 v64, v51, v64
	v_add_f32_e32 v147, v64, v65
	v_frexp_mant_f32_e32 v64, v146
	v_cmp_gt_f32_e32 vcc, s31, v64
	v_cvt_f64_f32_e32 v[64:65], v146
	v_frexp_exp_i32_f64_e32 v64, v[64:65]
	v_subbrev_co_u32_e32 v64, vcc, 0, v64, vcc
	v_sub_u32_e32 v65, 0, v64
	v_ldexp_f32 v146, v146, v65
	v_ldexp_f32 v65, v147, v65
	v_add_f32_e32 v147, -1.0, v146
	v_add_f32_e32 v148, 1.0, v147
	v_sub_f32_e32 v148, v146, v148
	v_add_f32_e32 v148, v65, v148
	v_add_f32_e32 v149, v147, v148
	v_sub_f32_e32 v147, v149, v147
	v_sub_f32_e32 v147, v148, v147
	v_add_f32_e32 v148, 1.0, v146
	v_add_f32_e32 v150, -1.0, v148
	v_sub_f32_e32 v146, v146, v150
	v_add_f32_e32 v65, v65, v146
	v_add_f32_e32 v146, v148, v65
	v_sub_f32_e32 v148, v146, v148
	v_sub_f32_e32 v65, v65, v148
	v_rcp_f32_e32 v148, v146
	v_cvt_f32_i32_e32 v64, v64
	v_cmp_neq_f32_e32 vcc, s35, v51
	v_mul_f32_e32 v150, v149, v148
	v_mul_f32_e32 v151, v146, v150
	v_fma_f32 v152, v150, v146, -v151
	v_fmac_f32_e32 v152, v150, v65
	v_add_f32_e32 v153, v151, v152
	v_sub_f32_e32 v154, v149, v153
	v_sub_f32_e32 v149, v149, v154
	v_sub_f32_e32 v151, v153, v151
	v_sub_f32_e32 v149, v149, v153
	v_add_f32_e32 v147, v147, v149
	v_sub_f32_e32 v149, v151, v152
	v_add_f32_e32 v147, v149, v147
	v_add_f32_e32 v149, v154, v147
	v_mul_f32_e32 v151, v148, v149
	v_mul_f32_e32 v152, v146, v151
	v_fma_f32 v146, v151, v146, -v152
	v_fmac_f32_e32 v146, v151, v65
	v_sub_f32_e32 v65, v154, v149
	v_add_f32_e32 v65, v147, v65
	v_add_f32_e32 v147, v152, v146
	v_sub_f32_e32 v153, v149, v147
	v_sub_f32_e32 v149, v149, v153
	v_sub_f32_e32 v152, v147, v152
	v_sub_f32_e32 v147, v149, v147
	v_add_f32_e32 v65, v65, v147
	v_sub_f32_e32 v146, v152, v146
	v_add_f32_e32 v65, v146, v65
	v_add_f32_e32 v146, v150, v151
	v_add_f32_e32 v65, v153, v65
	v_sub_f32_e32 v147, v146, v150
	v_mul_f32_e32 v65, v148, v65
	v_sub_f32_e32 v147, v151, v147
	v_add_f32_e32 v65, v147, v65
	v_mul_f32_e32 v150, 0x3f317218, v64
	v_add_f32_e32 v147, v146, v65
	v_fma_f32 v151, v64, s34, -v150
	v_mul_f32_e32 v148, v147, v147
	v_fmac_f32_e32 v151, 0xb102e308, v64
	v_sub_f32_e32 v64, v147, v146
	v_fmamk_f32 v149, v148, 0x3e9b6dac, v184
	v_sub_f32_e32 v64, v65, v64
	v_add_f32_e32 v65, v150, v151
	v_fmaak_f32 v149, v148, v149, 0x3f2aaada
	v_sub_f32_e32 v146, v65, v150
	v_ldexp_f32 v150, v147, 1
	v_mul_f32_e32 v147, v147, v148
	v_mul_f32_e32 v147, v147, v149
	v_add_f32_e32 v148, v150, v147
	v_sub_f32_e32 v149, v148, v150
	v_ldexp_f32 v64, v64, 1
	v_sub_f32_e32 v147, v147, v149
	v_add_f32_e32 v64, v64, v147
	v_add_f32_e32 v147, v148, v64
	v_sub_f32_e32 v148, v147, v148
	v_sub_f32_e32 v64, v64, v148
	v_add_f32_e32 v148, v65, v147
	v_sub_f32_e32 v149, v148, v65
	v_sub_f32_e32 v150, v148, v149
	v_sub_f32_e32 v146, v151, v146
	v_sub_f32_e32 v65, v65, v150
	v_sub_f32_e32 v147, v147, v149
	v_add_f32_e32 v65, v147, v65
	v_add_f32_e32 v147, v146, v64
	v_sub_f32_e32 v149, v147, v146
	v_sub_f32_e32 v150, v147, v149
	v_sub_f32_e32 v146, v146, v150
	v_sub_f32_e32 v64, v64, v149
	v_add_f32_e32 v65, v147, v65
	v_add_f32_e32 v64, v64, v146
	v_add_f32_e32 v146, v148, v65
	v_sub_f32_e32 v147, v146, v148
	v_sub_f32_e32 v65, v65, v147
	v_add_f32_e32 v64, v64, v65
	v_add_f32_e32 v64, v146, v64
	v_cndmask_b32_e32 v64, v185, v64, vcc
	v_cmp_ngt_f32_e32 vcc, -1.0, v51
	s_nop 1
	v_cndmask_b32_e32 v64, v186, v64, vcc
	v_cmp_neq_f32_e32 vcc, -1.0, v51
	s_nop 1
	v_cndmask_b32_e32 v64, v187, v64, vcc
	v_cmp_lt_f32_e64 vcc, |v51|, s36
	s_nop 1
	v_cndmask_b32_e32 v51, v64, v51, vcc
	v_add_f32_e32 v50, v50, v51
	v_sub_f32_e32 v50, -0.5, v50
	v_mul_f32_e32 v50, 0x3fb8aa3b, v50
	v_exp_f32_e32 v50, v50
	v_lshlrev_b64 v[64:65], 12, v[126:127]
	v_xor_b32_e32 v146, 0x80000000, v50
	v_lshl_add_u64 v[50:51], v[70:71], 0, v[64:65]
	global_store_dword v[50:51], v146, off
	global_load_dword v50, v[66:67], off offset:128
	s_waitcnt vmcnt(0)
	v_mov_b32_e32 v241, v50
	v_add_f32_e32 v50, v34, v50
	v_max_f32_e64 v34, -v50, 0
	v_mul_f32_e64 v50, |v50|, s30
	v_exp_f32_e32 v50, v50
	s_nop 0
	v_add_f32_e32 v51, 1.0, v50
	v_add_f32_e32 v126, -1.0, v51
	v_sub_f32_e32 v127, v126, v51
	v_add_f32_e32 v127, 1.0, v127
	v_sub_f32_e32 v126, v50, v126
	v_add_f32_e32 v146, v126, v127
	v_frexp_mant_f32_e32 v126, v51
	v_cmp_gt_f32_e32 vcc, s31, v126
	v_cvt_f64_f32_e32 v[126:127], v51
	v_frexp_exp_i32_f64_e32 v126, v[126:127]
	v_subbrev_co_u32_e32 v126, vcc, 0, v126, vcc
	v_sub_u32_e32 v127, 0, v126
	v_ldexp_f32 v51, v51, v127
	v_ldexp_f32 v127, v146, v127
	v_add_f32_e32 v146, -1.0, v51
	v_add_f32_e32 v147, 1.0, v146
	v_sub_f32_e32 v147, v51, v147
	v_add_f32_e32 v147, v127, v147
	v_add_f32_e32 v148, v146, v147
	v_sub_f32_e32 v146, v148, v146
	v_sub_f32_e32 v146, v147, v146
	v_add_f32_e32 v147, 1.0, v51
	v_add_f32_e32 v149, -1.0, v147
	v_sub_f32_e32 v51, v51, v149
	v_add_f32_e32 v51, v127, v51
	v_add_f32_e32 v127, v147, v51
	v_sub_f32_e32 v147, v127, v147
	v_sub_f32_e32 v51, v51, v147
	v_rcp_f32_e32 v147, v127
	v_cvt_f32_i32_e32 v126, v126
	v_cmp_neq_f32_e32 vcc, s35, v50
	v_mul_f32_e32 v149, v148, v147
	v_mul_f32_e32 v150, v127, v149
	v_fma_f32 v151, v149, v127, -v150
	v_fmac_f32_e32 v151, v149, v51
	v_add_f32_e32 v152, v150, v151
	v_sub_f32_e32 v153, v148, v152
	v_sub_f32_e32 v148, v148, v153
	v_sub_f32_e32 v150, v152, v150
	v_sub_f32_e32 v148, v148, v152
	v_add_f32_e32 v146, v146, v148
	v_sub_f32_e32 v148, v150, v151
	v_add_f32_e32 v146, v148, v146
	v_add_f32_e32 v148, v153, v146
	v_mul_f32_e32 v150, v147, v148
	v_mul_f32_e32 v151, v127, v150
	v_fma_f32 v127, v150, v127, -v151
	v_fmac_f32_e32 v127, v150, v51
	v_sub_f32_e32 v51, v153, v148
	v_add_f32_e32 v51, v146, v51
	v_add_f32_e32 v146, v151, v127
	v_sub_f32_e32 v152, v148, v146
	v_sub_f32_e32 v148, v148, v152
	v_sub_f32_e32 v151, v146, v151
	v_sub_f32_e32 v146, v148, v146
	v_add_f32_e32 v51, v51, v146
	v_sub_f32_e32 v127, v151, v127
	v_add_f32_e32 v51, v127, v51
	v_add_f32_e32 v127, v149, v150
	v_add_f32_e32 v51, v152, v51
	v_sub_f32_e32 v146, v127, v149
	v_mul_f32_e32 v51, v147, v51
	v_sub_f32_e32 v146, v150, v146
	v_add_f32_e32 v51, v146, v51
	v_mul_f32_e32 v149, 0x3f317218, v126
	v_add_f32_e32 v146, v127, v51
	v_fma_f32 v150, v126, s34, -v149
	v_mul_f32_e32 v147, v146, v146
	v_fmac_f32_e32 v150, 0xb102e308, v126
	v_sub_f32_e32 v126, v146, v127
	v_fmamk_f32 v148, v147, 0x3e9b6dac, v184
	v_sub_f32_e32 v51, v51, v126
	v_add_f32_e32 v126, v149, v150
	v_fmaak_f32 v148, v147, v148, 0x3f2aaada
	v_sub_f32_e32 v127, v126, v149
	v_ldexp_f32 v149, v146, 1
	v_mul_f32_e32 v146, v146, v147
	v_mul_f32_e32 v146, v146, v148
	v_add_f32_e32 v147, v149, v146
	v_sub_f32_e32 v148, v147, v149
	v_ldexp_f32 v51, v51, 1
	v_sub_f32_e32 v146, v146, v148
	v_add_f32_e32 v51, v51, v146
	v_add_f32_e32 v146, v147, v51
	v_sub_f32_e32 v147, v146, v147
	v_sub_f32_e32 v51, v51, v147
	v_add_f32_e32 v147, v126, v146
	v_sub_f32_e32 v148, v147, v126
	v_sub_f32_e32 v149, v147, v148
	v_sub_f32_e32 v127, v150, v127
	v_sub_f32_e32 v126, v126, v149
	v_sub_f32_e32 v146, v146, v148
	v_add_f32_e32 v126, v146, v126
	v_add_f32_e32 v146, v127, v51
	v_sub_f32_e32 v148, v146, v127
	v_sub_f32_e32 v149, v146, v148
	v_sub_f32_e32 v127, v127, v149
	v_sub_f32_e32 v51, v51, v148
	v_add_f32_e32 v126, v146, v126
	v_add_f32_e32 v51, v51, v127
	v_add_f32_e32 v127, v147, v126
	v_sub_f32_e32 v146, v127, v147
	v_sub_f32_e32 v126, v126, v146
	v_add_f32_e32 v51, v51, v126
	v_add_f32_e32 v51, v127, v51
	v_cndmask_b32_e32 v51, v185, v51, vcc
	v_cmp_ngt_f32_e32 vcc, -1.0, v50
	v_lshl_add_u64 v[126:127], s[16:17], 0, v[128:129]
	s_nop 0
	v_cndmask_b32_e32 v51, v186, v51, vcc
	v_cmp_neq_f32_e32 vcc, -1.0, v50
	s_nop 1
	v_cndmask_b32_e32 v51, v187, v51, vcc
	v_cmp_lt_f32_e64 vcc, |v50|, s36
	s_nop 1
	v_cndmask_b32_e32 v50, v51, v50, vcc
	v_add_f32_e32 v34, v34, v50
	v_sub_f32_e32 v34, -0.5, v34
	v_mul_f32_e32 v34, 0x3fb8aa3b, v34
	v_exp_f32_e32 v34, v34
	v_lshlrev_b64 v[50:51], 2, v[98:99]
	v_lshl_add_u64 v[126:127], v[126:127], 0, v[50:51]
	v_xor_b32_e32 v34, 0x80000000, v34
	global_store_dword v[126:127], v34, off
	v_mov_b32_e32 v34, v241
	v_add_f32_e32 v35, v35, v34
	v_max_f32_e64 v34, -v35, 0
	v_mul_f32_e64 v35, |v35|, s30
	v_exp_f32_e32 v35, v35
	s_nop 0
	v_add_f32_e32 v98, 1.0, v35
	v_add_f32_e32 v126, -1.0, v98
	v_sub_f32_e32 v127, v126, v98
	v_add_f32_e32 v127, 1.0, v127
	v_sub_f32_e32 v126, v35, v126
	v_add_f32_e32 v128, v126, v127
	v_frexp_mant_f32_e32 v126, v98
	v_cmp_gt_f32_e32 vcc, s31, v126
	v_cvt_f64_f32_e32 v[126:127], v98
	v_frexp_exp_i32_f64_e32 v126, v[126:127]
	v_subbrev_co_u32_e32 v126, vcc, 0, v126, vcc
	v_sub_u32_e32 v127, 0, v126
	v_ldexp_f32 v98, v98, v127
	v_ldexp_f32 v127, v128, v127
	v_add_f32_e32 v128, -1.0, v98
	v_add_f32_e32 v129, 1.0, v128
	v_sub_f32_e32 v129, v98, v129
	v_add_f32_e32 v129, v127, v129
	v_add_f32_e32 v146, v128, v129
	v_sub_f32_e32 v128, v146, v128
	v_sub_f32_e32 v128, v129, v128
	v_add_f32_e32 v129, 1.0, v98
	v_add_f32_e32 v147, -1.0, v129
	v_sub_f32_e32 v98, v98, v147
	v_add_f32_e32 v98, v127, v98
	v_add_f32_e32 v127, v129, v98
	v_sub_f32_e32 v129, v127, v129
	v_sub_f32_e32 v98, v98, v129
	v_rcp_f32_e32 v129, v127
	v_cvt_f32_i32_e32 v126, v126
	v_cmp_neq_f32_e32 vcc, s35, v35
	v_mul_f32_e32 v147, v146, v129
	v_mul_f32_e32 v148, v127, v147
	v_fma_f32 v149, v147, v127, -v148
	v_fmac_f32_e32 v149, v147, v98
	v_add_f32_e32 v150, v148, v149
	v_sub_f32_e32 v151, v146, v150
	v_sub_f32_e32 v146, v146, v151
	v_sub_f32_e32 v148, v150, v148
	v_sub_f32_e32 v146, v146, v150
	v_add_f32_e32 v128, v128, v146
	v_sub_f32_e32 v146, v148, v149
	v_add_f32_e32 v128, v146, v128
	v_add_f32_e32 v146, v151, v128
	v_mul_f32_e32 v148, v129, v146
	v_mul_f32_e32 v149, v127, v148
	v_fma_f32 v127, v148, v127, -v149
	v_fmac_f32_e32 v127, v148, v98
	v_sub_f32_e32 v98, v151, v146
	v_add_f32_e32 v98, v128, v98
	v_add_f32_e32 v128, v149, v127
	v_sub_f32_e32 v150, v146, v128
	v_sub_f32_e32 v146, v146, v150
	v_sub_f32_e32 v149, v128, v149
	v_sub_f32_e32 v128, v146, v128
	v_add_f32_e32 v98, v98, v128
	v_sub_f32_e32 v127, v149, v127
	v_add_f32_e32 v98, v127, v98
	v_add_f32_e32 v127, v147, v148
	v_add_f32_e32 v98, v150, v98
	v_sub_f32_e32 v128, v127, v147
	v_mul_f32_e32 v98, v129, v98
	v_sub_f32_e32 v128, v148, v128
	v_add_f32_e32 v98, v128, v98
	v_mul_f32_e32 v147, 0x3f317218, v126
	v_add_f32_e32 v128, v127, v98
	v_fma_f32 v148, v126, s34, -v147
	v_mul_f32_e32 v129, v128, v128
	v_fmac_f32_e32 v148, 0xb102e308, v126
	v_sub_f32_e32 v126, v128, v127
	v_fmamk_f32 v146, v129, 0x3e9b6dac, v184
	v_sub_f32_e32 v98, v98, v126
	v_add_f32_e32 v126, v147, v148
	v_fmaak_f32 v146, v129, v146, 0x3f2aaada
	v_sub_f32_e32 v127, v126, v147
	v_ldexp_f32 v147, v128, 1
	v_mul_f32_e32 v128, v128, v129
	v_mul_f32_e32 v128, v128, v146
	v_add_f32_e32 v129, v147, v128
	v_sub_f32_e32 v146, v129, v147
	v_ldexp_f32 v98, v98, 1
	v_sub_f32_e32 v128, v128, v146
	v_add_f32_e32 v98, v98, v128
	v_add_f32_e32 v128, v129, v98
	v_sub_f32_e32 v129, v128, v129
	v_sub_f32_e32 v98, v98, v129
	v_add_f32_e32 v129, v126, v128
	v_sub_f32_e32 v146, v129, v126
	v_sub_f32_e32 v147, v129, v146
	v_sub_f32_e32 v127, v148, v127
	v_sub_f32_e32 v126, v126, v147
	v_sub_f32_e32 v128, v128, v146
	v_add_f32_e32 v126, v128, v126
	v_add_f32_e32 v128, v127, v98
	v_sub_f32_e32 v146, v128, v127
	v_sub_f32_e32 v147, v128, v146
	v_sub_f32_e32 v127, v127, v147
	v_sub_f32_e32 v98, v98, v146
	v_add_f32_e32 v126, v128, v126
	v_add_f32_e32 v98, v98, v127
	v_add_f32_e32 v127, v129, v126
	v_sub_f32_e32 v128, v127, v129
	v_sub_f32_e32 v126, v126, v128
	v_add_f32_e32 v98, v98, v126
	v_add_f32_e32 v98, v127, v98
	v_cndmask_b32_e32 v98, v185, v98, vcc
	v_cmp_ngt_f32_e32 vcc, -1.0, v35
	s_nop 1
	v_cndmask_b32_e32 v98, v186, v98, vcc
	v_cmp_neq_f32_e32 vcc, -1.0, v35
	s_nop 1
	v_cndmask_b32_e32 v98, v187, v98, vcc
	v_cmp_lt_f32_e64 vcc, |v35|, s36
	s_nop 1
	v_cndmask_b32_e32 v35, v98, v35, vcc
	v_add_f32_e32 v34, v34, v35
	v_sub_f32_e32 v34, -0.5, v34
	v_mul_f32_e32 v34, 0x3fb8aa3b, v34
	v_exp_f32_e32 v34, v34
	s_nop 0
	v_xor_b32_e32 v98, 0x80000000, v34
	v_lshl_add_u64 v[34:35], s[16:17], 0, v[130:131]
	v_lshl_add_u64 v[34:35], v[34:35], 0, v[50:51]
	global_store_dword v[34:35], v98, off
	v_mov_b32_e32 v34, v241
	v_add_f32_e32 v35, v36, v34
	v_max_f32_e64 v34, -v35, 0
	v_mul_f32_e64 v35, |v35|, s30
	v_exp_f32_e32 v35, v35
	s_nop 0
	v_add_f32_e32 v36, 1.0, v35
	v_add_f32_e32 v98, -1.0, v36
	v_sub_f32_e32 v126, v98, v36
	v_add_f32_e32 v126, 1.0, v126
	v_sub_f32_e32 v98, v35, v98
	v_add_f32_e32 v98, v98, v126
	v_frexp_mant_f32_e32 v126, v36
	v_cmp_gt_f32_e32 vcc, s31, v126
	v_cvt_f64_f32_e32 v[126:127], v36
	v_frexp_exp_i32_f64_e32 v126, v[126:127]
	v_subbrev_co_u32_e32 v126, vcc, 0, v126, vcc
	v_sub_u32_e32 v127, 0, v126
	v_ldexp_f32 v36, v36, v127
	v_ldexp_f32 v98, v98, v127
	v_add_f32_e32 v127, -1.0, v36
	v_add_f32_e32 v128, 1.0, v127
	v_sub_f32_e32 v128, v36, v128
	v_add_f32_e32 v128, v98, v128
	v_add_f32_e32 v129, v127, v128
	v_sub_f32_e32 v127, v129, v127
	v_sub_f32_e32 v127, v128, v127
	v_add_f32_e32 v128, 1.0, v36
	v_add_f32_e32 v130, -1.0, v128
	v_sub_f32_e32 v36, v36, v130
	v_add_f32_e32 v36, v98, v36
	v_add_f32_e32 v98, v128, v36
	v_sub_f32_e32 v128, v98, v128
	v_sub_f32_e32 v36, v36, v128
	v_rcp_f32_e32 v128, v98
	v_cvt_f32_i32_e32 v126, v126
	v_cmp_neq_f32_e32 vcc, s35, v35
	v_mul_f32_e32 v130, v129, v128
	v_mul_f32_e32 v131, v98, v130
	v_fma_f32 v146, v130, v98, -v131
	v_fmac_f32_e32 v146, v130, v36
	v_add_f32_e32 v147, v131, v146
	v_sub_f32_e32 v148, v129, v147
	v_sub_f32_e32 v129, v129, v148
	v_sub_f32_e32 v131, v147, v131
	v_sub_f32_e32 v129, v129, v147
	v_add_f32_e32 v127, v127, v129
	v_sub_f32_e32 v129, v131, v146
	v_add_f32_e32 v127, v129, v127
	v_add_f32_e32 v129, v148, v127
	v_mul_f32_e32 v131, v128, v129
	v_mul_f32_e32 v146, v98, v131
	v_fma_f32 v98, v131, v98, -v146
	v_fmac_f32_e32 v98, v131, v36
	v_sub_f32_e32 v36, v148, v129
	v_add_f32_e32 v36, v127, v36
	v_add_f32_e32 v127, v146, v98
	v_sub_f32_e32 v147, v129, v127
	v_sub_f32_e32 v129, v129, v147
	v_sub_f32_e32 v146, v127, v146
	v_sub_f32_e32 v127, v129, v127
	v_add_f32_e32 v36, v36, v127
	v_sub_f32_e32 v98, v146, v98
	v_add_f32_e32 v36, v98, v36
	v_add_f32_e32 v98, v130, v131
	v_add_f32_e32 v36, v147, v36
	v_sub_f32_e32 v127, v98, v130
	v_mul_f32_e32 v36, v128, v36
	v_sub_f32_e32 v127, v131, v127
	v_add_f32_e32 v36, v127, v36
	v_mul_f32_e32 v130, 0x3f317218, v126
	v_add_f32_e32 v127, v98, v36
	v_fma_f32 v131, v126, s34, -v130
	v_mul_f32_e32 v128, v127, v127
	v_fmac_f32_e32 v131, 0xb102e308, v126
	v_sub_f32_e32 v98, v127, v98
	v_fmamk_f32 v129, v128, 0x3e9b6dac, v184
	v_sub_f32_e32 v36, v36, v98
	v_add_f32_e32 v98, v130, v131
	v_fmaak_f32 v129, v128, v129, 0x3f2aaada
	v_sub_f32_e32 v126, v98, v130
	v_ldexp_f32 v130, v127, 1
	v_mul_f32_e32 v127, v127, v128
	v_mul_f32_e32 v127, v127, v129
	v_add_f32_e32 v128, v130, v127
	v_sub_f32_e32 v129, v128, v130
	v_ldexp_f32 v36, v36, 1
	v_sub_f32_e32 v127, v127, v129
	v_add_f32_e32 v36, v36, v127
	v_add_f32_e32 v127, v128, v36
	v_sub_f32_e32 v128, v127, v128
	v_sub_f32_e32 v36, v36, v128
	v_add_f32_e32 v128, v98, v127
	v_sub_f32_e32 v129, v128, v98
	v_sub_f32_e32 v130, v128, v129
	v_sub_f32_e32 v126, v131, v126
	v_sub_f32_e32 v98, v98, v130
	v_sub_f32_e32 v127, v127, v129
	v_add_f32_e32 v98, v127, v98
	v_add_f32_e32 v127, v126, v36
	v_sub_f32_e32 v129, v127, v126
	v_sub_f32_e32 v130, v127, v129
	v_sub_f32_e32 v126, v126, v130
	v_sub_f32_e32 v36, v36, v129
	v_add_f32_e32 v98, v127, v98
	v_add_f32_e32 v36, v36, v126
	v_add_f32_e32 v126, v128, v98
	v_sub_f32_e32 v127, v126, v128
	v_sub_f32_e32 v98, v98, v127
	v_add_f32_e32 v36, v36, v98
	v_add_f32_e32 v36, v126, v36
	v_cndmask_b32_e32 v36, v185, v36, vcc
	v_cmp_ngt_f32_e32 vcc, -1.0, v35
	s_nop 1
	v_cndmask_b32_e32 v36, v186, v36, vcc
	v_cmp_neq_f32_e32 vcc, -1.0, v35
	s_nop 1
	v_cndmask_b32_e32 v36, v187, v36, vcc
	v_cmp_lt_f32_e64 vcc, |v35|, s36
	s_nop 1
	v_cndmask_b32_e32 v35, v36, v35, vcc
	v_add_f32_e32 v34, v34, v35
	v_sub_f32_e32 v34, -0.5, v34
	v_mul_f32_e32 v34, 0x3fb8aa3b, v34
	v_exp_f32_e32 v34, v34
	s_nop 0
	v_xor_b32_e32 v36, 0x80000000, v34
	v_lshl_add_u64 v[34:35], s[16:17], 0, v[132:133]
	v_lshl_add_u64 v[34:35], v[34:35], 0, v[50:51]
	global_store_dword v[34:35], v36, off
	v_mov_b32_e32 v34, v241
	v_add_f32_e32 v35, v37, v34
	v_max_f32_e64 v34, -v35, 0
	v_mul_f32_e64 v35, |v35|, s30
	v_exp_f32_e32 v35, v35
	s_nop 0
	v_add_f32_e32 v98, 1.0, v35
	v_add_f32_e32 v36, -1.0, v98
	v_sub_f32_e32 v37, v36, v98
	v_add_f32_e32 v37, 1.0, v37
	v_sub_f32_e32 v36, v35, v36
	v_add_f32_e32 v126, v36, v37
	v_frexp_mant_f32_e32 v36, v98
	v_cmp_gt_f32_e32 vcc, s31, v36
	v_cvt_f64_f32_e32 v[36:37], v98
	v_frexp_exp_i32_f64_e32 v36, v[36:37]
	v_subbrev_co_u32_e32 v36, vcc, 0, v36, vcc
	v_sub_u32_e32 v37, 0, v36
	v_ldexp_f32 v98, v98, v37
	v_ldexp_f32 v37, v126, v37
	v_add_f32_e32 v126, -1.0, v98
	v_add_f32_e32 v127, 1.0, v126
	v_sub_f32_e32 v127, v98, v127
	v_add_f32_e32 v127, v37, v127
	v_add_f32_e32 v128, v126, v127
	v_sub_f32_e32 v126, v128, v126
	v_sub_f32_e32 v126, v127, v126
	v_add_f32_e32 v127, 1.0, v98
	v_add_f32_e32 v129, -1.0, v127
	v_sub_f32_e32 v98, v98, v129
	v_add_f32_e32 v37, v37, v98
	v_add_f32_e32 v98, v127, v37
	v_sub_f32_e32 v127, v98, v127
	v_sub_f32_e32 v37, v37, v127
	v_rcp_f32_e32 v127, v98
	v_cvt_f32_i32_e32 v36, v36
	v_cmp_neq_f32_e32 vcc, s35, v35
	v_mul_f32_e32 v129, v128, v127
	v_mul_f32_e32 v130, v98, v129
	v_fma_f32 v131, v129, v98, -v130
	v_fmac_f32_e32 v131, v129, v37
	v_add_f32_e32 v132, v130, v131
	v_sub_f32_e32 v133, v128, v132
	v_sub_f32_e32 v128, v128, v133
	v_sub_f32_e32 v130, v132, v130
	v_sub_f32_e32 v128, v128, v132
	v_add_f32_e32 v126, v126, v128
	v_sub_f32_e32 v128, v130, v131
	v_add_f32_e32 v126, v128, v126
	v_add_f32_e32 v128, v133, v126
	v_mul_f32_e32 v130, v127, v128
	v_mul_f32_e32 v131, v98, v130
	v_fma_f32 v98, v130, v98, -v131
	v_fmac_f32_e32 v98, v130, v37
	v_sub_f32_e32 v37, v133, v128
	v_add_f32_e32 v37, v126, v37
	v_add_f32_e32 v126, v131, v98
	v_sub_f32_e32 v132, v128, v126
	v_sub_f32_e32 v128, v128, v132
	v_sub_f32_e32 v131, v126, v131
	v_sub_f32_e32 v126, v128, v126
	v_add_f32_e32 v37, v37, v126
	v_sub_f32_e32 v98, v131, v98
	v_add_f32_e32 v37, v98, v37
	v_add_f32_e32 v98, v129, v130
	v_add_f32_e32 v37, v132, v37
	v_sub_f32_e32 v126, v98, v129
	v_mul_f32_e32 v37, v127, v37
	v_sub_f32_e32 v126, v130, v126
	v_add_f32_e32 v37, v126, v37
	v_mul_f32_e32 v129, 0x3f317218, v36
	v_add_f32_e32 v126, v98, v37
	v_fma_f32 v130, v36, s34, -v129
	v_mul_f32_e32 v127, v126, v126
	v_fmac_f32_e32 v130, 0xb102e308, v36
	v_sub_f32_e32 v36, v126, v98
	v_fmamk_f32 v128, v127, 0x3e9b6dac, v184
	v_sub_f32_e32 v36, v37, v36
	v_add_f32_e32 v37, v129, v130
	v_fmaak_f32 v128, v127, v128, 0x3f2aaada
	v_sub_f32_e32 v98, v37, v129
	v_ldexp_f32 v129, v126, 1
	v_mul_f32_e32 v126, v126, v127
	v_mul_f32_e32 v126, v126, v128
	v_add_f32_e32 v127, v129, v126
	v_sub_f32_e32 v128, v127, v129
	v_ldexp_f32 v36, v36, 1
	v_sub_f32_e32 v126, v126, v128
	v_add_f32_e32 v36, v36, v126
	v_add_f32_e32 v126, v127, v36
	v_sub_f32_e32 v127, v126, v127
	v_sub_f32_e32 v36, v36, v127
	v_add_f32_e32 v127, v37, v126
	v_sub_f32_e32 v128, v127, v37
	v_sub_f32_e32 v129, v127, v128
	v_sub_f32_e32 v98, v130, v98
	v_sub_f32_e32 v37, v37, v129
	v_sub_f32_e32 v126, v126, v128
	v_add_f32_e32 v37, v126, v37
	v_add_f32_e32 v126, v98, v36
	v_sub_f32_e32 v128, v126, v98
	v_sub_f32_e32 v129, v126, v128
	v_sub_f32_e32 v98, v98, v129
	v_sub_f32_e32 v36, v36, v128
	v_add_f32_e32 v37, v126, v37
	v_add_f32_e32 v36, v36, v98
	v_add_f32_e32 v98, v127, v37
	v_sub_f32_e32 v126, v98, v127
	v_sub_f32_e32 v37, v37, v126
	v_add_f32_e32 v36, v36, v37
	v_add_f32_e32 v36, v98, v36
	v_cndmask_b32_e32 v36, v185, v36, vcc
	v_cmp_ngt_f32_e32 vcc, -1.0, v35
	s_nop 1
	v_cndmask_b32_e32 v36, v186, v36, vcc
	v_cmp_neq_f32_e32 vcc, -1.0, v35
	s_nop 1
	v_cndmask_b32_e32 v36, v187, v36, vcc
	v_cmp_lt_f32_e64 vcc, |v35|, s36
	s_nop 1
	v_cndmask_b32_e32 v35, v36, v35, vcc
	v_add_f32_e32 v34, v34, v35
	v_sub_f32_e32 v34, -0.5, v34
	v_mul_f32_e32 v34, 0x3fb8aa3b, v34
	v_exp_f32_e32 v34, v34
	s_nop 0
	v_xor_b32_e32 v36, 0x80000000, v34
	v_lshl_add_u64 v[34:35], s[16:17], 0, v[52:53]
	v_lshl_add_u64 v[34:35], v[34:35], 0, v[50:51]
	global_store_dword v[34:35], v36, off
	v_mov_b32_e32 v34, v241
	v_add_f32_e32 v35, v38, v34
	v_max_f32_e64 v34, -v35, 0
	v_mul_f32_e64 v35, |v35|, s30
	v_exp_f32_e32 v35, v35
	s_nop 0
	v_add_f32_e32 v38, 1.0, v35
	v_add_f32_e32 v36, -1.0, v38
	v_sub_f32_e32 v37, v36, v38
	v_add_f32_e32 v37, 1.0, v37
	v_sub_f32_e32 v36, v35, v36
	v_add_f32_e32 v52, v36, v37
	v_frexp_mant_f32_e32 v36, v38
	v_cmp_gt_f32_e32 vcc, s31, v36
	v_cvt_f64_f32_e32 v[36:37], v38
	v_frexp_exp_i32_f64_e32 v36, v[36:37]
	v_subbrev_co_u32_e32 v36, vcc, 0, v36, vcc
	v_sub_u32_e32 v37, 0, v36
	v_ldexp_f32 v38, v38, v37
	v_ldexp_f32 v37, v52, v37
	v_add_f32_e32 v52, -1.0, v38
	v_add_f32_e32 v53, 1.0, v52
	v_sub_f32_e32 v53, v38, v53
	v_add_f32_e32 v53, v37, v53
	v_add_f32_e32 v98, v52, v53
	v_sub_f32_e32 v52, v98, v52
	v_sub_f32_e32 v52, v53, v52
	v_add_f32_e32 v53, 1.0, v38
	v_add_f32_e32 v126, -1.0, v53
	v_sub_f32_e32 v38, v38, v126
	v_add_f32_e32 v37, v37, v38
	v_add_f32_e32 v38, v53, v37
	v_sub_f32_e32 v53, v38, v53
	v_sub_f32_e32 v37, v37, v53
	v_rcp_f32_e32 v53, v38
	v_cvt_f32_i32_e32 v36, v36
	v_cmp_neq_f32_e32 vcc, s35, v35
	v_mul_f32_e32 v126, v98, v53
	v_mul_f32_e32 v127, v38, v126
	v_fma_f32 v128, v126, v38, -v127
	v_fmac_f32_e32 v128, v126, v37
	v_add_f32_e32 v129, v127, v128
	v_sub_f32_e32 v130, v98, v129
	v_sub_f32_e32 v98, v98, v130
	v_sub_f32_e32 v127, v129, v127
	v_sub_f32_e32 v98, v98, v129
	v_add_f32_e32 v52, v52, v98
	v_sub_f32_e32 v98, v127, v128
	v_add_f32_e32 v52, v98, v52
	v_add_f32_e32 v98, v130, v52
	v_mul_f32_e32 v127, v53, v98
	v_mul_f32_e32 v128, v38, v127
	v_fma_f32 v38, v127, v38, -v128
	v_fmac_f32_e32 v38, v127, v37
	v_sub_f32_e32 v37, v130, v98
	v_add_f32_e32 v37, v52, v37
	v_add_f32_e32 v52, v128, v38
	v_sub_f32_e32 v129, v98, v52
	v_sub_f32_e32 v98, v98, v129
	v_sub_f32_e32 v128, v52, v128
	v_sub_f32_e32 v52, v98, v52
	v_add_f32_e32 v37, v37, v52
	v_sub_f32_e32 v38, v128, v38
	v_add_f32_e32 v37, v38, v37
	v_add_f32_e32 v38, v126, v127
	v_add_f32_e32 v37, v129, v37
	v_sub_f32_e32 v52, v38, v126
	v_mul_f32_e32 v37, v53, v37
	v_sub_f32_e32 v52, v127, v52
	v_add_f32_e32 v37, v52, v37
	v_mul_f32_e32 v126, 0x3f317218, v36
	v_add_f32_e32 v52, v38, v37
	v_fma_f32 v127, v36, s34, -v126
	v_mul_f32_e32 v53, v52, v52
	v_fmac_f32_e32 v127, 0xb102e308, v36
	v_sub_f32_e32 v36, v52, v38
	v_fmamk_f32 v98, v53, 0x3e9b6dac, v184
	v_sub_f32_e32 v36, v37, v36
	v_add_f32_e32 v37, v126, v127
	v_fmaak_f32 v98, v53, v98, 0x3f2aaada
	v_sub_f32_e32 v38, v37, v126
	v_ldexp_f32 v126, v52, 1
	v_mul_f32_e32 v52, v52, v53
	v_mul_f32_e32 v52, v52, v98
	v_add_f32_e32 v53, v126, v52
	v_sub_f32_e32 v98, v53, v126
	v_ldexp_f32 v36, v36, 1
	v_sub_f32_e32 v52, v52, v98
	v_add_f32_e32 v36, v36, v52
	v_add_f32_e32 v52, v53, v36
	v_sub_f32_e32 v53, v52, v53
	v_sub_f32_e32 v36, v36, v53
	v_add_f32_e32 v53, v37, v52
	v_sub_f32_e32 v98, v53, v37
	v_sub_f32_e32 v126, v53, v98
	v_sub_f32_e32 v38, v127, v38
	v_sub_f32_e32 v37, v37, v126
	v_sub_f32_e32 v52, v52, v98
	v_add_f32_e32 v37, v52, v37
	v_add_f32_e32 v52, v38, v36
	v_sub_f32_e32 v98, v52, v38
	v_sub_f32_e32 v126, v52, v98
	v_sub_f32_e32 v38, v38, v126
	v_sub_f32_e32 v36, v36, v98
	v_add_f32_e32 v37, v52, v37
	v_add_f32_e32 v36, v36, v38
	v_add_f32_e32 v38, v53, v37
	v_sub_f32_e32 v52, v38, v53
	v_sub_f32_e32 v37, v37, v52
	v_add_f32_e32 v36, v36, v37
	v_add_f32_e32 v36, v38, v36
	v_cndmask_b32_e32 v36, v185, v36, vcc
	v_cmp_ngt_f32_e32 vcc, -1.0, v35
	s_nop 1
	v_cndmask_b32_e32 v36, v186, v36, vcc
	v_cmp_neq_f32_e32 vcc, -1.0, v35
	s_nop 1
	v_cndmask_b32_e32 v36, v187, v36, vcc
	v_cmp_lt_f32_e64 vcc, |v35|, s36
	s_nop 1
	v_cndmask_b32_e32 v35, v36, v35, vcc
	v_add_f32_e32 v34, v34, v35
	v_sub_f32_e32 v34, -0.5, v34
	v_mul_f32_e32 v34, 0x3fb8aa3b, v34
	v_exp_f32_e32 v34, v34
	s_nop 0
	v_xor_b32_e32 v36, 0x80000000, v34
	v_lshl_add_u64 v[34:35], s[16:17], 0, v[134:135]
	v_lshl_add_u64 v[34:35], v[34:35], 0, v[50:51]
	global_store_dword v[34:35], v36, off
	v_mov_b32_e32 v34, v241
	v_add_f32_e32 v35, v39, v34
	v_max_f32_e64 v34, -v35, 0
	v_mul_f32_e64 v35, |v35|, s30
	v_exp_f32_e32 v35, v35
	s_nop 0
	v_add_f32_e32 v38, 1.0, v35
	v_add_f32_e32 v36, -1.0, v38
	v_sub_f32_e32 v37, v36, v38
	v_add_f32_e32 v37, 1.0, v37
	v_sub_f32_e32 v36, v35, v36
	v_add_f32_e32 v39, v36, v37
	v_frexp_mant_f32_e32 v36, v38
	v_cmp_gt_f32_e32 vcc, s31, v36
	v_cvt_f64_f32_e32 v[36:37], v38
	v_frexp_exp_i32_f64_e32 v36, v[36:37]
	v_subbrev_co_u32_e32 v36, vcc, 0, v36, vcc
	v_sub_u32_e32 v37, 0, v36
	v_ldexp_f32 v38, v38, v37
	v_ldexp_f32 v37, v39, v37
	v_add_f32_e32 v39, -1.0, v38
	v_add_f32_e32 v52, 1.0, v39
	v_sub_f32_e32 v52, v38, v52
	v_add_f32_e32 v52, v37, v52
	v_add_f32_e32 v53, v39, v52
	v_sub_f32_e32 v39, v53, v39
	v_sub_f32_e32 v39, v52, v39
	v_add_f32_e32 v52, 1.0, v38
	v_add_f32_e32 v98, -1.0, v52
	v_sub_f32_e32 v38, v38, v98
	v_add_f32_e32 v37, v37, v38
	v_add_f32_e32 v38, v52, v37
	v_sub_f32_e32 v52, v38, v52
	v_sub_f32_e32 v37, v37, v52
	v_rcp_f32_e32 v52, v38
	v_cvt_f32_i32_e32 v36, v36
	v_cmp_neq_f32_e32 vcc, s35, v35
	v_mul_f32_e32 v98, v53, v52
	v_mul_f32_e32 v126, v38, v98
	v_fma_f32 v127, v98, v38, -v126
	v_fmac_f32_e32 v127, v98, v37
	v_add_f32_e32 v128, v126, v127
	v_sub_f32_e32 v129, v53, v128
	v_sub_f32_e32 v53, v53, v129
	v_sub_f32_e32 v126, v128, v126
	v_sub_f32_e32 v53, v53, v128
	v_add_f32_e32 v39, v39, v53
	v_sub_f32_e32 v53, v126, v127
	v_add_f32_e32 v39, v53, v39
	v_add_f32_e32 v53, v129, v39
	v_mul_f32_e32 v126, v52, v53
	v_mul_f32_e32 v127, v38, v126
	v_fma_f32 v38, v126, v38, -v127
	v_fmac_f32_e32 v38, v126, v37
	v_sub_f32_e32 v37, v129, v53
	v_add_f32_e32 v37, v39, v37
	v_add_f32_e32 v39, v127, v38
	v_sub_f32_e32 v128, v53, v39
	v_sub_f32_e32 v53, v53, v128
	v_sub_f32_e32 v127, v39, v127
	v_sub_f32_e32 v39, v53, v39
	v_add_f32_e32 v37, v37, v39
	v_sub_f32_e32 v38, v127, v38
	v_add_f32_e32 v37, v38, v37
	v_add_f32_e32 v38, v98, v126
	v_add_f32_e32 v37, v128, v37
	v_sub_f32_e32 v39, v38, v98
	v_mul_f32_e32 v37, v52, v37
	v_sub_f32_e32 v39, v126, v39
	v_add_f32_e32 v37, v39, v37
	v_mul_f32_e32 v98, 0x3f317218, v36
	v_add_f32_e32 v39, v38, v37
	v_fma_f32 v126, v36, s34, -v98
	v_mul_f32_e32 v52, v39, v39
	v_fmac_f32_e32 v126, 0xb102e308, v36
	v_sub_f32_e32 v36, v39, v38
	v_fmamk_f32 v53, v52, 0x3e9b6dac, v184
	v_sub_f32_e32 v36, v37, v36
	v_add_f32_e32 v37, v98, v126
	v_fmaak_f32 v53, v52, v53, 0x3f2aaada
	v_sub_f32_e32 v38, v37, v98
	v_ldexp_f32 v98, v39, 1
	v_mul_f32_e32 v39, v39, v52
	v_mul_f32_e32 v39, v39, v53
	v_add_f32_e32 v52, v98, v39
	v_sub_f32_e32 v53, v52, v98
	v_ldexp_f32 v36, v36, 1
	v_sub_f32_e32 v39, v39, v53
	v_add_f32_e32 v36, v36, v39
	v_add_f32_e32 v39, v52, v36
	v_sub_f32_e32 v52, v39, v52
	v_sub_f32_e32 v36, v36, v52
	v_add_f32_e32 v52, v37, v39
	v_sub_f32_e32 v53, v52, v37
	v_sub_f32_e32 v98, v52, v53
	v_sub_f32_e32 v38, v126, v38
	v_sub_f32_e32 v37, v37, v98
	v_sub_f32_e32 v39, v39, v53
	v_add_f32_e32 v37, v39, v37
	v_add_f32_e32 v39, v38, v36
	v_sub_f32_e32 v53, v39, v38
	v_sub_f32_e32 v98, v39, v53
	v_sub_f32_e32 v38, v38, v98
	v_sub_f32_e32 v36, v36, v53
	v_add_f32_e32 v37, v39, v37
	v_add_f32_e32 v36, v36, v38
	v_add_f32_e32 v38, v52, v37
	v_sub_f32_e32 v39, v38, v52
	v_sub_f32_e32 v37, v37, v39
	v_add_f32_e32 v36, v36, v37
	v_add_f32_e32 v36, v38, v36
	v_cndmask_b32_e32 v36, v185, v36, vcc
	v_cmp_ngt_f32_e32 vcc, -1.0, v35
	s_nop 1
	v_cndmask_b32_e32 v36, v186, v36, vcc
	v_cmp_neq_f32_e32 vcc, -1.0, v35
	s_nop 1
	v_cndmask_b32_e32 v36, v187, v36, vcc
	v_cmp_lt_f32_e64 vcc, |v35|, s36
	s_nop 1
	v_cndmask_b32_e32 v35, v36, v35, vcc
	v_add_f32_e32 v34, v34, v35
	v_sub_f32_e32 v34, -0.5, v34
	v_mul_f32_e32 v34, 0x3fb8aa3b, v34
	v_exp_f32_e32 v34, v34
	s_nop 0
	v_xor_b32_e32 v36, 0x80000000, v34
	v_lshl_add_u64 v[34:35], s[16:17], 0, v[54:55]
	v_lshl_add_u64 v[34:35], v[34:35], 0, v[50:51]
	global_store_dword v[34:35], v36, off
	v_mov_b32_e32 v34, v241
	v_add_f32_e32 v35, v40, v34
	v_max_f32_e64 v34, -v35, 0
	v_mul_f32_e64 v35, |v35|, s30
	v_exp_f32_e32 v35, v35
	s_nop 0
	v_add_f32_e32 v38, 1.0, v35
	v_add_f32_e32 v36, -1.0, v38
	v_sub_f32_e32 v37, v36, v38
	v_add_f32_e32 v37, 1.0, v37
	v_sub_f32_e32 v36, v35, v36
	v_add_f32_e32 v39, v36, v37
	v_frexp_mant_f32_e32 v36, v38
	v_cmp_gt_f32_e32 vcc, s31, v36
	v_cvt_f64_f32_e32 v[36:37], v38
	v_frexp_exp_i32_f64_e32 v36, v[36:37]
	v_subbrev_co_u32_e32 v36, vcc, 0, v36, vcc
	v_sub_u32_e32 v37, 0, v36
	v_ldexp_f32 v38, v38, v37
	v_ldexp_f32 v37, v39, v37
	v_add_f32_e32 v39, -1.0, v38
	v_add_f32_e32 v40, 1.0, v39
	v_sub_f32_e32 v40, v38, v40
	v_add_f32_e32 v40, v37, v40
	v_add_f32_e32 v52, v39, v40
	v_sub_f32_e32 v39, v52, v39
	v_sub_f32_e32 v39, v40, v39
	v_add_f32_e32 v40, 1.0, v38
	v_add_f32_e32 v53, -1.0, v40
	v_sub_f32_e32 v38, v38, v53
	v_add_f32_e32 v37, v37, v38
	v_add_f32_e32 v38, v40, v37
	v_sub_f32_e32 v40, v38, v40
	v_sub_f32_e32 v37, v37, v40
	v_rcp_f32_e32 v40, v38
	v_cvt_f32_i32_e32 v36, v36
	v_cmp_neq_f32_e32 vcc, s35, v35
	v_mul_f32_e32 v53, v52, v40
	v_mul_f32_e32 v54, v38, v53
	v_fma_f32 v55, v53, v38, -v54
	v_fmac_f32_e32 v55, v53, v37
	v_add_f32_e32 v98, v54, v55
	v_sub_f32_e32 v126, v52, v98
	v_sub_f32_e32 v52, v52, v126
	v_sub_f32_e32 v54, v98, v54
	v_sub_f32_e32 v52, v52, v98
	v_add_f32_e32 v39, v39, v52
	v_sub_f32_e32 v52, v54, v55
	v_add_f32_e32 v39, v52, v39
	v_add_f32_e32 v52, v126, v39
	v_mul_f32_e32 v54, v40, v52
	v_mul_f32_e32 v55, v38, v54
	v_fma_f32 v38, v54, v38, -v55
	v_fmac_f32_e32 v38, v54, v37
	v_sub_f32_e32 v37, v126, v52
	v_add_f32_e32 v37, v39, v37
	v_add_f32_e32 v39, v55, v38
	v_sub_f32_e32 v98, v52, v39
	v_sub_f32_e32 v52, v52, v98
	v_sub_f32_e32 v55, v39, v55
	v_sub_f32_e32 v39, v52, v39
	v_add_f32_e32 v37, v37, v39
	v_sub_f32_e32 v38, v55, v38
	v_add_f32_e32 v37, v38, v37
	v_add_f32_e32 v38, v53, v54
	v_add_f32_e32 v37, v98, v37
	v_sub_f32_e32 v39, v38, v53
	v_mul_f32_e32 v37, v40, v37
	v_sub_f32_e32 v39, v54, v39
	v_add_f32_e32 v37, v39, v37
	v_mul_f32_e32 v53, 0x3f317218, v36
	v_add_f32_e32 v39, v38, v37
	v_fma_f32 v54, v36, s34, -v53
	v_mul_f32_e32 v40, v39, v39
	v_fmac_f32_e32 v54, 0xb102e308, v36
	v_sub_f32_e32 v36, v39, v38
	v_fmamk_f32 v52, v40, 0x3e9b6dac, v184
	v_sub_f32_e32 v36, v37, v36
	v_add_f32_e32 v37, v53, v54
	v_fmaak_f32 v52, v40, v52, 0x3f2aaada
	v_sub_f32_e32 v38, v37, v53
	v_ldexp_f32 v53, v39, 1
	v_mul_f32_e32 v39, v39, v40
	v_mul_f32_e32 v39, v39, v52
	v_add_f32_e32 v40, v53, v39
	v_sub_f32_e32 v52, v40, v53
	v_ldexp_f32 v36, v36, 1
	v_sub_f32_e32 v39, v39, v52
	v_add_f32_e32 v36, v36, v39
	v_add_f32_e32 v39, v40, v36
	v_sub_f32_e32 v40, v39, v40
	v_sub_f32_e32 v36, v36, v40
	v_add_f32_e32 v40, v37, v39
	v_sub_f32_e32 v52, v40, v37
	v_sub_f32_e32 v53, v40, v52
	v_sub_f32_e32 v38, v54, v38
	v_sub_f32_e32 v37, v37, v53
	v_sub_f32_e32 v39, v39, v52
	v_add_f32_e32 v37, v39, v37
	v_add_f32_e32 v39, v38, v36
	v_sub_f32_e32 v52, v39, v38
	v_sub_f32_e32 v53, v39, v52
	v_sub_f32_e32 v38, v38, v53
	v_sub_f32_e32 v36, v36, v52
	v_add_f32_e32 v37, v39, v37
	v_add_f32_e32 v36, v36, v38
	v_add_f32_e32 v38, v40, v37
	v_sub_f32_e32 v39, v38, v40
	v_sub_f32_e32 v37, v37, v39
	v_add_f32_e32 v36, v36, v37
	v_add_f32_e32 v36, v38, v36
	v_cndmask_b32_e32 v36, v185, v36, vcc
	v_cmp_ngt_f32_e32 vcc, -1.0, v35
	s_nop 1
	v_cndmask_b32_e32 v36, v186, v36, vcc
	v_cmp_neq_f32_e32 vcc, -1.0, v35
	s_nop 1
	v_cndmask_b32_e32 v36, v187, v36, vcc
	v_cmp_lt_f32_e64 vcc, |v35|, s36
	s_nop 1
	v_cndmask_b32_e32 v35, v36, v35, vcc
	v_add_f32_e32 v34, v34, v35
	v_sub_f32_e32 v34, -0.5, v34
	v_mul_f32_e32 v34, 0x3fb8aa3b, v34
	v_exp_f32_e32 v34, v34
	s_nop 0
	v_xor_b32_e32 v36, 0x80000000, v34
	v_lshl_add_u64 v[34:35], s[16:17], 0, v[136:137]
	v_lshl_add_u64 v[34:35], v[34:35], 0, v[50:51]
	global_store_dword v[34:35], v36, off
	v_mov_b32_e32 v34, v241
	v_add_f32_e32 v35, v41, v34
	v_max_f32_e64 v34, -v35, 0
	v_mul_f32_e64 v35, |v35|, s30
	v_exp_f32_e32 v35, v35
	s_nop 0
	v_add_f32_e32 v38, 1.0, v35
	v_add_f32_e32 v36, -1.0, v38
	v_sub_f32_e32 v37, v36, v38
	v_add_f32_e32 v37, 1.0, v37
	v_sub_f32_e32 v36, v35, v36
	v_add_f32_e32 v39, v36, v37
	v_frexp_mant_f32_e32 v36, v38
	v_cmp_gt_f32_e32 vcc, s31, v36
	v_cvt_f64_f32_e32 v[36:37], v38
	v_frexp_exp_i32_f64_e32 v36, v[36:37]
	v_subbrev_co_u32_e32 v36, vcc, 0, v36, vcc
	v_sub_u32_e32 v37, 0, v36
	v_ldexp_f32 v38, v38, v37
	v_ldexp_f32 v37, v39, v37
	v_add_f32_e32 v39, -1.0, v38
	v_add_f32_e32 v40, 1.0, v39
	v_sub_f32_e32 v40, v38, v40
	v_add_f32_e32 v40, v37, v40
	v_add_f32_e32 v41, v39, v40
	v_sub_f32_e32 v39, v41, v39
	v_sub_f32_e32 v39, v40, v39
	v_add_f32_e32 v40, 1.0, v38
	v_add_f32_e32 v52, -1.0, v40
	v_sub_f32_e32 v38, v38, v52
	v_add_f32_e32 v37, v37, v38
	v_add_f32_e32 v38, v40, v37
	v_sub_f32_e32 v40, v38, v40
	v_sub_f32_e32 v37, v37, v40
	v_rcp_f32_e32 v40, v38
	v_cvt_f32_i32_e32 v36, v36
	v_cmp_neq_f32_e32 vcc, s35, v35
	v_mul_f32_e32 v52, v41, v40
	v_mul_f32_e32 v53, v38, v52
	v_fma_f32 v54, v52, v38, -v53
	v_fmac_f32_e32 v54, v52, v37
	v_add_f32_e32 v55, v53, v54
	v_sub_f32_e32 v98, v41, v55
	v_sub_f32_e32 v41, v41, v98
	v_sub_f32_e32 v53, v55, v53
	v_sub_f32_e32 v41, v41, v55
	v_add_f32_e32 v39, v39, v41
	v_sub_f32_e32 v41, v53, v54
	v_add_f32_e32 v39, v41, v39
	v_add_f32_e32 v41, v98, v39
	v_mul_f32_e32 v53, v40, v41
	v_mul_f32_e32 v54, v38, v53
	v_fma_f32 v38, v53, v38, -v54
	v_fmac_f32_e32 v38, v53, v37
	v_sub_f32_e32 v37, v98, v41
	v_add_f32_e32 v37, v39, v37
	v_add_f32_e32 v39, v54, v38
	v_sub_f32_e32 v55, v41, v39
	v_sub_f32_e32 v41, v41, v55
	v_sub_f32_e32 v54, v39, v54
	v_sub_f32_e32 v39, v41, v39
	v_add_f32_e32 v37, v37, v39
	v_sub_f32_e32 v38, v54, v38
	v_add_f32_e32 v37, v38, v37
	v_add_f32_e32 v38, v52, v53
	v_add_f32_e32 v37, v55, v37
	v_sub_f32_e32 v39, v38, v52
	v_mul_f32_e32 v37, v40, v37
	v_sub_f32_e32 v39, v53, v39
	v_add_f32_e32 v37, v39, v37
	v_mul_f32_e32 v52, 0x3f317218, v36
	v_add_f32_e32 v39, v38, v37
	v_fma_f32 v53, v36, s34, -v52
	v_mul_f32_e32 v40, v39, v39
	v_fmac_f32_e32 v53, 0xb102e308, v36
	v_sub_f32_e32 v36, v39, v38
	v_fmamk_f32 v41, v40, 0x3e9b6dac, v184
	v_sub_f32_e32 v36, v37, v36
	v_add_f32_e32 v37, v52, v53
	v_fmaak_f32 v41, v40, v41, 0x3f2aaada
	v_sub_f32_e32 v38, v37, v52
	v_ldexp_f32 v52, v39, 1
	v_mul_f32_e32 v39, v39, v40
	v_mul_f32_e32 v39, v39, v41
	v_add_f32_e32 v40, v52, v39
	v_sub_f32_e32 v41, v40, v52
	v_ldexp_f32 v36, v36, 1
	v_sub_f32_e32 v39, v39, v41
	v_add_f32_e32 v36, v36, v39
	v_add_f32_e32 v39, v40, v36
	v_sub_f32_e32 v40, v39, v40
	v_sub_f32_e32 v36, v36, v40
	v_add_f32_e32 v40, v37, v39
	v_sub_f32_e32 v41, v40, v37
	v_sub_f32_e32 v52, v40, v41
	v_sub_f32_e32 v38, v53, v38
	v_sub_f32_e32 v37, v37, v52
	v_sub_f32_e32 v39, v39, v41
	v_add_f32_e32 v37, v39, v37
	v_add_f32_e32 v39, v38, v36
	v_sub_f32_e32 v41, v39, v38
	v_sub_f32_e32 v52, v39, v41
	v_sub_f32_e32 v38, v38, v52
	v_sub_f32_e32 v36, v36, v41
	v_add_f32_e32 v37, v39, v37
	v_add_f32_e32 v36, v36, v38
	v_add_f32_e32 v38, v40, v37
	v_sub_f32_e32 v39, v38, v40
	v_sub_f32_e32 v37, v37, v39
	v_add_f32_e32 v36, v36, v37
	v_add_f32_e32 v36, v38, v36
	v_cndmask_b32_e32 v36, v185, v36, vcc
	v_cmp_ngt_f32_e32 vcc, -1.0, v35
	s_nop 1
	v_cndmask_b32_e32 v36, v186, v36, vcc
	v_cmp_neq_f32_e32 vcc, -1.0, v35
	s_nop 1
	v_cndmask_b32_e32 v36, v187, v36, vcc
	v_cmp_lt_f32_e64 vcc, |v35|, s36
	s_nop 1
	v_cndmask_b32_e32 v35, v36, v35, vcc
	v_add_f32_e32 v34, v34, v35
	v_sub_f32_e32 v34, -0.5, v34
	v_mul_f32_e32 v34, 0x3fb8aa3b, v34
	v_exp_f32_e32 v34, v34
	s_nop 0
	v_xor_b32_e32 v36, 0x80000000, v34
	v_lshl_add_u64 v[34:35], s[16:17], 0, v[56:57]
	v_lshl_add_u64 v[34:35], v[34:35], 0, v[50:51]
	global_store_dword v[34:35], v36, off
	v_mov_b32_e32 v34, v241
	v_add_f32_e32 v35, v42, v34
	v_max_f32_e64 v34, -v35, 0
	v_mul_f32_e64 v35, |v35|, s30
	v_exp_f32_e32 v35, v35
	s_nop 0
	v_add_f32_e32 v38, 1.0, v35
	v_add_f32_e32 v36, -1.0, v38
	v_sub_f32_e32 v37, v36, v38
	v_add_f32_e32 v37, 1.0, v37
	v_sub_f32_e32 v36, v35, v36
	v_add_f32_e32 v39, v36, v37
	v_frexp_mant_f32_e32 v36, v38
	v_cmp_gt_f32_e32 vcc, s31, v36
	v_cvt_f64_f32_e32 v[36:37], v38
	v_frexp_exp_i32_f64_e32 v36, v[36:37]
	v_subbrev_co_u32_e32 v36, vcc, 0, v36, vcc
	v_sub_u32_e32 v37, 0, v36
	v_ldexp_f32 v38, v38, v37
	v_ldexp_f32 v37, v39, v37
	v_add_f32_e32 v39, -1.0, v38
	v_add_f32_e32 v40, 1.0, v39
	v_sub_f32_e32 v40, v38, v40
	v_add_f32_e32 v40, v37, v40
	v_add_f32_e32 v41, v39, v40
	v_sub_f32_e32 v39, v41, v39
	v_sub_f32_e32 v39, v40, v39
	v_add_f32_e32 v40, 1.0, v38
	v_add_f32_e32 v42, -1.0, v40
	v_sub_f32_e32 v38, v38, v42
	v_add_f32_e32 v37, v37, v38
	v_add_f32_e32 v38, v40, v37
	v_sub_f32_e32 v40, v38, v40
	v_sub_f32_e32 v37, v37, v40
	v_rcp_f32_e32 v40, v38
	v_cvt_f32_i32_e32 v36, v36
	v_cmp_neq_f32_e32 vcc, s35, v35
	v_mul_f32_e32 v42, v41, v40
	v_mul_f32_e32 v52, v38, v42
	v_fma_f32 v53, v42, v38, -v52
	v_fmac_f32_e32 v53, v42, v37
	v_add_f32_e32 v54, v52, v53
	v_sub_f32_e32 v55, v41, v54
	v_sub_f32_e32 v41, v41, v55
	v_sub_f32_e32 v52, v54, v52
	v_sub_f32_e32 v41, v41, v54
	v_add_f32_e32 v39, v39, v41
	v_sub_f32_e32 v41, v52, v53
	v_add_f32_e32 v39, v41, v39
	v_add_f32_e32 v41, v55, v39
	v_mul_f32_e32 v52, v40, v41
	v_mul_f32_e32 v53, v38, v52
	v_fma_f32 v38, v52, v38, -v53
	v_fmac_f32_e32 v38, v52, v37
	v_sub_f32_e32 v37, v55, v41
	v_add_f32_e32 v37, v39, v37
	v_add_f32_e32 v39, v53, v38
	v_sub_f32_e32 v54, v41, v39
	v_sub_f32_e32 v41, v41, v54
	v_sub_f32_e32 v53, v39, v53
	v_sub_f32_e32 v39, v41, v39
	v_add_f32_e32 v37, v37, v39
	v_sub_f32_e32 v38, v53, v38
	v_add_f32_e32 v37, v38, v37
	v_add_f32_e32 v38, v42, v52
	v_add_f32_e32 v37, v54, v37
	v_sub_f32_e32 v39, v38, v42
	v_mul_f32_e32 v37, v40, v37
	v_sub_f32_e32 v39, v52, v39
	v_add_f32_e32 v37, v39, v37
	v_mul_f32_e32 v42, 0x3f317218, v36
	v_add_f32_e32 v39, v38, v37
	v_fma_f32 v52, v36, s34, -v42
	v_mul_f32_e32 v40, v39, v39
	v_fmac_f32_e32 v52, 0xb102e308, v36
	v_sub_f32_e32 v36, v39, v38
	v_fmamk_f32 v41, v40, 0x3e9b6dac, v184
	v_sub_f32_e32 v36, v37, v36
	v_add_f32_e32 v37, v42, v52
	v_fmaak_f32 v41, v40, v41, 0x3f2aaada
	v_sub_f32_e32 v38, v37, v42
	v_ldexp_f32 v42, v39, 1
	v_mul_f32_e32 v39, v39, v40
	v_mul_f32_e32 v39, v39, v41
	v_add_f32_e32 v40, v42, v39
	v_sub_f32_e32 v41, v40, v42
	v_ldexp_f32 v36, v36, 1
	v_sub_f32_e32 v39, v39, v41
	v_add_f32_e32 v36, v36, v39
	v_add_f32_e32 v39, v40, v36
	v_sub_f32_e32 v40, v39, v40
	v_sub_f32_e32 v36, v36, v40
	v_add_f32_e32 v40, v37, v39
	v_sub_f32_e32 v41, v40, v37
	v_sub_f32_e32 v42, v40, v41
	v_sub_f32_e32 v38, v52, v38
	v_sub_f32_e32 v37, v37, v42
	v_sub_f32_e32 v39, v39, v41
	v_add_f32_e32 v37, v39, v37
	v_add_f32_e32 v39, v38, v36
	v_sub_f32_e32 v41, v39, v38
	v_sub_f32_e32 v42, v39, v41
	v_sub_f32_e32 v38, v38, v42
	v_sub_f32_e32 v36, v36, v41
	v_add_f32_e32 v37, v39, v37
	v_add_f32_e32 v36, v36, v38
	v_add_f32_e32 v38, v40, v37
	v_sub_f32_e32 v39, v38, v40
	v_sub_f32_e32 v37, v37, v39
	v_add_f32_e32 v36, v36, v37
	v_add_f32_e32 v36, v38, v36
	v_cndmask_b32_e32 v36, v185, v36, vcc
	v_cmp_ngt_f32_e32 vcc, -1.0, v35
	s_nop 1
	v_cndmask_b32_e32 v36, v186, v36, vcc
	v_cmp_neq_f32_e32 vcc, -1.0, v35
	s_nop 1
	v_cndmask_b32_e32 v36, v187, v36, vcc
	v_cmp_lt_f32_e64 vcc, |v35|, s36
	s_nop 1
	v_cndmask_b32_e32 v35, v36, v35, vcc
	v_add_f32_e32 v34, v34, v35
	v_sub_f32_e32 v34, -0.5, v34
	v_mul_f32_e32 v34, 0x3fb8aa3b, v34
	v_exp_f32_e32 v34, v34
	s_nop 0
	v_xor_b32_e32 v36, 0x80000000, v34
	v_lshl_add_u64 v[34:35], s[16:17], 0, v[138:139]
	v_lshl_add_u64 v[34:35], v[34:35], 0, v[50:51]
	global_store_dword v[34:35], v36, off
	v_mov_b32_e32 v34, v241
	v_add_f32_e32 v35, v43, v34
	v_max_f32_e64 v34, -v35, 0
	v_mul_f32_e64 v35, |v35|, s30
	v_exp_f32_e32 v35, v35
	s_nop 0
	v_add_f32_e32 v38, 1.0, v35
	v_add_f32_e32 v36, -1.0, v38
	v_sub_f32_e32 v37, v36, v38
	v_add_f32_e32 v37, 1.0, v37
	v_sub_f32_e32 v36, v35, v36
	v_add_f32_e32 v39, v36, v37
	v_frexp_mant_f32_e32 v36, v38
	v_cmp_gt_f32_e32 vcc, s31, v36
	v_cvt_f64_f32_e32 v[36:37], v38
	v_frexp_exp_i32_f64_e32 v36, v[36:37]
	v_subbrev_co_u32_e32 v36, vcc, 0, v36, vcc
	v_sub_u32_e32 v37, 0, v36
	v_ldexp_f32 v38, v38, v37
	v_ldexp_f32 v37, v39, v37
	v_add_f32_e32 v39, -1.0, v38
	v_add_f32_e32 v40, 1.0, v39
	v_sub_f32_e32 v40, v38, v40
	v_add_f32_e32 v40, v37, v40
	v_add_f32_e32 v41, v39, v40
	v_sub_f32_e32 v39, v41, v39
	v_sub_f32_e32 v39, v40, v39
	v_add_f32_e32 v40, 1.0, v38
	v_add_f32_e32 v42, -1.0, v40
	v_sub_f32_e32 v38, v38, v42
	v_add_f32_e32 v37, v37, v38
	v_add_f32_e32 v38, v40, v37
	v_sub_f32_e32 v40, v38, v40
	v_sub_f32_e32 v37, v37, v40
	v_rcp_f32_e32 v40, v38
	v_cvt_f32_i32_e32 v36, v36
	v_cmp_neq_f32_e32 vcc, s35, v35
	v_mul_f32_e32 v42, v41, v40
	v_mul_f32_e32 v43, v38, v42
	v_fma_f32 v52, v42, v38, -v43
	v_fmac_f32_e32 v52, v42, v37
	v_add_f32_e32 v53, v43, v52
	v_sub_f32_e32 v54, v41, v53
	v_sub_f32_e32 v41, v41, v54
	v_sub_f32_e32 v43, v53, v43
	v_sub_f32_e32 v41, v41, v53
	v_add_f32_e32 v39, v39, v41
	v_sub_f32_e32 v41, v43, v52
	v_add_f32_e32 v39, v41, v39
	v_add_f32_e32 v41, v54, v39
	v_mul_f32_e32 v43, v40, v41
	v_mul_f32_e32 v52, v38, v43
	v_fma_f32 v38, v43, v38, -v52
	v_fmac_f32_e32 v38, v43, v37
	v_sub_f32_e32 v37, v54, v41
	v_add_f32_e32 v37, v39, v37
	v_add_f32_e32 v39, v52, v38
	v_sub_f32_e32 v53, v41, v39
	v_sub_f32_e32 v41, v41, v53
	v_sub_f32_e32 v52, v39, v52
	v_sub_f32_e32 v39, v41, v39
	v_add_f32_e32 v37, v37, v39
	v_sub_f32_e32 v38, v52, v38
	v_add_f32_e32 v37, v38, v37
	v_add_f32_e32 v38, v42, v43
	v_add_f32_e32 v37, v53, v37
	v_sub_f32_e32 v39, v38, v42
	v_mul_f32_e32 v37, v40, v37
	v_sub_f32_e32 v39, v43, v39
	v_add_f32_e32 v37, v39, v37
	v_mul_f32_e32 v42, 0x3f317218, v36
	v_add_f32_e32 v39, v38, v37
	v_fma_f32 v43, v36, s34, -v42
	v_mul_f32_e32 v40, v39, v39
	v_fmac_f32_e32 v43, 0xb102e308, v36
	v_sub_f32_e32 v36, v39, v38
	v_fmamk_f32 v41, v40, 0x3e9b6dac, v184
	v_sub_f32_e32 v36, v37, v36
	v_add_f32_e32 v37, v42, v43
	v_fmaak_f32 v41, v40, v41, 0x3f2aaada
	v_sub_f32_e32 v38, v37, v42
	v_ldexp_f32 v42, v39, 1
	v_mul_f32_e32 v39, v39, v40
	v_mul_f32_e32 v39, v39, v41
	v_add_f32_e32 v40, v42, v39
	v_sub_f32_e32 v41, v40, v42
	v_ldexp_f32 v36, v36, 1
	v_sub_f32_e32 v39, v39, v41
	v_add_f32_e32 v36, v36, v39
	v_add_f32_e32 v39, v40, v36
	v_sub_f32_e32 v40, v39, v40
	v_sub_f32_e32 v36, v36, v40
	v_add_f32_e32 v40, v37, v39
	v_sub_f32_e32 v41, v40, v37
	v_sub_f32_e32 v42, v40, v41
	v_sub_f32_e32 v38, v43, v38
	v_sub_f32_e32 v37, v37, v42
	v_sub_f32_e32 v39, v39, v41
	v_add_f32_e32 v37, v39, v37
	v_add_f32_e32 v39, v38, v36
	v_sub_f32_e32 v41, v39, v38
	v_sub_f32_e32 v42, v39, v41
	v_sub_f32_e32 v38, v38, v42
	v_sub_f32_e32 v36, v36, v41
	v_add_f32_e32 v37, v39, v37
	v_add_f32_e32 v36, v36, v38
	v_add_f32_e32 v38, v40, v37
	v_sub_f32_e32 v39, v38, v40
	v_sub_f32_e32 v37, v37, v39
	v_add_f32_e32 v36, v36, v37
	v_add_f32_e32 v36, v38, v36
	v_cndmask_b32_e32 v36, v185, v36, vcc
	v_cmp_ngt_f32_e32 vcc, -1.0, v35
	s_nop 1
	v_cndmask_b32_e32 v36, v186, v36, vcc
	v_cmp_neq_f32_e32 vcc, -1.0, v35
	s_nop 1
	v_cndmask_b32_e32 v36, v187, v36, vcc
	v_cmp_lt_f32_e64 vcc, |v35|, s36
	s_nop 1
	v_cndmask_b32_e32 v35, v36, v35, vcc
	v_add_f32_e32 v34, v34, v35
	v_sub_f32_e32 v34, -0.5, v34
	v_mul_f32_e32 v34, 0x3fb8aa3b, v34
	v_exp_f32_e32 v34, v34
	s_nop 0
	v_xor_b32_e32 v36, 0x80000000, v34
	v_lshl_add_u64 v[34:35], s[16:17], 0, v[58:59]
	v_lshl_add_u64 v[34:35], v[34:35], 0, v[50:51]
	global_store_dword v[34:35], v36, off
	v_mov_b32_e32 v34, v241
	v_add_f32_e32 v35, v44, v34
	v_max_f32_e64 v34, -v35, 0
	v_mul_f32_e64 v35, |v35|, s30
	v_exp_f32_e32 v35, v35
	s_nop 0
	v_add_f32_e32 v38, 1.0, v35
	v_add_f32_e32 v36, -1.0, v38
	v_sub_f32_e32 v37, v36, v38
	v_add_f32_e32 v37, 1.0, v37
	v_sub_f32_e32 v36, v35, v36
	v_add_f32_e32 v39, v36, v37
	v_frexp_mant_f32_e32 v36, v38
	v_cmp_gt_f32_e32 vcc, s31, v36
	v_cvt_f64_f32_e32 v[36:37], v38
	v_frexp_exp_i32_f64_e32 v36, v[36:37]
	v_subbrev_co_u32_e32 v36, vcc, 0, v36, vcc
	v_sub_u32_e32 v37, 0, v36
	v_ldexp_f32 v38, v38, v37
	v_ldexp_f32 v37, v39, v37
	v_add_f32_e32 v39, -1.0, v38
	v_add_f32_e32 v40, 1.0, v39
	v_sub_f32_e32 v40, v38, v40
	v_add_f32_e32 v40, v37, v40
	v_add_f32_e32 v41, v39, v40
	v_sub_f32_e32 v39, v41, v39
	v_sub_f32_e32 v39, v40, v39
	v_add_f32_e32 v40, 1.0, v38
	v_add_f32_e32 v42, -1.0, v40
	v_sub_f32_e32 v38, v38, v42
	v_add_f32_e32 v37, v37, v38
	v_add_f32_e32 v38, v40, v37
	v_sub_f32_e32 v40, v38, v40
	v_sub_f32_e32 v37, v37, v40
	v_rcp_f32_e32 v40, v38
	v_cvt_f32_i32_e32 v36, v36
	v_cmp_neq_f32_e32 vcc, s35, v35
	v_mul_f32_e32 v42, v41, v40
	v_mul_f32_e32 v43, v38, v42
	v_fma_f32 v44, v42, v38, -v43
	v_fmac_f32_e32 v44, v42, v37
	v_add_f32_e32 v52, v43, v44
	v_sub_f32_e32 v53, v41, v52
	v_sub_f32_e32 v41, v41, v53
	v_sub_f32_e32 v43, v52, v43
	v_sub_f32_e32 v41, v41, v52
	v_add_f32_e32 v39, v39, v41
	v_sub_f32_e32 v41, v43, v44
	v_add_f32_e32 v39, v41, v39
	v_add_f32_e32 v41, v53, v39
	v_mul_f32_e32 v43, v40, v41
	v_mul_f32_e32 v44, v38, v43
	v_fma_f32 v38, v43, v38, -v44
	v_fmac_f32_e32 v38, v43, v37
	v_sub_f32_e32 v37, v53, v41
	v_add_f32_e32 v37, v39, v37
	v_add_f32_e32 v39, v44, v38
	v_sub_f32_e32 v52, v41, v39
	v_sub_f32_e32 v41, v41, v52
	v_sub_f32_e32 v44, v39, v44
	v_sub_f32_e32 v39, v41, v39
	v_add_f32_e32 v37, v37, v39
	v_sub_f32_e32 v38, v44, v38
	v_add_f32_e32 v37, v38, v37
	v_add_f32_e32 v38, v42, v43
	v_add_f32_e32 v37, v52, v37
	v_sub_f32_e32 v39, v38, v42
	v_mul_f32_e32 v37, v40, v37
	v_sub_f32_e32 v39, v43, v39
	v_add_f32_e32 v37, v39, v37
	v_mul_f32_e32 v42, 0x3f317218, v36
	v_add_f32_e32 v39, v38, v37
	v_fma_f32 v43, v36, s34, -v42
	v_mul_f32_e32 v40, v39, v39
	v_fmac_f32_e32 v43, 0xb102e308, v36
	v_sub_f32_e32 v36, v39, v38
	v_fmamk_f32 v41, v40, 0x3e9b6dac, v184
	v_sub_f32_e32 v36, v37, v36
	v_add_f32_e32 v37, v42, v43
	v_fmaak_f32 v41, v40, v41, 0x3f2aaada
	v_sub_f32_e32 v38, v37, v42
	v_ldexp_f32 v42, v39, 1
	v_mul_f32_e32 v39, v39, v40
	v_mul_f32_e32 v39, v39, v41
	v_add_f32_e32 v40, v42, v39
	v_sub_f32_e32 v41, v40, v42
	v_ldexp_f32 v36, v36, 1
	v_sub_f32_e32 v39, v39, v41
	v_add_f32_e32 v36, v36, v39
	v_add_f32_e32 v39, v40, v36
	v_sub_f32_e32 v40, v39, v40
	v_sub_f32_e32 v36, v36, v40
	v_add_f32_e32 v40, v37, v39
	v_sub_f32_e32 v41, v40, v37
	v_sub_f32_e32 v42, v40, v41
	v_sub_f32_e32 v38, v43, v38
	v_sub_f32_e32 v37, v37, v42
	v_sub_f32_e32 v39, v39, v41
	v_add_f32_e32 v37, v39, v37
	v_add_f32_e32 v39, v38, v36
	v_sub_f32_e32 v41, v39, v38
	v_sub_f32_e32 v42, v39, v41
	v_sub_f32_e32 v38, v38, v42
	v_sub_f32_e32 v36, v36, v41
	v_add_f32_e32 v37, v39, v37
	v_add_f32_e32 v36, v36, v38
	v_add_f32_e32 v38, v40, v37
	v_sub_f32_e32 v39, v38, v40
	v_sub_f32_e32 v37, v37, v39
	v_add_f32_e32 v36, v36, v37
	v_add_f32_e32 v36, v38, v36
	v_cndmask_b32_e32 v36, v185, v36, vcc
	v_cmp_ngt_f32_e32 vcc, -1.0, v35
	s_nop 1
	v_cndmask_b32_e32 v36, v186, v36, vcc
	v_cmp_neq_f32_e32 vcc, -1.0, v35
	s_nop 1
	v_cndmask_b32_e32 v36, v187, v36, vcc
	v_cmp_lt_f32_e64 vcc, |v35|, s36
	s_nop 1
	v_cndmask_b32_e32 v35, v36, v35, vcc
	v_add_f32_e32 v34, v34, v35
	v_sub_f32_e32 v34, -0.5, v34
	v_mul_f32_e32 v34, 0x3fb8aa3b, v34
	v_exp_f32_e32 v34, v34
	s_nop 0
	v_xor_b32_e32 v36, 0x80000000, v34
	v_lshl_add_u64 v[34:35], s[16:17], 0, v[140:141]
	v_lshl_add_u64 v[34:35], v[34:35], 0, v[50:51]
	global_store_dword v[34:35], v36, off
	v_mov_b32_e32 v34, v241
	v_add_f32_e32 v35, v45, v34
	v_max_f32_e64 v34, -v35, 0
	v_mul_f32_e64 v35, |v35|, s30
	v_exp_f32_e32 v35, v35
	s_nop 0
	v_add_f32_e32 v38, 1.0, v35
	v_add_f32_e32 v36, -1.0, v38
	v_sub_f32_e32 v37, v36, v38
	v_add_f32_e32 v37, 1.0, v37
	v_sub_f32_e32 v36, v35, v36
	v_add_f32_e32 v39, v36, v37
	v_frexp_mant_f32_e32 v36, v38
	v_cmp_gt_f32_e32 vcc, s31, v36
	v_cvt_f64_f32_e32 v[36:37], v38
	v_frexp_exp_i32_f64_e32 v36, v[36:37]
	v_subbrev_co_u32_e32 v36, vcc, 0, v36, vcc
	v_sub_u32_e32 v37, 0, v36
	v_ldexp_f32 v38, v38, v37
	v_ldexp_f32 v37, v39, v37
	v_add_f32_e32 v39, -1.0, v38
	v_add_f32_e32 v40, 1.0, v39
	v_sub_f32_e32 v40, v38, v40
	v_add_f32_e32 v40, v37, v40
	v_add_f32_e32 v41, v39, v40
	v_sub_f32_e32 v39, v41, v39
	v_sub_f32_e32 v39, v40, v39
	v_add_f32_e32 v40, 1.0, v38
	v_add_f32_e32 v42, -1.0, v40
	v_sub_f32_e32 v38, v38, v42
	v_add_f32_e32 v37, v37, v38
	v_add_f32_e32 v38, v40, v37
	v_sub_f32_e32 v40, v38, v40
	v_sub_f32_e32 v37, v37, v40
	v_rcp_f32_e32 v40, v38
	v_cvt_f32_i32_e32 v36, v36
	v_cmp_neq_f32_e32 vcc, s35, v35
	v_mul_f32_e32 v42, v41, v40
	v_mul_f32_e32 v43, v38, v42
	v_fma_f32 v44, v42, v38, -v43
	v_fmac_f32_e32 v44, v42, v37
	v_add_f32_e32 v45, v43, v44
	v_sub_f32_e32 v52, v41, v45
	v_sub_f32_e32 v41, v41, v52
	v_sub_f32_e32 v43, v45, v43
	v_sub_f32_e32 v41, v41, v45
	v_add_f32_e32 v39, v39, v41
	v_sub_f32_e32 v41, v43, v44
	v_add_f32_e32 v39, v41, v39
	v_add_f32_e32 v41, v52, v39
	v_mul_f32_e32 v43, v40, v41
	v_mul_f32_e32 v44, v38, v43
	v_fma_f32 v38, v43, v38, -v44
	v_fmac_f32_e32 v38, v43, v37
	v_sub_f32_e32 v37, v52, v41
	v_add_f32_e32 v37, v39, v37
	v_add_f32_e32 v39, v44, v38
	v_sub_f32_e32 v45, v41, v39
	v_sub_f32_e32 v41, v41, v45
	v_sub_f32_e32 v44, v39, v44
	v_sub_f32_e32 v39, v41, v39
	v_add_f32_e32 v37, v37, v39
	v_sub_f32_e32 v38, v44, v38
	v_add_f32_e32 v37, v38, v37
	v_add_f32_e32 v38, v42, v43
	v_add_f32_e32 v37, v45, v37
	v_sub_f32_e32 v39, v38, v42
	v_mul_f32_e32 v37, v40, v37
	v_sub_f32_e32 v39, v43, v39
	v_add_f32_e32 v37, v39, v37
	v_mul_f32_e32 v42, 0x3f317218, v36
	v_add_f32_e32 v39, v38, v37
	v_fma_f32 v43, v36, s34, -v42
	v_mul_f32_e32 v40, v39, v39
	v_fmac_f32_e32 v43, 0xb102e308, v36
	v_sub_f32_e32 v36, v39, v38
	v_fmamk_f32 v41, v40, 0x3e9b6dac, v184
	v_sub_f32_e32 v36, v37, v36
	v_add_f32_e32 v37, v42, v43
	v_fmaak_f32 v41, v40, v41, 0x3f2aaada
	v_sub_f32_e32 v38, v37, v42
	v_ldexp_f32 v42, v39, 1
	v_mul_f32_e32 v39, v39, v40
	v_mul_f32_e32 v39, v39, v41
	v_add_f32_e32 v40, v42, v39
	v_sub_f32_e32 v41, v40, v42
	v_ldexp_f32 v36, v36, 1
	v_sub_f32_e32 v39, v39, v41
	v_add_f32_e32 v36, v36, v39
	v_add_f32_e32 v39, v40, v36
	v_sub_f32_e32 v40, v39, v40
	v_sub_f32_e32 v36, v36, v40
	v_add_f32_e32 v40, v37, v39
	v_sub_f32_e32 v41, v40, v37
	v_sub_f32_e32 v42, v40, v41
	v_sub_f32_e32 v38, v43, v38
	v_sub_f32_e32 v37, v37, v42
	v_sub_f32_e32 v39, v39, v41
	v_add_f32_e32 v37, v39, v37
	v_add_f32_e32 v39, v38, v36
	v_sub_f32_e32 v41, v39, v38
	v_sub_f32_e32 v42, v39, v41
	v_sub_f32_e32 v38, v38, v42
	v_sub_f32_e32 v36, v36, v41
	v_add_f32_e32 v37, v39, v37
	v_add_f32_e32 v36, v36, v38
	v_add_f32_e32 v38, v40, v37
	v_sub_f32_e32 v39, v38, v40
	v_sub_f32_e32 v37, v37, v39
	v_add_f32_e32 v36, v36, v37
	v_add_f32_e32 v36, v38, v36
	v_cndmask_b32_e32 v36, v185, v36, vcc
	v_cmp_ngt_f32_e32 vcc, -1.0, v35
	s_nop 1
	v_cndmask_b32_e32 v36, v186, v36, vcc
	v_cmp_neq_f32_e32 vcc, -1.0, v35
	s_nop 1
	v_cndmask_b32_e32 v36, v187, v36, vcc
	v_cmp_lt_f32_e64 vcc, |v35|, s36
	s_nop 1
	v_cndmask_b32_e32 v35, v36, v35, vcc
	v_add_f32_e32 v34, v34, v35
	v_sub_f32_e32 v34, -0.5, v34
	v_mul_f32_e32 v34, 0x3fb8aa3b, v34
	v_exp_f32_e32 v34, v34
	s_nop 0
	v_xor_b32_e32 v36, 0x80000000, v34
	v_lshl_add_u64 v[34:35], s[16:17], 0, v[60:61]
	v_lshl_add_u64 v[34:35], v[34:35], 0, v[50:51]
	global_store_dword v[34:35], v36, off
	v_mov_b32_e32 v34, v241
	v_add_f32_e32 v35, v46, v34
	v_max_f32_e64 v34, -v35, 0
	v_mul_f32_e64 v35, |v35|, s30
	v_exp_f32_e32 v35, v35
	s_nop 0
	v_add_f32_e32 v38, 1.0, v35
	v_add_f32_e32 v36, -1.0, v38
	v_sub_f32_e32 v37, v36, v38
	v_add_f32_e32 v37, 1.0, v37
	v_sub_f32_e32 v36, v35, v36
	v_add_f32_e32 v39, v36, v37
	v_frexp_mant_f32_e32 v36, v38
	v_cmp_gt_f32_e32 vcc, s31, v36
	v_cvt_f64_f32_e32 v[36:37], v38
	v_frexp_exp_i32_f64_e32 v36, v[36:37]
	v_subbrev_co_u32_e32 v36, vcc, 0, v36, vcc
	v_sub_u32_e32 v37, 0, v36
	v_ldexp_f32 v38, v38, v37
	v_ldexp_f32 v37, v39, v37
	v_add_f32_e32 v39, -1.0, v38
	v_add_f32_e32 v40, 1.0, v39
	v_sub_f32_e32 v40, v38, v40
	v_add_f32_e32 v40, v37, v40
	v_add_f32_e32 v41, v39, v40
	v_sub_f32_e32 v39, v41, v39
	v_sub_f32_e32 v39, v40, v39
	v_add_f32_e32 v40, 1.0, v38
	v_add_f32_e32 v42, -1.0, v40
	v_sub_f32_e32 v38, v38, v42
	v_add_f32_e32 v37, v37, v38
	v_add_f32_e32 v38, v40, v37
	v_sub_f32_e32 v40, v38, v40
	v_sub_f32_e32 v37, v37, v40
	v_rcp_f32_e32 v40, v38
	v_cvt_f32_i32_e32 v36, v36
	v_cmp_neq_f32_e32 vcc, s35, v35
	v_mul_f32_e32 v42, v41, v40
	v_mul_f32_e32 v43, v38, v42
	v_fma_f32 v44, v42, v38, -v43
	v_fmac_f32_e32 v44, v42, v37
	v_add_f32_e32 v45, v43, v44
	v_sub_f32_e32 v46, v41, v45
	v_sub_f32_e32 v41, v41, v46
	v_sub_f32_e32 v43, v45, v43
	v_sub_f32_e32 v41, v41, v45
	v_add_f32_e32 v39, v39, v41
	v_sub_f32_e32 v41, v43, v44
	v_add_f32_e32 v39, v41, v39
	v_add_f32_e32 v41, v46, v39
	v_mul_f32_e32 v43, v40, v41
	v_mul_f32_e32 v44, v38, v43
	v_fma_f32 v38, v43, v38, -v44
	v_fmac_f32_e32 v38, v43, v37
	v_sub_f32_e32 v37, v46, v41
	v_add_f32_e32 v37, v39, v37
	v_add_f32_e32 v39, v44, v38
	v_sub_f32_e32 v45, v41, v39
	v_sub_f32_e32 v41, v41, v45
	v_sub_f32_e32 v44, v39, v44
	v_sub_f32_e32 v39, v41, v39
	v_add_f32_e32 v37, v37, v39
	v_sub_f32_e32 v38, v44, v38
	v_add_f32_e32 v37, v38, v37
	v_add_f32_e32 v38, v42, v43
	v_add_f32_e32 v37, v45, v37
	v_sub_f32_e32 v39, v38, v42
	v_mul_f32_e32 v37, v40, v37
	v_sub_f32_e32 v39, v43, v39
	v_add_f32_e32 v37, v39, v37
	v_mul_f32_e32 v42, 0x3f317218, v36
	v_add_f32_e32 v39, v38, v37
	v_fma_f32 v43, v36, s34, -v42
	v_mul_f32_e32 v40, v39, v39
	v_fmac_f32_e32 v43, 0xb102e308, v36
	v_sub_f32_e32 v36, v39, v38
	v_fmamk_f32 v41, v40, 0x3e9b6dac, v184
	v_sub_f32_e32 v36, v37, v36
	v_add_f32_e32 v37, v42, v43
	v_fmaak_f32 v41, v40, v41, 0x3f2aaada
	v_sub_f32_e32 v38, v37, v42
	v_ldexp_f32 v42, v39, 1
	v_mul_f32_e32 v39, v39, v40
	v_mul_f32_e32 v39, v39, v41
	v_add_f32_e32 v40, v42, v39
	v_sub_f32_e32 v41, v40, v42
	v_ldexp_f32 v36, v36, 1
	v_sub_f32_e32 v39, v39, v41
	v_add_f32_e32 v36, v36, v39
	v_add_f32_e32 v39, v40, v36
	v_sub_f32_e32 v40, v39, v40
	v_sub_f32_e32 v36, v36, v40
	v_add_f32_e32 v40, v37, v39
	v_sub_f32_e32 v41, v40, v37
	v_sub_f32_e32 v42, v40, v41
	v_sub_f32_e32 v38, v43, v38
	v_sub_f32_e32 v37, v37, v42
	v_sub_f32_e32 v39, v39, v41
	v_add_f32_e32 v37, v39, v37
	v_add_f32_e32 v39, v38, v36
	v_sub_f32_e32 v41, v39, v38
	v_sub_f32_e32 v42, v39, v41
	v_sub_f32_e32 v38, v38, v42
	v_sub_f32_e32 v36, v36, v41
	v_add_f32_e32 v37, v39, v37
	v_add_f32_e32 v36, v36, v38
	v_add_f32_e32 v38, v40, v37
	v_sub_f32_e32 v39, v38, v40
	v_sub_f32_e32 v37, v37, v39
	v_add_f32_e32 v36, v36, v37
	v_add_f32_e32 v36, v38, v36
	v_cndmask_b32_e32 v36, v185, v36, vcc
	v_cmp_ngt_f32_e32 vcc, -1.0, v35
	s_nop 1
	v_cndmask_b32_e32 v36, v186, v36, vcc
	v_cmp_neq_f32_e32 vcc, -1.0, v35
	s_nop 1
	v_cndmask_b32_e32 v36, v187, v36, vcc
	v_cmp_lt_f32_e64 vcc, |v35|, s36
	s_nop 1
	v_cndmask_b32_e32 v35, v36, v35, vcc
	v_add_f32_e32 v34, v34, v35
	v_sub_f32_e32 v34, -0.5, v34
	v_mul_f32_e32 v34, 0x3fb8aa3b, v34
	v_exp_f32_e32 v34, v34
	s_nop 0
	v_xor_b32_e32 v36, 0x80000000, v34
	v_lshl_add_u64 v[34:35], s[16:17], 0, v[142:143]
	v_lshl_add_u64 v[34:35], v[34:35], 0, v[50:51]
	global_store_dword v[34:35], v36, off
	v_mov_b32_e32 v34, v241
	v_add_f32_e32 v35, v47, v34
	v_max_f32_e64 v34, -v35, 0
	v_mul_f32_e64 v35, |v35|, s30
	v_exp_f32_e32 v35, v35
	s_nop 0
	v_add_f32_e32 v38, 1.0, v35
	v_add_f32_e32 v36, -1.0, v38
	v_sub_f32_e32 v37, v36, v38
	v_add_f32_e32 v37, 1.0, v37
	v_sub_f32_e32 v36, v35, v36
	v_add_f32_e32 v39, v36, v37
	v_frexp_mant_f32_e32 v36, v38
	v_cmp_gt_f32_e32 vcc, s31, v36
	v_cvt_f64_f32_e32 v[36:37], v38
	v_frexp_exp_i32_f64_e32 v36, v[36:37]
	v_subbrev_co_u32_e32 v36, vcc, 0, v36, vcc
	v_sub_u32_e32 v37, 0, v36
	v_ldexp_f32 v38, v38, v37
	v_ldexp_f32 v37, v39, v37
	v_add_f32_e32 v39, -1.0, v38
	v_add_f32_e32 v40, 1.0, v39
	v_sub_f32_e32 v40, v38, v40
	v_add_f32_e32 v40, v37, v40
	v_add_f32_e32 v41, v39, v40
	v_sub_f32_e32 v39, v41, v39
	v_sub_f32_e32 v39, v40, v39
	v_add_f32_e32 v40, 1.0, v38
	v_add_f32_e32 v42, -1.0, v40
	v_sub_f32_e32 v38, v38, v42
	v_add_f32_e32 v37, v37, v38
	v_add_f32_e32 v38, v40, v37
	v_sub_f32_e32 v40, v38, v40
	v_sub_f32_e32 v37, v37, v40
	v_rcp_f32_e32 v40, v38
	v_cvt_f32_i32_e32 v36, v36
	v_cmp_neq_f32_e32 vcc, s35, v35
	v_mul_f32_e32 v42, v41, v40
	v_mul_f32_e32 v43, v38, v42
	v_fma_f32 v44, v42, v38, -v43
	v_fmac_f32_e32 v44, v42, v37
	v_add_f32_e32 v45, v43, v44
	v_sub_f32_e32 v46, v41, v45
	v_sub_f32_e32 v41, v41, v46
	v_sub_f32_e32 v43, v45, v43
	v_sub_f32_e32 v41, v41, v45
	v_add_f32_e32 v39, v39, v41
	v_sub_f32_e32 v41, v43, v44
	v_add_f32_e32 v39, v41, v39
	v_add_f32_e32 v41, v46, v39
	v_mul_f32_e32 v43, v40, v41
	v_mul_f32_e32 v44, v38, v43
	v_fma_f32 v38, v43, v38, -v44
	v_fmac_f32_e32 v38, v43, v37
	v_sub_f32_e32 v37, v46, v41
	v_add_f32_e32 v37, v39, v37
	v_add_f32_e32 v39, v44, v38
	v_sub_f32_e32 v45, v41, v39
	v_sub_f32_e32 v41, v41, v45
	v_sub_f32_e32 v44, v39, v44
	v_sub_f32_e32 v39, v41, v39
	v_add_f32_e32 v37, v37, v39
	v_sub_f32_e32 v38, v44, v38
	v_add_f32_e32 v37, v38, v37
	v_add_f32_e32 v38, v42, v43
	v_add_f32_e32 v37, v45, v37
	v_sub_f32_e32 v39, v38, v42
	v_mul_f32_e32 v37, v40, v37
	v_sub_f32_e32 v39, v43, v39
	v_add_f32_e32 v37, v39, v37
	v_mul_f32_e32 v42, 0x3f317218, v36
	v_add_f32_e32 v39, v38, v37
	v_fma_f32 v43, v36, s34, -v42
	v_mul_f32_e32 v40, v39, v39
	v_fmac_f32_e32 v43, 0xb102e308, v36
	v_sub_f32_e32 v36, v39, v38
	v_fmamk_f32 v41, v40, 0x3e9b6dac, v184
	v_sub_f32_e32 v36, v37, v36
	v_add_f32_e32 v37, v42, v43
	v_fmaak_f32 v41, v40, v41, 0x3f2aaada
	v_sub_f32_e32 v38, v37, v42
	v_ldexp_f32 v42, v39, 1
	v_mul_f32_e32 v39, v39, v40
	v_mul_f32_e32 v39, v39, v41
	v_add_f32_e32 v40, v42, v39
	v_sub_f32_e32 v41, v40, v42
	v_ldexp_f32 v36, v36, 1
	v_sub_f32_e32 v39, v39, v41
	v_add_f32_e32 v36, v36, v39
	v_add_f32_e32 v39, v40, v36
	v_sub_f32_e32 v40, v39, v40
	v_sub_f32_e32 v36, v36, v40
	v_add_f32_e32 v40, v37, v39
	v_sub_f32_e32 v41, v40, v37
	v_sub_f32_e32 v42, v40, v41
	v_sub_f32_e32 v38, v43, v38
	v_sub_f32_e32 v37, v37, v42
	v_sub_f32_e32 v39, v39, v41
	v_add_f32_e32 v37, v39, v37
	v_add_f32_e32 v39, v38, v36
	v_sub_f32_e32 v41, v39, v38
	v_sub_f32_e32 v42, v39, v41
	v_sub_f32_e32 v38, v38, v42
	v_sub_f32_e32 v36, v36, v41
	v_add_f32_e32 v37, v39, v37
	v_add_f32_e32 v36, v36, v38
	v_add_f32_e32 v38, v40, v37
	v_sub_f32_e32 v39, v38, v40
	v_sub_f32_e32 v37, v37, v39
	v_add_f32_e32 v36, v36, v37
	v_add_f32_e32 v36, v38, v36
	v_cndmask_b32_e32 v36, v185, v36, vcc
	v_cmp_ngt_f32_e32 vcc, -1.0, v35
	s_nop 1
	v_cndmask_b32_e32 v36, v186, v36, vcc
	v_cmp_neq_f32_e32 vcc, -1.0, v35
	s_nop 1
	v_cndmask_b32_e32 v36, v187, v36, vcc
	v_cmp_lt_f32_e64 vcc, |v35|, s36
	s_nop 1
	v_cndmask_b32_e32 v35, v36, v35, vcc
	v_add_f32_e32 v34, v34, v35
	v_sub_f32_e32 v34, -0.5, v34
	v_mul_f32_e32 v34, 0x3fb8aa3b, v34
	v_exp_f32_e32 v34, v34
	s_nop 0
	v_xor_b32_e32 v36, 0x80000000, v34
	v_lshl_add_u64 v[34:35], s[16:17], 0, v[62:63]
	v_lshl_add_u64 v[34:35], v[34:35], 0, v[50:51]
	global_store_dword v[34:35], v36, off
	v_mov_b32_e32 v34, v241
	v_add_f32_e32 v35, v48, v34
	v_max_f32_e64 v34, -v35, 0
	v_mul_f32_e64 v35, |v35|, s30
	v_exp_f32_e32 v35, v35
	s_nop 0
	v_add_f32_e32 v38, 1.0, v35
	v_add_f32_e32 v36, -1.0, v38
	v_sub_f32_e32 v37, v36, v38
	v_add_f32_e32 v37, 1.0, v37
	v_sub_f32_e32 v36, v35, v36
	v_add_f32_e32 v39, v36, v37
	v_frexp_mant_f32_e32 v36, v38
	v_cmp_gt_f32_e32 vcc, s31, v36
	v_cvt_f64_f32_e32 v[36:37], v38
	v_frexp_exp_i32_f64_e32 v36, v[36:37]
	v_subbrev_co_u32_e32 v36, vcc, 0, v36, vcc
	v_sub_u32_e32 v37, 0, v36
	v_ldexp_f32 v38, v38, v37
	v_ldexp_f32 v37, v39, v37
	v_add_f32_e32 v39, -1.0, v38
	v_add_f32_e32 v40, 1.0, v39
	v_sub_f32_e32 v40, v38, v40
	v_add_f32_e32 v40, v37, v40
	v_add_f32_e32 v41, v39, v40
	v_sub_f32_e32 v39, v41, v39
	v_sub_f32_e32 v39, v40, v39
	v_add_f32_e32 v40, 1.0, v38
	v_add_f32_e32 v42, -1.0, v40
	v_sub_f32_e32 v38, v38, v42
	v_add_f32_e32 v37, v37, v38
	v_add_f32_e32 v38, v40, v37
	v_sub_f32_e32 v40, v38, v40
	v_sub_f32_e32 v37, v37, v40
	v_rcp_f32_e32 v40, v38
	v_cvt_f32_i32_e32 v36, v36
	v_cmp_neq_f32_e32 vcc, s35, v35
	v_mul_f32_e32 v42, v41, v40
	v_mul_f32_e32 v43, v38, v42
	v_fma_f32 v44, v42, v38, -v43
	v_fmac_f32_e32 v44, v42, v37
	v_add_f32_e32 v45, v43, v44
	v_sub_f32_e32 v46, v41, v45
	v_sub_f32_e32 v41, v41, v46
	v_sub_f32_e32 v43, v45, v43
	v_sub_f32_e32 v41, v41, v45
	v_add_f32_e32 v39, v39, v41
	v_sub_f32_e32 v41, v43, v44
	v_add_f32_e32 v39, v41, v39
	v_add_f32_e32 v41, v46, v39
	v_mul_f32_e32 v43, v40, v41
	v_mul_f32_e32 v44, v38, v43
	v_fma_f32 v38, v43, v38, -v44
	v_fmac_f32_e32 v38, v43, v37
	v_sub_f32_e32 v37, v46, v41
	v_add_f32_e32 v37, v39, v37
	v_add_f32_e32 v39, v44, v38
	v_sub_f32_e32 v45, v41, v39
	v_sub_f32_e32 v41, v41, v45
	v_sub_f32_e32 v44, v39, v44
	v_sub_f32_e32 v39, v41, v39
	v_add_f32_e32 v37, v37, v39
	v_sub_f32_e32 v38, v44, v38
	v_add_f32_e32 v37, v38, v37
	v_add_f32_e32 v38, v42, v43
	v_add_f32_e32 v37, v45, v37
	v_sub_f32_e32 v39, v38, v42
	v_mul_f32_e32 v37, v40, v37
	v_sub_f32_e32 v39, v43, v39
	v_add_f32_e32 v37, v39, v37
	v_mul_f32_e32 v42, 0x3f317218, v36
	v_add_f32_e32 v39, v38, v37
	v_fma_f32 v43, v36, s34, -v42
	v_mul_f32_e32 v40, v39, v39
	v_fmac_f32_e32 v43, 0xb102e308, v36
	v_sub_f32_e32 v36, v39, v38
	v_fmamk_f32 v41, v40, 0x3e9b6dac, v184
	v_sub_f32_e32 v36, v37, v36
	v_add_f32_e32 v37, v42, v43
	v_fmaak_f32 v41, v40, v41, 0x3f2aaada
	v_sub_f32_e32 v38, v37, v42
	v_ldexp_f32 v42, v39, 1
	v_mul_f32_e32 v39, v39, v40
	v_mul_f32_e32 v39, v39, v41
	v_add_f32_e32 v40, v42, v39
	v_sub_f32_e32 v41, v40, v42
	v_ldexp_f32 v36, v36, 1
	v_sub_f32_e32 v39, v39, v41
	v_add_f32_e32 v36, v36, v39
	v_add_f32_e32 v39, v40, v36
	v_sub_f32_e32 v40, v39, v40
	v_sub_f32_e32 v36, v36, v40
	v_add_f32_e32 v40, v37, v39
	v_sub_f32_e32 v41, v40, v37
	v_sub_f32_e32 v42, v40, v41
	v_sub_f32_e32 v38, v43, v38
	v_sub_f32_e32 v37, v37, v42
	v_sub_f32_e32 v39, v39, v41
	v_add_f32_e32 v37, v39, v37
	v_add_f32_e32 v39, v38, v36
	v_sub_f32_e32 v41, v39, v38
	v_sub_f32_e32 v42, v39, v41
	v_sub_f32_e32 v38, v38, v42
	v_sub_f32_e32 v36, v36, v41
	v_add_f32_e32 v37, v39, v37
	v_add_f32_e32 v36, v36, v38
	v_add_f32_e32 v38, v40, v37
	v_sub_f32_e32 v39, v38, v40
	v_sub_f32_e32 v37, v37, v39
	v_add_f32_e32 v36, v36, v37
	v_add_f32_e32 v36, v38, v36
	v_cndmask_b32_e32 v36, v185, v36, vcc
	v_cmp_ngt_f32_e32 vcc, -1.0, v35
	s_nop 1
	v_cndmask_b32_e32 v36, v186, v36, vcc
	v_cmp_neq_f32_e32 vcc, -1.0, v35
	s_nop 1
	v_cndmask_b32_e32 v36, v187, v36, vcc
	v_cmp_lt_f32_e64 vcc, |v35|, s36
	s_nop 1
	v_cndmask_b32_e32 v35, v36, v35, vcc
	v_add_f32_e32 v34, v34, v35
	v_sub_f32_e32 v34, -0.5, v34
	v_mul_f32_e32 v34, 0x3fb8aa3b, v34
	v_exp_f32_e32 v34, v34
	s_nop 0
	v_xor_b32_e32 v36, 0x80000000, v34
	v_lshl_add_u64 v[34:35], s[16:17], 0, v[144:145]
	v_lshl_add_u64 v[34:35], v[34:35], 0, v[50:51]
	global_store_dword v[34:35], v36, off
	v_mov_b32_e32 v34, v241
	v_add_f32_e32 v35, v49, v34
	v_max_f32_e64 v34, -v35, 0
	v_mul_f32_e64 v35, |v35|, s30
	v_exp_f32_e32 v35, v35
	s_nop 0
	v_add_f32_e32 v38, 1.0, v35
	v_add_f32_e32 v36, -1.0, v38
	v_sub_f32_e32 v37, v36, v38
	v_add_f32_e32 v37, 1.0, v37
	v_sub_f32_e32 v36, v35, v36
	v_add_f32_e32 v39, v36, v37
	v_frexp_mant_f32_e32 v36, v38
	v_cmp_gt_f32_e32 vcc, s31, v36
	v_cvt_f64_f32_e32 v[36:37], v38
	v_frexp_exp_i32_f64_e32 v36, v[36:37]
	v_subbrev_co_u32_e32 v36, vcc, 0, v36, vcc
	v_sub_u32_e32 v37, 0, v36
	v_ldexp_f32 v38, v38, v37
	v_ldexp_f32 v37, v39, v37
	v_add_f32_e32 v39, -1.0, v38
	v_add_f32_e32 v40, 1.0, v39
	v_sub_f32_e32 v40, v38, v40
	v_add_f32_e32 v40, v37, v40
	v_add_f32_e32 v41, v39, v40
	v_sub_f32_e32 v39, v41, v39
	v_sub_f32_e32 v39, v40, v39
	v_add_f32_e32 v40, 1.0, v38
	v_add_f32_e32 v42, -1.0, v40
	v_sub_f32_e32 v38, v38, v42
	v_add_f32_e32 v37, v37, v38
	v_add_f32_e32 v38, v40, v37
	v_sub_f32_e32 v40, v38, v40
	v_sub_f32_e32 v37, v37, v40
	v_rcp_f32_e32 v40, v38
	v_cvt_f32_i32_e32 v36, v36
	v_cmp_neq_f32_e32 vcc, s35, v35
	v_mul_f32_e32 v42, v41, v40
	v_mul_f32_e32 v43, v38, v42
	v_fma_f32 v44, v42, v38, -v43
	v_fmac_f32_e32 v44, v42, v37
	v_add_f32_e32 v45, v43, v44
	v_sub_f32_e32 v46, v41, v45
	v_sub_f32_e32 v41, v41, v46
	v_sub_f32_e32 v43, v45, v43
	v_sub_f32_e32 v41, v41, v45
	v_add_f32_e32 v39, v39, v41
	v_sub_f32_e32 v41, v43, v44
	v_add_f32_e32 v39, v41, v39
	v_add_f32_e32 v41, v46, v39
	v_mul_f32_e32 v43, v40, v41
	v_mul_f32_e32 v44, v38, v43
	v_fma_f32 v38, v43, v38, -v44
	v_fmac_f32_e32 v38, v43, v37
	v_sub_f32_e32 v37, v46, v41
	v_add_f32_e32 v37, v39, v37
	v_add_f32_e32 v39, v44, v38
	v_sub_f32_e32 v45, v41, v39
	v_sub_f32_e32 v41, v41, v45
	v_sub_f32_e32 v44, v39, v44
	v_sub_f32_e32 v39, v41, v39
	v_add_f32_e32 v37, v37, v39
	v_sub_f32_e32 v38, v44, v38
	v_add_f32_e32 v37, v38, v37
	v_add_f32_e32 v38, v42, v43
	v_add_f32_e32 v37, v45, v37
	v_sub_f32_e32 v39, v38, v42
	v_mul_f32_e32 v37, v40, v37
	v_sub_f32_e32 v39, v43, v39
	v_add_f32_e32 v37, v39, v37
	v_mul_f32_e32 v42, 0x3f317218, v36
	v_add_f32_e32 v39, v38, v37
	v_fma_f32 v43, v36, s34, -v42
	v_mul_f32_e32 v40, v39, v39
	v_fmac_f32_e32 v43, 0xb102e308, v36
	v_sub_f32_e32 v36, v39, v38
	v_fmamk_f32 v41, v40, 0x3e9b6dac, v184
	v_sub_f32_e32 v36, v37, v36
	v_add_f32_e32 v37, v42, v43
	v_fmaak_f32 v41, v40, v41, 0x3f2aaada
	v_sub_f32_e32 v38, v37, v42
	v_ldexp_f32 v42, v39, 1
	v_mul_f32_e32 v39, v39, v40
	v_mul_f32_e32 v39, v39, v41
	v_add_f32_e32 v40, v42, v39
	v_sub_f32_e32 v41, v40, v42
	v_ldexp_f32 v36, v36, 1
	v_sub_f32_e32 v39, v39, v41
	v_add_f32_e32 v36, v36, v39
	v_add_f32_e32 v39, v40, v36
	v_sub_f32_e32 v40, v39, v40
	v_sub_f32_e32 v36, v36, v40
	v_add_f32_e32 v40, v37, v39
	v_sub_f32_e32 v41, v40, v37
	v_sub_f32_e32 v42, v40, v41
	v_sub_f32_e32 v38, v43, v38
	v_sub_f32_e32 v37, v37, v42
	v_sub_f32_e32 v39, v39, v41
	v_add_f32_e32 v37, v39, v37
	v_add_f32_e32 v39, v38, v36
	v_sub_f32_e32 v41, v39, v38
	v_sub_f32_e32 v42, v39, v41
	v_sub_f32_e32 v38, v38, v42
	v_sub_f32_e32 v36, v36, v41
	v_add_f32_e32 v37, v39, v37
	v_add_f32_e32 v36, v36, v38
	v_add_f32_e32 v38, v40, v37
	v_sub_f32_e32 v39, v38, v40
	v_sub_f32_e32 v37, v37, v39
	v_add_f32_e32 v36, v36, v37
	v_add_f32_e32 v36, v38, v36
	v_cndmask_b32_e32 v36, v185, v36, vcc
	v_cmp_ngt_f32_e32 vcc, -1.0, v35
	s_nop 1
	v_cndmask_b32_e32 v36, v186, v36, vcc
	v_cmp_neq_f32_e32 vcc, -1.0, v35
	s_nop 1
	v_cndmask_b32_e32 v36, v187, v36, vcc
	v_cmp_lt_f32_e64 vcc, |v35|, s36
	s_nop 1
	v_cndmask_b32_e32 v35, v36, v35, vcc
	v_add_f32_e32 v34, v34, v35
	v_sub_f32_e32 v34, -0.5, v34
	v_mul_f32_e32 v34, 0x3fb8aa3b, v34
	v_exp_f32_e32 v34, v34
	s_nop 0
	v_xor_b32_e32 v36, 0x80000000, v34
	v_lshl_add_u64 v[34:35], s[16:17], 0, v[64:65]
	v_lshl_add_u64 v[34:35], v[34:35], 0, v[50:51]
	global_store_dword v[34:35], v36, off
	v_mov_b32_e32 v34, v240
	v_add_f32_e32 v34, v18, v34
	v_max_f32_e64 v18, -v34, 0
	v_mul_f32_e64 v34, |v34|, s30
	v_exp_f32_e32 v34, v34
	s_nop 0
	v_add_f32_e32 v35, 1.0, v34
	v_add_f32_e32 v36, -1.0, v35
	v_sub_f32_e32 v37, v36, v35
	v_add_f32_e32 v37, 1.0, v37
	v_sub_f32_e32 v36, v34, v36
	v_add_f32_e32 v38, v36, v37
	v_frexp_mant_f32_e32 v36, v35
	v_cmp_gt_f32_e32 vcc, s31, v36
	v_cvt_f64_f32_e32 v[36:37], v35
	v_frexp_exp_i32_f64_e32 v36, v[36:37]
	v_subbrev_co_u32_e32 v36, vcc, 0, v36, vcc
	v_sub_u32_e32 v37, 0, v36
	v_ldexp_f32 v35, v35, v37
	v_ldexp_f32 v37, v38, v37
	v_add_f32_e32 v38, -1.0, v35
	v_add_f32_e32 v39, 1.0, v38
	v_sub_f32_e32 v39, v35, v39
	v_add_f32_e32 v39, v37, v39
	v_add_f32_e32 v40, v38, v39
	v_sub_f32_e32 v38, v40, v38
	v_sub_f32_e32 v38, v39, v38
	v_add_f32_e32 v39, 1.0, v35
	v_add_f32_e32 v41, -1.0, v39
	v_sub_f32_e32 v35, v35, v41
	v_add_f32_e32 v35, v37, v35
	v_add_f32_e32 v37, v39, v35
	v_sub_f32_e32 v39, v37, v39
	v_sub_f32_e32 v35, v35, v39
	v_rcp_f32_e32 v39, v37
	v_cvt_f32_i32_e32 v36, v36
	v_cmp_neq_f32_e32 vcc, s35, v34
	v_mul_f32_e32 v41, v40, v39
	v_mul_f32_e32 v42, v37, v41
	v_fma_f32 v43, v41, v37, -v42
	v_fmac_f32_e32 v43, v41, v35
	v_add_f32_e32 v44, v42, v43
	v_sub_f32_e32 v45, v40, v44
	v_sub_f32_e32 v40, v40, v45
	v_sub_f32_e32 v42, v44, v42
	v_sub_f32_e32 v40, v40, v44
	v_add_f32_e32 v38, v38, v40
	v_sub_f32_e32 v40, v42, v43
	v_add_f32_e32 v38, v40, v38
	v_add_f32_e32 v40, v45, v38
	v_mul_f32_e32 v42, v39, v40
	v_mul_f32_e32 v43, v37, v42
	v_fma_f32 v37, v42, v37, -v43
	v_fmac_f32_e32 v37, v42, v35
	v_sub_f32_e32 v35, v45, v40
	v_add_f32_e32 v35, v38, v35
	v_add_f32_e32 v38, v43, v37
	v_sub_f32_e32 v44, v40, v38
	v_sub_f32_e32 v40, v40, v44
	v_sub_f32_e32 v43, v38, v43
	v_sub_f32_e32 v38, v40, v38
	v_add_f32_e32 v35, v35, v38
	v_sub_f32_e32 v37, v43, v37
	v_add_f32_e32 v35, v37, v35
	v_add_f32_e32 v37, v41, v42
	v_add_f32_e32 v35, v44, v35
	v_sub_f32_e32 v38, v37, v41
	v_mul_f32_e32 v35, v39, v35
	v_sub_f32_e32 v38, v42, v38
	v_add_f32_e32 v35, v38, v35
	v_mul_f32_e32 v41, 0x3f317218, v36
	v_add_f32_e32 v38, v37, v35
	v_fma_f32 v42, v36, s34, -v41
	v_mul_f32_e32 v39, v38, v38
	v_fmac_f32_e32 v42, 0xb102e308, v36
	v_sub_f32_e32 v36, v38, v37
	v_fmamk_f32 v40, v39, 0x3e9b6dac, v184
	v_sub_f32_e32 v35, v35, v36
	v_add_f32_e32 v36, v41, v42
	v_fmaak_f32 v40, v39, v40, 0x3f2aaada
	v_sub_f32_e32 v37, v36, v41
	v_ldexp_f32 v41, v38, 1
	v_mul_f32_e32 v38, v38, v39
	v_mul_f32_e32 v38, v38, v40
	v_add_f32_e32 v39, v41, v38
	v_sub_f32_e32 v40, v39, v41
	v_ldexp_f32 v35, v35, 1
	v_sub_f32_e32 v38, v38, v40
	v_add_f32_e32 v35, v35, v38
	v_add_f32_e32 v38, v39, v35
	v_sub_f32_e32 v39, v38, v39
	v_sub_f32_e32 v35, v35, v39
	v_add_f32_e32 v39, v36, v38
	v_sub_f32_e32 v40, v39, v36
	v_sub_f32_e32 v41, v39, v40
	v_sub_f32_e32 v37, v42, v37
	v_sub_f32_e32 v36, v36, v41
	v_sub_f32_e32 v38, v38, v40
	v_add_f32_e32 v36, v38, v36
	v_add_f32_e32 v38, v37, v35
	v_sub_f32_e32 v40, v38, v37
	v_sub_f32_e32 v41, v38, v40
	v_sub_f32_e32 v37, v37, v41
	v_sub_f32_e32 v35, v35, v40
	v_add_f32_e32 v36, v38, v36
	v_add_f32_e32 v35, v35, v37
	v_add_f32_e32 v37, v39, v36
	v_sub_f32_e32 v38, v37, v39
	v_sub_f32_e32 v36, v36, v38
	v_add_f32_e32 v35, v35, v36
	v_add_f32_e32 v35, v37, v35
	v_cndmask_b32_e32 v35, v185, v35, vcc
	v_cmp_ngt_f32_e32 vcc, -1.0, v34
	s_nop 1
	v_cndmask_b32_e32 v35, v186, v35, vcc
	v_cmp_neq_f32_e32 vcc, -1.0, v34
	s_nop 1
	v_cndmask_b32_e32 v35, v187, v35, vcc
	v_cmp_lt_f32_e64 vcc, |v34|, s36
	s_nop 1
	v_cndmask_b32_e32 v34, v35, v34, vcc
	v_add_f32_e32 v18, v18, v34
	v_sub_f32_e32 v18, -0.5, v18
	v_mul_f32_e32 v18, 0x3fb8aa3b, v18
	v_exp_f32_e32 v18, v18
	v_lshlrev_b64 v[34:35], 12, v[124:125]
	v_lshl_add_u64 v[36:37], v[70:71], 0, v[34:35]
	v_lshl_add_u64 v[34:35], s[16:17], 0, v[34:35]
	v_xor_b32_e32 v18, 0x80000000, v18
	global_store_dword v[36:37], v18, off
	v_mov_b32_e32 v18, v240
	v_lshl_add_u64 v[34:35], v[34:35], 0, v[50:51]
	v_add_f32_e32 v19, v19, v18
	v_max_f32_e64 v18, -v19, 0
	v_mul_f32_e64 v19, |v19|, s30
	v_exp_f32_e32 v19, v19
	s_nop 0
	v_add_f32_e32 v38, 1.0, v19
	v_add_f32_e32 v36, -1.0, v38
	v_sub_f32_e32 v37, v36, v38
	v_add_f32_e32 v37, 1.0, v37
	v_sub_f32_e32 v36, v19, v36
	v_add_f32_e32 v39, v36, v37
	v_frexp_mant_f32_e32 v36, v38
	v_cmp_gt_f32_e32 vcc, s31, v36
	v_cvt_f64_f32_e32 v[36:37], v38
	v_frexp_exp_i32_f64_e32 v36, v[36:37]
	v_subbrev_co_u32_e32 v36, vcc, 0, v36, vcc
	v_sub_u32_e32 v37, 0, v36
	v_ldexp_f32 v38, v38, v37
	v_ldexp_f32 v37, v39, v37
	v_add_f32_e32 v39, -1.0, v38
	v_add_f32_e32 v40, 1.0, v39
	v_sub_f32_e32 v40, v38, v40
	v_add_f32_e32 v40, v37, v40
	v_add_f32_e32 v41, v39, v40
	v_sub_f32_e32 v39, v41, v39
	v_sub_f32_e32 v39, v40, v39
	v_add_f32_e32 v40, 1.0, v38
	v_add_f32_e32 v42, -1.0, v40
	v_sub_f32_e32 v38, v38, v42
	v_add_f32_e32 v37, v37, v38
	v_add_f32_e32 v38, v40, v37
	v_sub_f32_e32 v40, v38, v40
	v_sub_f32_e32 v37, v37, v40
	v_rcp_f32_e32 v40, v38
	v_cvt_f32_i32_e32 v36, v36
	v_cmp_neq_f32_e32 vcc, s35, v19
	v_mul_f32_e32 v42, v41, v40
	v_mul_f32_e32 v43, v38, v42
	v_fma_f32 v44, v42, v38, -v43
	v_fmac_f32_e32 v44, v42, v37
	v_add_f32_e32 v45, v43, v44
	v_sub_f32_e32 v46, v41, v45
	v_sub_f32_e32 v41, v41, v46
	v_sub_f32_e32 v43, v45, v43
	v_sub_f32_e32 v41, v41, v45
	v_add_f32_e32 v39, v39, v41
	v_sub_f32_e32 v41, v43, v44
	v_add_f32_e32 v39, v41, v39
	v_add_f32_e32 v41, v46, v39
	v_mul_f32_e32 v43, v40, v41
	v_mul_f32_e32 v44, v38, v43
	v_fma_f32 v38, v43, v38, -v44
	v_fmac_f32_e32 v38, v43, v37
	v_sub_f32_e32 v37, v46, v41
	v_add_f32_e32 v37, v39, v37
	v_add_f32_e32 v39, v44, v38
	v_sub_f32_e32 v45, v41, v39
	v_sub_f32_e32 v41, v41, v45
	v_sub_f32_e32 v44, v39, v44
	v_sub_f32_e32 v39, v41, v39
	v_add_f32_e32 v37, v37, v39
	v_sub_f32_e32 v38, v44, v38
	v_add_f32_e32 v37, v38, v37
	v_add_f32_e32 v38, v42, v43
	v_add_f32_e32 v37, v45, v37
	v_sub_f32_e32 v39, v38, v42
	v_mul_f32_e32 v37, v40, v37
	v_sub_f32_e32 v39, v43, v39
	v_add_f32_e32 v37, v39, v37
	v_mul_f32_e32 v42, 0x3f317218, v36
	v_add_f32_e32 v39, v38, v37
	v_fma_f32 v43, v36, s34, -v42
	v_mul_f32_e32 v40, v39, v39
	v_fmac_f32_e32 v43, 0xb102e308, v36
	v_sub_f32_e32 v36, v39, v38
	v_fmamk_f32 v41, v40, 0x3e9b6dac, v184
	v_sub_f32_e32 v36, v37, v36
	v_add_f32_e32 v37, v42, v43
	v_fmaak_f32 v41, v40, v41, 0x3f2aaada
	v_sub_f32_e32 v38, v37, v42
	v_ldexp_f32 v42, v39, 1
	v_mul_f32_e32 v39, v39, v40
	v_mul_f32_e32 v39, v39, v41
	v_add_f32_e32 v40, v42, v39
	v_sub_f32_e32 v41, v40, v42
	v_ldexp_f32 v36, v36, 1
	v_sub_f32_e32 v39, v39, v41
	v_add_f32_e32 v36, v36, v39
	v_add_f32_e32 v39, v40, v36
	v_sub_f32_e32 v40, v39, v40
	v_sub_f32_e32 v36, v36, v40
	v_add_f32_e32 v40, v37, v39
	v_sub_f32_e32 v41, v40, v37
	v_sub_f32_e32 v42, v40, v41
	v_sub_f32_e32 v38, v43, v38
	v_sub_f32_e32 v37, v37, v42
	v_sub_f32_e32 v39, v39, v41
	v_add_f32_e32 v37, v39, v37
	v_add_f32_e32 v39, v38, v36
	v_sub_f32_e32 v41, v39, v38
	v_sub_f32_e32 v42, v39, v41
	v_sub_f32_e32 v38, v38, v42
	v_sub_f32_e32 v36, v36, v41
	v_add_f32_e32 v37, v39, v37
	v_add_f32_e32 v36, v36, v38
	v_add_f32_e32 v38, v40, v37
	v_sub_f32_e32 v39, v38, v40
	v_sub_f32_e32 v37, v37, v39
	v_add_f32_e32 v36, v36, v37
	v_add_f32_e32 v36, v38, v36
	v_cndmask_b32_e32 v36, v185, v36, vcc
	v_cmp_ngt_f32_e32 vcc, -1.0, v19
	s_nop 1
	v_cndmask_b32_e32 v36, v186, v36, vcc
	v_cmp_neq_f32_e32 vcc, -1.0, v19
	s_nop 1
	v_cndmask_b32_e32 v36, v187, v36, vcc
	v_cmp_lt_f32_e64 vcc, |v19|, s36
	s_nop 1
	v_cndmask_b32_e32 v19, v36, v19, vcc
	v_add_f32_e32 v18, v18, v19
	v_sub_f32_e32 v18, -0.5, v18
	v_mul_f32_e32 v18, 0x3fb8aa3b, v18
	v_exp_f32_e32 v18, v18
	s_nop 0
	v_xor_b32_e32 v38, 0x80000000, v18
	v_lshlrev_b64 v[18:19], 12, v[122:123]
	v_lshl_add_u64 v[36:37], v[70:71], 0, v[18:19]
	global_store_dword v[36:37], v38, off
	v_mov_b32_e32 v36, v240
	v_add_f32_e32 v36, v20, v36
	v_max_f32_e64 v20, -v36, 0
	v_mul_f32_e64 v36, |v36|, s30
	v_exp_f32_e32 v36, v36
	s_nop 0
	v_add_f32_e32 v37, 1.0, v36
	v_add_f32_e32 v38, -1.0, v37
	v_sub_f32_e32 v39, v38, v37
	v_add_f32_e32 v39, 1.0, v39
	v_sub_f32_e32 v38, v36, v38
	v_add_f32_e32 v40, v38, v39
	v_frexp_mant_f32_e32 v38, v37
	v_cmp_gt_f32_e32 vcc, s31, v38
	v_cvt_f64_f32_e32 v[38:39], v37
	v_frexp_exp_i32_f64_e32 v38, v[38:39]
	v_subbrev_co_u32_e32 v38, vcc, 0, v38, vcc
	v_sub_u32_e32 v39, 0, v38
	v_ldexp_f32 v37, v37, v39
	v_ldexp_f32 v39, v40, v39
	v_add_f32_e32 v40, -1.0, v37
	v_add_f32_e32 v41, 1.0, v40
	v_sub_f32_e32 v41, v37, v41
	v_add_f32_e32 v41, v39, v41
	v_add_f32_e32 v42, v40, v41
	v_sub_f32_e32 v40, v42, v40
	v_sub_f32_e32 v40, v41, v40
	v_add_f32_e32 v41, 1.0, v37
	v_add_f32_e32 v43, -1.0, v41
	v_sub_f32_e32 v37, v37, v43
	v_add_f32_e32 v37, v39, v37
	v_add_f32_e32 v39, v41, v37
	v_sub_f32_e32 v41, v39, v41
	v_sub_f32_e32 v37, v37, v41
	v_rcp_f32_e32 v41, v39
	v_cvt_f32_i32_e32 v38, v38
	v_cmp_neq_f32_e32 vcc, s35, v36
	v_mul_f32_e32 v43, v42, v41
	v_mul_f32_e32 v44, v39, v43
	v_fma_f32 v45, v43, v39, -v44
	v_fmac_f32_e32 v45, v43, v37
	v_add_f32_e32 v46, v44, v45
	v_sub_f32_e32 v47, v42, v46
	v_sub_f32_e32 v42, v42, v47
	v_sub_f32_e32 v44, v46, v44
	v_sub_f32_e32 v42, v42, v46
	v_add_f32_e32 v40, v40, v42
	v_sub_f32_e32 v42, v44, v45
	v_add_f32_e32 v40, v42, v40
	v_add_f32_e32 v42, v47, v40
	v_mul_f32_e32 v44, v41, v42
	v_mul_f32_e32 v45, v39, v44
	v_fma_f32 v39, v44, v39, -v45
	v_fmac_f32_e32 v39, v44, v37
	v_sub_f32_e32 v37, v47, v42
	v_add_f32_e32 v37, v40, v37
	v_add_f32_e32 v40, v45, v39
	v_sub_f32_e32 v46, v42, v40
	v_sub_f32_e32 v42, v42, v46
	v_sub_f32_e32 v45, v40, v45
	v_sub_f32_e32 v40, v42, v40
	v_add_f32_e32 v37, v37, v40
	v_sub_f32_e32 v39, v45, v39
	v_add_f32_e32 v37, v39, v37
	v_add_f32_e32 v39, v43, v44
	v_add_f32_e32 v37, v46, v37
	v_sub_f32_e32 v40, v39, v43
	v_mul_f32_e32 v37, v41, v37
	v_sub_f32_e32 v40, v44, v40
	v_add_f32_e32 v37, v40, v37
	v_mul_f32_e32 v43, 0x3f317218, v38
	v_add_f32_e32 v40, v39, v37
	v_fma_f32 v44, v38, s34, -v43
	v_mul_f32_e32 v41, v40, v40
	v_fmac_f32_e32 v44, 0xb102e308, v38
	v_sub_f32_e32 v38, v40, v39
	v_fmamk_f32 v42, v41, 0x3e9b6dac, v184
	v_sub_f32_e32 v37, v37, v38
	v_add_f32_e32 v38, v43, v44
	v_fmaak_f32 v42, v41, v42, 0x3f2aaada
	v_sub_f32_e32 v39, v38, v43
	v_ldexp_f32 v43, v40, 1
	v_mul_f32_e32 v40, v40, v41
	v_mul_f32_e32 v40, v40, v42
	v_add_f32_e32 v41, v43, v40
	v_sub_f32_e32 v42, v41, v43
	v_ldexp_f32 v37, v37, 1
	v_sub_f32_e32 v40, v40, v42
	v_add_f32_e32 v37, v37, v40
	v_add_f32_e32 v40, v41, v37
	v_sub_f32_e32 v41, v40, v41
	v_sub_f32_e32 v37, v37, v41
	v_add_f32_e32 v41, v38, v40
	v_sub_f32_e32 v42, v41, v38
	v_sub_f32_e32 v43, v41, v42
	v_sub_f32_e32 v39, v44, v39
	v_sub_f32_e32 v38, v38, v43
	v_sub_f32_e32 v40, v40, v42
	v_add_f32_e32 v38, v40, v38
	v_add_f32_e32 v40, v39, v37
	v_sub_f32_e32 v42, v40, v39
	v_sub_f32_e32 v43, v40, v42
	v_sub_f32_e32 v39, v39, v43
	v_sub_f32_e32 v37, v37, v42
	v_add_f32_e32 v38, v40, v38
	v_add_f32_e32 v37, v37, v39
	v_add_f32_e32 v39, v41, v38
	v_sub_f32_e32 v40, v39, v41
	v_sub_f32_e32 v38, v38, v40
	v_add_f32_e32 v37, v37, v38
	v_add_f32_e32 v37, v39, v37
	v_cndmask_b32_e32 v37, v185, v37, vcc
	v_cmp_ngt_f32_e32 vcc, -1.0, v36
	s_nop 1
	v_cndmask_b32_e32 v37, v186, v37, vcc
	v_cmp_neq_f32_e32 vcc, -1.0, v36
	s_nop 1
	v_cndmask_b32_e32 v37, v187, v37, vcc
	v_cmp_lt_f32_e64 vcc, |v36|, s36
	s_nop 1
	v_cndmask_b32_e32 v36, v37, v36, vcc
	v_add_f32_e32 v20, v20, v36
	v_sub_f32_e32 v20, -0.5, v20
	v_mul_f32_e32 v20, 0x3fb8aa3b, v20
	v_exp_f32_e32 v20, v20
	v_lshlrev_b64 v[36:37], 12, v[96:97]
	v_lshl_add_u64 v[38:39], v[70:71], 0, v[36:37]
	v_xor_b32_e32 v20, 0x80000000, v20
	global_store_dword v[38:39], v20, off
	v_mov_b32_e32 v20, v240
	v_add_f32_e32 v21, v21, v20
	v_max_f32_e64 v20, -v21, 0
	v_mul_f32_e64 v21, |v21|, s30
	v_exp_f32_e32 v21, v21
	s_nop 0
	v_add_f32_e32 v40, 1.0, v21
	v_add_f32_e32 v38, -1.0, v40
	v_sub_f32_e32 v39, v38, v40
	v_add_f32_e32 v39, 1.0, v39
	v_sub_f32_e32 v38, v21, v38
	v_add_f32_e32 v41, v38, v39
	v_frexp_mant_f32_e32 v38, v40
	v_cmp_gt_f32_e32 vcc, s31, v38
	v_cvt_f64_f32_e32 v[38:39], v40
	v_frexp_exp_i32_f64_e32 v38, v[38:39]
	v_subbrev_co_u32_e32 v38, vcc, 0, v38, vcc
	v_sub_u32_e32 v39, 0, v38
	v_ldexp_f32 v40, v40, v39
	v_ldexp_f32 v39, v41, v39
	v_add_f32_e32 v41, -1.0, v40
	v_add_f32_e32 v42, 1.0, v41
	v_sub_f32_e32 v42, v40, v42
	v_add_f32_e32 v42, v39, v42
	v_add_f32_e32 v43, v41, v42
	v_sub_f32_e32 v41, v43, v41
	v_sub_f32_e32 v41, v42, v41
	v_add_f32_e32 v42, 1.0, v40
	v_add_f32_e32 v44, -1.0, v42
	v_sub_f32_e32 v40, v40, v44
	v_add_f32_e32 v39, v39, v40
	v_add_f32_e32 v40, v42, v39
	v_sub_f32_e32 v42, v40, v42
	v_sub_f32_e32 v39, v39, v42
	v_rcp_f32_e32 v42, v40
	v_cvt_f32_i32_e32 v38, v38
	v_cmp_neq_f32_e32 vcc, s35, v21
	v_mul_f32_e32 v44, v43, v42
	v_mul_f32_e32 v45, v40, v44
	v_fma_f32 v46, v44, v40, -v45
	v_fmac_f32_e32 v46, v44, v39
	v_add_f32_e32 v47, v45, v46
	v_sub_f32_e32 v48, v43, v47
	v_sub_f32_e32 v43, v43, v48
	v_sub_f32_e32 v45, v47, v45
	v_sub_f32_e32 v43, v43, v47
	v_add_f32_e32 v41, v41, v43
	v_sub_f32_e32 v43, v45, v46
	v_add_f32_e32 v41, v43, v41
	v_add_f32_e32 v43, v48, v41
	v_mul_f32_e32 v45, v42, v43
	v_mul_f32_e32 v46, v40, v45
	v_fma_f32 v40, v45, v40, -v46
	v_fmac_f32_e32 v40, v45, v39
	v_sub_f32_e32 v39, v48, v43
	v_add_f32_e32 v39, v41, v39
	v_add_f32_e32 v41, v46, v40
	v_sub_f32_e32 v47, v43, v41
	v_sub_f32_e32 v43, v43, v47
	v_sub_f32_e32 v46, v41, v46
	v_sub_f32_e32 v41, v43, v41
	v_add_f32_e32 v39, v39, v41
	v_sub_f32_e32 v40, v46, v40
	v_add_f32_e32 v39, v40, v39
	v_add_f32_e32 v40, v44, v45
	v_add_f32_e32 v39, v47, v39
	v_sub_f32_e32 v41, v40, v44
	v_mul_f32_e32 v39, v42, v39
	v_sub_f32_e32 v41, v45, v41
	v_add_f32_e32 v39, v41, v39
	v_mul_f32_e32 v44, 0x3f317218, v38
	v_add_f32_e32 v41, v40, v39
	v_fma_f32 v45, v38, s34, -v44
	v_mul_f32_e32 v42, v41, v41
	v_fmac_f32_e32 v45, 0xb102e308, v38
	v_sub_f32_e32 v38, v41, v40
	v_fmamk_f32 v43, v42, 0x3e9b6dac, v184
	v_sub_f32_e32 v38, v39, v38
	v_add_f32_e32 v39, v44, v45
	v_fmaak_f32 v43, v42, v43, 0x3f2aaada
	v_sub_f32_e32 v40, v39, v44
	v_ldexp_f32 v44, v41, 1
	v_mul_f32_e32 v41, v41, v42
	v_mul_f32_e32 v41, v41, v43
	v_add_f32_e32 v42, v44, v41
	v_sub_f32_e32 v43, v42, v44
	v_ldexp_f32 v38, v38, 1
	v_sub_f32_e32 v41, v41, v43
	v_add_f32_e32 v38, v38, v41
	v_add_f32_e32 v41, v42, v38
	v_sub_f32_e32 v42, v41, v42
	v_sub_f32_e32 v38, v38, v42
	v_add_f32_e32 v42, v39, v41
	v_sub_f32_e32 v43, v42, v39
	v_sub_f32_e32 v44, v42, v43
	v_sub_f32_e32 v40, v45, v40
	v_sub_f32_e32 v39, v39, v44
	v_sub_f32_e32 v41, v41, v43
	v_add_f32_e32 v39, v41, v39
	v_add_f32_e32 v41, v40, v38
	v_sub_f32_e32 v43, v41, v40
	v_sub_f32_e32 v44, v41, v43
	v_sub_f32_e32 v40, v40, v44
	v_sub_f32_e32 v38, v38, v43
	v_add_f32_e32 v39, v41, v39
	v_add_f32_e32 v38, v38, v40
	v_add_f32_e32 v40, v42, v39
	v_sub_f32_e32 v41, v40, v42
	v_sub_f32_e32 v39, v39, v41
	v_add_f32_e32 v38, v38, v39
	v_add_f32_e32 v38, v40, v38
	v_cndmask_b32_e32 v38, v185, v38, vcc
	v_cmp_ngt_f32_e32 vcc, -1.0, v21
	s_nop 1
	v_cndmask_b32_e32 v38, v186, v38, vcc
	v_cmp_neq_f32_e32 vcc, -1.0, v21
	s_nop 1
	v_cndmask_b32_e32 v38, v187, v38, vcc
	v_cmp_lt_f32_e64 vcc, |v21|, s36
	s_nop 1
	v_cndmask_b32_e32 v21, v38, v21, vcc
	v_add_f32_e32 v20, v20, v21
	v_sub_f32_e32 v20, -0.5, v20
	v_mul_f32_e32 v20, 0x3fb8aa3b, v20
	v_exp_f32_e32 v20, v20
	s_nop 0
	v_xor_b32_e32 v40, 0x80000000, v20
	v_lshlrev_b64 v[20:21], 12, v[94:95]
	v_lshl_add_u64 v[38:39], v[70:71], 0, v[20:21]
	global_store_dword v[38:39], v40, off
	v_mov_b32_e32 v38, v240
	v_add_f32_e32 v38, v22, v38
	v_max_f32_e64 v22, -v38, 0
	v_mul_f32_e64 v38, |v38|, s30
	v_exp_f32_e32 v38, v38
	s_nop 0
	v_add_f32_e32 v39, 1.0, v38
	v_add_f32_e32 v40, -1.0, v39
	v_sub_f32_e32 v41, v40, v39
	v_add_f32_e32 v41, 1.0, v41
	v_sub_f32_e32 v40, v38, v40
	v_add_f32_e32 v42, v40, v41
	v_frexp_mant_f32_e32 v40, v39
	v_cmp_gt_f32_e32 vcc, s31, v40
	v_cvt_f64_f32_e32 v[40:41], v39
	v_frexp_exp_i32_f64_e32 v40, v[40:41]
	v_subbrev_co_u32_e32 v40, vcc, 0, v40, vcc
	v_sub_u32_e32 v41, 0, v40
	v_ldexp_f32 v39, v39, v41
	v_ldexp_f32 v41, v42, v41
	v_add_f32_e32 v42, -1.0, v39
	v_add_f32_e32 v43, 1.0, v42
	v_sub_f32_e32 v43, v39, v43
	v_add_f32_e32 v43, v41, v43
	v_add_f32_e32 v44, v42, v43
	v_sub_f32_e32 v42, v44, v42
	v_sub_f32_e32 v42, v43, v42
	v_add_f32_e32 v43, 1.0, v39
	v_add_f32_e32 v45, -1.0, v43
	v_sub_f32_e32 v39, v39, v45
	v_add_f32_e32 v39, v41, v39
	v_add_f32_e32 v41, v43, v39
	v_sub_f32_e32 v43, v41, v43
	v_sub_f32_e32 v39, v39, v43
	v_rcp_f32_e32 v43, v41
	v_cvt_f32_i32_e32 v40, v40
	v_cmp_neq_f32_e32 vcc, s35, v38
	v_mul_f32_e32 v45, v44, v43
	v_mul_f32_e32 v46, v41, v45
	v_fma_f32 v47, v45, v41, -v46
	v_fmac_f32_e32 v47, v45, v39
	v_add_f32_e32 v48, v46, v47
	v_sub_f32_e32 v49, v44, v48
	v_sub_f32_e32 v44, v44, v49
	v_sub_f32_e32 v46, v48, v46
	v_sub_f32_e32 v44, v44, v48
	v_add_f32_e32 v42, v42, v44
	v_sub_f32_e32 v44, v46, v47
	v_add_f32_e32 v42, v44, v42
	v_add_f32_e32 v44, v49, v42
	v_mul_f32_e32 v46, v43, v44
	v_mul_f32_e32 v47, v41, v46
	v_fma_f32 v41, v46, v41, -v47
	v_fmac_f32_e32 v41, v46, v39
	v_sub_f32_e32 v39, v49, v44
	v_add_f32_e32 v39, v42, v39
	v_add_f32_e32 v42, v47, v41
	v_sub_f32_e32 v48, v44, v42
	v_sub_f32_e32 v44, v44, v48
	v_sub_f32_e32 v47, v42, v47
	v_sub_f32_e32 v42, v44, v42
	v_add_f32_e32 v39, v39, v42
	v_sub_f32_e32 v41, v47, v41
	v_add_f32_e32 v39, v41, v39
	v_add_f32_e32 v41, v45, v46
	v_add_f32_e32 v39, v48, v39
	v_sub_f32_e32 v42, v41, v45
	v_mul_f32_e32 v39, v43, v39
	v_sub_f32_e32 v42, v46, v42
	v_add_f32_e32 v39, v42, v39
	v_mul_f32_e32 v45, 0x3f317218, v40
	v_add_f32_e32 v42, v41, v39
	v_fma_f32 v46, v40, s34, -v45
	v_mul_f32_e32 v43, v42, v42
	v_fmac_f32_e32 v46, 0xb102e308, v40
	v_sub_f32_e32 v40, v42, v41
	v_fmamk_f32 v44, v43, 0x3e9b6dac, v184
	v_sub_f32_e32 v39, v39, v40
	v_add_f32_e32 v40, v45, v46
	v_fmaak_f32 v44, v43, v44, 0x3f2aaada
	v_sub_f32_e32 v41, v40, v45
	v_ldexp_f32 v45, v42, 1
	v_mul_f32_e32 v42, v42, v43
	v_mul_f32_e32 v42, v42, v44
	v_add_f32_e32 v43, v45, v42
	v_sub_f32_e32 v44, v43, v45
	v_ldexp_f32 v39, v39, 1
	v_sub_f32_e32 v42, v42, v44
	v_add_f32_e32 v39, v39, v42
	v_add_f32_e32 v42, v43, v39
	v_sub_f32_e32 v43, v42, v43
	v_sub_f32_e32 v39, v39, v43
	v_add_f32_e32 v43, v40, v42
	v_sub_f32_e32 v44, v43, v40
	v_sub_f32_e32 v45, v43, v44
	v_sub_f32_e32 v41, v46, v41
	v_sub_f32_e32 v40, v40, v45
	v_sub_f32_e32 v42, v42, v44
	v_add_f32_e32 v40, v42, v40
	v_add_f32_e32 v42, v41, v39
	v_sub_f32_e32 v44, v42, v41
	v_sub_f32_e32 v45, v42, v44
	v_sub_f32_e32 v41, v41, v45
	v_sub_f32_e32 v39, v39, v44
	v_add_f32_e32 v40, v42, v40
	v_add_f32_e32 v39, v39, v41
	v_add_f32_e32 v41, v43, v40
	v_sub_f32_e32 v42, v41, v43
	v_sub_f32_e32 v40, v40, v42
	v_add_f32_e32 v39, v39, v40
	v_add_f32_e32 v39, v41, v39
	v_cndmask_b32_e32 v39, v185, v39, vcc
	v_cmp_ngt_f32_e32 vcc, -1.0, v38
	s_nop 1
	v_cndmask_b32_e32 v39, v186, v39, vcc
	v_cmp_neq_f32_e32 vcc, -1.0, v38
	s_nop 1
	v_cndmask_b32_e32 v39, v187, v39, vcc
	v_cmp_lt_f32_e64 vcc, |v38|, s36
	s_nop 1
	v_cndmask_b32_e32 v38, v39, v38, vcc
	v_add_f32_e32 v22, v22, v38
	v_sub_f32_e32 v22, -0.5, v22
	v_mul_f32_e32 v22, 0x3fb8aa3b, v22
	v_exp_f32_e32 v22, v22
	v_lshlrev_b64 v[38:39], 12, v[92:93]
	v_lshl_add_u64 v[40:41], v[70:71], 0, v[38:39]
	v_xor_b32_e32 v22, 0x80000000, v22
	global_store_dword v[40:41], v22, off
	v_mov_b32_e32 v22, v240
	v_add_f32_e32 v23, v23, v22
	v_max_f32_e64 v22, -v23, 0
	v_mul_f32_e64 v23, |v23|, s30
	v_exp_f32_e32 v23, v23
	s_nop 0
	v_add_f32_e32 v42, 1.0, v23
	v_add_f32_e32 v40, -1.0, v42
	v_sub_f32_e32 v41, v40, v42
	v_add_f32_e32 v41, 1.0, v41
	v_sub_f32_e32 v40, v23, v40
	v_add_f32_e32 v43, v40, v41
	v_frexp_mant_f32_e32 v40, v42
	v_cmp_gt_f32_e32 vcc, s31, v40
	v_cvt_f64_f32_e32 v[40:41], v42
	v_frexp_exp_i32_f64_e32 v40, v[40:41]
	v_subbrev_co_u32_e32 v40, vcc, 0, v40, vcc
	v_sub_u32_e32 v41, 0, v40
	v_ldexp_f32 v42, v42, v41
	v_ldexp_f32 v41, v43, v41
	v_add_f32_e32 v43, -1.0, v42
	v_add_f32_e32 v44, 1.0, v43
	v_sub_f32_e32 v44, v42, v44
	v_add_f32_e32 v44, v41, v44
	v_add_f32_e32 v45, v43, v44
	v_sub_f32_e32 v43, v45, v43
	v_sub_f32_e32 v43, v44, v43
	v_add_f32_e32 v44, 1.0, v42
	v_add_f32_e32 v46, -1.0, v44
	v_sub_f32_e32 v42, v42, v46
	v_add_f32_e32 v41, v41, v42
	v_add_f32_e32 v42, v44, v41
	v_sub_f32_e32 v44, v42, v44
	v_sub_f32_e32 v41, v41, v44
	v_rcp_f32_e32 v44, v42
	v_cvt_f32_i32_e32 v40, v40
	v_cmp_neq_f32_e32 vcc, s35, v23
	v_mul_f32_e32 v46, v45, v44
	v_mul_f32_e32 v47, v42, v46
	v_fma_f32 v48, v46, v42, -v47
	v_fmac_f32_e32 v48, v46, v41
	v_add_f32_e32 v49, v47, v48
	v_sub_f32_e32 v52, v45, v49
	v_sub_f32_e32 v45, v45, v52
	v_sub_f32_e32 v47, v49, v47
	v_sub_f32_e32 v45, v45, v49
	v_add_f32_e32 v43, v43, v45
	v_sub_f32_e32 v45, v47, v48
	v_add_f32_e32 v43, v45, v43
	v_add_f32_e32 v45, v52, v43
	v_mul_f32_e32 v47, v44, v45
	v_mul_f32_e32 v48, v42, v47
	v_fma_f32 v42, v47, v42, -v48
	v_fmac_f32_e32 v42, v47, v41
	v_sub_f32_e32 v41, v52, v45
	v_add_f32_e32 v41, v43, v41
	v_add_f32_e32 v43, v48, v42
	v_sub_f32_e32 v49, v45, v43
	v_sub_f32_e32 v45, v45, v49
	v_sub_f32_e32 v48, v43, v48
	v_sub_f32_e32 v43, v45, v43
	v_add_f32_e32 v41, v41, v43
	v_sub_f32_e32 v42, v48, v42
	v_add_f32_e32 v41, v42, v41
	v_add_f32_e32 v42, v46, v47
	v_add_f32_e32 v41, v49, v41
	v_sub_f32_e32 v43, v42, v46
	v_mul_f32_e32 v41, v44, v41
	v_sub_f32_e32 v43, v47, v43
	v_add_f32_e32 v41, v43, v41
	v_mul_f32_e32 v46, 0x3f317218, v40
	v_add_f32_e32 v43, v42, v41
	v_fma_f32 v47, v40, s34, -v46
	v_mul_f32_e32 v44, v43, v43
	v_fmac_f32_e32 v47, 0xb102e308, v40
	v_sub_f32_e32 v40, v43, v42
	v_fmamk_f32 v45, v44, 0x3e9b6dac, v184
	v_sub_f32_e32 v40, v41, v40
	v_add_f32_e32 v41, v46, v47
	v_fmaak_f32 v45, v44, v45, 0x3f2aaada
	v_sub_f32_e32 v42, v41, v46
	v_ldexp_f32 v46, v43, 1
	v_mul_f32_e32 v43, v43, v44
	v_mul_f32_e32 v43, v43, v45
	v_add_f32_e32 v44, v46, v43
	v_sub_f32_e32 v45, v44, v46
	v_ldexp_f32 v40, v40, 1
	v_sub_f32_e32 v43, v43, v45
	v_add_f32_e32 v40, v40, v43
	v_add_f32_e32 v43, v44, v40
	v_sub_f32_e32 v44, v43, v44
	v_sub_f32_e32 v40, v40, v44
	v_add_f32_e32 v44, v41, v43
	v_sub_f32_e32 v45, v44, v41
	v_sub_f32_e32 v46, v44, v45
	v_sub_f32_e32 v42, v47, v42
	v_sub_f32_e32 v41, v41, v46
	v_sub_f32_e32 v43, v43, v45
	v_add_f32_e32 v41, v43, v41
	v_add_f32_e32 v43, v42, v40
	v_sub_f32_e32 v45, v43, v42
	v_sub_f32_e32 v46, v43, v45
	v_sub_f32_e32 v42, v42, v46
	v_sub_f32_e32 v40, v40, v45
	v_add_f32_e32 v41, v43, v41
	v_add_f32_e32 v40, v40, v42
	v_add_f32_e32 v42, v44, v41
	v_sub_f32_e32 v43, v42, v44
	v_sub_f32_e32 v41, v41, v43
	v_add_f32_e32 v40, v40, v41
	v_add_f32_e32 v40, v42, v40
	v_cndmask_b32_e32 v40, v185, v40, vcc
	v_cmp_ngt_f32_e32 vcc, -1.0, v23
	s_nop 1
	v_cndmask_b32_e32 v40, v186, v40, vcc
	v_cmp_neq_f32_e32 vcc, -1.0, v23
	s_nop 1
	v_cndmask_b32_e32 v40, v187, v40, vcc
	v_cmp_lt_f32_e64 vcc, |v23|, s36
	s_nop 1
	v_cndmask_b32_e32 v23, v40, v23, vcc
	v_add_f32_e32 v22, v22, v23
	v_sub_f32_e32 v22, -0.5, v22
	v_mul_f32_e32 v22, 0x3fb8aa3b, v22
	v_exp_f32_e32 v22, v22
	s_nop 0
	v_xor_b32_e32 v42, 0x80000000, v22
	v_lshlrev_b64 v[22:23], 12, v[90:91]
	v_lshl_add_u64 v[40:41], v[70:71], 0, v[22:23]
	global_store_dword v[40:41], v42, off
	v_mov_b32_e32 v40, v240
	v_add_f32_e32 v40, v24, v40
	v_max_f32_e64 v24, -v40, 0
	v_mul_f32_e64 v40, |v40|, s30
	v_exp_f32_e32 v40, v40
	s_nop 0
	v_add_f32_e32 v41, 1.0, v40
	v_add_f32_e32 v42, -1.0, v41
	v_sub_f32_e32 v43, v42, v41
	v_add_f32_e32 v43, 1.0, v43
	v_sub_f32_e32 v42, v40, v42
	v_add_f32_e32 v44, v42, v43
	v_frexp_mant_f32_e32 v42, v41
	v_cmp_gt_f32_e32 vcc, s31, v42
	v_cvt_f64_f32_e32 v[42:43], v41
	v_frexp_exp_i32_f64_e32 v42, v[42:43]
	v_subbrev_co_u32_e32 v42, vcc, 0, v42, vcc
	v_sub_u32_e32 v43, 0, v42
	v_ldexp_f32 v41, v41, v43
	v_ldexp_f32 v43, v44, v43
	v_add_f32_e32 v44, -1.0, v41
	v_add_f32_e32 v45, 1.0, v44
	v_sub_f32_e32 v45, v41, v45
	v_add_f32_e32 v45, v43, v45
	v_add_f32_e32 v46, v44, v45
	v_sub_f32_e32 v44, v46, v44
	v_sub_f32_e32 v44, v45, v44
	v_add_f32_e32 v45, 1.0, v41
	v_add_f32_e32 v47, -1.0, v45
	v_sub_f32_e32 v41, v41, v47
	v_add_f32_e32 v41, v43, v41
	v_add_f32_e32 v43, v45, v41
	v_sub_f32_e32 v45, v43, v45
	v_sub_f32_e32 v41, v41, v45
	v_rcp_f32_e32 v45, v43
	v_cvt_f32_i32_e32 v42, v42
	v_cmp_neq_f32_e32 vcc, s35, v40
	v_mul_f32_e32 v47, v46, v45
	v_mul_f32_e32 v48, v43, v47
	v_fma_f32 v49, v47, v43, -v48
	v_fmac_f32_e32 v49, v47, v41
	v_add_f32_e32 v52, v48, v49
	v_sub_f32_e32 v53, v46, v52
	v_sub_f32_e32 v46, v46, v53
	v_sub_f32_e32 v48, v52, v48
	v_sub_f32_e32 v46, v46, v52
	v_add_f32_e32 v44, v44, v46
	v_sub_f32_e32 v46, v48, v49
	v_add_f32_e32 v44, v46, v44
	v_add_f32_e32 v46, v53, v44
	v_mul_f32_e32 v48, v45, v46
	v_mul_f32_e32 v49, v43, v48
	v_fma_f32 v43, v48, v43, -v49
	v_fmac_f32_e32 v43, v48, v41
	v_sub_f32_e32 v41, v53, v46
	v_add_f32_e32 v41, v44, v41
	v_add_f32_e32 v44, v49, v43
	v_sub_f32_e32 v52, v46, v44
	v_sub_f32_e32 v46, v46, v52
	v_sub_f32_e32 v49, v44, v49
	v_sub_f32_e32 v44, v46, v44
	v_add_f32_e32 v41, v41, v44
	v_sub_f32_e32 v43, v49, v43
	v_add_f32_e32 v41, v43, v41
	v_add_f32_e32 v43, v47, v48
	v_add_f32_e32 v41, v52, v41
	v_sub_f32_e32 v44, v43, v47
	v_mul_f32_e32 v41, v45, v41
	v_sub_f32_e32 v44, v48, v44
	v_add_f32_e32 v41, v44, v41
	v_mul_f32_e32 v47, 0x3f317218, v42
	v_add_f32_e32 v44, v43, v41
	v_fma_f32 v48, v42, s34, -v47
	v_mul_f32_e32 v45, v44, v44
	v_fmac_f32_e32 v48, 0xb102e308, v42
	v_sub_f32_e32 v42, v44, v43
	v_fmamk_f32 v46, v45, 0x3e9b6dac, v184
	v_sub_f32_e32 v41, v41, v42
	v_add_f32_e32 v42, v47, v48
	v_fmaak_f32 v46, v45, v46, 0x3f2aaada
	v_sub_f32_e32 v43, v42, v47
	v_ldexp_f32 v47, v44, 1
	v_mul_f32_e32 v44, v44, v45
	v_mul_f32_e32 v44, v44, v46
	v_add_f32_e32 v45, v47, v44
	v_sub_f32_e32 v46, v45, v47
	v_ldexp_f32 v41, v41, 1
	v_sub_f32_e32 v44, v44, v46
	v_add_f32_e32 v41, v41, v44
	v_add_f32_e32 v44, v45, v41
	v_sub_f32_e32 v45, v44, v45
	v_sub_f32_e32 v41, v41, v45
	v_add_f32_e32 v45, v42, v44
	v_sub_f32_e32 v46, v45, v42
	v_sub_f32_e32 v47, v45, v46
	v_sub_f32_e32 v43, v48, v43
	v_sub_f32_e32 v42, v42, v47
	v_sub_f32_e32 v44, v44, v46
	v_add_f32_e32 v42, v44, v42
	v_add_f32_e32 v44, v43, v41
	v_sub_f32_e32 v46, v44, v43
	v_sub_f32_e32 v47, v44, v46
	v_sub_f32_e32 v43, v43, v47
	v_sub_f32_e32 v41, v41, v46
	v_add_f32_e32 v42, v44, v42
	v_add_f32_e32 v41, v41, v43
	v_add_f32_e32 v43, v45, v42
	v_sub_f32_e32 v44, v43, v45
	v_sub_f32_e32 v42, v42, v44
	v_add_f32_e32 v41, v41, v42
	v_add_f32_e32 v41, v43, v41
	v_cndmask_b32_e32 v41, v185, v41, vcc
	v_cmp_ngt_f32_e32 vcc, -1.0, v40
	s_nop 1
	v_cndmask_b32_e32 v41, v186, v41, vcc
	v_cmp_neq_f32_e32 vcc, -1.0, v40
	s_nop 1
	v_cndmask_b32_e32 v41, v187, v41, vcc
	v_cmp_lt_f32_e64 vcc, |v40|, s36
	s_nop 1
	v_cndmask_b32_e32 v40, v41, v40, vcc
	v_add_f32_e32 v24, v24, v40
	v_sub_f32_e32 v24, -0.5, v24
	v_mul_f32_e32 v24, 0x3fb8aa3b, v24
	v_exp_f32_e32 v24, v24
	v_lshlrev_b64 v[40:41], 12, v[88:89]
	v_lshl_add_u64 v[42:43], v[70:71], 0, v[40:41]
	v_xor_b32_e32 v24, 0x80000000, v24
	global_store_dword v[42:43], v24, off
	v_mov_b32_e32 v24, v240
	v_add_f32_e32 v25, v25, v24
	v_max_f32_e64 v24, -v25, 0
	v_mul_f32_e64 v25, |v25|, s30
	v_exp_f32_e32 v25, v25
	s_nop 0
	v_add_f32_e32 v44, 1.0, v25
	v_add_f32_e32 v42, -1.0, v44
	v_sub_f32_e32 v43, v42, v44
	v_add_f32_e32 v43, 1.0, v43
	v_sub_f32_e32 v42, v25, v42
	v_add_f32_e32 v45, v42, v43
	v_frexp_mant_f32_e32 v42, v44
	v_cmp_gt_f32_e32 vcc, s31, v42
	v_cvt_f64_f32_e32 v[42:43], v44
	v_frexp_exp_i32_f64_e32 v42, v[42:43]
	v_subbrev_co_u32_e32 v42, vcc, 0, v42, vcc
	v_sub_u32_e32 v43, 0, v42
	v_ldexp_f32 v44, v44, v43
	v_ldexp_f32 v43, v45, v43
	v_add_f32_e32 v45, -1.0, v44
	v_add_f32_e32 v46, 1.0, v45
	v_sub_f32_e32 v46, v44, v46
	v_add_f32_e32 v46, v43, v46
	v_add_f32_e32 v47, v45, v46
	v_sub_f32_e32 v45, v47, v45
	v_sub_f32_e32 v45, v46, v45
	v_add_f32_e32 v46, 1.0, v44
	v_add_f32_e32 v48, -1.0, v46
	v_sub_f32_e32 v44, v44, v48
	v_add_f32_e32 v43, v43, v44
	v_add_f32_e32 v44, v46, v43
	v_sub_f32_e32 v46, v44, v46
	v_sub_f32_e32 v43, v43, v46
	v_rcp_f32_e32 v46, v44
	v_cvt_f32_i32_e32 v42, v42
	v_cmp_neq_f32_e32 vcc, s35, v25
	v_mul_f32_e32 v48, v47, v46
	v_mul_f32_e32 v49, v44, v48
	v_fma_f32 v52, v48, v44, -v49
	v_fmac_f32_e32 v52, v48, v43
	v_add_f32_e32 v53, v49, v52
	v_sub_f32_e32 v54, v47, v53
	v_sub_f32_e32 v47, v47, v54
	v_sub_f32_e32 v49, v53, v49
	v_sub_f32_e32 v47, v47, v53
	v_add_f32_e32 v45, v45, v47
	v_sub_f32_e32 v47, v49, v52
	v_add_f32_e32 v45, v47, v45
	v_add_f32_e32 v47, v54, v45
	v_mul_f32_e32 v49, v46, v47
	v_mul_f32_e32 v52, v44, v49
	v_fma_f32 v44, v49, v44, -v52
	v_fmac_f32_e32 v44, v49, v43
	v_sub_f32_e32 v43, v54, v47
	v_add_f32_e32 v43, v45, v43
	v_add_f32_e32 v45, v52, v44
	v_sub_f32_e32 v53, v47, v45
	v_sub_f32_e32 v47, v47, v53
	v_sub_f32_e32 v52, v45, v52
	v_sub_f32_e32 v45, v47, v45
	v_add_f32_e32 v43, v43, v45
	v_sub_f32_e32 v44, v52, v44
	v_add_f32_e32 v43, v44, v43
	v_add_f32_e32 v44, v48, v49
	v_add_f32_e32 v43, v53, v43
	v_sub_f32_e32 v45, v44, v48
	v_mul_f32_e32 v43, v46, v43
	v_sub_f32_e32 v45, v49, v45
	v_add_f32_e32 v43, v45, v43
	v_mul_f32_e32 v48, 0x3f317218, v42
	v_add_f32_e32 v45, v44, v43
	v_fma_f32 v49, v42, s34, -v48
	v_mul_f32_e32 v46, v45, v45
	v_fmac_f32_e32 v49, 0xb102e308, v42
	v_sub_f32_e32 v42, v45, v44
	v_fmamk_f32 v47, v46, 0x3e9b6dac, v184
	v_sub_f32_e32 v42, v43, v42
	v_add_f32_e32 v43, v48, v49
	v_fmaak_f32 v47, v46, v47, 0x3f2aaada
	v_sub_f32_e32 v44, v43, v48
	v_ldexp_f32 v48, v45, 1
	v_mul_f32_e32 v45, v45, v46
	v_mul_f32_e32 v45, v45, v47
	v_add_f32_e32 v46, v48, v45
	v_sub_f32_e32 v47, v46, v48
	v_ldexp_f32 v42, v42, 1
	v_sub_f32_e32 v45, v45, v47
	v_add_f32_e32 v42, v42, v45
	v_add_f32_e32 v45, v46, v42
	v_sub_f32_e32 v46, v45, v46
	v_sub_f32_e32 v42, v42, v46
	v_add_f32_e32 v46, v43, v45
	v_sub_f32_e32 v47, v46, v43
	v_sub_f32_e32 v48, v46, v47
	v_sub_f32_e32 v44, v49, v44
	v_sub_f32_e32 v43, v43, v48
	v_sub_f32_e32 v45, v45, v47
	v_add_f32_e32 v43, v45, v43
	v_add_f32_e32 v45, v44, v42
	v_sub_f32_e32 v47, v45, v44
	v_sub_f32_e32 v48, v45, v47
	v_sub_f32_e32 v44, v44, v48
	v_sub_f32_e32 v42, v42, v47
	v_add_f32_e32 v43, v45, v43
	v_add_f32_e32 v42, v42, v44
	v_add_f32_e32 v44, v46, v43
	v_sub_f32_e32 v45, v44, v46
	v_sub_f32_e32 v43, v43, v45
	v_add_f32_e32 v42, v42, v43
	v_add_f32_e32 v42, v44, v42
	v_cndmask_b32_e32 v42, v185, v42, vcc
	v_cmp_ngt_f32_e32 vcc, -1.0, v25
	s_nop 1
	v_cndmask_b32_e32 v42, v186, v42, vcc
	v_cmp_neq_f32_e32 vcc, -1.0, v25
	s_nop 1
	v_cndmask_b32_e32 v42, v187, v42, vcc
	v_cmp_lt_f32_e64 vcc, |v25|, s36
	s_nop 1
	v_cndmask_b32_e32 v25, v42, v25, vcc
	v_add_f32_e32 v24, v24, v25
	v_sub_f32_e32 v24, -0.5, v24
	v_mul_f32_e32 v24, 0x3fb8aa3b, v24
	v_exp_f32_e32 v24, v24
	s_nop 0
	v_xor_b32_e32 v44, 0x80000000, v24
	v_lshlrev_b64 v[24:25], 12, v[86:87]
	v_lshl_add_u64 v[42:43], v[70:71], 0, v[24:25]
	global_store_dword v[42:43], v44, off
	v_mov_b32_e32 v42, v240
	v_add_f32_e32 v42, v26, v42
	v_max_f32_e64 v26, -v42, 0
	v_mul_f32_e64 v42, |v42|, s30
	v_exp_f32_e32 v42, v42
	s_nop 0
	v_add_f32_e32 v43, 1.0, v42
	v_add_f32_e32 v44, -1.0, v43
	v_sub_f32_e32 v45, v44, v43
	v_add_f32_e32 v45, 1.0, v45
	v_sub_f32_e32 v44, v42, v44
	v_add_f32_e32 v46, v44, v45
	v_frexp_mant_f32_e32 v44, v43
	v_cmp_gt_f32_e32 vcc, s31, v44
	v_cvt_f64_f32_e32 v[44:45], v43
	v_frexp_exp_i32_f64_e32 v44, v[44:45]
	v_subbrev_co_u32_e32 v44, vcc, 0, v44, vcc
	v_sub_u32_e32 v45, 0, v44
	v_ldexp_f32 v43, v43, v45
	v_ldexp_f32 v45, v46, v45
	v_add_f32_e32 v46, -1.0, v43
	v_add_f32_e32 v47, 1.0, v46
	v_sub_f32_e32 v47, v43, v47
	v_add_f32_e32 v47, v45, v47
	v_add_f32_e32 v48, v46, v47
	v_sub_f32_e32 v46, v48, v46
	v_sub_f32_e32 v46, v47, v46
	v_add_f32_e32 v47, 1.0, v43
	v_add_f32_e32 v49, -1.0, v47
	v_sub_f32_e32 v43, v43, v49
	v_add_f32_e32 v43, v45, v43
	v_add_f32_e32 v45, v47, v43
	v_sub_f32_e32 v47, v45, v47
	v_sub_f32_e32 v43, v43, v47
	v_rcp_f32_e32 v47, v45
	v_cvt_f32_i32_e32 v44, v44
	v_cmp_neq_f32_e32 vcc, s35, v42
	v_mul_f32_e32 v49, v48, v47
	v_mul_f32_e32 v52, v45, v49
	v_fma_f32 v53, v49, v45, -v52
	v_fmac_f32_e32 v53, v49, v43
	v_add_f32_e32 v54, v52, v53
	v_sub_f32_e32 v55, v48, v54
	v_sub_f32_e32 v48, v48, v55
	v_sub_f32_e32 v52, v54, v52
	v_sub_f32_e32 v48, v48, v54
	v_add_f32_e32 v46, v46, v48
	v_sub_f32_e32 v48, v52, v53
	v_add_f32_e32 v46, v48, v46
	v_add_f32_e32 v48, v55, v46
	v_mul_f32_e32 v52, v47, v48
	v_mul_f32_e32 v53, v45, v52
	v_fma_f32 v45, v52, v45, -v53
	v_fmac_f32_e32 v45, v52, v43
	v_sub_f32_e32 v43, v55, v48
	v_add_f32_e32 v43, v46, v43
	v_add_f32_e32 v46, v53, v45
	v_sub_f32_e32 v54, v48, v46
	v_sub_f32_e32 v48, v48, v54
	v_sub_f32_e32 v53, v46, v53
	v_sub_f32_e32 v46, v48, v46
	v_add_f32_e32 v43, v43, v46
	v_sub_f32_e32 v45, v53, v45
	v_add_f32_e32 v43, v45, v43
	v_add_f32_e32 v45, v49, v52
	v_add_f32_e32 v43, v54, v43
	v_sub_f32_e32 v46, v45, v49
	v_mul_f32_e32 v43, v47, v43
	v_sub_f32_e32 v46, v52, v46
	v_add_f32_e32 v43, v46, v43
	v_mul_f32_e32 v49, 0x3f317218, v44
	v_add_f32_e32 v46, v45, v43
	v_fma_f32 v52, v44, s34, -v49
	v_mul_f32_e32 v47, v46, v46
	v_fmac_f32_e32 v52, 0xb102e308, v44
	v_sub_f32_e32 v44, v46, v45
	v_fmamk_f32 v48, v47, 0x3e9b6dac, v184
	v_sub_f32_e32 v43, v43, v44
	v_add_f32_e32 v44, v49, v52
	v_fmaak_f32 v48, v47, v48, 0x3f2aaada
	v_sub_f32_e32 v45, v44, v49
	v_ldexp_f32 v49, v46, 1
	v_mul_f32_e32 v46, v46, v47
	v_mul_f32_e32 v46, v46, v48
	v_add_f32_e32 v47, v49, v46
	v_sub_f32_e32 v48, v47, v49
	v_ldexp_f32 v43, v43, 1
	v_sub_f32_e32 v46, v46, v48
	v_add_f32_e32 v43, v43, v46
	v_add_f32_e32 v46, v47, v43
	v_sub_f32_e32 v47, v46, v47
	v_sub_f32_e32 v43, v43, v47
	v_add_f32_e32 v47, v44, v46
	v_sub_f32_e32 v48, v47, v44
	v_sub_f32_e32 v49, v47, v48
	v_sub_f32_e32 v45, v52, v45
	v_sub_f32_e32 v44, v44, v49
	v_sub_f32_e32 v46, v46, v48
	v_add_f32_e32 v44, v46, v44
	v_add_f32_e32 v46, v45, v43
	v_sub_f32_e32 v48, v46, v45
	v_sub_f32_e32 v49, v46, v48
	v_sub_f32_e32 v45, v45, v49
	v_sub_f32_e32 v43, v43, v48
	v_add_f32_e32 v44, v46, v44
	v_add_f32_e32 v43, v43, v45
	v_add_f32_e32 v45, v47, v44
	v_sub_f32_e32 v46, v45, v47
	v_sub_f32_e32 v44, v44, v46
	v_add_f32_e32 v43, v43, v44
	v_add_f32_e32 v43, v45, v43
	v_cndmask_b32_e32 v43, v185, v43, vcc
	v_cmp_ngt_f32_e32 vcc, -1.0, v42
	s_nop 1
	v_cndmask_b32_e32 v43, v186, v43, vcc
	v_cmp_neq_f32_e32 vcc, -1.0, v42
	s_nop 1
	v_cndmask_b32_e32 v43, v187, v43, vcc
	v_cmp_lt_f32_e64 vcc, |v42|, s36
	s_nop 1
	v_cndmask_b32_e32 v42, v43, v42, vcc
	v_add_f32_e32 v26, v26, v42
	v_sub_f32_e32 v26, -0.5, v26
	v_mul_f32_e32 v26, 0x3fb8aa3b, v26
	v_exp_f32_e32 v26, v26
	v_lshlrev_b64 v[42:43], 12, v[84:85]
	v_lshl_add_u64 v[44:45], v[70:71], 0, v[42:43]
	v_xor_b32_e32 v26, 0x80000000, v26
	global_store_dword v[44:45], v26, off
	v_mov_b32_e32 v26, v240
	v_add_f32_e32 v27, v27, v26
	v_max_f32_e64 v26, -v27, 0
	v_mul_f32_e64 v27, |v27|, s30
	v_exp_f32_e32 v27, v27
	s_nop 0
	v_add_f32_e32 v46, 1.0, v27
	v_add_f32_e32 v44, -1.0, v46
	v_sub_f32_e32 v45, v44, v46
	v_add_f32_e32 v45, 1.0, v45
	v_sub_f32_e32 v44, v27, v44
	v_add_f32_e32 v47, v44, v45
	v_frexp_mant_f32_e32 v44, v46
	v_cmp_gt_f32_e32 vcc, s31, v44
	v_cvt_f64_f32_e32 v[44:45], v46
	v_frexp_exp_i32_f64_e32 v44, v[44:45]
	v_subbrev_co_u32_e32 v44, vcc, 0, v44, vcc
	v_sub_u32_e32 v45, 0, v44
	v_ldexp_f32 v46, v46, v45
	v_ldexp_f32 v45, v47, v45
	v_add_f32_e32 v47, -1.0, v46
	v_add_f32_e32 v48, 1.0, v47
	v_sub_f32_e32 v48, v46, v48
	v_add_f32_e32 v48, v45, v48
	v_add_f32_e32 v49, v47, v48
	v_sub_f32_e32 v47, v49, v47
	v_sub_f32_e32 v47, v48, v47
	v_add_f32_e32 v48, 1.0, v46
	v_add_f32_e32 v52, -1.0, v48
	v_sub_f32_e32 v46, v46, v52
	v_add_f32_e32 v45, v45, v46
	v_add_f32_e32 v46, v48, v45
	v_sub_f32_e32 v48, v46, v48
	v_sub_f32_e32 v45, v45, v48
	v_rcp_f32_e32 v48, v46
	v_cvt_f32_i32_e32 v44, v44
	v_cmp_neq_f32_e32 vcc, s35, v27
	v_mul_f32_e32 v52, v49, v48
	v_mul_f32_e32 v53, v46, v52
	v_fma_f32 v54, v52, v46, -v53
	v_fmac_f32_e32 v54, v52, v45
	v_add_f32_e32 v55, v53, v54
	v_sub_f32_e32 v56, v49, v55
	v_sub_f32_e32 v49, v49, v56
	v_sub_f32_e32 v53, v55, v53
	v_sub_f32_e32 v49, v49, v55
	v_add_f32_e32 v47, v47, v49
	v_sub_f32_e32 v49, v53, v54
	v_add_f32_e32 v47, v49, v47
	v_add_f32_e32 v49, v56, v47
	v_mul_f32_e32 v53, v48, v49
	v_mul_f32_e32 v54, v46, v53
	v_fma_f32 v46, v53, v46, -v54
	v_fmac_f32_e32 v46, v53, v45
	v_sub_f32_e32 v45, v56, v49
	v_add_f32_e32 v45, v47, v45
	v_add_f32_e32 v47, v54, v46
	v_sub_f32_e32 v55, v49, v47
	v_sub_f32_e32 v49, v49, v55
	v_sub_f32_e32 v54, v47, v54
	v_sub_f32_e32 v47, v49, v47
	v_add_f32_e32 v45, v45, v47
	v_sub_f32_e32 v46, v54, v46
	v_add_f32_e32 v45, v46, v45
	v_add_f32_e32 v46, v52, v53
	v_add_f32_e32 v45, v55, v45
	v_sub_f32_e32 v47, v46, v52
	v_mul_f32_e32 v45, v48, v45
	v_sub_f32_e32 v47, v53, v47
	v_add_f32_e32 v45, v47, v45
	v_mul_f32_e32 v52, 0x3f317218, v44
	v_add_f32_e32 v47, v46, v45
	v_fma_f32 v53, v44, s34, -v52
	v_mul_f32_e32 v48, v47, v47
	v_fmac_f32_e32 v53, 0xb102e308, v44
	v_sub_f32_e32 v44, v47, v46
	v_fmamk_f32 v49, v48, 0x3e9b6dac, v184
	v_sub_f32_e32 v44, v45, v44
	v_add_f32_e32 v45, v52, v53
	v_fmaak_f32 v49, v48, v49, 0x3f2aaada
	v_sub_f32_e32 v46, v45, v52
	v_ldexp_f32 v52, v47, 1
	v_mul_f32_e32 v47, v47, v48
	v_mul_f32_e32 v47, v47, v49
	v_add_f32_e32 v48, v52, v47
	v_sub_f32_e32 v49, v48, v52
	v_ldexp_f32 v44, v44, 1
	v_sub_f32_e32 v47, v47, v49
	v_add_f32_e32 v44, v44, v47
	v_add_f32_e32 v47, v48, v44
	v_sub_f32_e32 v48, v47, v48
	v_sub_f32_e32 v44, v44, v48
	v_add_f32_e32 v48, v45, v47
	v_sub_f32_e32 v49, v48, v45
	v_sub_f32_e32 v52, v48, v49
	v_sub_f32_e32 v46, v53, v46
	v_sub_f32_e32 v45, v45, v52
	v_sub_f32_e32 v47, v47, v49
	v_add_f32_e32 v45, v47, v45
	v_add_f32_e32 v47, v46, v44
	v_sub_f32_e32 v49, v47, v46
	v_sub_f32_e32 v52, v47, v49
	v_sub_f32_e32 v46, v46, v52
	v_sub_f32_e32 v44, v44, v49
	v_add_f32_e32 v45, v47, v45
	v_add_f32_e32 v44, v44, v46
	v_add_f32_e32 v46, v48, v45
	v_sub_f32_e32 v47, v46, v48
	v_sub_f32_e32 v45, v45, v47
	v_add_f32_e32 v44, v44, v45
	v_add_f32_e32 v44, v46, v44
	v_cndmask_b32_e32 v44, v185, v44, vcc
	v_cmp_ngt_f32_e32 vcc, -1.0, v27
	s_nop 1
	v_cndmask_b32_e32 v44, v186, v44, vcc
	v_cmp_neq_f32_e32 vcc, -1.0, v27
	s_nop 1
	v_cndmask_b32_e32 v44, v187, v44, vcc
	v_cmp_lt_f32_e64 vcc, |v27|, s36
	s_nop 1
	v_cndmask_b32_e32 v27, v44, v27, vcc
	v_add_f32_e32 v26, v26, v27
	v_sub_f32_e32 v26, -0.5, v26
	v_mul_f32_e32 v26, 0x3fb8aa3b, v26
	v_exp_f32_e32 v26, v26
	s_nop 0
	v_xor_b32_e32 v46, 0x80000000, v26
	v_lshlrev_b64 v[26:27], 12, v[82:83]
	v_lshl_add_u64 v[44:45], v[70:71], 0, v[26:27]
	global_store_dword v[44:45], v46, off
	v_mov_b32_e32 v44, v240
	v_add_f32_e32 v44, v28, v44
	v_max_f32_e64 v28, -v44, 0
	v_mul_f32_e64 v44, |v44|, s30
	v_exp_f32_e32 v44, v44
	s_nop 0
	v_add_f32_e32 v45, 1.0, v44
	v_add_f32_e32 v46, -1.0, v45
	v_sub_f32_e32 v47, v46, v45
	v_add_f32_e32 v47, 1.0, v47
	v_sub_f32_e32 v46, v44, v46
	v_add_f32_e32 v48, v46, v47
	v_frexp_mant_f32_e32 v46, v45
	v_cmp_gt_f32_e32 vcc, s31, v46
	v_cvt_f64_f32_e32 v[46:47], v45
	v_frexp_exp_i32_f64_e32 v46, v[46:47]
	v_subbrev_co_u32_e32 v46, vcc, 0, v46, vcc
	v_sub_u32_e32 v47, 0, v46
	v_ldexp_f32 v45, v45, v47
	v_ldexp_f32 v47, v48, v47
	v_add_f32_e32 v48, -1.0, v45
	v_add_f32_e32 v49, 1.0, v48
	v_sub_f32_e32 v49, v45, v49
	v_add_f32_e32 v49, v47, v49
	v_add_f32_e32 v52, v48, v49
	v_sub_f32_e32 v48, v52, v48
	v_sub_f32_e32 v48, v49, v48
	v_add_f32_e32 v49, 1.0, v45
	v_add_f32_e32 v53, -1.0, v49
	v_sub_f32_e32 v45, v45, v53
	v_add_f32_e32 v45, v47, v45
	v_add_f32_e32 v47, v49, v45
	v_sub_f32_e32 v49, v47, v49
	v_sub_f32_e32 v45, v45, v49
	v_rcp_f32_e32 v49, v47
	v_cvt_f32_i32_e32 v46, v46
	v_cmp_neq_f32_e32 vcc, s35, v44
	v_mul_f32_e32 v53, v52, v49
	v_mul_f32_e32 v54, v47, v53
	v_fma_f32 v55, v53, v47, -v54
	v_fmac_f32_e32 v55, v53, v45
	v_add_f32_e32 v56, v54, v55
	v_sub_f32_e32 v57, v52, v56
	v_sub_f32_e32 v52, v52, v57
	v_sub_f32_e32 v54, v56, v54
	v_sub_f32_e32 v52, v52, v56
	v_add_f32_e32 v48, v48, v52
	v_sub_f32_e32 v52, v54, v55
	v_add_f32_e32 v48, v52, v48
	v_add_f32_e32 v52, v57, v48
	v_mul_f32_e32 v54, v49, v52
	v_mul_f32_e32 v55, v47, v54
	v_fma_f32 v47, v54, v47, -v55
	v_fmac_f32_e32 v47, v54, v45
	v_sub_f32_e32 v45, v57, v52
	v_add_f32_e32 v45, v48, v45
	v_add_f32_e32 v48, v55, v47
	v_sub_f32_e32 v56, v52, v48
	v_sub_f32_e32 v52, v52, v56
	v_sub_f32_e32 v55, v48, v55
	v_sub_f32_e32 v48, v52, v48
	v_add_f32_e32 v45, v45, v48
	v_sub_f32_e32 v47, v55, v47
	v_add_f32_e32 v45, v47, v45
	v_add_f32_e32 v47, v53, v54
	v_add_f32_e32 v45, v56, v45
	v_sub_f32_e32 v48, v47, v53
	v_mul_f32_e32 v45, v49, v45
	v_sub_f32_e32 v48, v54, v48
	v_add_f32_e32 v45, v48, v45
	v_mul_f32_e32 v53, 0x3f317218, v46
	v_add_f32_e32 v48, v47, v45
	v_fma_f32 v54, v46, s34, -v53
	v_mul_f32_e32 v49, v48, v48
	v_fmac_f32_e32 v54, 0xb102e308, v46
	v_sub_f32_e32 v46, v48, v47
	v_fmamk_f32 v52, v49, 0x3e9b6dac, v184
	v_sub_f32_e32 v45, v45, v46
	v_add_f32_e32 v46, v53, v54
	v_fmaak_f32 v52, v49, v52, 0x3f2aaada
	v_sub_f32_e32 v47, v46, v53
	v_ldexp_f32 v53, v48, 1
	v_mul_f32_e32 v48, v48, v49
	v_mul_f32_e32 v48, v48, v52
	v_add_f32_e32 v49, v53, v48
	v_sub_f32_e32 v52, v49, v53
	v_ldexp_f32 v45, v45, 1
	v_sub_f32_e32 v48, v48, v52
	v_add_f32_e32 v45, v45, v48
	v_add_f32_e32 v48, v49, v45
	v_sub_f32_e32 v49, v48, v49
	v_sub_f32_e32 v45, v45, v49
	v_add_f32_e32 v49, v46, v48
	v_sub_f32_e32 v52, v49, v46
	v_sub_f32_e32 v53, v49, v52
	v_sub_f32_e32 v47, v54, v47
	v_sub_f32_e32 v46, v46, v53
	v_sub_f32_e32 v48, v48, v52
	v_add_f32_e32 v46, v48, v46
	v_add_f32_e32 v48, v47, v45
	v_sub_f32_e32 v52, v48, v47
	v_sub_f32_e32 v53, v48, v52
	v_sub_f32_e32 v47, v47, v53
	v_sub_f32_e32 v45, v45, v52
	v_add_f32_e32 v46, v48, v46
	v_add_f32_e32 v45, v45, v47
	v_add_f32_e32 v47, v49, v46
	v_sub_f32_e32 v48, v47, v49
	v_sub_f32_e32 v46, v46, v48
	v_add_f32_e32 v45, v45, v46
	v_add_f32_e32 v45, v47, v45
	v_cndmask_b32_e32 v45, v185, v45, vcc
	v_cmp_ngt_f32_e32 vcc, -1.0, v44
	s_nop 1
	v_cndmask_b32_e32 v45, v186, v45, vcc
	v_cmp_neq_f32_e32 vcc, -1.0, v44
	s_nop 1
	v_cndmask_b32_e32 v45, v187, v45, vcc
	v_cmp_lt_f32_e64 vcc, |v44|, s36
	s_nop 1
	v_cndmask_b32_e32 v44, v45, v44, vcc
	v_add_f32_e32 v28, v28, v44
	v_sub_f32_e32 v28, -0.5, v28
	v_mul_f32_e32 v28, 0x3fb8aa3b, v28
	v_exp_f32_e32 v28, v28
	v_lshlrev_b64 v[44:45], 12, v[80:81]
	v_lshl_add_u64 v[46:47], v[70:71], 0, v[44:45]
	v_xor_b32_e32 v28, 0x80000000, v28
	global_store_dword v[46:47], v28, off
	v_mov_b32_e32 v28, v240
	v_add_f32_e32 v29, v29, v28
	v_max_f32_e64 v28, -v29, 0
	v_mul_f32_e64 v29, |v29|, s30
	v_exp_f32_e32 v29, v29
	s_nop 0
	v_add_f32_e32 v48, 1.0, v29
	v_add_f32_e32 v46, -1.0, v48
	v_sub_f32_e32 v47, v46, v48
	v_add_f32_e32 v47, 1.0, v47
	v_sub_f32_e32 v46, v29, v46
	v_add_f32_e32 v49, v46, v47
	v_frexp_mant_f32_e32 v46, v48
	v_cmp_gt_f32_e32 vcc, s31, v46
	v_cvt_f64_f32_e32 v[46:47], v48
	v_frexp_exp_i32_f64_e32 v46, v[46:47]
	v_subbrev_co_u32_e32 v46, vcc, 0, v46, vcc
	v_sub_u32_e32 v47, 0, v46
	v_ldexp_f32 v48, v48, v47
	v_ldexp_f32 v47, v49, v47
	v_add_f32_e32 v49, -1.0, v48
	v_add_f32_e32 v52, 1.0, v49
	v_sub_f32_e32 v52, v48, v52
	v_add_f32_e32 v52, v47, v52
	v_add_f32_e32 v53, v49, v52
	v_sub_f32_e32 v49, v53, v49
	v_sub_f32_e32 v49, v52, v49
	v_add_f32_e32 v52, 1.0, v48
	v_add_f32_e32 v54, -1.0, v52
	v_sub_f32_e32 v48, v48, v54
	v_add_f32_e32 v47, v47, v48
	v_add_f32_e32 v48, v52, v47
	v_sub_f32_e32 v52, v48, v52
	v_sub_f32_e32 v47, v47, v52
	v_rcp_f32_e32 v52, v48
	v_cvt_f32_i32_e32 v46, v46
	v_cmp_neq_f32_e32 vcc, s35, v29
	v_mul_f32_e32 v54, v53, v52
	v_mul_f32_e32 v55, v48, v54
	v_fma_f32 v56, v54, v48, -v55
	v_fmac_f32_e32 v56, v54, v47
	v_add_f32_e32 v57, v55, v56
	v_sub_f32_e32 v58, v53, v57
	v_sub_f32_e32 v53, v53, v58
	v_sub_f32_e32 v55, v57, v55
	v_sub_f32_e32 v53, v53, v57
	v_add_f32_e32 v49, v49, v53
	v_sub_f32_e32 v53, v55, v56
	v_add_f32_e32 v49, v53, v49
	v_add_f32_e32 v53, v58, v49
	v_mul_f32_e32 v55, v52, v53
	v_mul_f32_e32 v56, v48, v55
	v_fma_f32 v48, v55, v48, -v56
	v_fmac_f32_e32 v48, v55, v47
	v_sub_f32_e32 v47, v58, v53
	v_add_f32_e32 v47, v49, v47
	v_add_f32_e32 v49, v56, v48
	v_sub_f32_e32 v57, v53, v49
	v_sub_f32_e32 v53, v53, v57
	v_sub_f32_e32 v56, v49, v56
	v_sub_f32_e32 v49, v53, v49
	v_add_f32_e32 v47, v47, v49
	v_sub_f32_e32 v48, v56, v48
	v_add_f32_e32 v47, v48, v47
	v_add_f32_e32 v48, v54, v55
	v_add_f32_e32 v47, v57, v47
	v_sub_f32_e32 v49, v48, v54
	v_mul_f32_e32 v47, v52, v47
	v_sub_f32_e32 v49, v55, v49
	v_add_f32_e32 v47, v49, v47
	v_mul_f32_e32 v54, 0x3f317218, v46
	v_add_f32_e32 v49, v48, v47
	v_fma_f32 v55, v46, s34, -v54
	v_mul_f32_e32 v52, v49, v49
	v_fmac_f32_e32 v55, 0xb102e308, v46
	v_sub_f32_e32 v46, v49, v48
	v_fmamk_f32 v53, v52, 0x3e9b6dac, v184
	v_sub_f32_e32 v46, v47, v46
	v_add_f32_e32 v47, v54, v55
	v_fmaak_f32 v53, v52, v53, 0x3f2aaada
	v_sub_f32_e32 v48, v47, v54
	v_ldexp_f32 v54, v49, 1
	v_mul_f32_e32 v49, v49, v52
	v_mul_f32_e32 v49, v49, v53
	v_add_f32_e32 v52, v54, v49
	v_sub_f32_e32 v53, v52, v54
	v_ldexp_f32 v46, v46, 1
	v_sub_f32_e32 v49, v49, v53
	v_add_f32_e32 v46, v46, v49
	v_add_f32_e32 v49, v52, v46
	v_sub_f32_e32 v52, v49, v52
	v_sub_f32_e32 v46, v46, v52
	v_add_f32_e32 v52, v47, v49
	v_sub_f32_e32 v53, v52, v47
	v_sub_f32_e32 v54, v52, v53
	v_sub_f32_e32 v48, v55, v48
	v_sub_f32_e32 v47, v47, v54
	v_sub_f32_e32 v49, v49, v53
	v_add_f32_e32 v47, v49, v47
	v_add_f32_e32 v49, v48, v46
	v_sub_f32_e32 v53, v49, v48
	v_sub_f32_e32 v54, v49, v53
	v_sub_f32_e32 v48, v48, v54
	v_sub_f32_e32 v46, v46, v53
	v_add_f32_e32 v47, v49, v47
	v_add_f32_e32 v46, v46, v48
	v_add_f32_e32 v48, v52, v47
	v_sub_f32_e32 v49, v48, v52
	v_sub_f32_e32 v47, v47, v49
	v_add_f32_e32 v46, v46, v47
	v_add_f32_e32 v46, v48, v46
	v_cndmask_b32_e32 v46, v185, v46, vcc
	v_cmp_ngt_f32_e32 vcc, -1.0, v29
	s_nop 1
	v_cndmask_b32_e32 v46, v186, v46, vcc
	v_cmp_neq_f32_e32 vcc, -1.0, v29
	s_nop 1
	v_cndmask_b32_e32 v46, v187, v46, vcc
	v_cmp_lt_f32_e64 vcc, |v29|, s36
	s_nop 1
	v_cndmask_b32_e32 v29, v46, v29, vcc
	v_add_f32_e32 v28, v28, v29
	v_sub_f32_e32 v28, -0.5, v28
	v_mul_f32_e32 v28, 0x3fb8aa3b, v28
	v_exp_f32_e32 v28, v28
	s_nop 0
	v_xor_b32_e32 v48, 0x80000000, v28
	v_lshlrev_b64 v[28:29], 12, v[78:79]
	v_lshl_add_u64 v[46:47], v[70:71], 0, v[28:29]
	global_store_dword v[46:47], v48, off
	v_mov_b32_e32 v46, v240
	v_add_f32_e32 v46, v30, v46
	v_max_f32_e64 v30, -v46, 0
	v_mul_f32_e64 v46, |v46|, s30
	v_exp_f32_e32 v46, v46
	s_nop 0
	v_add_f32_e32 v47, 1.0, v46
	v_add_f32_e32 v48, -1.0, v47
	v_sub_f32_e32 v49, v48, v47
	v_add_f32_e32 v49, 1.0, v49
	v_sub_f32_e32 v48, v46, v48
	v_add_f32_e32 v52, v48, v49
	v_frexp_mant_f32_e32 v48, v47
	v_cmp_gt_f32_e32 vcc, s31, v48
	v_cvt_f64_f32_e32 v[48:49], v47
	v_frexp_exp_i32_f64_e32 v48, v[48:49]
	v_subbrev_co_u32_e32 v48, vcc, 0, v48, vcc
	v_sub_u32_e32 v49, 0, v48
	v_ldexp_f32 v47, v47, v49
	v_ldexp_f32 v49, v52, v49
	v_add_f32_e32 v52, -1.0, v47
	v_add_f32_e32 v53, 1.0, v52
	v_sub_f32_e32 v53, v47, v53
	v_add_f32_e32 v53, v49, v53
	v_add_f32_e32 v54, v52, v53
	v_sub_f32_e32 v52, v54, v52
	v_sub_f32_e32 v52, v53, v52
	v_add_f32_e32 v53, 1.0, v47
	v_add_f32_e32 v55, -1.0, v53
	v_sub_f32_e32 v47, v47, v55
	v_add_f32_e32 v47, v49, v47
	v_add_f32_e32 v49, v53, v47
	v_sub_f32_e32 v53, v49, v53
	v_sub_f32_e32 v47, v47, v53
	v_rcp_f32_e32 v53, v49
	v_cvt_f32_i32_e32 v48, v48
	v_cmp_neq_f32_e32 vcc, s35, v46
	v_mul_f32_e32 v55, v54, v53
	v_mul_f32_e32 v56, v49, v55
	v_fma_f32 v57, v55, v49, -v56
	v_fmac_f32_e32 v57, v55, v47
	v_add_f32_e32 v58, v56, v57
	v_sub_f32_e32 v59, v54, v58
	v_sub_f32_e32 v54, v54, v59
	v_sub_f32_e32 v56, v58, v56
	v_sub_f32_e32 v54, v54, v58
	v_add_f32_e32 v52, v52, v54
	v_sub_f32_e32 v54, v56, v57
	v_add_f32_e32 v52, v54, v52
	v_add_f32_e32 v54, v59, v52
	v_mul_f32_e32 v56, v53, v54
	v_mul_f32_e32 v57, v49, v56
	v_fma_f32 v49, v56, v49, -v57
	v_fmac_f32_e32 v49, v56, v47
	v_sub_f32_e32 v47, v59, v54
	v_add_f32_e32 v47, v52, v47
	v_add_f32_e32 v52, v57, v49
	v_sub_f32_e32 v58, v54, v52
	v_sub_f32_e32 v54, v54, v58
	v_sub_f32_e32 v57, v52, v57
	v_sub_f32_e32 v52, v54, v52
	v_add_f32_e32 v47, v47, v52
	v_sub_f32_e32 v49, v57, v49
	v_add_f32_e32 v47, v49, v47
	v_add_f32_e32 v49, v55, v56
	v_add_f32_e32 v47, v58, v47
	v_sub_f32_e32 v52, v49, v55
	v_mul_f32_e32 v47, v53, v47
	v_sub_f32_e32 v52, v56, v52
	v_add_f32_e32 v47, v52, v47
	v_mul_f32_e32 v55, 0x3f317218, v48
	v_add_f32_e32 v52, v49, v47
	v_fma_f32 v56, v48, s34, -v55
	v_mul_f32_e32 v53, v52, v52
	v_fmac_f32_e32 v56, 0xb102e308, v48
	v_sub_f32_e32 v48, v52, v49
	v_fmamk_f32 v54, v53, 0x3e9b6dac, v184
	v_sub_f32_e32 v47, v47, v48
	v_add_f32_e32 v48, v55, v56
	v_fmaak_f32 v54, v53, v54, 0x3f2aaada
	v_sub_f32_e32 v49, v48, v55
	v_ldexp_f32 v55, v52, 1
	v_mul_f32_e32 v52, v52, v53
	v_mul_f32_e32 v52, v52, v54
	v_add_f32_e32 v53, v55, v52
	v_sub_f32_e32 v54, v53, v55
	v_ldexp_f32 v47, v47, 1
	v_sub_f32_e32 v52, v52, v54
	v_add_f32_e32 v47, v47, v52
	v_add_f32_e32 v52, v53, v47
	v_sub_f32_e32 v53, v52, v53
	v_sub_f32_e32 v47, v47, v53
	v_add_f32_e32 v53, v48, v52
	v_sub_f32_e32 v54, v53, v48
	v_sub_f32_e32 v55, v53, v54
	v_sub_f32_e32 v49, v56, v49
	v_sub_f32_e32 v48, v48, v55
	v_sub_f32_e32 v52, v52, v54
	v_add_f32_e32 v48, v52, v48
	v_add_f32_e32 v52, v49, v47
	v_sub_f32_e32 v54, v52, v49
	v_sub_f32_e32 v55, v52, v54
	v_sub_f32_e32 v49, v49, v55
	v_sub_f32_e32 v47, v47, v54
	v_add_f32_e32 v48, v52, v48
	v_add_f32_e32 v47, v47, v49
	v_add_f32_e32 v49, v53, v48
	v_sub_f32_e32 v52, v49, v53
	v_sub_f32_e32 v48, v48, v52
	v_add_f32_e32 v47, v47, v48
	v_add_f32_e32 v47, v49, v47
	v_cndmask_b32_e32 v47, v185, v47, vcc
	v_cmp_ngt_f32_e32 vcc, -1.0, v46
	s_nop 1
	v_cndmask_b32_e32 v47, v186, v47, vcc
	v_cmp_neq_f32_e32 vcc, -1.0, v46
	s_nop 1
	v_cndmask_b32_e32 v47, v187, v47, vcc
	v_cmp_lt_f32_e64 vcc, |v46|, s36
	s_nop 1
	v_cndmask_b32_e32 v46, v47, v46, vcc
	v_add_f32_e32 v30, v30, v46
	v_sub_f32_e32 v30, -0.5, v30
	v_mul_f32_e32 v30, 0x3fb8aa3b, v30
	v_exp_f32_e32 v30, v30
	v_lshlrev_b64 v[46:47], 12, v[76:77]
	v_lshl_add_u64 v[48:49], v[70:71], 0, v[46:47]
	v_xor_b32_e32 v30, 0x80000000, v30
	global_store_dword v[48:49], v30, off
	v_mov_b32_e32 v30, v240
	v_add_f32_e32 v31, v31, v30
	v_max_f32_e64 v30, -v31, 0
	v_mul_f32_e64 v31, |v31|, s30
	v_exp_f32_e32 v31, v31
	s_nop 0
	v_add_f32_e32 v52, 1.0, v31
	v_add_f32_e32 v48, -1.0, v52
	v_sub_f32_e32 v49, v48, v52
	v_add_f32_e32 v49, 1.0, v49
	v_sub_f32_e32 v48, v31, v48
	v_add_f32_e32 v53, v48, v49
	v_frexp_mant_f32_e32 v48, v52
	v_cmp_gt_f32_e32 vcc, s31, v48
	v_cvt_f64_f32_e32 v[48:49], v52
	v_frexp_exp_i32_f64_e32 v48, v[48:49]
	v_subbrev_co_u32_e32 v48, vcc, 0, v48, vcc
	v_sub_u32_e32 v49, 0, v48
	v_ldexp_f32 v52, v52, v49
	v_ldexp_f32 v49, v53, v49
	v_add_f32_e32 v53, -1.0, v52
	v_add_f32_e32 v54, 1.0, v53
	v_sub_f32_e32 v54, v52, v54
	v_add_f32_e32 v54, v49, v54
	v_add_f32_e32 v55, v53, v54
	v_sub_f32_e32 v53, v55, v53
	v_sub_f32_e32 v53, v54, v53
	v_add_f32_e32 v54, 1.0, v52
	v_add_f32_e32 v56, -1.0, v54
	v_sub_f32_e32 v52, v52, v56
	v_add_f32_e32 v49, v49, v52
	v_add_f32_e32 v52, v54, v49
	v_sub_f32_e32 v54, v52, v54
	v_sub_f32_e32 v49, v49, v54
	v_rcp_f32_e32 v54, v52
	v_cvt_f32_i32_e32 v48, v48
	v_cmp_neq_f32_e32 vcc, s35, v31
	v_mul_f32_e32 v56, v55, v54
	v_mul_f32_e32 v57, v52, v56
	v_fma_f32 v58, v56, v52, -v57
	v_fmac_f32_e32 v58, v56, v49
	v_add_f32_e32 v59, v57, v58
	v_sub_f32_e32 v60, v55, v59
	v_sub_f32_e32 v55, v55, v60
	v_sub_f32_e32 v57, v59, v57
	v_sub_f32_e32 v55, v55, v59
	v_add_f32_e32 v53, v53, v55
	v_sub_f32_e32 v55, v57, v58
	v_add_f32_e32 v53, v55, v53
	v_add_f32_e32 v55, v60, v53
	v_mul_f32_e32 v57, v54, v55
	v_mul_f32_e32 v58, v52, v57
	v_fma_f32 v52, v57, v52, -v58
	v_fmac_f32_e32 v52, v57, v49
	v_sub_f32_e32 v49, v60, v55
	v_add_f32_e32 v49, v53, v49
	v_add_f32_e32 v53, v58, v52
	v_sub_f32_e32 v59, v55, v53
	v_sub_f32_e32 v55, v55, v59
	v_sub_f32_e32 v58, v53, v58
	v_sub_f32_e32 v53, v55, v53
	v_add_f32_e32 v49, v49, v53
	v_sub_f32_e32 v52, v58, v52
	v_add_f32_e32 v49, v52, v49
	v_add_f32_e32 v52, v56, v57
	v_add_f32_e32 v49, v59, v49
	v_sub_f32_e32 v53, v52, v56
	v_mul_f32_e32 v49, v54, v49
	v_sub_f32_e32 v53, v57, v53
	v_add_f32_e32 v49, v53, v49
	v_mul_f32_e32 v56, 0x3f317218, v48
	v_add_f32_e32 v53, v52, v49
	v_fma_f32 v57, v48, s34, -v56
	v_mul_f32_e32 v54, v53, v53
	v_fmac_f32_e32 v57, 0xb102e308, v48
	v_sub_f32_e32 v48, v53, v52
	v_fmamk_f32 v55, v54, 0x3e9b6dac, v184
	v_sub_f32_e32 v48, v49, v48
	v_add_f32_e32 v49, v56, v57
	v_fmaak_f32 v55, v54, v55, 0x3f2aaada
	v_sub_f32_e32 v52, v49, v56
	v_ldexp_f32 v56, v53, 1
	v_mul_f32_e32 v53, v53, v54
	v_mul_f32_e32 v53, v53, v55
	v_add_f32_e32 v54, v56, v53
	v_sub_f32_e32 v55, v54, v56
	v_ldexp_f32 v48, v48, 1
	v_sub_f32_e32 v53, v53, v55
	v_add_f32_e32 v48, v48, v53
	v_add_f32_e32 v53, v54, v48
	v_sub_f32_e32 v54, v53, v54
	v_sub_f32_e32 v48, v48, v54
	v_add_f32_e32 v54, v49, v53
	v_sub_f32_e32 v55, v54, v49
	v_sub_f32_e32 v56, v54, v55
	v_sub_f32_e32 v52, v57, v52
	v_sub_f32_e32 v49, v49, v56
	v_sub_f32_e32 v53, v53, v55
	v_add_f32_e32 v49, v53, v49
	v_add_f32_e32 v53, v52, v48
	v_sub_f32_e32 v55, v53, v52
	v_sub_f32_e32 v56, v53, v55
	v_sub_f32_e32 v52, v52, v56
	v_sub_f32_e32 v48, v48, v55
	v_add_f32_e32 v49, v53, v49
	v_add_f32_e32 v48, v48, v52
	v_add_f32_e32 v52, v54, v49
	v_sub_f32_e32 v53, v52, v54
	v_sub_f32_e32 v49, v49, v53
	v_add_f32_e32 v48, v48, v49
	v_add_f32_e32 v48, v52, v48
	v_cndmask_b32_e32 v48, v185, v48, vcc
	v_cmp_ngt_f32_e32 vcc, -1.0, v31
	s_nop 1
	v_cndmask_b32_e32 v48, v186, v48, vcc
	v_cmp_neq_f32_e32 vcc, -1.0, v31
	s_nop 1
	v_cndmask_b32_e32 v48, v187, v48, vcc
	v_cmp_lt_f32_e64 vcc, |v31|, s36
	s_nop 1
	v_cndmask_b32_e32 v31, v48, v31, vcc
	v_add_f32_e32 v30, v30, v31
	v_sub_f32_e32 v30, -0.5, v30
	v_mul_f32_e32 v30, 0x3fb8aa3b, v30
	v_exp_f32_e32 v30, v30
	s_nop 0
	v_xor_b32_e32 v52, 0x80000000, v30
	v_lshlrev_b64 v[30:31], 12, v[74:75]
	v_lshl_add_u64 v[48:49], v[70:71], 0, v[30:31]
	global_store_dword v[48:49], v52, off
	v_mov_b32_e32 v48, v240
	v_add_f32_e32 v48, v32, v48
	v_max_f32_e64 v32, -v48, 0
	v_mul_f32_e64 v48, |v48|, s30
	v_exp_f32_e32 v48, v48
	s_nop 0
	v_add_f32_e32 v49, 1.0, v48
	v_add_f32_e32 v52, -1.0, v49
	v_sub_f32_e32 v53, v52, v49
	v_add_f32_e32 v53, 1.0, v53
	v_sub_f32_e32 v52, v48, v52
	v_add_f32_e32 v54, v52, v53
	v_frexp_mant_f32_e32 v52, v49
	v_cmp_gt_f32_e32 vcc, s31, v52
	v_cvt_f64_f32_e32 v[52:53], v49
	v_frexp_exp_i32_f64_e32 v52, v[52:53]
	v_subbrev_co_u32_e32 v52, vcc, 0, v52, vcc
	v_sub_u32_e32 v53, 0, v52
	v_ldexp_f32 v49, v49, v53
	v_ldexp_f32 v53, v54, v53
	v_add_f32_e32 v54, -1.0, v49
	v_add_f32_e32 v55, 1.0, v54
	v_sub_f32_e32 v55, v49, v55
	v_add_f32_e32 v55, v53, v55
	v_add_f32_e32 v56, v54, v55
	v_sub_f32_e32 v54, v56, v54
	v_sub_f32_e32 v54, v55, v54
	v_add_f32_e32 v55, 1.0, v49
	v_add_f32_e32 v57, -1.0, v55
	v_sub_f32_e32 v49, v49, v57
	v_add_f32_e32 v49, v53, v49
	v_add_f32_e32 v53, v55, v49
	v_sub_f32_e32 v55, v53, v55
	v_sub_f32_e32 v49, v49, v55
	v_rcp_f32_e32 v55, v53
	v_cvt_f32_i32_e32 v52, v52
	v_cmp_neq_f32_e32 vcc, s35, v48
	v_mul_f32_e32 v57, v56, v55
	v_mul_f32_e32 v58, v53, v57
	v_fma_f32 v59, v57, v53, -v58
	v_fmac_f32_e32 v59, v57, v49
	v_add_f32_e32 v60, v58, v59
	v_sub_f32_e32 v61, v56, v60
	v_sub_f32_e32 v56, v56, v61
	v_sub_f32_e32 v58, v60, v58
	v_sub_f32_e32 v56, v56, v60
	v_add_f32_e32 v54, v54, v56
	v_sub_f32_e32 v56, v58, v59
	v_add_f32_e32 v54, v56, v54
	v_add_f32_e32 v56, v61, v54
	v_mul_f32_e32 v58, v55, v56
	v_mul_f32_e32 v59, v53, v58
	v_fma_f32 v53, v58, v53, -v59
	v_fmac_f32_e32 v53, v58, v49
	v_sub_f32_e32 v49, v61, v56
	v_add_f32_e32 v49, v54, v49
	v_add_f32_e32 v54, v59, v53
	v_sub_f32_e32 v60, v56, v54
	v_sub_f32_e32 v56, v56, v60
	v_sub_f32_e32 v59, v54, v59
	v_sub_f32_e32 v54, v56, v54
	v_add_f32_e32 v49, v49, v54
	v_sub_f32_e32 v53, v59, v53
	v_add_f32_e32 v49, v53, v49
	v_add_f32_e32 v53, v57, v58
	v_add_f32_e32 v49, v60, v49
	v_sub_f32_e32 v54, v53, v57
	v_mul_f32_e32 v49, v55, v49
	v_sub_f32_e32 v54, v58, v54
	v_add_f32_e32 v49, v54, v49
	v_mul_f32_e32 v57, 0x3f317218, v52
	v_add_f32_e32 v54, v53, v49
	v_fma_f32 v58, v52, s34, -v57
	v_mul_f32_e32 v55, v54, v54
	v_fmac_f32_e32 v58, 0xb102e308, v52
	v_sub_f32_e32 v52, v54, v53
	v_fmamk_f32 v56, v55, 0x3e9b6dac, v184
	v_sub_f32_e32 v49, v49, v52
	v_add_f32_e32 v52, v57, v58
	v_fmaak_f32 v56, v55, v56, 0x3f2aaada
	v_sub_f32_e32 v53, v52, v57
	v_ldexp_f32 v57, v54, 1
	v_mul_f32_e32 v54, v54, v55
	v_mul_f32_e32 v54, v54, v56
	v_add_f32_e32 v55, v57, v54
	v_sub_f32_e32 v56, v55, v57
	v_ldexp_f32 v49, v49, 1
	v_sub_f32_e32 v54, v54, v56
	v_add_f32_e32 v49, v49, v54
	v_add_f32_e32 v54, v55, v49
	v_sub_f32_e32 v55, v54, v55
	v_sub_f32_e32 v49, v49, v55
	v_add_f32_e32 v55, v52, v54
	v_sub_f32_e32 v56, v55, v52
	v_sub_f32_e32 v57, v55, v56
	v_sub_f32_e32 v53, v58, v53
	v_sub_f32_e32 v52, v52, v57
	v_sub_f32_e32 v54, v54, v56
	v_add_f32_e32 v52, v54, v52
	v_add_f32_e32 v54, v53, v49
	v_sub_f32_e32 v56, v54, v53
	v_sub_f32_e32 v57, v54, v56
	v_sub_f32_e32 v53, v53, v57
	v_sub_f32_e32 v49, v49, v56
	v_add_f32_e32 v52, v54, v52
	v_add_f32_e32 v49, v49, v53
	v_add_f32_e32 v53, v55, v52
	v_sub_f32_e32 v54, v53, v55
	v_sub_f32_e32 v52, v52, v54
	v_add_f32_e32 v49, v49, v52
	v_add_f32_e32 v49, v53, v49
	v_cndmask_b32_e32 v49, v185, v49, vcc
	v_cmp_ngt_f32_e32 vcc, -1.0, v48
	s_nop 1
	v_cndmask_b32_e32 v49, v186, v49, vcc
	v_cmp_neq_f32_e32 vcc, -1.0, v48
	s_nop 1
	v_cndmask_b32_e32 v49, v187, v49, vcc
	v_cmp_lt_f32_e64 vcc, |v48|, s36
	s_nop 1
	v_cndmask_b32_e32 v48, v49, v48, vcc
	v_add_f32_e32 v32, v32, v48
	v_sub_f32_e32 v32, -0.5, v32
	v_mul_f32_e32 v32, 0x3fb8aa3b, v32
	v_exp_f32_e32 v32, v32
	v_lshlrev_b64 v[48:49], 12, v[72:73]
	v_lshl_add_u64 v[52:53], v[70:71], 0, v[48:49]
	v_xor_b32_e32 v32, 0x80000000, v32
	global_store_dword v[52:53], v32, off
	v_mov_b32_e32 v32, v240
	v_add_f32_e32 v33, v33, v32
	v_max_f32_e64 v32, -v33, 0
	v_mul_f32_e64 v33, |v33|, s30
	v_exp_f32_e32 v33, v33
	s_nop 0
	v_add_f32_e32 v54, 1.0, v33
	v_add_f32_e32 v52, -1.0, v54
	v_sub_f32_e32 v53, v52, v54
	v_add_f32_e32 v53, 1.0, v53
	v_sub_f32_e32 v52, v33, v52
	v_add_f32_e32 v55, v52, v53
	v_frexp_mant_f32_e32 v52, v54
	v_cmp_gt_f32_e32 vcc, s31, v52
	v_cvt_f64_f32_e32 v[52:53], v54
	v_frexp_exp_i32_f64_e32 v52, v[52:53]
	v_subbrev_co_u32_e32 v52, vcc, 0, v52, vcc
	v_sub_u32_e32 v53, 0, v52
	v_ldexp_f32 v54, v54, v53
	v_ldexp_f32 v53, v55, v53
	v_add_f32_e32 v55, -1.0, v54
	v_add_f32_e32 v56, 1.0, v55
	v_sub_f32_e32 v56, v54, v56
	v_add_f32_e32 v56, v53, v56
	v_add_f32_e32 v57, v55, v56
	v_sub_f32_e32 v55, v57, v55
	v_sub_f32_e32 v55, v56, v55
	v_add_f32_e32 v56, 1.0, v54
	v_add_f32_e32 v58, -1.0, v56
	v_sub_f32_e32 v54, v54, v58
	v_add_f32_e32 v53, v53, v54
	v_add_f32_e32 v54, v56, v53
	v_sub_f32_e32 v56, v54, v56
	v_sub_f32_e32 v53, v53, v56
	v_rcp_f32_e32 v56, v54
	v_cvt_f32_i32_e32 v52, v52
	v_cmp_neq_f32_e32 vcc, s35, v33
	v_mul_f32_e32 v58, v57, v56
	v_mul_f32_e32 v59, v54, v58
	v_fma_f32 v60, v58, v54, -v59
	v_fmac_f32_e32 v60, v58, v53
	v_add_f32_e32 v61, v59, v60
	v_sub_f32_e32 v62, v57, v61
	v_sub_f32_e32 v57, v57, v62
	v_sub_f32_e32 v59, v61, v59
	v_sub_f32_e32 v57, v57, v61
	v_add_f32_e32 v55, v55, v57
	v_sub_f32_e32 v57, v59, v60
	v_add_f32_e32 v55, v57, v55
	v_add_f32_e32 v57, v62, v55
	v_mul_f32_e32 v59, v56, v57
	v_mul_f32_e32 v60, v54, v59
	v_fma_f32 v54, v59, v54, -v60
	v_fmac_f32_e32 v54, v59, v53
	v_sub_f32_e32 v53, v62, v57
	v_add_f32_e32 v53, v55, v53
	v_add_f32_e32 v55, v60, v54
	v_sub_f32_e32 v61, v57, v55
	v_sub_f32_e32 v57, v57, v61
	v_sub_f32_e32 v60, v55, v60
	v_sub_f32_e32 v55, v57, v55
	v_add_f32_e32 v53, v53, v55
	v_sub_f32_e32 v54, v60, v54
	v_add_f32_e32 v53, v54, v53
	v_add_f32_e32 v54, v58, v59
	v_add_f32_e32 v53, v61, v53
	v_sub_f32_e32 v55, v54, v58
	v_mul_f32_e32 v53, v56, v53
	v_sub_f32_e32 v55, v59, v55
	v_add_f32_e32 v53, v55, v53
	v_mul_f32_e32 v58, 0x3f317218, v52
	v_add_f32_e32 v55, v54, v53
	v_fma_f32 v59, v52, s34, -v58
	v_mul_f32_e32 v56, v55, v55
	v_fmac_f32_e32 v59, 0xb102e308, v52
	v_sub_f32_e32 v52, v55, v54
	v_fmamk_f32 v57, v56, 0x3e9b6dac, v184
	v_sub_f32_e32 v52, v53, v52
	v_add_f32_e32 v53, v58, v59
	v_fmaak_f32 v57, v56, v57, 0x3f2aaada
	v_sub_f32_e32 v54, v53, v58
	v_ldexp_f32 v58, v55, 1
	v_mul_f32_e32 v55, v55, v56
	v_mul_f32_e32 v55, v55, v57
	v_add_f32_e32 v56, v58, v55
	v_sub_f32_e32 v57, v56, v58
	v_ldexp_f32 v52, v52, 1
	v_sub_f32_e32 v55, v55, v57
	v_add_f32_e32 v52, v52, v55
	v_add_f32_e32 v55, v56, v52
	v_sub_f32_e32 v56, v55, v56
	v_sub_f32_e32 v52, v52, v56
	v_add_f32_e32 v56, v53, v55
	v_sub_f32_e32 v57, v56, v53
	v_sub_f32_e32 v58, v56, v57
	v_sub_f32_e32 v54, v59, v54
	v_sub_f32_e32 v53, v53, v58
	v_sub_f32_e32 v55, v55, v57
	v_add_f32_e32 v53, v55, v53
	v_add_f32_e32 v55, v54, v52
	v_sub_f32_e32 v57, v55, v54
	v_sub_f32_e32 v58, v55, v57
	v_sub_f32_e32 v54, v54, v58
	v_sub_f32_e32 v52, v52, v57
	v_add_f32_e32 v53, v55, v53
	v_add_f32_e32 v52, v52, v54
	v_add_f32_e32 v54, v56, v53
	v_sub_f32_e32 v55, v54, v56
	v_sub_f32_e32 v53, v53, v55
	v_add_f32_e32 v52, v52, v53
	v_add_f32_e32 v52, v54, v52
	v_cndmask_b32_e32 v52, v185, v52, vcc
	v_cmp_ngt_f32_e32 vcc, -1.0, v33
	s_nop 1
	v_cndmask_b32_e32 v52, v186, v52, vcc
	v_cmp_neq_f32_e32 vcc, -1.0, v33
	s_nop 1
	v_cndmask_b32_e32 v52, v187, v52, vcc
	v_cmp_lt_f32_e64 vcc, |v33|, s36
	s_nop 1
	v_cndmask_b32_e32 v33, v52, v33, vcc
	v_add_f32_e32 v32, v32, v33
	v_sub_f32_e32 v32, -0.5, v32
	v_mul_f32_e32 v32, 0x3fb8aa3b, v32
	v_exp_f32_e32 v32, v32
	s_nop 0
	v_xor_b32_e32 v54, 0x80000000, v32
	v_lshlrev_b64 v[32:33], 12, v[68:69]
	v_lshl_add_u64 v[52:53], v[70:71], 0, v[32:33]
	global_store_dword v[52:53], v54, off
	v_mov_b32_e32 v52, v241
	v_add_f32_e32 v52, v2, v52
	v_max_f32_e64 v2, -v52, 0
	v_mul_f32_e64 v52, |v52|, s30
	v_exp_f32_e32 v52, v52
	s_nop 0
	v_add_f32_e32 v53, 1.0, v52
	v_add_f32_e32 v54, -1.0, v53
	v_sub_f32_e32 v55, v54, v53
	v_add_f32_e32 v55, 1.0, v55
	v_sub_f32_e32 v54, v52, v54
	v_add_f32_e32 v56, v54, v55
	v_frexp_mant_f32_e32 v54, v53
	v_cmp_gt_f32_e32 vcc, s31, v54
	v_cvt_f64_f32_e32 v[54:55], v53
	v_frexp_exp_i32_f64_e32 v54, v[54:55]
	v_subbrev_co_u32_e32 v54, vcc, 0, v54, vcc
	v_sub_u32_e32 v55, 0, v54
	v_ldexp_f32 v53, v53, v55
	v_ldexp_f32 v55, v56, v55
	v_add_f32_e32 v56, -1.0, v53
	v_add_f32_e32 v57, 1.0, v56
	v_sub_f32_e32 v57, v53, v57
	v_add_f32_e32 v57, v55, v57
	v_add_f32_e32 v58, v56, v57
	v_sub_f32_e32 v56, v58, v56
	v_sub_f32_e32 v56, v57, v56
	v_add_f32_e32 v57, 1.0, v53
	v_add_f32_e32 v59, -1.0, v57
	v_sub_f32_e32 v53, v53, v59
	v_add_f32_e32 v53, v55, v53
	v_add_f32_e32 v55, v57, v53
	v_sub_f32_e32 v57, v55, v57
	v_sub_f32_e32 v53, v53, v57
	v_rcp_f32_e32 v57, v55
	v_cvt_f32_i32_e32 v54, v54
	v_cmp_neq_f32_e32 vcc, s35, v52
	v_mul_f32_e32 v59, v58, v57
	v_mul_f32_e32 v60, v55, v59
	v_fma_f32 v61, v59, v55, -v60
	v_fmac_f32_e32 v61, v59, v53
	v_add_f32_e32 v62, v60, v61
	v_sub_f32_e32 v63, v58, v62
	v_sub_f32_e32 v58, v58, v63
	v_sub_f32_e32 v60, v62, v60
	v_sub_f32_e32 v58, v58, v62
	v_add_f32_e32 v56, v56, v58
	v_sub_f32_e32 v58, v60, v61
	v_add_f32_e32 v56, v58, v56
	v_add_f32_e32 v58, v63, v56
	v_mul_f32_e32 v60, v57, v58
	v_mul_f32_e32 v61, v55, v60
	v_fma_f32 v55, v60, v55, -v61
	v_fmac_f32_e32 v55, v60, v53
	v_sub_f32_e32 v53, v63, v58
	v_add_f32_e32 v53, v56, v53
	v_add_f32_e32 v56, v61, v55
	v_sub_f32_e32 v62, v58, v56
	v_sub_f32_e32 v58, v58, v62
	v_sub_f32_e32 v61, v56, v61
	v_sub_f32_e32 v56, v58, v56
	v_add_f32_e32 v53, v53, v56
	v_sub_f32_e32 v55, v61, v55
	v_add_f32_e32 v53, v55, v53
	v_add_f32_e32 v55, v59, v60
	v_add_f32_e32 v53, v62, v53
	v_sub_f32_e32 v56, v55, v59
	v_mul_f32_e32 v53, v57, v53
	v_sub_f32_e32 v56, v60, v56
	v_add_f32_e32 v53, v56, v53
	v_mul_f32_e32 v59, 0x3f317218, v54
	v_add_f32_e32 v56, v55, v53
	v_fma_f32 v60, v54, s34, -v59
	v_mul_f32_e32 v57, v56, v56
	v_fmac_f32_e32 v60, 0xb102e308, v54
	v_sub_f32_e32 v54, v56, v55
	v_fmamk_f32 v58, v57, 0x3e9b6dac, v184
	v_sub_f32_e32 v53, v53, v54
	v_add_f32_e32 v54, v59, v60
	v_fmaak_f32 v58, v57, v58, 0x3f2aaada
	v_sub_f32_e32 v55, v54, v59
	v_ldexp_f32 v59, v56, 1
	v_mul_f32_e32 v56, v56, v57
	v_mul_f32_e32 v56, v56, v58
	v_add_f32_e32 v57, v59, v56
	v_sub_f32_e32 v58, v57, v59
	v_ldexp_f32 v53, v53, 1
	v_sub_f32_e32 v56, v56, v58
	v_add_f32_e32 v53, v53, v56
	v_add_f32_e32 v56, v57, v53
	v_sub_f32_e32 v57, v56, v57
	v_sub_f32_e32 v53, v53, v57
	v_add_f32_e32 v57, v54, v56
	v_sub_f32_e32 v58, v57, v54
	v_sub_f32_e32 v59, v57, v58
	v_sub_f32_e32 v55, v60, v55
	v_sub_f32_e32 v54, v54, v59
	v_sub_f32_e32 v56, v56, v58
	v_add_f32_e32 v54, v56, v54
	v_add_f32_e32 v56, v55, v53
	v_sub_f32_e32 v58, v56, v55
	v_sub_f32_e32 v59, v56, v58
	v_sub_f32_e32 v55, v55, v59
	v_sub_f32_e32 v53, v53, v58
	v_add_f32_e32 v54, v56, v54
	v_add_f32_e32 v53, v53, v55
	v_add_f32_e32 v55, v57, v54
	v_sub_f32_e32 v56, v55, v57
	v_sub_f32_e32 v54, v54, v56
	v_add_f32_e32 v53, v53, v54
	v_add_f32_e32 v53, v55, v53
	v_cndmask_b32_e32 v53, v185, v53, vcc
	v_cmp_ngt_f32_e32 vcc, -1.0, v52
	s_nop 1
	v_cndmask_b32_e32 v53, v186, v53, vcc
	v_cmp_neq_f32_e32 vcc, -1.0, v52
	s_nop 1
	v_cndmask_b32_e32 v53, v187, v53, vcc
	v_cmp_lt_f32_e64 vcc, |v52|, s36
	s_nop 1
	v_cndmask_b32_e32 v52, v53, v52, vcc
	v_add_f32_e32 v2, v2, v52
	v_sub_f32_e32 v2, -0.5, v2
	v_mul_f32_e32 v2, 0x3fb8aa3b, v2
	v_exp_f32_e32 v2, v2
	s_nop 0
	v_xor_b32_e32 v2, 0x80000000, v2
	global_store_dword v[34:35], v2, off
	v_mov_b32_e32 v2, v241
	v_add_f32_e32 v3, v3, v2
	v_max_f32_e64 v2, -v3, 0
	v_mul_f32_e64 v3, |v3|, s30
	v_exp_f32_e32 v3, v3
	s_nop 0
	v_add_f32_e32 v52, 1.0, v3
	v_add_f32_e32 v34, -1.0, v52
	v_sub_f32_e32 v35, v34, v52
	v_add_f32_e32 v35, 1.0, v35
	v_sub_f32_e32 v34, v3, v34
	v_add_f32_e32 v53, v34, v35
	v_frexp_mant_f32_e32 v34, v52
	v_cmp_gt_f32_e32 vcc, s31, v34
	v_cvt_f64_f32_e32 v[34:35], v52
	v_frexp_exp_i32_f64_e32 v34, v[34:35]
	v_subbrev_co_u32_e32 v34, vcc, 0, v34, vcc
	v_sub_u32_e32 v35, 0, v34
	v_ldexp_f32 v52, v52, v35
	v_ldexp_f32 v35, v53, v35
	v_add_f32_e32 v53, -1.0, v52
	v_add_f32_e32 v54, 1.0, v53
	v_sub_f32_e32 v54, v52, v54
	v_add_f32_e32 v54, v35, v54
	v_add_f32_e32 v55, v53, v54
	v_sub_f32_e32 v53, v55, v53
	v_sub_f32_e32 v53, v54, v53
	v_add_f32_e32 v54, 1.0, v52
	v_add_f32_e32 v56, -1.0, v54
	v_sub_f32_e32 v52, v52, v56
	v_add_f32_e32 v35, v35, v52
	v_add_f32_e32 v52, v54, v35
	v_sub_f32_e32 v54, v52, v54
	v_sub_f32_e32 v35, v35, v54
	v_rcp_f32_e32 v54, v52
	v_cvt_f32_i32_e32 v34, v34
	v_cmp_neq_f32_e32 vcc, s35, v3
	v_mul_f32_e32 v56, v55, v54
	v_mul_f32_e32 v57, v52, v56
	v_fma_f32 v58, v56, v52, -v57
	v_fmac_f32_e32 v58, v56, v35
	v_add_f32_e32 v59, v57, v58
	v_sub_f32_e32 v60, v55, v59
	v_sub_f32_e32 v55, v55, v60
	v_sub_f32_e32 v57, v59, v57
	v_sub_f32_e32 v55, v55, v59
	v_add_f32_e32 v53, v53, v55
	v_sub_f32_e32 v55, v57, v58
	v_add_f32_e32 v53, v55, v53
	v_add_f32_e32 v55, v60, v53
	v_mul_f32_e32 v57, v54, v55
	v_mul_f32_e32 v58, v52, v57
	v_fma_f32 v52, v57, v52, -v58
	v_fmac_f32_e32 v52, v57, v35
	v_sub_f32_e32 v35, v60, v55
	v_add_f32_e32 v35, v53, v35
	v_add_f32_e32 v53, v58, v52
	v_sub_f32_e32 v59, v55, v53
	v_sub_f32_e32 v55, v55, v59
	v_sub_f32_e32 v58, v53, v58
	v_sub_f32_e32 v53, v55, v53
	v_add_f32_e32 v35, v35, v53
	v_sub_f32_e32 v52, v58, v52
	v_add_f32_e32 v35, v52, v35
	v_add_f32_e32 v52, v56, v57
	v_add_f32_e32 v35, v59, v35
	v_sub_f32_e32 v53, v52, v56
	v_mul_f32_e32 v35, v54, v35
	v_sub_f32_e32 v53, v57, v53
	v_add_f32_e32 v35, v53, v35
	v_mul_f32_e32 v56, 0x3f317218, v34
	v_add_f32_e32 v53, v52, v35
	v_fma_f32 v57, v34, s34, -v56
	v_mul_f32_e32 v54, v53, v53
	v_fmac_f32_e32 v57, 0xb102e308, v34
	v_sub_f32_e32 v34, v53, v52
	v_fmamk_f32 v55, v54, 0x3e9b6dac, v184
	v_sub_f32_e32 v34, v35, v34
	v_add_f32_e32 v35, v56, v57
	v_fmaak_f32 v55, v54, v55, 0x3f2aaada
	v_sub_f32_e32 v52, v35, v56
	v_ldexp_f32 v56, v53, 1
	v_mul_f32_e32 v53, v53, v54
	v_mul_f32_e32 v53, v53, v55
	v_add_f32_e32 v54, v56, v53
	v_sub_f32_e32 v55, v54, v56
	v_ldexp_f32 v34, v34, 1
	v_sub_f32_e32 v53, v53, v55
	v_add_f32_e32 v34, v34, v53
	v_add_f32_e32 v53, v54, v34
	v_sub_f32_e32 v54, v53, v54
	v_sub_f32_e32 v34, v34, v54
	v_add_f32_e32 v54, v35, v53
	v_sub_f32_e32 v55, v54, v35
	v_sub_f32_e32 v56, v54, v55
	v_sub_f32_e32 v52, v57, v52
	v_sub_f32_e32 v35, v35, v56
	v_sub_f32_e32 v53, v53, v55
	v_add_f32_e32 v35, v53, v35
	v_add_f32_e32 v53, v52, v34
	v_sub_f32_e32 v55, v53, v52
	v_sub_f32_e32 v56, v53, v55
	v_sub_f32_e32 v52, v52, v56
	v_sub_f32_e32 v34, v34, v55
	v_add_f32_e32 v35, v53, v35
	v_add_f32_e32 v34, v34, v52
	v_add_f32_e32 v52, v54, v35
	v_sub_f32_e32 v53, v52, v54
	v_sub_f32_e32 v35, v35, v53
	v_add_f32_e32 v34, v34, v35
	v_add_f32_e32 v34, v52, v34
	v_cndmask_b32_e32 v34, v185, v34, vcc
	v_cmp_ngt_f32_e32 vcc, -1.0, v3
	s_nop 1
	v_cndmask_b32_e32 v34, v186, v34, vcc
	v_cmp_neq_f32_e32 vcc, -1.0, v3
	s_nop 1
	v_cndmask_b32_e32 v34, v187, v34, vcc
	v_cmp_lt_f32_e64 vcc, |v3|, s36
	s_nop 1
	v_cndmask_b32_e32 v3, v34, v3, vcc
	v_add_f32_e32 v2, v2, v3
	v_sub_f32_e32 v2, -0.5, v2
	v_mul_f32_e32 v2, 0x3fb8aa3b, v2
	v_exp_f32_e32 v2, v2
	s_nop 0
	v_xor_b32_e32 v34, 0x80000000, v2
	v_lshl_add_u64 v[2:3], s[16:17], 0, v[18:19]
	v_lshl_add_u64 v[2:3], v[2:3], 0, v[50:51]
	global_store_dword v[2:3], v34, off
	v_mov_b32_e32 v2, v241
	v_add_f32_e32 v3, v4, v2
	v_max_f32_e64 v2, -v3, 0
	v_mul_f32_e64 v3, |v3|, s30
	v_exp_f32_e32 v3, v3
	s_nop 0
	v_add_f32_e32 v4, 1.0, v3
	v_add_f32_e32 v18, -1.0, v4
	v_sub_f32_e32 v19, v18, v4
	v_add_f32_e32 v19, 1.0, v19
	v_sub_f32_e32 v18, v3, v18
	v_add_f32_e32 v34, v18, v19
	v_frexp_mant_f32_e32 v18, v4
	v_cmp_gt_f32_e32 vcc, s31, v18
	v_cvt_f64_f32_e32 v[18:19], v4
	v_frexp_exp_i32_f64_e32 v18, v[18:19]
	v_subbrev_co_u32_e32 v18, vcc, 0, v18, vcc
	v_sub_u32_e32 v19, 0, v18
	v_ldexp_f32 v4, v4, v19
	v_ldexp_f32 v19, v34, v19
	v_add_f32_e32 v34, -1.0, v4
	v_add_f32_e32 v35, 1.0, v34
	v_sub_f32_e32 v35, v4, v35
	v_add_f32_e32 v35, v19, v35
	v_add_f32_e32 v52, v34, v35
	v_sub_f32_e32 v34, v52, v34
	v_sub_f32_e32 v34, v35, v34
	v_add_f32_e32 v35, 1.0, v4
	v_add_f32_e32 v53, -1.0, v35
	v_sub_f32_e32 v4, v4, v53
	v_add_f32_e32 v4, v19, v4
	v_add_f32_e32 v19, v35, v4
	v_sub_f32_e32 v35, v19, v35
	v_sub_f32_e32 v4, v4, v35
	v_rcp_f32_e32 v35, v19
	v_cvt_f32_i32_e32 v18, v18
	v_cmp_neq_f32_e32 vcc, s35, v3
	v_mul_f32_e32 v53, v52, v35
	v_mul_f32_e32 v54, v19, v53
	v_fma_f32 v55, v53, v19, -v54
	v_fmac_f32_e32 v55, v53, v4
	v_add_f32_e32 v56, v54, v55
	v_sub_f32_e32 v57, v52, v56
	v_sub_f32_e32 v52, v52, v57
	v_sub_f32_e32 v54, v56, v54
	v_sub_f32_e32 v52, v52, v56
	v_add_f32_e32 v34, v34, v52
	v_sub_f32_e32 v52, v54, v55
	v_add_f32_e32 v34, v52, v34
	v_add_f32_e32 v52, v57, v34
	v_mul_f32_e32 v54, v35, v52
	v_mul_f32_e32 v55, v19, v54
	v_fma_f32 v19, v54, v19, -v55
	v_fmac_f32_e32 v19, v54, v4
	v_sub_f32_e32 v4, v57, v52
	v_add_f32_e32 v4, v34, v4
	v_add_f32_e32 v34, v55, v19
	v_sub_f32_e32 v56, v52, v34
	v_sub_f32_e32 v52, v52, v56
	v_sub_f32_e32 v55, v34, v55
	v_sub_f32_e32 v34, v52, v34
	v_add_f32_e32 v4, v4, v34
	v_sub_f32_e32 v19, v55, v19
	v_add_f32_e32 v4, v19, v4
	v_add_f32_e32 v19, v53, v54
	v_add_f32_e32 v4, v56, v4
	v_sub_f32_e32 v34, v19, v53
	v_mul_f32_e32 v4, v35, v4
	v_sub_f32_e32 v34, v54, v34
	v_add_f32_e32 v4, v34, v4
	v_mul_f32_e32 v53, 0x3f317218, v18
	v_add_f32_e32 v34, v19, v4
	v_fma_f32 v54, v18, s34, -v53
	v_mul_f32_e32 v35, v34, v34
	v_fmac_f32_e32 v54, 0xb102e308, v18
	v_sub_f32_e32 v18, v34, v19
	v_fmamk_f32 v52, v35, 0x3e9b6dac, v184
	v_sub_f32_e32 v4, v4, v18
	v_add_f32_e32 v18, v53, v54
	v_fmaak_f32 v52, v35, v52, 0x3f2aaada
	v_sub_f32_e32 v19, v18, v53
	v_ldexp_f32 v53, v34, 1
	v_mul_f32_e32 v34, v34, v35
	v_mul_f32_e32 v34, v34, v52
	v_add_f32_e32 v35, v53, v34
	v_sub_f32_e32 v52, v35, v53
	v_ldexp_f32 v4, v4, 1
	v_sub_f32_e32 v34, v34, v52
	v_add_f32_e32 v4, v4, v34
	v_add_f32_e32 v34, v35, v4
	v_sub_f32_e32 v35, v34, v35
	v_sub_f32_e32 v4, v4, v35
	v_add_f32_e32 v35, v18, v34
	v_sub_f32_e32 v52, v35, v18
	v_sub_f32_e32 v53, v35, v52
	v_sub_f32_e32 v19, v54, v19
	v_sub_f32_e32 v18, v18, v53
	v_sub_f32_e32 v34, v34, v52
	v_add_f32_e32 v18, v34, v18
	v_add_f32_e32 v34, v19, v4
	v_sub_f32_e32 v52, v34, v19
	v_sub_f32_e32 v53, v34, v52
	v_sub_f32_e32 v19, v19, v53
	v_sub_f32_e32 v4, v4, v52
	v_add_f32_e32 v18, v34, v18
	v_add_f32_e32 v4, v4, v19
	v_add_f32_e32 v19, v35, v18
	v_sub_f32_e32 v34, v19, v35
	v_sub_f32_e32 v18, v18, v34
	v_add_f32_e32 v4, v4, v18
	v_add_f32_e32 v4, v19, v4
	v_cndmask_b32_e32 v4, v185, v4, vcc
	v_cmp_ngt_f32_e32 vcc, -1.0, v3
	s_nop 1
	v_cndmask_b32_e32 v4, v186, v4, vcc
	v_cmp_neq_f32_e32 vcc, -1.0, v3
	s_nop 1
	v_cndmask_b32_e32 v4, v187, v4, vcc
	v_cmp_lt_f32_e64 vcc, |v3|, s36
	s_nop 1
	v_cndmask_b32_e32 v3, v4, v3, vcc
	v_add_f32_e32 v2, v2, v3
	v_sub_f32_e32 v2, -0.5, v2
	v_mul_f32_e32 v2, 0x3fb8aa3b, v2
	v_exp_f32_e32 v2, v2
	s_nop 0
	v_xor_b32_e32 v4, 0x80000000, v2
	v_lshl_add_u64 v[2:3], s[16:17], 0, v[36:37]
	v_lshl_add_u64 v[2:3], v[2:3], 0, v[50:51]
	global_store_dword v[2:3], v4, off
	v_mov_b32_e32 v2, v241
	v_add_f32_e32 v3, v5, v2
	v_max_f32_e64 v2, -v3, 0
	v_mul_f32_e64 v3, |v3|, s30
	v_exp_f32_e32 v3, v3
	s_nop 0
	v_add_f32_e32 v18, 1.0, v3
	v_add_f32_e32 v4, -1.0, v18
	v_sub_f32_e32 v5, v4, v18
	v_add_f32_e32 v5, 1.0, v5
	v_sub_f32_e32 v4, v3, v4
	v_add_f32_e32 v19, v4, v5
	v_frexp_mant_f32_e32 v4, v18
	v_cmp_gt_f32_e32 vcc, s31, v4
	v_cvt_f64_f32_e32 v[4:5], v18
	v_frexp_exp_i32_f64_e32 v4, v[4:5]
	v_subbrev_co_u32_e32 v4, vcc, 0, v4, vcc
	v_sub_u32_e32 v5, 0, v4
	v_ldexp_f32 v18, v18, v5
	v_ldexp_f32 v5, v19, v5
	v_add_f32_e32 v19, -1.0, v18
	v_add_f32_e32 v34, 1.0, v19
	v_sub_f32_e32 v34, v18, v34
	v_add_f32_e32 v34, v5, v34
	v_add_f32_e32 v35, v19, v34
	v_sub_f32_e32 v19, v35, v19
	v_sub_f32_e32 v19, v34, v19
	v_add_f32_e32 v34, 1.0, v18
	v_add_f32_e32 v36, -1.0, v34
	v_sub_f32_e32 v18, v18, v36
	v_add_f32_e32 v5, v5, v18
	v_add_f32_e32 v18, v34, v5
	v_sub_f32_e32 v34, v18, v34
	v_sub_f32_e32 v5, v5, v34
	v_rcp_f32_e32 v34, v18
	v_cvt_f32_i32_e32 v4, v4
	v_cmp_neq_f32_e32 vcc, s35, v3
	v_mul_f32_e32 v36, v35, v34
	v_mul_f32_e32 v37, v18, v36
	v_fma_f32 v52, v36, v18, -v37
	v_fmac_f32_e32 v52, v36, v5
	v_add_f32_e32 v53, v37, v52
	v_sub_f32_e32 v54, v35, v53
	v_sub_f32_e32 v35, v35, v54
	v_sub_f32_e32 v37, v53, v37
	v_sub_f32_e32 v35, v35, v53
	v_add_f32_e32 v19, v19, v35
	v_sub_f32_e32 v35, v37, v52
	v_add_f32_e32 v19, v35, v19
	v_add_f32_e32 v35, v54, v19
	v_mul_f32_e32 v37, v34, v35
	v_mul_f32_e32 v52, v18, v37
	v_fma_f32 v18, v37, v18, -v52
	v_fmac_f32_e32 v18, v37, v5
	v_sub_f32_e32 v5, v54, v35
	v_add_f32_e32 v5, v19, v5
	v_add_f32_e32 v19, v52, v18
	v_sub_f32_e32 v53, v35, v19
	v_sub_f32_e32 v35, v35, v53
	v_sub_f32_e32 v52, v19, v52
	v_sub_f32_e32 v19, v35, v19
	v_add_f32_e32 v5, v5, v19
	v_sub_f32_e32 v18, v52, v18
	v_add_f32_e32 v5, v18, v5
	v_add_f32_e32 v18, v36, v37
	v_add_f32_e32 v5, v53, v5
	v_sub_f32_e32 v19, v18, v36
	v_mul_f32_e32 v5, v34, v5
	v_sub_f32_e32 v19, v37, v19
	v_add_f32_e32 v5, v19, v5
	v_mul_f32_e32 v36, 0x3f317218, v4
	v_add_f32_e32 v19, v18, v5
	v_fma_f32 v37, v4, s34, -v36
	v_mul_f32_e32 v34, v19, v19
	v_fmac_f32_e32 v37, 0xb102e308, v4
	v_sub_f32_e32 v4, v19, v18
	v_fmamk_f32 v35, v34, 0x3e9b6dac, v184
	v_sub_f32_e32 v4, v5, v4
	v_add_f32_e32 v5, v36, v37
	v_fmaak_f32 v35, v34, v35, 0x3f2aaada
	v_sub_f32_e32 v18, v5, v36
	v_ldexp_f32 v36, v19, 1
	v_mul_f32_e32 v19, v19, v34
	v_mul_f32_e32 v19, v19, v35
	v_add_f32_e32 v34, v36, v19
	v_sub_f32_e32 v35, v34, v36
	v_ldexp_f32 v4, v4, 1
	v_sub_f32_e32 v19, v19, v35
	v_add_f32_e32 v4, v4, v19
	v_add_f32_e32 v19, v34, v4
	v_sub_f32_e32 v34, v19, v34
	v_sub_f32_e32 v4, v4, v34
	v_add_f32_e32 v34, v5, v19
	v_sub_f32_e32 v35, v34, v5
	v_sub_f32_e32 v36, v34, v35
	v_sub_f32_e32 v18, v37, v18
	v_sub_f32_e32 v5, v5, v36
	v_sub_f32_e32 v19, v19, v35
	v_add_f32_e32 v5, v19, v5
	v_add_f32_e32 v19, v18, v4
	v_sub_f32_e32 v35, v19, v18
	v_sub_f32_e32 v36, v19, v35
	v_sub_f32_e32 v18, v18, v36
	v_sub_f32_e32 v4, v4, v35
	v_add_f32_e32 v5, v19, v5
	v_add_f32_e32 v4, v4, v18
	v_add_f32_e32 v18, v34, v5
	v_sub_f32_e32 v19, v18, v34
	v_sub_f32_e32 v5, v5, v19
	v_add_f32_e32 v4, v4, v5
	v_add_f32_e32 v4, v18, v4
	v_cndmask_b32_e32 v4, v185, v4, vcc
	v_cmp_ngt_f32_e32 vcc, -1.0, v3
	s_nop 1
	v_cndmask_b32_e32 v4, v186, v4, vcc
	v_cmp_neq_f32_e32 vcc, -1.0, v3
	s_nop 1
	v_cndmask_b32_e32 v4, v187, v4, vcc
	v_cmp_lt_f32_e64 vcc, |v3|, s36
	s_nop 1
	v_cndmask_b32_e32 v3, v4, v3, vcc
	v_add_f32_e32 v2, v2, v3
	v_sub_f32_e32 v2, -0.5, v2
	v_mul_f32_e32 v2, 0x3fb8aa3b, v2
	v_exp_f32_e32 v2, v2
	s_nop 0
	v_xor_b32_e32 v4, 0x80000000, v2
	v_lshl_add_u64 v[2:3], s[16:17], 0, v[20:21]
	v_lshl_add_u64 v[2:3], v[2:3], 0, v[50:51]
	global_store_dword v[2:3], v4, off
	v_mov_b32_e32 v2, v241
	v_add_f32_e32 v3, v6, v2
	v_max_f32_e64 v2, -v3, 0
	v_mul_f32_e64 v3, |v3|, s30
	v_exp_f32_e32 v3, v3
	s_nop 0
	v_add_f32_e32 v6, 1.0, v3
	v_add_f32_e32 v4, -1.0, v6
	v_sub_f32_e32 v5, v4, v6
	v_add_f32_e32 v5, 1.0, v5
	v_sub_f32_e32 v4, v3, v4
	v_add_f32_e32 v18, v4, v5
	v_frexp_mant_f32_e32 v4, v6
	v_cmp_gt_f32_e32 vcc, s31, v4
	v_cvt_f64_f32_e32 v[4:5], v6
	v_frexp_exp_i32_f64_e32 v4, v[4:5]
	v_subbrev_co_u32_e32 v4, vcc, 0, v4, vcc
	v_sub_u32_e32 v5, 0, v4
	v_ldexp_f32 v6, v6, v5
	v_ldexp_f32 v5, v18, v5
	v_add_f32_e32 v18, -1.0, v6
	v_add_f32_e32 v19, 1.0, v18
	v_sub_f32_e32 v19, v6, v19
	v_add_f32_e32 v19, v5, v19
	v_add_f32_e32 v20, v18, v19
	v_sub_f32_e32 v18, v20, v18
	v_sub_f32_e32 v18, v19, v18
	v_add_f32_e32 v19, 1.0, v6
	v_add_f32_e32 v21, -1.0, v19
	v_sub_f32_e32 v6, v6, v21
	v_add_f32_e32 v5, v5, v6
	v_add_f32_e32 v6, v19, v5
	v_sub_f32_e32 v19, v6, v19
	v_sub_f32_e32 v5, v5, v19
	v_rcp_f32_e32 v19, v6
	v_cvt_f32_i32_e32 v4, v4
	v_cmp_neq_f32_e32 vcc, s35, v3
	v_mul_f32_e32 v21, v20, v19
	v_mul_f32_e32 v34, v6, v21
	v_fma_f32 v35, v21, v6, -v34
	v_fmac_f32_e32 v35, v21, v5
	v_add_f32_e32 v36, v34, v35
	v_sub_f32_e32 v37, v20, v36
	v_sub_f32_e32 v20, v20, v37
	v_sub_f32_e32 v34, v36, v34
	v_sub_f32_e32 v20, v20, v36
	v_add_f32_e32 v18, v18, v20
	v_sub_f32_e32 v20, v34, v35
	v_add_f32_e32 v18, v20, v18
	v_add_f32_e32 v20, v37, v18
	v_mul_f32_e32 v34, v19, v20
	v_mul_f32_e32 v35, v6, v34
	v_fma_f32 v6, v34, v6, -v35
	v_fmac_f32_e32 v6, v34, v5
	v_sub_f32_e32 v5, v37, v20
	v_add_f32_e32 v5, v18, v5
	v_add_f32_e32 v18, v35, v6
	v_sub_f32_e32 v36, v20, v18
	v_sub_f32_e32 v20, v20, v36
	v_sub_f32_e32 v35, v18, v35
	v_sub_f32_e32 v18, v20, v18
	v_add_f32_e32 v5, v5, v18
	v_sub_f32_e32 v6, v35, v6
	v_add_f32_e32 v5, v6, v5
	v_add_f32_e32 v6, v21, v34
	v_add_f32_e32 v5, v36, v5
	v_sub_f32_e32 v18, v6, v21
	v_mul_f32_e32 v5, v19, v5
	v_sub_f32_e32 v18, v34, v18
	v_add_f32_e32 v5, v18, v5
	v_mul_f32_e32 v21, 0x3f317218, v4
	v_add_f32_e32 v18, v6, v5
	v_fma_f32 v34, v4, s34, -v21
	v_mul_f32_e32 v19, v18, v18
	v_fmac_f32_e32 v34, 0xb102e308, v4
	v_sub_f32_e32 v4, v18, v6
	v_fmamk_f32 v20, v19, 0x3e9b6dac, v184
	v_sub_f32_e32 v4, v5, v4
	v_add_f32_e32 v5, v21, v34
	v_fmaak_f32 v20, v19, v20, 0x3f2aaada
	v_sub_f32_e32 v6, v5, v21
	v_ldexp_f32 v21, v18, 1
	v_mul_f32_e32 v18, v18, v19
	v_mul_f32_e32 v18, v18, v20
	v_add_f32_e32 v19, v21, v18
	v_sub_f32_e32 v20, v19, v21
	v_ldexp_f32 v4, v4, 1
	v_sub_f32_e32 v18, v18, v20
	v_add_f32_e32 v4, v4, v18
	v_add_f32_e32 v18, v19, v4
	v_sub_f32_e32 v19, v18, v19
	v_sub_f32_e32 v4, v4, v19
	v_add_f32_e32 v19, v5, v18
	v_sub_f32_e32 v20, v19, v5
	v_sub_f32_e32 v21, v19, v20
	v_sub_f32_e32 v6, v34, v6
	v_sub_f32_e32 v5, v5, v21
	v_sub_f32_e32 v18, v18, v20
	v_add_f32_e32 v5, v18, v5
	v_add_f32_e32 v18, v6, v4
	v_sub_f32_e32 v20, v18, v6
	v_sub_f32_e32 v21, v18, v20
	v_sub_f32_e32 v6, v6, v21
	v_sub_f32_e32 v4, v4, v20
	v_add_f32_e32 v5, v18, v5
	v_add_f32_e32 v4, v4, v6
	v_add_f32_e32 v6, v19, v5
	v_sub_f32_e32 v18, v6, v19
	v_sub_f32_e32 v5, v5, v18
	v_add_f32_e32 v4, v4, v5
	v_add_f32_e32 v4, v6, v4
	v_cndmask_b32_e32 v4, v185, v4, vcc
	v_cmp_ngt_f32_e32 vcc, -1.0, v3
	s_nop 1
	v_cndmask_b32_e32 v4, v186, v4, vcc
	v_cmp_neq_f32_e32 vcc, -1.0, v3
	s_nop 1
	v_cndmask_b32_e32 v4, v187, v4, vcc
	v_cmp_lt_f32_e64 vcc, |v3|, s36
	s_nop 1
	v_cndmask_b32_e32 v3, v4, v3, vcc
	v_add_f32_e32 v2, v2, v3
	v_sub_f32_e32 v2, -0.5, v2
	v_mul_f32_e32 v2, 0x3fb8aa3b, v2
	v_exp_f32_e32 v2, v2
	s_nop 0
	v_xor_b32_e32 v4, 0x80000000, v2
	v_lshl_add_u64 v[2:3], s[16:17], 0, v[38:39]
	v_lshl_add_u64 v[2:3], v[2:3], 0, v[50:51]
	global_store_dword v[2:3], v4, off
	v_mov_b32_e32 v2, v241
	v_add_f32_e32 v3, v7, v2
	v_max_f32_e64 v2, -v3, 0
	v_mul_f32_e64 v3, |v3|, s30
	v_exp_f32_e32 v3, v3
	s_nop 0
	v_add_f32_e32 v6, 1.0, v3
	v_add_f32_e32 v4, -1.0, v6
	v_sub_f32_e32 v5, v4, v6
	v_add_f32_e32 v5, 1.0, v5
	v_sub_f32_e32 v4, v3, v4
	v_add_f32_e32 v7, v4, v5
	v_frexp_mant_f32_e32 v4, v6
	v_cmp_gt_f32_e32 vcc, s31, v4
	v_cvt_f64_f32_e32 v[4:5], v6
	v_frexp_exp_i32_f64_e32 v4, v[4:5]
	v_subbrev_co_u32_e32 v4, vcc, 0, v4, vcc
	v_sub_u32_e32 v5, 0, v4
	v_ldexp_f32 v6, v6, v5
	v_ldexp_f32 v5, v7, v5
	v_add_f32_e32 v7, -1.0, v6
	v_add_f32_e32 v18, 1.0, v7
	v_sub_f32_e32 v18, v6, v18
	v_add_f32_e32 v18, v5, v18
	v_add_f32_e32 v19, v7, v18
	v_sub_f32_e32 v7, v19, v7
	v_sub_f32_e32 v7, v18, v7
	v_add_f32_e32 v18, 1.0, v6
	v_add_f32_e32 v20, -1.0, v18
	v_sub_f32_e32 v6, v6, v20
	v_add_f32_e32 v5, v5, v6
	v_add_f32_e32 v6, v18, v5
	v_sub_f32_e32 v18, v6, v18
	v_sub_f32_e32 v5, v5, v18
	v_rcp_f32_e32 v18, v6
	v_cvt_f32_i32_e32 v4, v4
	v_cmp_neq_f32_e32 vcc, s35, v3
	v_mul_f32_e32 v20, v19, v18
	v_mul_f32_e32 v21, v6, v20
	v_fma_f32 v34, v20, v6, -v21
	v_fmac_f32_e32 v34, v20, v5
	v_add_f32_e32 v35, v21, v34
	v_sub_f32_e32 v36, v19, v35
	v_sub_f32_e32 v19, v19, v36
	v_sub_f32_e32 v21, v35, v21
	v_sub_f32_e32 v19, v19, v35
	v_add_f32_e32 v7, v7, v19
	v_sub_f32_e32 v19, v21, v34
	v_add_f32_e32 v7, v19, v7
	v_add_f32_e32 v19, v36, v7
	v_mul_f32_e32 v21, v18, v19
	v_mul_f32_e32 v34, v6, v21
	v_fma_f32 v6, v21, v6, -v34
	v_fmac_f32_e32 v6, v21, v5
	v_sub_f32_e32 v5, v36, v19
	v_add_f32_e32 v5, v7, v5
	v_add_f32_e32 v7, v34, v6
	v_sub_f32_e32 v35, v19, v7
	v_sub_f32_e32 v19, v19, v35
	v_sub_f32_e32 v34, v7, v34
	v_sub_f32_e32 v7, v19, v7
	v_add_f32_e32 v5, v5, v7
	v_sub_f32_e32 v6, v34, v6
	v_add_f32_e32 v5, v6, v5
	v_add_f32_e32 v6, v20, v21
	v_add_f32_e32 v5, v35, v5
	v_sub_f32_e32 v7, v6, v20
	v_mul_f32_e32 v5, v18, v5
	v_sub_f32_e32 v7, v21, v7
	v_add_f32_e32 v5, v7, v5
	v_mul_f32_e32 v20, 0x3f317218, v4
	v_add_f32_e32 v7, v6, v5
	v_fma_f32 v21, v4, s34, -v20
	v_mul_f32_e32 v18, v7, v7
	v_fmac_f32_e32 v21, 0xb102e308, v4
	v_sub_f32_e32 v4, v7, v6
	v_fmamk_f32 v19, v18, 0x3e9b6dac, v184
	v_sub_f32_e32 v4, v5, v4
	v_add_f32_e32 v5, v20, v21
	v_fmaak_f32 v19, v18, v19, 0x3f2aaada
	v_sub_f32_e32 v6, v5, v20
	v_ldexp_f32 v20, v7, 1
	v_mul_f32_e32 v7, v7, v18
	v_mul_f32_e32 v7, v7, v19
	v_add_f32_e32 v18, v20, v7
	v_sub_f32_e32 v19, v18, v20
	v_ldexp_f32 v4, v4, 1
	v_sub_f32_e32 v7, v7, v19
	v_add_f32_e32 v4, v4, v7
	v_add_f32_e32 v7, v18, v4
	v_sub_f32_e32 v18, v7, v18
	v_sub_f32_e32 v4, v4, v18
	v_add_f32_e32 v18, v5, v7
	v_sub_f32_e32 v19, v18, v5
	v_sub_f32_e32 v20, v18, v19
	v_sub_f32_e32 v6, v21, v6
	v_sub_f32_e32 v5, v5, v20
	v_sub_f32_e32 v7, v7, v19
	v_add_f32_e32 v5, v7, v5
	v_add_f32_e32 v7, v6, v4
	v_sub_f32_e32 v19, v7, v6
	v_sub_f32_e32 v20, v7, v19
	v_sub_f32_e32 v6, v6, v20
	v_sub_f32_e32 v4, v4, v19
	v_add_f32_e32 v5, v7, v5
	v_add_f32_e32 v4, v4, v6
	v_add_f32_e32 v6, v18, v5
	v_sub_f32_e32 v7, v6, v18
	v_sub_f32_e32 v5, v5, v7
	v_add_f32_e32 v4, v4, v5
	v_add_f32_e32 v4, v6, v4
	v_cndmask_b32_e32 v4, v185, v4, vcc
	v_cmp_ngt_f32_e32 vcc, -1.0, v3
	s_nop 1
	v_cndmask_b32_e32 v4, v186, v4, vcc
	v_cmp_neq_f32_e32 vcc, -1.0, v3
	s_nop 1
	v_cndmask_b32_e32 v4, v187, v4, vcc
	v_cmp_lt_f32_e64 vcc, |v3|, s36
	s_nop 1
	v_cndmask_b32_e32 v3, v4, v3, vcc
	v_add_f32_e32 v2, v2, v3
	v_sub_f32_e32 v2, -0.5, v2
	v_mul_f32_e32 v2, 0x3fb8aa3b, v2
	v_exp_f32_e32 v2, v2
	s_nop 0
	v_xor_b32_e32 v4, 0x80000000, v2
	v_lshl_add_u64 v[2:3], s[16:17], 0, v[22:23]
	v_lshl_add_u64 v[2:3], v[2:3], 0, v[50:51]
	global_store_dword v[2:3], v4, off
	v_mov_b32_e32 v2, v241
	v_add_f32_e32 v3, v8, v2
	v_max_f32_e64 v2, -v3, 0
	v_mul_f32_e64 v3, |v3|, s30
	v_exp_f32_e32 v3, v3
	s_nop 0
	v_add_f32_e32 v6, 1.0, v3
	v_add_f32_e32 v4, -1.0, v6
	v_sub_f32_e32 v5, v4, v6
	v_add_f32_e32 v5, 1.0, v5
	v_sub_f32_e32 v4, v3, v4
	v_add_f32_e32 v7, v4, v5
	v_frexp_mant_f32_e32 v4, v6
	v_cmp_gt_f32_e32 vcc, s31, v4
	v_cvt_f64_f32_e32 v[4:5], v6
	v_frexp_exp_i32_f64_e32 v4, v[4:5]
	v_subbrev_co_u32_e32 v4, vcc, 0, v4, vcc
	v_sub_u32_e32 v5, 0, v4
	v_ldexp_f32 v6, v6, v5
	v_ldexp_f32 v5, v7, v5
	v_add_f32_e32 v7, -1.0, v6
	v_add_f32_e32 v8, 1.0, v7
	v_sub_f32_e32 v8, v6, v8
	v_add_f32_e32 v8, v5, v8
	v_add_f32_e32 v18, v7, v8
	v_sub_f32_e32 v7, v18, v7
	v_sub_f32_e32 v7, v8, v7
	v_add_f32_e32 v8, 1.0, v6
	v_add_f32_e32 v19, -1.0, v8
	v_sub_f32_e32 v6, v6, v19
	v_add_f32_e32 v5, v5, v6
	v_add_f32_e32 v6, v8, v5
	v_sub_f32_e32 v8, v6, v8
	v_sub_f32_e32 v5, v5, v8
	v_rcp_f32_e32 v8, v6
	v_cvt_f32_i32_e32 v4, v4
	v_cmp_neq_f32_e32 vcc, s35, v3
	v_mul_f32_e32 v19, v18, v8
	v_mul_f32_e32 v20, v6, v19
	v_fma_f32 v21, v19, v6, -v20
	v_fmac_f32_e32 v21, v19, v5
	v_add_f32_e32 v22, v20, v21
	v_sub_f32_e32 v23, v18, v22
	v_sub_f32_e32 v18, v18, v23
	v_sub_f32_e32 v20, v22, v20
	v_sub_f32_e32 v18, v18, v22
	v_add_f32_e32 v7, v7, v18
	v_sub_f32_e32 v18, v20, v21
	v_add_f32_e32 v7, v18, v7
	v_add_f32_e32 v18, v23, v7
	v_mul_f32_e32 v20, v8, v18
	v_mul_f32_e32 v21, v6, v20
	v_fma_f32 v6, v20, v6, -v21
	v_fmac_f32_e32 v6, v20, v5
	v_sub_f32_e32 v5, v23, v18
	v_add_f32_e32 v5, v7, v5
	v_add_f32_e32 v7, v21, v6
	v_sub_f32_e32 v22, v18, v7
	v_sub_f32_e32 v18, v18, v22
	v_sub_f32_e32 v21, v7, v21
	v_sub_f32_e32 v7, v18, v7
	v_add_f32_e32 v5, v5, v7
	v_sub_f32_e32 v6, v21, v6
	v_add_f32_e32 v5, v6, v5
	v_add_f32_e32 v6, v19, v20
	v_add_f32_e32 v5, v22, v5
	v_sub_f32_e32 v7, v6, v19
	v_mul_f32_e32 v5, v8, v5
	v_sub_f32_e32 v7, v20, v7
	v_add_f32_e32 v5, v7, v5
	v_mul_f32_e32 v19, 0x3f317218, v4
	v_add_f32_e32 v7, v6, v5
	v_fma_f32 v20, v4, s34, -v19
	v_mul_f32_e32 v8, v7, v7
	v_fmac_f32_e32 v20, 0xb102e308, v4
	v_sub_f32_e32 v4, v7, v6
	v_fmamk_f32 v18, v8, 0x3e9b6dac, v184
	v_sub_f32_e32 v4, v5, v4
	v_add_f32_e32 v5, v19, v20
	v_fmaak_f32 v18, v8, v18, 0x3f2aaada
	v_sub_f32_e32 v6, v5, v19
	v_ldexp_f32 v19, v7, 1
	v_mul_f32_e32 v7, v7, v8
	v_mul_f32_e32 v7, v7, v18
	v_add_f32_e32 v8, v19, v7
	v_sub_f32_e32 v18, v8, v19
	v_ldexp_f32 v4, v4, 1
	v_sub_f32_e32 v7, v7, v18
	v_add_f32_e32 v4, v4, v7
	v_add_f32_e32 v7, v8, v4
	v_sub_f32_e32 v8, v7, v8
	v_sub_f32_e32 v4, v4, v8
	v_add_f32_e32 v8, v5, v7
	v_sub_f32_e32 v18, v8, v5
	v_sub_f32_e32 v19, v8, v18
	v_sub_f32_e32 v6, v20, v6
	v_sub_f32_e32 v5, v5, v19
	v_sub_f32_e32 v7, v7, v18
	v_add_f32_e32 v5, v7, v5
	v_add_f32_e32 v7, v6, v4
	v_sub_f32_e32 v18, v7, v6
	v_sub_f32_e32 v19, v7, v18
	v_sub_f32_e32 v6, v6, v19
	v_sub_f32_e32 v4, v4, v18
	v_add_f32_e32 v5, v7, v5
	v_add_f32_e32 v4, v4, v6
	v_add_f32_e32 v6, v8, v5
	v_sub_f32_e32 v7, v6, v8
	v_sub_f32_e32 v5, v5, v7
	v_add_f32_e32 v4, v4, v5
	v_add_f32_e32 v4, v6, v4
	v_cndmask_b32_e32 v4, v185, v4, vcc
	v_cmp_ngt_f32_e32 vcc, -1.0, v3
	s_nop 1
	v_cndmask_b32_e32 v4, v186, v4, vcc
	v_cmp_neq_f32_e32 vcc, -1.0, v3
	s_nop 1
	v_cndmask_b32_e32 v4, v187, v4, vcc
	v_cmp_lt_f32_e64 vcc, |v3|, s36
	s_nop 1
	v_cndmask_b32_e32 v3, v4, v3, vcc
	v_add_f32_e32 v2, v2, v3
	v_sub_f32_e32 v2, -0.5, v2
	v_mul_f32_e32 v2, 0x3fb8aa3b, v2
	v_exp_f32_e32 v2, v2
	s_nop 0
	v_xor_b32_e32 v4, 0x80000000, v2
	v_lshl_add_u64 v[2:3], s[16:17], 0, v[40:41]
	v_lshl_add_u64 v[2:3], v[2:3], 0, v[50:51]
	global_store_dword v[2:3], v4, off
	v_mov_b32_e32 v2, v241
	v_add_f32_e32 v3, v9, v2
	v_max_f32_e64 v2, -v3, 0
	v_mul_f32_e64 v3, |v3|, s30
	v_exp_f32_e32 v3, v3
	s_nop 0
	v_add_f32_e32 v6, 1.0, v3
	v_add_f32_e32 v4, -1.0, v6
	v_sub_f32_e32 v5, v4, v6
	v_add_f32_e32 v5, 1.0, v5
	v_sub_f32_e32 v4, v3, v4
	v_add_f32_e32 v7, v4, v5
	v_frexp_mant_f32_e32 v4, v6
	v_cmp_gt_f32_e32 vcc, s31, v4
	v_cvt_f64_f32_e32 v[4:5], v6
	v_frexp_exp_i32_f64_e32 v4, v[4:5]
	v_subbrev_co_u32_e32 v4, vcc, 0, v4, vcc
	v_sub_u32_e32 v5, 0, v4
	v_ldexp_f32 v6, v6, v5
	v_ldexp_f32 v5, v7, v5
	v_add_f32_e32 v7, -1.0, v6
	v_add_f32_e32 v8, 1.0, v7
	v_sub_f32_e32 v8, v6, v8
	v_add_f32_e32 v8, v5, v8
	v_add_f32_e32 v9, v7, v8
	v_sub_f32_e32 v7, v9, v7
	v_sub_f32_e32 v7, v8, v7
	v_add_f32_e32 v8, 1.0, v6
	v_add_f32_e32 v18, -1.0, v8
	v_sub_f32_e32 v6, v6, v18
	v_add_f32_e32 v5, v5, v6
	v_add_f32_e32 v6, v8, v5
	v_sub_f32_e32 v8, v6, v8
	v_sub_f32_e32 v5, v5, v8
	v_rcp_f32_e32 v8, v6
	v_cvt_f32_i32_e32 v4, v4
	v_cmp_neq_f32_e32 vcc, s35, v3
	v_mul_f32_e32 v18, v9, v8
	v_mul_f32_e32 v19, v6, v18
	v_fma_f32 v20, v18, v6, -v19
	v_fmac_f32_e32 v20, v18, v5
	v_add_f32_e32 v21, v19, v20
	v_sub_f32_e32 v22, v9, v21
	v_sub_f32_e32 v9, v9, v22
	v_sub_f32_e32 v19, v21, v19
	v_sub_f32_e32 v9, v9, v21
	v_add_f32_e32 v7, v7, v9
	v_sub_f32_e32 v9, v19, v20
	v_add_f32_e32 v7, v9, v7
	v_add_f32_e32 v9, v22, v7
	v_mul_f32_e32 v19, v8, v9
	v_mul_f32_e32 v20, v6, v19
	v_fma_f32 v6, v19, v6, -v20
	v_fmac_f32_e32 v6, v19, v5
	v_sub_f32_e32 v5, v22, v9
	v_add_f32_e32 v5, v7, v5
	v_add_f32_e32 v7, v20, v6
	v_sub_f32_e32 v21, v9, v7
	v_sub_f32_e32 v9, v9, v21
	v_sub_f32_e32 v20, v7, v20
	v_sub_f32_e32 v7, v9, v7
	v_add_f32_e32 v5, v5, v7
	v_sub_f32_e32 v6, v20, v6
	v_add_f32_e32 v5, v6, v5
	v_add_f32_e32 v6, v18, v19
	v_add_f32_e32 v5, v21, v5
	v_sub_f32_e32 v7, v6, v18
	v_mul_f32_e32 v5, v8, v5
	v_sub_f32_e32 v7, v19, v7
	v_add_f32_e32 v5, v7, v5
	v_mul_f32_e32 v18, 0x3f317218, v4
	v_add_f32_e32 v7, v6, v5
	v_fma_f32 v19, v4, s34, -v18
	v_mul_f32_e32 v8, v7, v7
	v_fmac_f32_e32 v19, 0xb102e308, v4
	v_sub_f32_e32 v4, v7, v6
	v_fmamk_f32 v9, v8, 0x3e9b6dac, v184
	v_sub_f32_e32 v4, v5, v4
	v_add_f32_e32 v5, v18, v19
	v_fmaak_f32 v9, v8, v9, 0x3f2aaada
	v_sub_f32_e32 v6, v5, v18
	v_ldexp_f32 v18, v7, 1
	v_mul_f32_e32 v7, v7, v8
	v_mul_f32_e32 v7, v7, v9
	v_add_f32_e32 v8, v18, v7
	v_sub_f32_e32 v9, v8, v18
	v_ldexp_f32 v4, v4, 1
	v_sub_f32_e32 v7, v7, v9
	v_add_f32_e32 v4, v4, v7
	v_add_f32_e32 v7, v8, v4
	v_sub_f32_e32 v8, v7, v8
	v_sub_f32_e32 v4, v4, v8
	v_add_f32_e32 v8, v5, v7
	v_sub_f32_e32 v9, v8, v5
	v_sub_f32_e32 v18, v8, v9
	v_sub_f32_e32 v6, v19, v6
	v_sub_f32_e32 v5, v5, v18
	v_sub_f32_e32 v7, v7, v9
	v_add_f32_e32 v5, v7, v5
	v_add_f32_e32 v7, v6, v4
	v_sub_f32_e32 v9, v7, v6
	v_sub_f32_e32 v18, v7, v9
	v_sub_f32_e32 v6, v6, v18
	v_sub_f32_e32 v4, v4, v9
	v_add_f32_e32 v5, v7, v5
	v_add_f32_e32 v4, v4, v6
	v_add_f32_e32 v6, v8, v5
	v_sub_f32_e32 v7, v6, v8
	v_sub_f32_e32 v5, v5, v7
	v_add_f32_e32 v4, v4, v5
	v_add_f32_e32 v4, v6, v4
	v_cndmask_b32_e32 v4, v185, v4, vcc
	v_cmp_ngt_f32_e32 vcc, -1.0, v3
	s_nop 1
	v_cndmask_b32_e32 v4, v186, v4, vcc
	v_cmp_neq_f32_e32 vcc, -1.0, v3
	s_nop 1
	v_cndmask_b32_e32 v4, v187, v4, vcc
	v_cmp_lt_f32_e64 vcc, |v3|, s36
	s_nop 1
	v_cndmask_b32_e32 v3, v4, v3, vcc
	v_add_f32_e32 v2, v2, v3
	v_sub_f32_e32 v2, -0.5, v2
	v_mul_f32_e32 v2, 0x3fb8aa3b, v2
	v_exp_f32_e32 v2, v2
	s_nop 0
	v_xor_b32_e32 v4, 0x80000000, v2
	v_lshl_add_u64 v[2:3], s[16:17], 0, v[24:25]
	v_lshl_add_u64 v[2:3], v[2:3], 0, v[50:51]
	global_store_dword v[2:3], v4, off
	v_mov_b32_e32 v2, v241
	v_add_f32_e32 v3, v10, v2
	v_max_f32_e64 v2, -v3, 0
	v_mul_f32_e64 v3, |v3|, s30
	v_exp_f32_e32 v3, v3
	s_nop 0
	v_add_f32_e32 v6, 1.0, v3
	v_add_f32_e32 v4, -1.0, v6
	v_sub_f32_e32 v5, v4, v6
	v_add_f32_e32 v5, 1.0, v5
	v_sub_f32_e32 v4, v3, v4
	v_add_f32_e32 v7, v4, v5
	v_frexp_mant_f32_e32 v4, v6
	v_cmp_gt_f32_e32 vcc, s31, v4
	v_cvt_f64_f32_e32 v[4:5], v6
	v_frexp_exp_i32_f64_e32 v4, v[4:5]
	v_subbrev_co_u32_e32 v4, vcc, 0, v4, vcc
	v_sub_u32_e32 v5, 0, v4
	v_ldexp_f32 v6, v6, v5
	v_ldexp_f32 v5, v7, v5
	v_add_f32_e32 v7, -1.0, v6
	v_add_f32_e32 v8, 1.0, v7
	v_sub_f32_e32 v8, v6, v8
	v_add_f32_e32 v8, v5, v8
	v_add_f32_e32 v9, v7, v8
	v_sub_f32_e32 v7, v9, v7
	v_sub_f32_e32 v7, v8, v7
	v_add_f32_e32 v8, 1.0, v6
	v_add_f32_e32 v10, -1.0, v8
	v_sub_f32_e32 v6, v6, v10
	v_add_f32_e32 v5, v5, v6
	v_add_f32_e32 v6, v8, v5
	v_sub_f32_e32 v8, v6, v8
	v_sub_f32_e32 v5, v5, v8
	v_rcp_f32_e32 v8, v6
	v_cvt_f32_i32_e32 v4, v4
	v_cmp_neq_f32_e32 vcc, s35, v3
	v_mul_f32_e32 v10, v9, v8
	v_mul_f32_e32 v18, v6, v10
	v_fma_f32 v19, v10, v6, -v18
	v_fmac_f32_e32 v19, v10, v5
	v_add_f32_e32 v20, v18, v19
	v_sub_f32_e32 v21, v9, v20
	v_sub_f32_e32 v9, v9, v21
	v_sub_f32_e32 v18, v20, v18
	v_sub_f32_e32 v9, v9, v20
	v_add_f32_e32 v7, v7, v9
	v_sub_f32_e32 v9, v18, v19
	v_add_f32_e32 v7, v9, v7
	v_add_f32_e32 v9, v21, v7
	v_mul_f32_e32 v18, v8, v9
	v_mul_f32_e32 v19, v6, v18
	v_fma_f32 v6, v18, v6, -v19
	v_fmac_f32_e32 v6, v18, v5
	v_sub_f32_e32 v5, v21, v9
	v_add_f32_e32 v5, v7, v5
	v_add_f32_e32 v7, v19, v6
	v_sub_f32_e32 v20, v9, v7
	v_sub_f32_e32 v9, v9, v20
	v_sub_f32_e32 v19, v7, v19
	v_sub_f32_e32 v7, v9, v7
	v_add_f32_e32 v5, v5, v7
	v_sub_f32_e32 v6, v19, v6
	v_add_f32_e32 v5, v6, v5
	v_add_f32_e32 v6, v10, v18
	v_add_f32_e32 v5, v20, v5
	v_sub_f32_e32 v7, v6, v10
	v_mul_f32_e32 v5, v8, v5
	v_sub_f32_e32 v7, v18, v7
	v_add_f32_e32 v5, v7, v5
	v_mul_f32_e32 v10, 0x3f317218, v4
	v_add_f32_e32 v7, v6, v5
	v_fma_f32 v18, v4, s34, -v10
	v_mul_f32_e32 v8, v7, v7
	v_fmac_f32_e32 v18, 0xb102e308, v4
	v_sub_f32_e32 v4, v7, v6
	v_fmamk_f32 v9, v8, 0x3e9b6dac, v184
	v_sub_f32_e32 v4, v5, v4
	v_add_f32_e32 v5, v10, v18
	v_fmaak_f32 v9, v8, v9, 0x3f2aaada
	v_sub_f32_e32 v6, v5, v10
	v_ldexp_f32 v10, v7, 1
	v_mul_f32_e32 v7, v7, v8
	v_mul_f32_e32 v7, v7, v9
	v_add_f32_e32 v8, v10, v7
	v_sub_f32_e32 v9, v8, v10
	v_ldexp_f32 v4, v4, 1
	v_sub_f32_e32 v7, v7, v9
	v_add_f32_e32 v4, v4, v7
	v_add_f32_e32 v7, v8, v4
	v_sub_f32_e32 v8, v7, v8
	v_sub_f32_e32 v4, v4, v8
	v_add_f32_e32 v8, v5, v7
	v_sub_f32_e32 v9, v8, v5
	v_sub_f32_e32 v10, v8, v9
	v_sub_f32_e32 v6, v18, v6
	v_sub_f32_e32 v5, v5, v10
	v_sub_f32_e32 v7, v7, v9
	v_add_f32_e32 v5, v7, v5
	v_add_f32_e32 v7, v6, v4
	v_sub_f32_e32 v9, v7, v6
	v_sub_f32_e32 v10, v7, v9
	v_sub_f32_e32 v6, v6, v10
	v_sub_f32_e32 v4, v4, v9
	v_add_f32_e32 v5, v7, v5
	v_add_f32_e32 v4, v4, v6
	v_add_f32_e32 v6, v8, v5
	v_sub_f32_e32 v7, v6, v8
	v_sub_f32_e32 v5, v5, v7
	v_add_f32_e32 v4, v4, v5
	v_add_f32_e32 v4, v6, v4
	v_cndmask_b32_e32 v4, v185, v4, vcc
	v_cmp_ngt_f32_e32 vcc, -1.0, v3
	s_nop 1
	v_cndmask_b32_e32 v4, v186, v4, vcc
	v_cmp_neq_f32_e32 vcc, -1.0, v3
	s_nop 1
	v_cndmask_b32_e32 v4, v187, v4, vcc
	v_cmp_lt_f32_e64 vcc, |v3|, s36
	s_nop 1
	v_cndmask_b32_e32 v3, v4, v3, vcc
	v_add_f32_e32 v2, v2, v3
	v_sub_f32_e32 v2, -0.5, v2
	v_mul_f32_e32 v2, 0x3fb8aa3b, v2
	v_exp_f32_e32 v2, v2
	s_nop 0
	v_xor_b32_e32 v4, 0x80000000, v2
	v_lshl_add_u64 v[2:3], s[16:17], 0, v[42:43]
	v_lshl_add_u64 v[2:3], v[2:3], 0, v[50:51]
	global_store_dword v[2:3], v4, off
	v_mov_b32_e32 v2, v241
	v_add_f32_e32 v3, v11, v2
	v_max_f32_e64 v2, -v3, 0
	v_mul_f32_e64 v3, |v3|, s30
	v_exp_f32_e32 v3, v3
	s_nop 0
	v_add_f32_e32 v6, 1.0, v3
	v_add_f32_e32 v4, -1.0, v6
	v_sub_f32_e32 v5, v4, v6
	v_add_f32_e32 v5, 1.0, v5
	v_sub_f32_e32 v4, v3, v4
	v_add_f32_e32 v7, v4, v5
	v_frexp_mant_f32_e32 v4, v6
	v_cmp_gt_f32_e32 vcc, s31, v4
	v_cvt_f64_f32_e32 v[4:5], v6
	v_frexp_exp_i32_f64_e32 v4, v[4:5]
	v_subbrev_co_u32_e32 v4, vcc, 0, v4, vcc
	v_sub_u32_e32 v5, 0, v4
	v_ldexp_f32 v6, v6, v5
	v_ldexp_f32 v5, v7, v5
	v_add_f32_e32 v7, -1.0, v6
	v_add_f32_e32 v8, 1.0, v7
	v_sub_f32_e32 v8, v6, v8
	v_add_f32_e32 v8, v5, v8
	v_add_f32_e32 v9, v7, v8
	v_sub_f32_e32 v7, v9, v7
	v_sub_f32_e32 v7, v8, v7
	v_add_f32_e32 v8, 1.0, v6
	v_add_f32_e32 v10, -1.0, v8
	v_sub_f32_e32 v6, v6, v10
	v_add_f32_e32 v5, v5, v6
	v_add_f32_e32 v6, v8, v5
	v_sub_f32_e32 v8, v6, v8
	v_sub_f32_e32 v5, v5, v8
	v_rcp_f32_e32 v8, v6
	v_cvt_f32_i32_e32 v4, v4
	v_cmp_neq_f32_e32 vcc, s35, v3
	v_mul_f32_e32 v10, v9, v8
	v_mul_f32_e32 v11, v6, v10
	v_fma_f32 v18, v10, v6, -v11
	v_fmac_f32_e32 v18, v10, v5
	v_add_f32_e32 v19, v11, v18
	v_sub_f32_e32 v20, v9, v19
	v_sub_f32_e32 v9, v9, v20
	v_sub_f32_e32 v11, v19, v11
	v_sub_f32_e32 v9, v9, v19
	v_add_f32_e32 v7, v7, v9
	v_sub_f32_e32 v9, v11, v18
	v_add_f32_e32 v7, v9, v7
	v_add_f32_e32 v9, v20, v7
	v_mul_f32_e32 v11, v8, v9
	v_mul_f32_e32 v18, v6, v11
	v_fma_f32 v6, v11, v6, -v18
	v_fmac_f32_e32 v6, v11, v5
	v_sub_f32_e32 v5, v20, v9
	v_add_f32_e32 v5, v7, v5
	v_add_f32_e32 v7, v18, v6
	v_sub_f32_e32 v19, v9, v7
	v_sub_f32_e32 v9, v9, v19
	v_sub_f32_e32 v18, v7, v18
	v_sub_f32_e32 v7, v9, v7
	v_add_f32_e32 v5, v5, v7
	v_sub_f32_e32 v6, v18, v6
	v_add_f32_e32 v5, v6, v5
	v_add_f32_e32 v6, v10, v11
	v_add_f32_e32 v5, v19, v5
	v_sub_f32_e32 v7, v6, v10
	v_mul_f32_e32 v5, v8, v5
	v_sub_f32_e32 v7, v11, v7
	v_add_f32_e32 v5, v7, v5
	v_mul_f32_e32 v10, 0x3f317218, v4
	v_add_f32_e32 v7, v6, v5
	v_fma_f32 v11, v4, s34, -v10
	v_mul_f32_e32 v8, v7, v7
	v_fmac_f32_e32 v11, 0xb102e308, v4
	v_sub_f32_e32 v4, v7, v6
	v_fmamk_f32 v9, v8, 0x3e9b6dac, v184
	v_sub_f32_e32 v4, v5, v4
	v_add_f32_e32 v5, v10, v11
	v_fmaak_f32 v9, v8, v9, 0x3f2aaada
	v_sub_f32_e32 v6, v5, v10
	v_ldexp_f32 v10, v7, 1
	v_mul_f32_e32 v7, v7, v8
	v_mul_f32_e32 v7, v7, v9
	v_add_f32_e32 v8, v10, v7
	v_sub_f32_e32 v9, v8, v10
	v_ldexp_f32 v4, v4, 1
	v_sub_f32_e32 v7, v7, v9
	v_add_f32_e32 v4, v4, v7
	v_add_f32_e32 v7, v8, v4
	v_sub_f32_e32 v8, v7, v8
	v_sub_f32_e32 v4, v4, v8
	v_add_f32_e32 v8, v5, v7
	v_sub_f32_e32 v9, v8, v5
	v_sub_f32_e32 v10, v8, v9
	v_sub_f32_e32 v6, v11, v6
	v_sub_f32_e32 v5, v5, v10
	v_sub_f32_e32 v7, v7, v9
	v_add_f32_e32 v5, v7, v5
	v_add_f32_e32 v7, v6, v4
	v_sub_f32_e32 v9, v7, v6
	v_sub_f32_e32 v10, v7, v9
	v_sub_f32_e32 v6, v6, v10
	v_sub_f32_e32 v4, v4, v9
	v_add_f32_e32 v5, v7, v5
	v_add_f32_e32 v4, v4, v6
	v_add_f32_e32 v6, v8, v5
	v_sub_f32_e32 v7, v6, v8
	v_sub_f32_e32 v5, v5, v7
	v_add_f32_e32 v4, v4, v5
	v_add_f32_e32 v4, v6, v4
	v_cndmask_b32_e32 v4, v185, v4, vcc
	v_cmp_ngt_f32_e32 vcc, -1.0, v3
	s_nop 1
	v_cndmask_b32_e32 v4, v186, v4, vcc
	v_cmp_neq_f32_e32 vcc, -1.0, v3
	s_nop 1
	v_cndmask_b32_e32 v4, v187, v4, vcc
	v_cmp_lt_f32_e64 vcc, |v3|, s36
	s_nop 1
	v_cndmask_b32_e32 v3, v4, v3, vcc
	v_add_f32_e32 v2, v2, v3
	v_sub_f32_e32 v2, -0.5, v2
	v_mul_f32_e32 v2, 0x3fb8aa3b, v2
	v_exp_f32_e32 v2, v2
	s_nop 0
	v_xor_b32_e32 v4, 0x80000000, v2
	v_lshl_add_u64 v[2:3], s[16:17], 0, v[26:27]
	v_lshl_add_u64 v[2:3], v[2:3], 0, v[50:51]
	global_store_dword v[2:3], v4, off
	v_mov_b32_e32 v2, v241
	v_add_f32_e32 v3, v12, v2
	v_max_f32_e64 v2, -v3, 0
	v_mul_f32_e64 v3, |v3|, s30
	v_exp_f32_e32 v3, v3
	s_nop 0
	v_add_f32_e32 v6, 1.0, v3
	v_add_f32_e32 v4, -1.0, v6
	v_sub_f32_e32 v5, v4, v6
	v_add_f32_e32 v5, 1.0, v5
	v_sub_f32_e32 v4, v3, v4
	v_add_f32_e32 v7, v4, v5
	v_frexp_mant_f32_e32 v4, v6
	v_cmp_gt_f32_e32 vcc, s31, v4
	v_cvt_f64_f32_e32 v[4:5], v6
	v_frexp_exp_i32_f64_e32 v4, v[4:5]
	v_subbrev_co_u32_e32 v4, vcc, 0, v4, vcc
	v_sub_u32_e32 v5, 0, v4
	v_ldexp_f32 v6, v6, v5
	v_ldexp_f32 v5, v7, v5
	v_add_f32_e32 v7, -1.0, v6
	v_add_f32_e32 v8, 1.0, v7
	v_sub_f32_e32 v8, v6, v8
	v_add_f32_e32 v8, v5, v8
	v_add_f32_e32 v9, v7, v8
	v_sub_f32_e32 v7, v9, v7
	v_sub_f32_e32 v7, v8, v7
	v_add_f32_e32 v8, 1.0, v6
	v_add_f32_e32 v10, -1.0, v8
	v_sub_f32_e32 v6, v6, v10
	v_add_f32_e32 v5, v5, v6
	v_add_f32_e32 v6, v8, v5
	v_sub_f32_e32 v8, v6, v8
	v_sub_f32_e32 v5, v5, v8
	v_rcp_f32_e32 v8, v6
	v_cvt_f32_i32_e32 v4, v4
	v_cmp_neq_f32_e32 vcc, s35, v3
	v_mul_f32_e32 v10, v9, v8
	v_mul_f32_e32 v11, v6, v10
	v_fma_f32 v12, v10, v6, -v11
	v_fmac_f32_e32 v12, v10, v5
	v_add_f32_e32 v18, v11, v12
	v_sub_f32_e32 v19, v9, v18
	v_sub_f32_e32 v9, v9, v19
	v_sub_f32_e32 v11, v18, v11
	v_sub_f32_e32 v9, v9, v18
	v_add_f32_e32 v7, v7, v9
	v_sub_f32_e32 v9, v11, v12
	v_add_f32_e32 v7, v9, v7
	v_add_f32_e32 v9, v19, v7
	v_mul_f32_e32 v11, v8, v9
	v_mul_f32_e32 v12, v6, v11
	v_fma_f32 v6, v11, v6, -v12
	v_fmac_f32_e32 v6, v11, v5
	v_sub_f32_e32 v5, v19, v9
	v_add_f32_e32 v5, v7, v5
	v_add_f32_e32 v7, v12, v6
	v_sub_f32_e32 v18, v9, v7
	v_sub_f32_e32 v9, v9, v18
	v_sub_f32_e32 v12, v7, v12
	v_sub_f32_e32 v7, v9, v7
	v_add_f32_e32 v5, v5, v7
	v_sub_f32_e32 v6, v12, v6
	v_add_f32_e32 v5, v6, v5
	v_add_f32_e32 v6, v10, v11
	v_add_f32_e32 v5, v18, v5
	v_sub_f32_e32 v7, v6, v10
	v_mul_f32_e32 v5, v8, v5
	v_sub_f32_e32 v7, v11, v7
	v_add_f32_e32 v5, v7, v5
	v_mul_f32_e32 v10, 0x3f317218, v4
	v_add_f32_e32 v7, v6, v5
	v_fma_f32 v11, v4, s34, -v10
	v_mul_f32_e32 v8, v7, v7
	v_fmac_f32_e32 v11, 0xb102e308, v4
	v_sub_f32_e32 v4, v7, v6
	v_fmamk_f32 v9, v8, 0x3e9b6dac, v184
	v_sub_f32_e32 v4, v5, v4
	v_add_f32_e32 v5, v10, v11
	v_fmaak_f32 v9, v8, v9, 0x3f2aaada
	v_sub_f32_e32 v6, v5, v10
	v_ldexp_f32 v10, v7, 1
	v_mul_f32_e32 v7, v7, v8
	v_mul_f32_e32 v7, v7, v9
	v_add_f32_e32 v8, v10, v7
	v_sub_f32_e32 v9, v8, v10
	v_ldexp_f32 v4, v4, 1
	v_sub_f32_e32 v7, v7, v9
	v_add_f32_e32 v4, v4, v7
	v_add_f32_e32 v7, v8, v4
	v_sub_f32_e32 v8, v7, v8
	v_sub_f32_e32 v4, v4, v8
	v_add_f32_e32 v8, v5, v7
	v_sub_f32_e32 v9, v8, v5
	v_sub_f32_e32 v10, v8, v9
	v_sub_f32_e32 v6, v11, v6
	v_sub_f32_e32 v5, v5, v10
	v_sub_f32_e32 v7, v7, v9
	v_add_f32_e32 v5, v7, v5
	v_add_f32_e32 v7, v6, v4
	v_sub_f32_e32 v9, v7, v6
	v_sub_f32_e32 v10, v7, v9
	v_sub_f32_e32 v6, v6, v10
	v_sub_f32_e32 v4, v4, v9
	v_add_f32_e32 v5, v7, v5
	v_add_f32_e32 v4, v4, v6
	v_add_f32_e32 v6, v8, v5
	v_sub_f32_e32 v7, v6, v8
	v_sub_f32_e32 v5, v5, v7
	v_add_f32_e32 v4, v4, v5
	v_add_f32_e32 v4, v6, v4
	v_cndmask_b32_e32 v4, v185, v4, vcc
	v_cmp_ngt_f32_e32 vcc, -1.0, v3
	s_nop 1
	v_cndmask_b32_e32 v4, v186, v4, vcc
	v_cmp_neq_f32_e32 vcc, -1.0, v3
	s_nop 1
	v_cndmask_b32_e32 v4, v187, v4, vcc
	v_cmp_lt_f32_e64 vcc, |v3|, s36
	s_nop 1
	v_cndmask_b32_e32 v3, v4, v3, vcc
	v_add_f32_e32 v2, v2, v3
	v_sub_f32_e32 v2, -0.5, v2
	v_mul_f32_e32 v2, 0x3fb8aa3b, v2
	v_exp_f32_e32 v2, v2
	s_nop 0
	v_xor_b32_e32 v4, 0x80000000, v2
	v_lshl_add_u64 v[2:3], s[16:17], 0, v[44:45]
	v_lshl_add_u64 v[2:3], v[2:3], 0, v[50:51]
	global_store_dword v[2:3], v4, off
	v_mov_b32_e32 v2, v241
	v_add_f32_e32 v3, v13, v2
	v_max_f32_e64 v2, -v3, 0
	v_mul_f32_e64 v3, |v3|, s30
	v_exp_f32_e32 v3, v3
	s_nop 0
	v_add_f32_e32 v6, 1.0, v3
	v_add_f32_e32 v4, -1.0, v6
	v_sub_f32_e32 v5, v4, v6
	v_add_f32_e32 v5, 1.0, v5
	v_sub_f32_e32 v4, v3, v4
	v_add_f32_e32 v7, v4, v5
	v_frexp_mant_f32_e32 v4, v6
	v_cmp_gt_f32_e32 vcc, s31, v4
	v_cvt_f64_f32_e32 v[4:5], v6
	v_frexp_exp_i32_f64_e32 v4, v[4:5]
	v_subbrev_co_u32_e32 v4, vcc, 0, v4, vcc
	v_sub_u32_e32 v5, 0, v4
	v_ldexp_f32 v6, v6, v5
	v_ldexp_f32 v5, v7, v5
	v_add_f32_e32 v7, -1.0, v6
	v_add_f32_e32 v8, 1.0, v7
	v_sub_f32_e32 v8, v6, v8
	v_add_f32_e32 v8, v5, v8
	v_add_f32_e32 v9, v7, v8
	v_sub_f32_e32 v7, v9, v7
	v_sub_f32_e32 v7, v8, v7
	v_add_f32_e32 v8, 1.0, v6
	v_add_f32_e32 v10, -1.0, v8
	v_sub_f32_e32 v6, v6, v10
	v_add_f32_e32 v5, v5, v6
	v_add_f32_e32 v6, v8, v5
	v_sub_f32_e32 v8, v6, v8
	v_sub_f32_e32 v5, v5, v8
	v_rcp_f32_e32 v8, v6
	v_cvt_f32_i32_e32 v4, v4
	v_cmp_neq_f32_e32 vcc, s35, v3
	v_mul_f32_e32 v10, v9, v8
	v_mul_f32_e32 v11, v6, v10
	v_fma_f32 v12, v10, v6, -v11
	v_fmac_f32_e32 v12, v10, v5
	v_add_f32_e32 v13, v11, v12
	v_sub_f32_e32 v18, v9, v13
	v_sub_f32_e32 v9, v9, v18
	v_sub_f32_e32 v11, v13, v11
	v_sub_f32_e32 v9, v9, v13
	v_add_f32_e32 v7, v7, v9
	v_sub_f32_e32 v9, v11, v12
	v_add_f32_e32 v7, v9, v7
	v_add_f32_e32 v9, v18, v7
	v_mul_f32_e32 v11, v8, v9
	v_mul_f32_e32 v12, v6, v11
	v_fma_f32 v6, v11, v6, -v12
	v_fmac_f32_e32 v6, v11, v5
	v_sub_f32_e32 v5, v18, v9
	v_add_f32_e32 v5, v7, v5
	v_add_f32_e32 v7, v12, v6
	v_sub_f32_e32 v13, v9, v7
	v_sub_f32_e32 v9, v9, v13
	v_sub_f32_e32 v12, v7, v12
	v_sub_f32_e32 v7, v9, v7
	v_add_f32_e32 v5, v5, v7
	v_sub_f32_e32 v6, v12, v6
	v_add_f32_e32 v5, v6, v5
	v_add_f32_e32 v6, v10, v11
	v_add_f32_e32 v5, v13, v5
	v_sub_f32_e32 v7, v6, v10
	v_mul_f32_e32 v5, v8, v5
	v_sub_f32_e32 v7, v11, v7
	v_add_f32_e32 v5, v7, v5
	v_mul_f32_e32 v10, 0x3f317218, v4
	v_add_f32_e32 v7, v6, v5
	v_fma_f32 v11, v4, s34, -v10
	v_mul_f32_e32 v8, v7, v7
	v_fmac_f32_e32 v11, 0xb102e308, v4
	v_sub_f32_e32 v4, v7, v6
	v_fmamk_f32 v9, v8, 0x3e9b6dac, v184
	v_sub_f32_e32 v4, v5, v4
	v_add_f32_e32 v5, v10, v11
	v_fmaak_f32 v9, v8, v9, 0x3f2aaada
	v_sub_f32_e32 v6, v5, v10
	v_ldexp_f32 v10, v7, 1
	v_mul_f32_e32 v7, v7, v8
	v_mul_f32_e32 v7, v7, v9
	v_add_f32_e32 v8, v10, v7
	v_sub_f32_e32 v9, v8, v10
	v_ldexp_f32 v4, v4, 1
	v_sub_f32_e32 v7, v7, v9
	v_add_f32_e32 v4, v4, v7
	v_add_f32_e32 v7, v8, v4
	v_sub_f32_e32 v8, v7, v8
	v_sub_f32_e32 v4, v4, v8
	v_add_f32_e32 v8, v5, v7
	v_sub_f32_e32 v9, v8, v5
	v_sub_f32_e32 v10, v8, v9
	v_sub_f32_e32 v6, v11, v6
	v_sub_f32_e32 v5, v5, v10
	v_sub_f32_e32 v7, v7, v9
	v_add_f32_e32 v5, v7, v5
	v_add_f32_e32 v7, v6, v4
	v_sub_f32_e32 v9, v7, v6
	v_sub_f32_e32 v10, v7, v9
	v_sub_f32_e32 v6, v6, v10
	v_sub_f32_e32 v4, v4, v9
	v_add_f32_e32 v5, v7, v5
	v_add_f32_e32 v4, v4, v6
	v_add_f32_e32 v6, v8, v5
	v_sub_f32_e32 v7, v6, v8
	v_sub_f32_e32 v5, v5, v7
	v_add_f32_e32 v4, v4, v5
	v_add_f32_e32 v4, v6, v4
	v_cndmask_b32_e32 v4, v185, v4, vcc
	v_cmp_ngt_f32_e32 vcc, -1.0, v3
	s_nop 1
	v_cndmask_b32_e32 v4, v186, v4, vcc
	v_cmp_neq_f32_e32 vcc, -1.0, v3
	s_nop 1
	v_cndmask_b32_e32 v4, v187, v4, vcc
	v_cmp_lt_f32_e64 vcc, |v3|, s36
	s_nop 1
	v_cndmask_b32_e32 v3, v4, v3, vcc
	v_add_f32_e32 v2, v2, v3
	v_sub_f32_e32 v2, -0.5, v2
	v_mul_f32_e32 v2, 0x3fb8aa3b, v2
	v_exp_f32_e32 v2, v2
	s_nop 0
	v_xor_b32_e32 v4, 0x80000000, v2
	v_lshl_add_u64 v[2:3], s[16:17], 0, v[28:29]
	v_lshl_add_u64 v[2:3], v[2:3], 0, v[50:51]
	global_store_dword v[2:3], v4, off
	v_mov_b32_e32 v2, v241
	v_add_f32_e32 v3, v14, v2
	v_max_f32_e64 v2, -v3, 0
	v_mul_f32_e64 v3, |v3|, s30
	v_exp_f32_e32 v3, v3
	s_nop 0
	v_add_f32_e32 v6, 1.0, v3
	v_add_f32_e32 v4, -1.0, v6
	v_sub_f32_e32 v5, v4, v6
	v_add_f32_e32 v5, 1.0, v5
	v_sub_f32_e32 v4, v3, v4
	v_add_f32_e32 v7, v4, v5
	v_frexp_mant_f32_e32 v4, v6
	v_cmp_gt_f32_e32 vcc, s31, v4
	v_cvt_f64_f32_e32 v[4:5], v6
	v_frexp_exp_i32_f64_e32 v4, v[4:5]
	v_subbrev_co_u32_e32 v4, vcc, 0, v4, vcc
	v_sub_u32_e32 v5, 0, v4
	v_ldexp_f32 v6, v6, v5
	v_ldexp_f32 v5, v7, v5
	v_add_f32_e32 v7, -1.0, v6
	v_add_f32_e32 v8, 1.0, v7
	v_sub_f32_e32 v8, v6, v8
	v_add_f32_e32 v8, v5, v8
	v_add_f32_e32 v9, v7, v8
	v_sub_f32_e32 v7, v9, v7
	v_sub_f32_e32 v7, v8, v7
	v_add_f32_e32 v8, 1.0, v6
	v_add_f32_e32 v10, -1.0, v8
	v_sub_f32_e32 v6, v6, v10
	v_add_f32_e32 v5, v5, v6
	v_add_f32_e32 v6, v8, v5
	v_sub_f32_e32 v8, v6, v8
	v_sub_f32_e32 v5, v5, v8
	v_rcp_f32_e32 v8, v6
	v_cvt_f32_i32_e32 v4, v4
	v_cmp_neq_f32_e32 vcc, s35, v3
	v_mul_f32_e32 v10, v9, v8
	v_mul_f32_e32 v11, v6, v10
	v_fma_f32 v12, v10, v6, -v11
	v_fmac_f32_e32 v12, v10, v5
	v_add_f32_e32 v13, v11, v12
	v_sub_f32_e32 v14, v9, v13
	v_sub_f32_e32 v9, v9, v14
	v_sub_f32_e32 v11, v13, v11
	v_sub_f32_e32 v9, v9, v13
	v_add_f32_e32 v7, v7, v9
	v_sub_f32_e32 v9, v11, v12
	v_add_f32_e32 v7, v9, v7
	v_add_f32_e32 v9, v14, v7
	v_mul_f32_e32 v11, v8, v9
	v_mul_f32_e32 v12, v6, v11
	v_fma_f32 v6, v11, v6, -v12
	v_fmac_f32_e32 v6, v11, v5
	v_sub_f32_e32 v5, v14, v9
	v_add_f32_e32 v5, v7, v5
	v_add_f32_e32 v7, v12, v6
	v_sub_f32_e32 v13, v9, v7
	v_sub_f32_e32 v9, v9, v13
	v_sub_f32_e32 v12, v7, v12
	v_sub_f32_e32 v7, v9, v7
	v_add_f32_e32 v5, v5, v7
	v_sub_f32_e32 v6, v12, v6
	v_add_f32_e32 v5, v6, v5
	v_add_f32_e32 v6, v10, v11
	v_add_f32_e32 v5, v13, v5
	v_sub_f32_e32 v7, v6, v10
	v_mul_f32_e32 v5, v8, v5
	v_sub_f32_e32 v7, v11, v7
	v_add_f32_e32 v5, v7, v5
	v_mul_f32_e32 v10, 0x3f317218, v4
	v_add_f32_e32 v7, v6, v5
	v_fma_f32 v11, v4, s34, -v10
	v_mul_f32_e32 v8, v7, v7
	v_fmac_f32_e32 v11, 0xb102e308, v4
	v_sub_f32_e32 v4, v7, v6
	v_fmamk_f32 v9, v8, 0x3e9b6dac, v184
	v_sub_f32_e32 v4, v5, v4
	v_add_f32_e32 v5, v10, v11
	v_fmaak_f32 v9, v8, v9, 0x3f2aaada
	v_sub_f32_e32 v6, v5, v10
	v_ldexp_f32 v10, v7, 1
	v_mul_f32_e32 v7, v7, v8
	v_mul_f32_e32 v7, v7, v9
	v_add_f32_e32 v8, v10, v7
	v_sub_f32_e32 v9, v8, v10
	v_ldexp_f32 v4, v4, 1
	v_sub_f32_e32 v7, v7, v9
	v_add_f32_e32 v4, v4, v7
	v_add_f32_e32 v7, v8, v4
	v_sub_f32_e32 v8, v7, v8
	v_sub_f32_e32 v4, v4, v8
	v_add_f32_e32 v8, v5, v7
	v_sub_f32_e32 v9, v8, v5
	v_sub_f32_e32 v10, v8, v9
	v_sub_f32_e32 v6, v11, v6
	v_sub_f32_e32 v5, v5, v10
	v_sub_f32_e32 v7, v7, v9
	v_add_f32_e32 v5, v7, v5
	v_add_f32_e32 v7, v6, v4
	v_sub_f32_e32 v9, v7, v6
	v_sub_f32_e32 v10, v7, v9
	v_sub_f32_e32 v6, v6, v10
	v_sub_f32_e32 v4, v4, v9
	v_add_f32_e32 v5, v7, v5
	v_add_f32_e32 v4, v4, v6
	v_add_f32_e32 v6, v8, v5
	v_sub_f32_e32 v7, v6, v8
	v_sub_f32_e32 v5, v5, v7
	v_add_f32_e32 v4, v4, v5
	v_add_f32_e32 v4, v6, v4
	v_cndmask_b32_e32 v4, v185, v4, vcc
	v_cmp_ngt_f32_e32 vcc, -1.0, v3
	s_nop 1
	v_cndmask_b32_e32 v4, v186, v4, vcc
	v_cmp_neq_f32_e32 vcc, -1.0, v3
	s_nop 1
	v_cndmask_b32_e32 v4, v187, v4, vcc
	v_cmp_lt_f32_e64 vcc, |v3|, s36
	s_nop 1
	v_cndmask_b32_e32 v3, v4, v3, vcc
	v_add_f32_e32 v2, v2, v3
	v_sub_f32_e32 v2, -0.5, v2
	v_mul_f32_e32 v2, 0x3fb8aa3b, v2
	v_exp_f32_e32 v2, v2
	s_nop 0
	v_xor_b32_e32 v4, 0x80000000, v2
	v_lshl_add_u64 v[2:3], s[16:17], 0, v[46:47]
	v_lshl_add_u64 v[2:3], v[2:3], 0, v[50:51]
	global_store_dword v[2:3], v4, off
	v_mov_b32_e32 v2, v241
	v_add_f32_e32 v3, v15, v2
	v_max_f32_e64 v2, -v3, 0
	v_mul_f32_e64 v3, |v3|, s30
	v_exp_f32_e32 v3, v3
	s_nop 0
	v_add_f32_e32 v6, 1.0, v3
	v_add_f32_e32 v4, -1.0, v6
	v_sub_f32_e32 v5, v4, v6
	v_add_f32_e32 v5, 1.0, v5
	v_sub_f32_e32 v4, v3, v4
	v_add_f32_e32 v7, v4, v5
	v_frexp_mant_f32_e32 v4, v6
	v_cmp_gt_f32_e32 vcc, s31, v4
	v_cvt_f64_f32_e32 v[4:5], v6
	v_frexp_exp_i32_f64_e32 v4, v[4:5]
	v_subbrev_co_u32_e32 v4, vcc, 0, v4, vcc
	v_sub_u32_e32 v5, 0, v4
	v_ldexp_f32 v6, v6, v5
	v_ldexp_f32 v5, v7, v5
	v_add_f32_e32 v7, -1.0, v6
	v_add_f32_e32 v8, 1.0, v7
	v_sub_f32_e32 v8, v6, v8
	v_add_f32_e32 v8, v5, v8
	v_add_f32_e32 v9, v7, v8
	v_sub_f32_e32 v7, v9, v7
	v_sub_f32_e32 v7, v8, v7
	v_add_f32_e32 v8, 1.0, v6
	v_add_f32_e32 v10, -1.0, v8
	v_sub_f32_e32 v6, v6, v10
	v_add_f32_e32 v5, v5, v6
	v_add_f32_e32 v6, v8, v5
	v_sub_f32_e32 v8, v6, v8
	v_sub_f32_e32 v5, v5, v8
	v_rcp_f32_e32 v8, v6
	v_cvt_f32_i32_e32 v4, v4
	v_cmp_neq_f32_e32 vcc, s35, v3
	v_mul_f32_e32 v10, v9, v8
	v_mul_f32_e32 v11, v6, v10
	v_fma_f32 v12, v10, v6, -v11
	v_fmac_f32_e32 v12, v10, v5
	v_add_f32_e32 v13, v11, v12
	v_sub_f32_e32 v14, v9, v13
	v_sub_f32_e32 v9, v9, v14
	v_sub_f32_e32 v11, v13, v11
	v_sub_f32_e32 v9, v9, v13
	v_add_f32_e32 v7, v7, v9
	v_sub_f32_e32 v9, v11, v12
	v_add_f32_e32 v7, v9, v7
	v_add_f32_e32 v9, v14, v7
	v_mul_f32_e32 v11, v8, v9
	v_mul_f32_e32 v12, v6, v11
	v_fma_f32 v6, v11, v6, -v12
	v_fmac_f32_e32 v6, v11, v5
	v_sub_f32_e32 v5, v14, v9
	v_add_f32_e32 v5, v7, v5
	v_add_f32_e32 v7, v12, v6
	v_sub_f32_e32 v13, v9, v7
	v_sub_f32_e32 v9, v9, v13
	v_sub_f32_e32 v12, v7, v12
	v_sub_f32_e32 v7, v9, v7
	v_add_f32_e32 v5, v5, v7
	v_sub_f32_e32 v6, v12, v6
	v_add_f32_e32 v5, v6, v5
	v_add_f32_e32 v6, v10, v11
	v_add_f32_e32 v5, v13, v5
	v_sub_f32_e32 v7, v6, v10
	v_mul_f32_e32 v5, v8, v5
	v_sub_f32_e32 v7, v11, v7
	v_add_f32_e32 v5, v7, v5
	v_mul_f32_e32 v10, 0x3f317218, v4
	v_add_f32_e32 v7, v6, v5
	v_fma_f32 v11, v4, s34, -v10
	v_mul_f32_e32 v8, v7, v7
	v_fmac_f32_e32 v11, 0xb102e308, v4
	v_sub_f32_e32 v4, v7, v6
	v_fmamk_f32 v9, v8, 0x3e9b6dac, v184
	v_sub_f32_e32 v4, v5, v4
	v_add_f32_e32 v5, v10, v11
	v_fmaak_f32 v9, v8, v9, 0x3f2aaada
	v_sub_f32_e32 v6, v5, v10
	v_ldexp_f32 v10, v7, 1
	v_mul_f32_e32 v7, v7, v8
	v_mul_f32_e32 v7, v7, v9
	v_add_f32_e32 v8, v10, v7
	v_sub_f32_e32 v9, v8, v10
	v_ldexp_f32 v4, v4, 1
	v_sub_f32_e32 v7, v7, v9
	v_add_f32_e32 v4, v4, v7
	v_add_f32_e32 v7, v8, v4
	v_sub_f32_e32 v8, v7, v8
	v_sub_f32_e32 v4, v4, v8
	v_add_f32_e32 v8, v5, v7
	v_sub_f32_e32 v9, v8, v5
	v_sub_f32_e32 v10, v8, v9
	v_sub_f32_e32 v6, v11, v6
	v_sub_f32_e32 v5, v5, v10
	v_sub_f32_e32 v7, v7, v9
	v_add_f32_e32 v5, v7, v5
	v_add_f32_e32 v7, v6, v4
	v_sub_f32_e32 v9, v7, v6
	v_sub_f32_e32 v10, v7, v9
	v_sub_f32_e32 v6, v6, v10
	v_sub_f32_e32 v4, v4, v9
	v_add_f32_e32 v5, v7, v5
	v_add_f32_e32 v4, v4, v6
	v_add_f32_e32 v6, v8, v5
	v_sub_f32_e32 v7, v6, v8
	v_sub_f32_e32 v5, v5, v7
	v_add_f32_e32 v4, v4, v5
	v_add_f32_e32 v4, v6, v4
	v_cndmask_b32_e32 v4, v185, v4, vcc
	v_cmp_ngt_f32_e32 vcc, -1.0, v3
	s_nop 1
	v_cndmask_b32_e32 v4, v186, v4, vcc
	v_cmp_neq_f32_e32 vcc, -1.0, v3
	s_nop 1
	v_cndmask_b32_e32 v4, v187, v4, vcc
	v_cmp_lt_f32_e64 vcc, |v3|, s36
	s_nop 1
	v_cndmask_b32_e32 v3, v4, v3, vcc
	v_add_f32_e32 v2, v2, v3
	v_sub_f32_e32 v2, -0.5, v2
	v_mul_f32_e32 v2, 0x3fb8aa3b, v2
	v_exp_f32_e32 v2, v2
	s_nop 0
	v_xor_b32_e32 v4, 0x80000000, v2
	v_lshl_add_u64 v[2:3], s[16:17], 0, v[30:31]
	v_lshl_add_u64 v[2:3], v[2:3], 0, v[50:51]
	global_store_dword v[2:3], v4, off
	v_mov_b32_e32 v2, v241
	v_add_f32_e32 v3, v16, v2
	v_max_f32_e64 v2, -v3, 0
	v_mul_f32_e64 v3, |v3|, s30
	v_exp_f32_e32 v3, v3
	s_nop 0
	v_add_f32_e32 v6, 1.0, v3
	v_add_f32_e32 v4, -1.0, v6
	v_sub_f32_e32 v5, v4, v6
	v_add_f32_e32 v5, 1.0, v5
	v_sub_f32_e32 v4, v3, v4
	v_add_f32_e32 v7, v4, v5
	v_frexp_mant_f32_e32 v4, v6
	v_cmp_gt_f32_e32 vcc, s31, v4
	v_cvt_f64_f32_e32 v[4:5], v6
	v_frexp_exp_i32_f64_e32 v4, v[4:5]
	v_subbrev_co_u32_e32 v4, vcc, 0, v4, vcc
	v_sub_u32_e32 v5, 0, v4
	v_ldexp_f32 v6, v6, v5
	v_ldexp_f32 v5, v7, v5
	v_add_f32_e32 v7, -1.0, v6
	v_add_f32_e32 v8, 1.0, v7
	v_sub_f32_e32 v8, v6, v8
	v_add_f32_e32 v8, v5, v8
	v_add_f32_e32 v9, v7, v8
	v_sub_f32_e32 v7, v9, v7
	v_sub_f32_e32 v7, v8, v7
	v_add_f32_e32 v8, 1.0, v6
	v_add_f32_e32 v10, -1.0, v8
	v_sub_f32_e32 v6, v6, v10
	v_add_f32_e32 v5, v5, v6
	v_add_f32_e32 v6, v8, v5
	v_sub_f32_e32 v8, v6, v8
	v_sub_f32_e32 v5, v5, v8
	v_rcp_f32_e32 v8, v6
	v_cvt_f32_i32_e32 v4, v4
	v_cmp_neq_f32_e32 vcc, s35, v3
	v_mul_f32_e32 v10, v9, v8
	v_mul_f32_e32 v11, v6, v10
	v_fma_f32 v12, v10, v6, -v11
	v_fmac_f32_e32 v12, v10, v5
	v_add_f32_e32 v13, v11, v12
	v_sub_f32_e32 v14, v9, v13
	v_sub_f32_e32 v9, v9, v14
	v_sub_f32_e32 v11, v13, v11
	v_sub_f32_e32 v9, v9, v13
	v_add_f32_e32 v7, v7, v9
	v_sub_f32_e32 v9, v11, v12
	v_add_f32_e32 v7, v9, v7
	v_add_f32_e32 v9, v14, v7
	v_mul_f32_e32 v11, v8, v9
	v_mul_f32_e32 v12, v6, v11
	v_fma_f32 v6, v11, v6, -v12
	v_fmac_f32_e32 v6, v11, v5
	v_sub_f32_e32 v5, v14, v9
	v_add_f32_e32 v5, v7, v5
	v_add_f32_e32 v7, v12, v6
	v_sub_f32_e32 v13, v9, v7
	v_sub_f32_e32 v9, v9, v13
	v_sub_f32_e32 v12, v7, v12
	v_sub_f32_e32 v7, v9, v7
	v_add_f32_e32 v5, v5, v7
	v_sub_f32_e32 v6, v12, v6
	v_add_f32_e32 v5, v6, v5
	v_add_f32_e32 v6, v10, v11
	v_add_f32_e32 v5, v13, v5
	v_sub_f32_e32 v7, v6, v10
	v_mul_f32_e32 v5, v8, v5
	v_sub_f32_e32 v7, v11, v7
	v_add_f32_e32 v5, v7, v5
	v_mul_f32_e32 v10, 0x3f317218, v4
	v_add_f32_e32 v7, v6, v5
	v_fma_f32 v11, v4, s34, -v10
	v_mul_f32_e32 v8, v7, v7
	v_fmac_f32_e32 v11, 0xb102e308, v4
	v_sub_f32_e32 v4, v7, v6
	v_fmamk_f32 v9, v8, 0x3e9b6dac, v184
	v_sub_f32_e32 v4, v5, v4
	v_add_f32_e32 v5, v10, v11
	v_fmaak_f32 v9, v8, v9, 0x3f2aaada
	v_sub_f32_e32 v6, v5, v10
	v_ldexp_f32 v10, v7, 1
	v_mul_f32_e32 v7, v7, v8
	v_mul_f32_e32 v7, v7, v9
	v_add_f32_e32 v8, v10, v7
	v_sub_f32_e32 v9, v8, v10
	v_ldexp_f32 v4, v4, 1
	v_sub_f32_e32 v7, v7, v9
	v_add_f32_e32 v4, v4, v7
	v_add_f32_e32 v7, v8, v4
	v_sub_f32_e32 v8, v7, v8
	v_sub_f32_e32 v4, v4, v8
	v_add_f32_e32 v8, v5, v7
	v_sub_f32_e32 v9, v8, v5
	v_sub_f32_e32 v10, v8, v9
	v_sub_f32_e32 v6, v11, v6
	v_sub_f32_e32 v5, v5, v10
	v_sub_f32_e32 v7, v7, v9
	v_add_f32_e32 v5, v7, v5
	v_add_f32_e32 v7, v6, v4
	v_sub_f32_e32 v9, v7, v6
	v_sub_f32_e32 v10, v7, v9
	v_sub_f32_e32 v6, v6, v10
	v_sub_f32_e32 v4, v4, v9
	v_add_f32_e32 v5, v7, v5
	v_add_f32_e32 v4, v4, v6
	v_add_f32_e32 v6, v8, v5
	v_sub_f32_e32 v7, v6, v8
	v_sub_f32_e32 v5, v5, v7
	v_add_f32_e32 v4, v4, v5
	v_add_f32_e32 v4, v6, v4
	v_cndmask_b32_e32 v4, v185, v4, vcc
	v_cmp_ngt_f32_e32 vcc, -1.0, v3
	s_nop 1
	v_cndmask_b32_e32 v4, v186, v4, vcc
	v_cmp_neq_f32_e32 vcc, -1.0, v3
	s_nop 1
	v_cndmask_b32_e32 v4, v187, v4, vcc
	v_cmp_lt_f32_e64 vcc, |v3|, s36
	s_nop 1
	v_cndmask_b32_e32 v3, v4, v3, vcc
	v_add_f32_e32 v2, v2, v3
	v_sub_f32_e32 v2, -0.5, v2
	v_mul_f32_e32 v2, 0x3fb8aa3b, v2
	v_exp_f32_e32 v2, v2
	s_nop 0
	v_xor_b32_e32 v4, 0x80000000, v2
	v_lshl_add_u64 v[2:3], s[16:17], 0, v[48:49]
	v_lshl_add_u64 v[2:3], v[2:3], 0, v[50:51]
	global_store_dword v[2:3], v4, off
	v_mov_b32_e32 v2, v241
	v_add_f32_e32 v3, v17, v2
	v_max_f32_e64 v2, -v3, 0
	v_mul_f32_e64 v3, |v3|, s30
	v_exp_f32_e32 v3, v3
	s_nop 0
	v_add_f32_e32 v6, 1.0, v3
	v_add_f32_e32 v4, -1.0, v6
	v_sub_f32_e32 v5, v4, v6
	v_add_f32_e32 v5, 1.0, v5
	v_sub_f32_e32 v4, v3, v4
	v_add_f32_e32 v7, v4, v5
	v_frexp_mant_f32_e32 v4, v6
	v_cmp_gt_f32_e32 vcc, s31, v4
	v_cvt_f64_f32_e32 v[4:5], v6
	v_frexp_exp_i32_f64_e32 v4, v[4:5]
	v_subbrev_co_u32_e32 v4, vcc, 0, v4, vcc
	v_sub_u32_e32 v5, 0, v4
	v_ldexp_f32 v6, v6, v5
	v_ldexp_f32 v5, v7, v5
	v_add_f32_e32 v7, -1.0, v6
	v_add_f32_e32 v8, 1.0, v7
	v_sub_f32_e32 v8, v6, v8
	v_add_f32_e32 v8, v5, v8
	v_add_f32_e32 v9, v7, v8
	v_sub_f32_e32 v7, v9, v7
	v_sub_f32_e32 v7, v8, v7
	v_add_f32_e32 v8, 1.0, v6
	v_add_f32_e32 v10, -1.0, v8
	v_sub_f32_e32 v6, v6, v10
	v_add_f32_e32 v5, v5, v6
	v_add_f32_e32 v6, v8, v5
	v_sub_f32_e32 v8, v6, v8
	v_sub_f32_e32 v5, v5, v8
	v_rcp_f32_e32 v8, v6
	v_cvt_f32_i32_e32 v4, v4
	v_cmp_neq_f32_e32 vcc, s35, v3
	v_mul_f32_e32 v10, v9, v8
	v_mul_f32_e32 v11, v6, v10
	v_fma_f32 v12, v10, v6, -v11
	v_fmac_f32_e32 v12, v10, v5
	v_add_f32_e32 v13, v11, v12
	v_sub_f32_e32 v14, v9, v13
	v_sub_f32_e32 v9, v9, v14
	v_sub_f32_e32 v11, v13, v11
	v_sub_f32_e32 v9, v9, v13
	v_add_f32_e32 v7, v7, v9
	v_sub_f32_e32 v9, v11, v12
	v_add_f32_e32 v7, v9, v7
	v_add_f32_e32 v9, v14, v7
	v_mul_f32_e32 v11, v8, v9
	v_mul_f32_e32 v12, v6, v11
	v_fma_f32 v6, v11, v6, -v12
	v_fmac_f32_e32 v6, v11, v5
	v_sub_f32_e32 v5, v14, v9
	v_add_f32_e32 v5, v7, v5
	v_add_f32_e32 v7, v12, v6
	v_sub_f32_e32 v13, v9, v7
	v_sub_f32_e32 v9, v9, v13
	v_sub_f32_e32 v12, v7, v12
	v_sub_f32_e32 v7, v9, v7
	v_add_f32_e32 v5, v5, v7
	v_sub_f32_e32 v6, v12, v6
	v_add_f32_e32 v5, v6, v5
	v_add_f32_e32 v6, v10, v11
	v_add_f32_e32 v5, v13, v5
	v_sub_f32_e32 v7, v6, v10
	v_mul_f32_e32 v5, v8, v5
	v_sub_f32_e32 v7, v11, v7
	v_add_f32_e32 v5, v7, v5
	v_mul_f32_e32 v10, 0x3f317218, v4
	v_add_f32_e32 v7, v6, v5
	v_fma_f32 v11, v4, s34, -v10
	v_mul_f32_e32 v8, v7, v7
	v_fmac_f32_e32 v11, 0xb102e308, v4
	v_sub_f32_e32 v4, v7, v6
	v_fmamk_f32 v9, v8, 0x3e9b6dac, v184
	v_sub_f32_e32 v4, v5, v4
	v_add_f32_e32 v5, v10, v11
	v_fmaak_f32 v9, v8, v9, 0x3f2aaada
	v_sub_f32_e32 v6, v5, v10
	v_ldexp_f32 v10, v7, 1
	v_mul_f32_e32 v7, v7, v8
	v_mul_f32_e32 v7, v7, v9
	v_add_f32_e32 v8, v10, v7
	v_sub_f32_e32 v9, v8, v10
	v_ldexp_f32 v4, v4, 1
	v_sub_f32_e32 v7, v7, v9
	v_add_f32_e32 v4, v4, v7
	v_add_f32_e32 v7, v8, v4
	v_sub_f32_e32 v8, v7, v8
	v_sub_f32_e32 v4, v4, v8
	v_add_f32_e32 v8, v5, v7
	v_sub_f32_e32 v9, v8, v5
	v_sub_f32_e32 v10, v8, v9
	v_sub_f32_e32 v6, v11, v6
	v_sub_f32_e32 v5, v5, v10
	v_sub_f32_e32 v7, v7, v9
	v_add_f32_e32 v5, v7, v5
	v_add_f32_e32 v7, v6, v4
	v_sub_f32_e32 v9, v7, v6
	v_sub_f32_e32 v10, v7, v9
	v_sub_f32_e32 v6, v6, v10
	v_sub_f32_e32 v4, v4, v9
	v_add_f32_e32 v5, v7, v5
	v_add_f32_e32 v4, v4, v6
	v_add_f32_e32 v6, v8, v5
	v_sub_f32_e32 v7, v6, v8
	v_sub_f32_e32 v5, v5, v7
	v_add_f32_e32 v4, v4, v5
	v_add_f32_e32 v4, v6, v4
	v_cndmask_b32_e32 v4, v185, v4, vcc
	v_cmp_ngt_f32_e32 vcc, -1.0, v3
	s_nop 1
	v_cndmask_b32_e32 v4, v186, v4, vcc
	v_cmp_neq_f32_e32 vcc, -1.0, v3
	s_nop 1
	v_cndmask_b32_e32 v4, v187, v4, vcc
	v_cmp_lt_f32_e64 vcc, |v3|, s36
	s_nop 1
	v_cndmask_b32_e32 v3, v4, v3, vcc
	v_add_f32_e32 v2, v2, v3
	v_sub_f32_e32 v2, -0.5, v2
	v_mul_f32_e32 v2, 0x3fb8aa3b, v2
	v_exp_f32_e32 v2, v2
	s_nop 0
	v_xor_b32_e32 v4, 0x80000000, v2
	v_lshl_add_u64 v[2:3], s[16:17], 0, v[32:33]
	v_lshl_add_u64 v[2:3], v[2:3], 0, v[50:51]
	global_store_dword v[2:3], v4, off

.LBB0_998:
	s_or_b64 exec, exec, s[2:3]
	s_waitcnt vmcnt(0)
	s_mov_b64 s[2:3], exec
	s_andn2_b64 exec, exec, s[82:83]
	v_lshlrev_b32_e32 v4, 16, v176
	v_lshlrev_b32_e32 v23, 16, v177
	v_lshlrev_b32_e32 v87, 16, v178
	v_cvt_pk_bf16_f32 v84, v23, s0
	v_lshlrev_b32_e32 v92, 16, v180
	v_mov_b32_e32 v26, v177
	v_mov_b32_e32 v24, v178
	v_mov_b32_e32 v86, v179
	v_mov_b32_e32 v22, v180
	v_lshlrev_b32_e32 v5, 16, v181
	v_lshlrev_b32_e32 v23, 16, v182
	v_lshlrev_b32_e32 v83, 16, v183
	v_cvt_pk_bf16_f32 v80, v23, s0
	v_lshlrev_b32_e32 v91, 16, v185
	v_mov_b32_e32 v26, v182
	v_mov_b32_e32 v24, v183
	v_mov_b32_e32 v82, v184
	v_mov_b32_e32 v22, v185
	v_lshlrev_b32_e32 v6, 16, v186
	v_lshlrev_b32_e32 v23, 16, v187
	v_lshlrev_b32_e32 v79, 16, v188
	v_cvt_pk_bf16_f32 v76, v23, s0
	v_lshlrev_b32_e32 v89, 16, v190
	v_mov_b32_e32 v26, v187
	v_mov_b32_e32 v24, v188
	v_mov_b32_e32 v78, v189
	v_mov_b32_e32 v22, v190
	v_lshlrev_b32_e32 v7, 16, v191
	v_lshlrev_b32_e32 v23, 16, v192
	v_lshlrev_b32_e32 v75, 16, v193
	v_cvt_pk_bf16_f32 v72, v23, s0
	v_lshlrev_b32_e32 v85, 16, v195
	v_mov_b32_e32 v26, v192
	v_mov_b32_e32 v24, v193
	v_mov_b32_e32 v74, v194
	v_mov_b32_e32 v22, v195
	v_lshlrev_b32_e32 v8, 16, v196
	v_lshlrev_b32_e32 v23, 16, v197
	v_lshlrev_b32_e32 v70, 16, v198
	v_cvt_pk_bf16_f32 v68, v23, s0
	v_lshlrev_b32_e32 v81, 16, v200
	v_mov_b32_e32 v26, v197
	v_mov_b32_e32 v24, v198
	v_mov_b32_e32 v69, v199
	v_mov_b32_e32 v22, v200
	v_lshlrev_b32_e32 v9, 16, v201
	v_lshlrev_b32_e32 v23, 16, v202
	v_lshlrev_b32_e32 v49, 16, v203
	v_cvt_pk_bf16_f32 v45, v23, s0
	v_lshlrev_b32_e32 v77, 16, v205
	v_mov_b32_e32 v26, v202
	v_mov_b32_e32 v24, v203
	v_mov_b32_e32 v48, v204
	v_mov_b32_e32 v22, v205
	v_lshlrev_b32_e32 v10, 16, v206
	v_lshlrev_b32_e32 v23, 16, v207
	v_lshlrev_b32_e32 v43, 16, v208
	v_cvt_pk_bf16_f32 v40, v23, s0
	v_lshlrev_b32_e32 v73, 16, v210
	v_mov_b32_e32 v26, v207
	v_mov_b32_e32 v24, v208
	v_mov_b32_e32 v42, v209
	v_mov_b32_e32 v22, v210
	v_lshlrev_b32_e32 v11, 16, v211
	v_lshlrev_b32_e32 v22, 16, v212
	v_cvt_pk_bf16_f32 v37, v22, s0
	v_lshlrev_b32_e32 v41, 16, v213
	v_lshlrev_b32_e32 v71, 16, v214
	v_mov_b32_e32 v28, v212
	v_mov_b32_e32 v24, v213
	v_mov_b32_e32 v25, v214
	v_mov_b32_e32 v39, v215
	v_lshlrev_b32_e32 v12, 16, v216
	v_lshlrev_b32_e32 v23, 16, v217
	v_lshlrev_b32_e32 v36, 16, v218
	v_cvt_pk_bf16_f32 v33, v23, s0
	v_lshlrev_b32_e32 v67, 16, v220
	v_mov_b32_e32 v26, v217
	v_mov_b32_e32 v24, v218
	v_mov_b32_e32 v35, v219
	v_mov_b32_e32 v22, v220
	v_lshlrev_b32_e32 v13, 16, v221
	v_lshlrev_b32_e32 v23, 16, v222
	v_lshlrev_b32_e32 v32, 16, v223
	v_cvt_pk_bf16_f32 v28, v23, s0
	v_lshlrev_b32_e32 v44, 16, v225
	v_mov_b32_e32 v26, v222
	v_mov_b32_e32 v24, v223
	v_mov_b32_e32 v31, v224
	v_mov_b32_e32 v22, v225
	v_lshlrev_b32_e32 v14, 16, v226
	v_lshlrev_b32_e32 v23, 16, v227
	v_lshlrev_b32_e32 v27, 16, v228
	v_cvt_pk_bf16_f32 v25, v23, s0
	v_lshlrev_b32_e32 v38, 16, v230
	v_mov_b32_e32 v24, v228
	v_mov_b32_e32 v26, v229
	v_mov_b32_e32 v22, v230
	v_lshlrev_b32_e32 v15, 16, v231
	v_lshlrev_b32_e32 v19, 16, v232
	v_lshlrev_b32_e32 v24, 16, v233
	v_cvt_pk_bf16_f32 v22, v19, s0
	v_lshlrev_b32_e32 v34, 16, v235
	v_mov_b32_e32 v23, v234
	v_mov_b32_e32 v18, v235
	s_mov_b64 exec, s[2:3]
	v_and_b32_e32 v254, 63, v0
	v_lshlrev_b32_e32 v255, 3, v254
	v_lshlrev_b32_e32 v254, 6, v254
	v_readfirstlane_b32 s94, v120
	s_nop 1
	s_sub_u32 s32, s94, 0x800
	s_cmp_lt_u32 s32, 0x4000
	s_cbranch_scc0 .Lp3tab_noconv
	v_max_f32_e64 v176, |v236|, |v237|
	v_max3_f32 v176, |v238|, |v239|, v176
	v_max3_f32 v176, |v240|, |v241|, v176
	v_max3_f32 v176, |v242|, |v243|, v176
	v_max3_f32 v176, |v246|, |v247|, v176
	v_max3_f32 v176, |v248|, |v249|, v176
	v_max3_f32 v176, |v250|, |v251|, v176
	v_max3_f32 v176, |v252|, |v253|, v176
	s_nop 1
	v_mov_b32_dpp v177, v176 quad_perm:[1,0,3,2] row_mask:0xf bank_mask:0xf bound_ctrl:1
	v_max_f32_e32 v177, v177, v177
	v_max_f32_e32 v176, v176, v177
	s_nop 1
	v_mov_b32_dpp v177, v176 quad_perm:[2,3,0,1] row_mask:0xf bank_mask:0xf bound_ctrl:1
	v_max_f32_e32 v177, v177, v177
	v_max_f32_e32 v176, v176, v177
	s_nop 1
	v_mov_b32_dpp v177, v176 row_half_mirror row_mask:0xf bank_mask:0xf bound_ctrl:1
	v_max_f32_e32 v177, v177, v177
	v_max_f32_e32 v176, v176, v177
	s_nop 1
	v_mov_b32_dpp v177, v176 row_mirror row_mask:0xf bank_mask:0xf bound_ctrl:1
	v_max_f32_e32 v177, v177, v177
	v_max_f32_e32 v176, v176, v177
	s_nop 0
	v_readlane_b32 s98, v176, 32
	v_readlane_b32 s99, v176, 48
	v_readlane_b32 s100, v176, 0
	v_readlane_b32 s101, v176, 16
	s_nop 1
	v_max_f32_e64 v176, s99, s99
	v_max_f32_e64 v177, s98, s98
	v_mov_b32_e32 v182, s101
	v_max_f32_e32 v176, v177, v176
	v_max3_f32 v176, s100, v182, v176
	v_mov_b32_e32 v188, 0x40c00000
	v_div_scale_f32 v179, s[98:99], v176, v176, v188
	v_rcp_f32_e32 v180, v179
	v_div_scale_f32 v181, vcc, v188, v176, v188
	v_fma_f32 v182, -v179, v180, 1.0
	v_fmac_f32_e32 v180, v182, v180
	v_mul_f32_e32 v183, v181, v180
	v_fma_f32 v182, -v179, v183, v181
	v_fmac_f32_e32 v183, v182, v180
	v_fma_f32 v182, -v179, v183, v181
	v_div_fmas_f32 v178, v182, v180, v183
	v_div_fixup_f32 v178, v178, v176, v188
	v_cmp_lt_f32_e32 vcc, 0, v176
	v_mov_b32_e32 v186, 0
	v_mov_b32_e32 v187, 0
	v_cndmask_b32_e32 v178, 0, v178, vcc
	v_mul_f32_e32 v184, 0x3e2aaaab, v176
	v_mul_f32_e32 v236, v236, v178
	v_mul_f32_e32 v237, v237, v178
	v_mul_f32_e32 v238, v238, v178
	v_mul_f32_e32 v239, v239, v178
	v_mul_f32_e32 v240, v240, v178
	v_mul_f32_e32 v241, v241, v178
	v_mul_f32_e32 v242, v242, v178
	v_mul_f32_e32 v243, v243, v178
	v_mul_f32_e32 v246, v246, v178
	v_mul_f32_e32 v247, v247, v178
	v_mul_f32_e32 v248, v248, v178
	v_mul_f32_e32 v249, v249, v178
	v_mul_f32_e32 v250, v250, v178
	v_mul_f32_e32 v251, v251, v178
	v_mul_f32_e32 v252, v252, v178
	v_mul_f32_e32 v253, v253, v178
	v_cvt_scalef32_pk_fp4_f32 v186, v236, v237, 1.0
	v_cvt_scalef32_pk_fp4_f32 v187, v246, v247, 1.0
	v_cvt_scalef32_pk_fp4_f32 v186, v238, v239, 1.0 op_sel:[0,0,1,0]
	v_cvt_scalef32_pk_fp4_f32 v187, v248, v249, 1.0 op_sel:[0,0,1,0]
	v_cvt_scalef32_pk_fp4_f32 v186, v240, v241, 1.0 op_sel:[0,0,0,1]
	v_cvt_scalef32_pk_fp4_f32 v187, v250, v251, 1.0 op_sel:[0,0,0,1]
	v_cvt_scalef32_pk_fp4_f32 v186, v242, v243, 1.0 op_sel:[0,0,1,1]
	v_cvt_scalef32_pk_fp4_f32 v187, v252, v253, 1.0 op_sel:[0,0,1,1]
	v_mov_b32_e32 v185, 0
	v_readlane_b32 s100, v244, 28
	v_readlane_b32 s101, v244, 29
	s_lshl_b32 s94, s32, 9
	s_nop 0
	s_add_u32 s100, s100, 0x4280000
	s_addc_u32 s101, s101, 0
	s_add_u32 s94, s100, s94
	s_addc_u32 s95, s101, 0
	global_store_dwordx2 v255, v[186:187], s[94:95]
	s_lshl_b32 s94, s32, 2
	s_add_u32 s100, s100, 0x6090800
	s_addc_u32 s101, s101, 0
	s_add_u32 s94, s100, s94
	s_addc_u32 s95, s101, 0
	s_mov_b64 s[98:99], exec
	s_mov_b64 exec, 1
	global_store_dword v185, v184, s[94:95]
	s_mov_b64 exec, s[98:99]
.Lp3tab_noconv:
	v_readfirstlane_b32 s94, v120
	s_nop 1
	s_cmp_lt_u32 s94, 0x4000
	s_cbranch_scc0 .Lp3tab_noload
	v_readlane_b32 s98, v244, 22
	v_readlane_b32 s99, v244, 23
	s_lshl_b32 s94, s94, 12
	s_nop 0
	s_add_u32 s94, s98, s94
	s_addc_u32 s95, s99, 0
	global_load_dwordx4 v[236:239], v254, s[94:95] nt
	global_load_dwordx4 v[240:243], v254, s[94:95] offset:16 nt
	global_load_dwordx4 v[246:249], v254, s[94:95] offset:32 nt
	global_load_dwordx4 v[250:253], v254, s[94:95] offset:48 nt
.Lp3tab_noload:
	v_lshlrev_b32_e32 v103, 16, v101
	v_lshlrev_b32_e32 v50, 2, v63
	v_lshl_add_u64 v[18:19], s[72:73], 0, v[50:51]
	v_mul_f32_e32 v50, v21, v103
	v_lshlrev_b32_e32 v101, 16, v102
	v_mul_f32_e32 v102, v50, v50
	s_nop 1
	v_mov_b32_dpp v102, v102 quad_perm:[1,0,3,2] row_mask:0xf bank_mask:0xf bound_ctrl:1
	v_fmac_f32_e32 v102, v50, v50
	s_nop 1
	v_add_f32_dpp v102, v102, v102 quad_perm:[2,3,0,1] row_mask:0xf bank_mask:0xf bound_ctrl:1
	s_nop 1
	v_add_f32_dpp v102, v102, v102 row_half_mirror row_mask:0xf bank_mask:0xf bound_ctrl:1
	s_nop 1
	v_add_f32_dpp v102, v102, v102 row_mirror row_mask:0xf bank_mask:0xf bound_ctrl:1
	s_nop 0
	v_readlane_b32 s33, v102, 0
	v_readlane_b32 s85, v102, 16
	v_readlane_b32 s84, v102, 32
	v_readlane_b32 s89, v102, 48
	v_add_f32_e32 v102, -1.0, v101
	v_fma_f32 v102, v20, v102, 1.0
	v_mul_f32_e32 v102, v102, v103
	v_mul_f32_e32 v103, v102, v16
	v_mul_f32_e32 v104, v17, v103
	s_nop 1
	v_mov_b32_dpp v104, v104 quad_perm:[1,0,3,2] row_mask:0xf bank_mask:0xf bound_ctrl:1
	v_fmac_f32_e32 v104, v17, v103
	s_nop 1
	v_add_f32_dpp v103, v104, v104 quad_perm:[2,3,0,1] row_mask:0xf bank_mask:0xf bound_ctrl:1
	v_lshlrev_b64 v[104:105], 6, v[64:65]
	v_lshl_add_u64 v[18:19], v[18:19], 0, v[104:105]
	v_add_f32_dpp v103, v103, v103 row_half_mirror row_mask:0xf bank_mask:0xf bound_ctrl:1
	s_nop 1
	v_add_f32_dpp v103, v103, v103 row_mirror row_mask:0xf bank_mask:0xf bound_ctrl:1
	s_nop 0
	v_readlane_b32 s2, v103, 0
	v_readlane_b32 s90, v103, 16
	v_readlane_b32 s3, v103, 32
	v_readlane_b32 s91, v103, 48
	s_and_saveexec_b64 s[48:49], s[0:1]
	s_cbranch_execz .LBB0_1000
	v_mov_b32_e32 v104, s90
	v_mov_b32_e32 v105, s91
	v_pk_add_f32 v[104:105], s[2:3], v[104:105]
	s_nop 0
	v_add_f32_e32 v103, v104, v105
	global_store_dword v[18:19], v103, off

.LBB0_1004:
	s_or_b64 exec, exec, s[2:3]
	v_mov_b32_e32 v50, s85
	v_mov_b32_e32 v100, s89
	v_add_f32_e32 v50, s33, v50
	v_add_f32_e32 v100, s84, v100
	v_add_f32_e32 v50, v50, v100
	v_mul_f32_e32 v100, 0x4f800000, v50
	v_cmp_gt_f32_e32 vcc, s88, v50
	v_lshlrev_b32_e32 v96, 16, v96
	v_lshlrev_b32_e32 v95, 16, v95
	v_cndmask_b32_e32 v50, v50, v100, vcc
	v_sqrt_f32_e32 v100, v50
	s_nop 0
	v_add_u32_e32 v101, -1, v100
	v_fma_f32 v102, -v101, v100, v50
	v_cmp_ge_f32_e64 s[48:49], 0, v102
	v_add_u32_e32 v102, 1, v100
	s_nop 0
	v_cndmask_b32_e64 v101, v100, v101, s[48:49]
	v_fma_f32 v100, -v102, v100, v50
	v_cmp_lt_f32_e64 s[48:49], 0, v100
	s_nop 1
	v_cndmask_b32_e64 v100, v101, v102, s[48:49]
	v_mul_f32_e32 v101, 0x37800000, v100
	v_cndmask_b32_e32 v100, v100, v101, vcc
	v_cmp_class_f32_e32 vcc, v50, v155
	s_nop 1
	v_cndmask_b32_e32 v50, v100, v50, vcc
	v_max_f32_e32 v50, 0x2b8cbccc, v50
	v_div_scale_f32 v100, s[2:3], v50, v50, v1
	v_rcp_f32_e32 v101, v100
	s_nop 0
	v_fma_f32 v102, -v100, v101, 1.0
	v_fmac_f32_e32 v101, v102, v101
	v_div_scale_f32 v102, vcc, v1, v50, v1
	v_mul_f32_e32 v103, v102, v101
	v_fma_f32 v104, -v100, v103, v102
	v_fmac_f32_e32 v103, v104, v101
	v_fma_f32 v100, -v100, v103, v102
	v_div_fmas_f32 v100, v100, v101, v103
	v_div_fixup_f32 v100, v100, v50, v1
	v_mul_f32_e32 v1, v100, v98
	v_lshlrev_b32_e32 v98, 16, v94
	v_add_f32_e32 v94, v97, v93
	v_mul_f32_e32 v50, 0xbfb8aa3b, v94
	v_exp_f32_e32 v97, v50
	v_mul_f32_e32 v50, 0x3fb8aa3b, v94
	v_exp_f32_e32 v93, v50
	v_mul_f32_e32 v16, v16, v100
	v_mul_f32_e32 v50, v97, v1
	v_mul_f32_e32 v1, v97, v99
	v_mul_f32_e32 v2, v93, v2
	v_cvt_pk_bf16_f32 v2, v2, s0
	ds_write_b16 v126, v2 offset:2592
	v_cvt_pk_bf16_f32 v2, v50, s0
	ds_write_b16 v126, v2 offset:4896
	v_cvt_pk_bf16_f32 v2, v1, s0
	ds_write_b16 v126, v2 offset:7200
	v_cvt_pk_bf16_f32 v2, v98, s0
	v_cvt_pk_bf16_f32 v16, v16, s0
	ds_write_b16 v126, v2 offset:13728
	v_mul_f32_e32 v2, v21, v96
	ds_write_b16 v126, v16 offset:288
	v_mul_f32_e32 v16, v2, v2
	s_nop 1
	v_mov_b32_dpp v16, v16 quad_perm:[1,0,3,2] row_mask:0xf bank_mask:0xf bound_ctrl:1
	v_fmac_f32_e32 v16, v2, v2
	s_nop 1
	v_add_f32_dpp v16, v16, v16 quad_perm:[2,3,0,1] row_mask:0xf bank_mask:0xf bound_ctrl:1
	s_nop 1
	v_add_f32_dpp v16, v16, v16 row_half_mirror row_mask:0xf bank_mask:0xf bound_ctrl:1
	s_nop 1
	v_add_f32_dpp v16, v16, v16 row_mirror row_mask:0xf bank_mask:0xf bound_ctrl:1
	s_nop 0
	v_readlane_b32 s33, v16, 0
	v_readlane_b32 s85, v16, 16
	v_readlane_b32 s84, v16, 32
	v_readlane_b32 s89, v16, 48
	v_add_f32_e32 v16, -1.0, v95
	v_fma_f32 v16, v20, v16, 1.0
	v_mul_f32_e32 v96, v16, v96
	v_mul_f32_e32 v16, v96, v3
	v_mul_f32_e32 v97, v17, v16
	s_nop 1
	v_mov_b32_dpp v97, v97 quad_perm:[1,0,3,2] row_mask:0xf bank_mask:0xf bound_ctrl:1
	v_fmac_f32_e32 v97, v17, v16
	s_nop 1
	v_add_f32_dpp v16, v97, v97 quad_perm:[2,3,0,1] row_mask:0xf bank_mask:0xf bound_ctrl:1
	s_nop 1
	v_add_f32_dpp v16, v16, v16 row_half_mirror row_mask:0xf bank_mask:0xf bound_ctrl:1
	s_nop 1
	v_add_f32_dpp v16, v16, v16 row_mirror row_mask:0xf bank_mask:0xf bound_ctrl:1
	s_nop 0
	v_readlane_b32 s48, v16, 0
	v_readlane_b32 s90, v16, 16
	v_readlane_b32 s49, v16, 32
	v_readlane_b32 s91, v16, 48
	s_and_saveexec_b64 s[2:3], s[0:1]
	s_cbranch_execz .LBB0_1006
	v_mov_b32_e32 v98, s90
	v_mov_b32_e32 v99, s91
	v_pk_add_f32 v[98:99], s[48:49], v[98:99]
	s_nop 0
	v_add_f32_e32 v16, v98, v99
	global_store_dword v[18:19], v16, off offset:192
.LBB0_1006:
	s_or_b64 exec, exec, s[2:3]
	v_mov_b32_e32 v16, s85
	v_mov_b32_e32 v97, s89
	v_add_f32_e32 v16, s33, v16
	v_add_f32_e32 v97, s84, v97
	v_add_f32_e32 v16, v16, v97
	v_mul_f32_e32 v97, 0x4f800000, v16
	v_cmp_gt_f32_e32 vcc, s88, v16
	s_nop 1
	v_cndmask_b32_e32 v16, v16, v97, vcc
	v_sqrt_f32_e32 v97, v16
	s_nop 0
	v_add_u32_e32 v98, -1, v97
	v_fma_f32 v99, -v98, v97, v16
	v_cmp_ge_f32_e64 s[48:49], 0, v99
	v_add_u32_e32 v99, 1, v97
	s_nop 0
	v_cndmask_b32_e64 v98, v97, v98, s[48:49]
	v_fma_f32 v97, -v99, v97, v16
	v_cmp_lt_f32_e64 s[48:49], 0, v97
	s_nop 1
	v_cndmask_b32_e64 v97, v98, v99, s[48:49]
	v_mul_f32_e32 v98, 0x37800000, v97
	v_cndmask_b32_e32 v97, v97, v98, vcc
	v_cmp_class_f32_e32 vcc, v16, v155
	s_nop 1
	v_cndmask_b32_e32 v16, v97, v16, vcc
	v_max_f32_e32 v16, 0x2b8cbccc, v16
	v_div_scale_f32 v97, s[2:3], v16, v16, v2
	v_rcp_f32_e32 v98, v97
	s_and_b64 s[2:3], s[0:1], s[78:79]
	v_fma_f32 v99, -v97, v98, 1.0
	v_fmac_f32_e32 v98, v99, v98
	v_div_scale_f32 v99, vcc, v2, v16, v2
	v_mul_f32_e32 v100, v99, v98
	v_fma_f32 v101, -v97, v100, v99
	v_fmac_f32_e32 v100, v101, v98
	v_fma_f32 v97, -v97, v100, v99
	v_div_fmas_f32 v97, v97, v98, v100
	v_div_fixup_f32 v97, v97, v16, v2
	v_add_f32_e32 v16, v94, v90
	v_mul_f32_e32 v2, 0xbfb8aa3b, v16
	v_exp_f32_e32 v94, v2
	v_mul_f32_e32 v2, 0x3fb8aa3b, v16
	v_exp_f32_e32 v2, v2
	v_mul_f32_e32 v95, v97, v95
	v_mul_f32_e32 v90, v94, v95
	v_lshlrev_b32_e32 v98, 16, v88
	v_mul_f32_e32 v3, v2, v3
	v_cvt_pk_bf16_f32 v3, v3, s0
	v_mul_f32_e32 v88, v94, v96
	ds_write_b16 v126, v3 offset:2736
	v_cvt_pk_bf16_f32 v3, v90, s0
	ds_write_b16 v126, v3 offset:5040
	v_cvt_pk_bf16_f32 v3, v88, s0
	v_mul_f32_e32 v93, v93, v97
	ds_write_b16 v126, v3 offset:7344
	v_cvt_pk_bf16_f32 v3, v98, s0
	v_cvt_pk_bf16_f32 v93, v93, s0
	ds_write_b16 v126, v3 offset:13872
	v_mul_f32_e32 v3, v21, v92
	ds_write_b16 v126, v93 offset:432
	v_mul_f32_e32 v93, v3, v3
	s_nop 1
	v_mov_b32_dpp v93, v93 quad_perm:[1,0,3,2] row_mask:0xf bank_mask:0xf bound_ctrl:1
	v_fmac_f32_e32 v93, v3, v3
	s_nop 1
	v_add_f32_dpp v93, v93, v93 quad_perm:[2,3,0,1] row_mask:0xf bank_mask:0xf bound_ctrl:1
	s_nop 1
	v_add_f32_dpp v93, v93, v93 row_half_mirror row_mask:0xf bank_mask:0xf bound_ctrl:1
	s_nop 1
	v_add_f32_dpp v93, v93, v93 row_mirror row_mask:0xf bank_mask:0xf bound_ctrl:1
	s_nop 0
	v_readlane_b32 s33, v93, 0
	v_readlane_b32 s90, v93, 16
	v_readlane_b32 s89, v93, 32
	v_readlane_b32 s91, v93, 48
	v_add_f32_e32 v93, -1.0, v87
	v_fma_f32 v93, v20, v93, 1.0
	v_mul_f32_e32 v92, v92, v93
	v_mul_f32_e32 v93, v92, v4
	v_mul_f32_e32 v94, v17, v93
	s_nop 1
	v_mov_b32_dpp v94, v94 quad_perm:[1,0,3,2] row_mask:0xf bank_mask:0xf bound_ctrl:1
	v_fmac_f32_e32 v94, v17, v93
	s_nop 1
	v_add_f32_dpp v93, v94, v94 quad_perm:[2,3,0,1] row_mask:0xf bank_mask:0xf bound_ctrl:1
	s_nop 1
	v_add_f32_dpp v93, v93, v93 row_half_mirror row_mask:0xf bank_mask:0xf bound_ctrl:1
	s_nop 1
	v_add_f32_dpp v93, v93, v93 row_mirror row_mask:0xf bank_mask:0xf bound_ctrl:1
	s_nop 0
	v_readlane_b32 s48, v93, 0
	v_readlane_b32 s92, v93, 16
	v_readlane_b32 s49, v93, 32
	v_readlane_b32 s93, v93, 48
	s_and_saveexec_b64 s[84:85], s[2:3]
	s_cbranch_execz .LBB0_1008
	v_mov_b32_e32 v94, s92
	v_mov_b32_e32 v95, s93
	v_pk_add_f32 v[94:95], s[48:49], v[94:95]
	s_nop 0
	v_add_f32_e32 v93, v94, v95
	global_store_dword v[18:19], v93, off offset:256

.LBB0_1424:
	v_lshl_add_u32 v2, s10, 2, v2
	v_add_u32_e32 v2, 0x4000, v2
	s_mov_b32 s0, 0x8000
	v_cmp_gt_i32_e32 vcc, s0, v2
	s_and_saveexec_b64 s[4:5], vcc
	s_cbranch_execz .LBB0_1429
	v_ashrrev_i32_e32 v3, 31, v2
	s_waitcnt vmcnt(6)
	v_and_b32_e32 v1, 63, v26
	v_lshlrev_b64 v[8:9], 9, v[2:3]
	v_readlane_b32 s16, v245, 7
	s_lshl_b32 s6, s2, 2
	v_lshl_or_b32 v8, v1, 3, v8
	v_readlane_b32 s18, v245, 9
	v_lshlrev_b32_e32 v4, 2, v1
	v_mov_b32_e32 v5, 0
	v_lshl_add_u64 v[6:7], v[2:3], 2, s[82:83]
	s_mov_b64 s[8:9], 0xa310800
	s_ashr_i32 s7, s6, 31
	v_lshl_add_u64 v[8:9], s[82:83], 0, v[8:9]
	s_mov_b64 s[12:13], 0x4280000
	v_readlane_b32 s17, v245, 8
	s_lshl_b32 s3, s18, 12
	v_cmp_eq_u32_e64 s[0:1], 0, v1
	v_lshl_add_u64 v[6:7], v[6:7], 0, s[8:9]
	s_lshl_b64 s[8:9], s[6:7], 2
	v_lshl_add_u64 v[8:9], v[8:9], 0, s[12:13]
	s_lshl_b64 s[12:13], s[6:7], 9
	v_lshlrev_b32_e32 v1, 10, v2
	s_add_i32 s3, s3, 0xfff80000
	s_mov_b64 s[16:17], 0
	v_mov_b32_e32 v3, s79
	v_mov_b32_e32 v12, s77
	v_mov_b32_e32 v13, s78
	v_mov_b32_e32 v14, s76
	v_lshlrev_b32_e32 v10, 4, v4
	v_mov_b32_e32 v11, v5
	s_mov_b32 s7, 0x40c00000
	s_movk_i32 s11, 0x7fff
	v_readlane_b32 s19, v245, 10
	s_branch .LBB0_1427

	.amdhsa_kernel _Z14fwd_megakernel6Params
		.amdhsa_group_segment_fixed_size 73744
		.amdhsa_private_segment_fixed_size 0
		.amdhsa_kernarg_size 584
		.amdhsa_user_sgpr_count 2
		.amdhsa_user_sgpr_dispatch_ptr 0
		.amdhsa_user_sgpr_queue_ptr 0
		.amdhsa_user_sgpr_kernarg_segment_ptr 1
		.amdhsa_user_sgpr_dispatch_id 0
		.amdhsa_user_sgpr_kernarg_preload_length 0
		.amdhsa_user_sgpr_kernarg_preload_offset 0
		.amdhsa_user_sgpr_private_segment_size 0
		.amdhsa_uses_dynamic_stack 0
		.amdhsa_enable_private_segment 0
		.amdhsa_system_sgpr_workgroup_id_x 1
		.amdhsa_system_sgpr_workgroup_id_y 0
		.amdhsa_system_sgpr_workgroup_id_z 0
		.amdhsa_system_sgpr_workgroup_info 0
		.amdhsa_system_vgpr_workitem_id 2
		.amdhsa_next_free_vgpr 256
		.amdhsa_next_free_sgpr 102
		.amdhsa_accum_offset 256
		.amdhsa_reserve_vcc 1
		.amdhsa_float_round_mode_32 0
		.amdhsa_float_round_mode_16_64 0
		.amdhsa_float_denorm_mode_32 3
		.amdhsa_float_denorm_mode_16_64 3
		.amdhsa_dx10_clamp 1
		.amdhsa_ieee_mode 1
		.amdhsa_fp16_overflow 0
		.amdhsa_tg_split 0
		.amdhsa_exception_fp_ieee_invalid_op 0
		.amdhsa_exception_fp_denorm_src 0
		.amdhsa_exception_fp_ieee_div_zero 0
		.amdhsa_exception_fp_ieee_overflow 0
		.amdhsa_exception_fp_ieee_underflow 0
		.amdhsa_exception_fp_ieee_inexact 0
		.amdhsa_exception_int_div_zero 0
	.end_amdhsa_kernel

amdhsa.kernels:
  - .agpr_count:     0
    .args:
      - .offset:         0
        .size:           328
        .value_kind:     by_value
      - .offset:         328
        .size:           4
        .value_kind:     hidden_block_count_x
      - .offset:         332
        .size:           4
        .value_kind:     hidden_block_count_y
      - .offset:         336
        .size:           4
        .value_kind:     hidden_block_count_z
      - .offset:         340
        .size:           2
        .value_kind:     hidden_group_size_x
      - .offset:         342
        .size:           2
        .value_kind:     hidden_group_size_y
      - .offset:         344
        .size:           2
        .value_kind:     hidden_group_size_z
      - .offset:         346
        .size:           2
        .value_kind:     hidden_remainder_x
      - .offset:         348
        .size:           2
        .value_kind:     hidden_remainder_y
      - .offset:         350
        .size:           2
        .value_kind:     hidden_remainder_z
      - .offset:         368
        .size:           8
        .value_kind:     hidden_global_offset_x
      - .offset:         376
        .size:           8
        .value_kind:     hidden_global_offset_y
      - .offset:         384
        .size:           8
        .value_kind:     hidden_global_offset_z
      - .offset:         392
        .size:           2
        .value_kind:     hidden_grid_dims
      - .offset:         416
        .size:           8
        .value_kind:     hidden_multigrid_sync_arg
    .group_segment_fixed_size: 73744
    .kernarg_segment_align: 8
    .kernarg_segment_size: 584
    .language:       OpenCL C
    .language_version:
      - 2
      - 0
    .max_flat_workgroup_size: 256
    .name:           _Z14fwd_megakernel6Params
    .private_segment_fixed_size: 0
    .sgpr_count:     108
    .sgpr_spill_count: 127
    .symbol:         _Z14fwd_megakernel6Params.kd
    .uniform_work_group_size: 1
    .uses_dynamic_stack: false
    .vgpr_count:     256
    .vgpr_spill_count: 0
    .wavefront_size: 64
